# v27 + redundant second lgkmcnt(0) wait behind each K-loop phase barrier removed
# baseline (speedup 1.0000x reference)
.Lpeel_13:
	ds_read_b128 v[152:155], v149
	ds_read_b128 v[156:159], v149 offset:1024
	s_add_i32 s37, s25, 2
	s_add_u32 s40, s38, 0xfff80080
	s_addc_u32 s41, s39, -1
	s_cmp_eq_u32 s36, s25
	s_cselect_b32 s43, s27, s41
	s_cselect_b32 s42, s26, s40
	s_cselect_b32 s41, s29, s23
	s_cselect_b32 s40, s28, s21
	v_lshl_add_u64 v[144:145], s[38:39], 0, v[140:141]
	s_add_i32 m0, s35, 0xc000
	global_load_lds_dwordx4 v[144:145], off
	v_lshl_add_u64 v[144:145], s[38:39], 0, v[142:143]
	s_add_i32 m0, s35, 0xe000
	s_nop 0
	global_load_lds_dwordx4 v[144:145], off
	s_waitcnt vmcnt(8)
	s_waitcnt lgkmcnt(0)
	s_barrier
	s_setprio 1
	v_mfma_f32_16x16x32_bf16 v[126:129], v[152:155], v[184:187], 0
	v_mfma_f32_16x16x32_bf16 v[122:125], v[160:163], v[184:187], 0
	v_mfma_f32_16x16x32_bf16 v[110:113], v[152:155], v[196:199], 0
	v_mfma_f32_16x16x32_bf16 v[106:109], v[160:163], v[196:199], 0
	v_mfma_f32_16x16x32_bf16 v[94:97], v[152:155], v[204:207], 0
	v_mfma_f32_16x16x32_bf16 v[90:93], v[160:163], v[204:207], 0
	v_mfma_f32_16x16x32_bf16 v[78:81], v[152:155], v[212:215], 0
	v_mfma_f32_16x16x32_bf16 v[74:77], v[160:163], v[212:215], 0
	v_mfma_f32_16x16x32_bf16 v[126:129], v[156:159], v[188:191], v[126:129]
	v_mfma_f32_16x16x32_bf16 v[122:125], v[164:167], v[188:191], v[122:125]
	v_mfma_f32_16x16x32_bf16 v[110:113], v[156:159], v[200:203], v[110:113]
	v_mfma_f32_16x16x32_bf16 v[106:109], v[164:167], v[200:203], v[106:109]
	v_mfma_f32_16x16x32_bf16 v[94:97], v[156:159], v[208:211], v[94:97]
	v_mfma_f32_16x16x32_bf16 v[90:93], v[164:167], v[208:211], v[90:93]
	v_mfma_f32_16x16x32_bf16 v[78:81], v[156:159], v[216:219], v[78:81]
	v_mfma_f32_16x16x32_bf16 v[74:77], v[164:167], v[216:219], v[74:77]
	s_setprio 0
	s_setprio 1
	v_mfma_f32_16x16x32_bf16 v[118:121], v[168:171], v[184:187], 0
	v_mfma_f32_16x16x32_bf16 v[114:117], v[176:179], v[184:187], 0
	v_mfma_f32_16x16x32_bf16 v[102:105], v[168:171], v[196:199], 0
	v_mfma_f32_16x16x32_bf16 v[98:101], v[176:179], v[196:199], 0
	v_mfma_f32_16x16x32_bf16 v[86:89], v[168:171], v[204:207], 0
	v_mfma_f32_16x16x32_bf16 v[82:85], v[176:179], v[204:207], 0
	v_mfma_f32_16x16x32_bf16 v[70:73], v[168:171], v[212:215], 0
	v_mfma_f32_16x16x32_bf16 v[66:69], v[176:179], v[212:215], 0
	v_mfma_f32_16x16x32_bf16 v[118:121], v[172:175], v[188:191], v[118:121]
	v_mfma_f32_16x16x32_bf16 v[114:117], v[180:183], v[188:191], v[114:117]
	v_mfma_f32_16x16x32_bf16 v[102:105], v[172:175], v[200:203], v[102:105]
	v_mfma_f32_16x16x32_bf16 v[98:101], v[180:183], v[200:203], v[98:101]
	v_mfma_f32_16x16x32_bf16 v[86:89], v[172:175], v[208:211], v[86:89]
	v_mfma_f32_16x16x32_bf16 v[82:85], v[180:183], v[208:211], v[82:85]
	v_mfma_f32_16x16x32_bf16 v[70:73], v[172:175], v[216:219], v[70:73]
	v_mfma_f32_16x16x32_bf16 v[66:69], v[180:183], v[216:219], v[66:69]
	s_setprio 0
	s_barrier
	s_add_i32 s25, s54, s33
	v_lshl_add_u64 v[144:145], s[40:41], 0, v[132:133]
	s_mov_b32 m0, s25
	ds_read_b128 v[184:187], v151 offset:16384
	ds_read_b128 v[188:191], v151 offset:17408
	ds_read_b128 v[196:199], v151 offset:18432
	ds_read_b128 v[200:203], v151 offset:19456
	ds_read_b128 v[204:207], v151 offset:20480
	ds_read_b128 v[208:211], v151 offset:21504
	ds_read_b128 v[212:215], v151 offset:22528
	ds_read_b128 v[216:219], v151 offset:23552
	global_load_lds_dwordx4 v[144:145], off
	s_add_i32 m0, s25, 0x2000
	s_add_u32 s44, s40, 0x80000
	v_lshl_add_u64 v[192:193], s[40:41], 0, v[136:137]
	s_addc_u32 s45, s41, 0
	s_add_i32 s25, s55, s33
	global_load_lds_dwordx4 v[192:193], off
	v_lshl_add_u64 v[220:221], s[44:45], 0, v[132:133]
	s_mov_b32 m0, s25
	v_lshl_add_u64 v[222:223], s[42:43], 0, v[134:135]
	global_load_lds_dwordx4 v[220:221], off
	v_lshl_add_u64 v[220:221], s[44:45], 0, v[136:137]
	s_add_i32 m0, s25, 0x2000
	s_nop 0
	global_load_lds_dwordx4 v[220:221], off
	v_lshl_add_u64 v[220:221], s[42:43], 0, v[130:131]
	s_mov_b32 m0, s35
	s_nop 0
	global_load_lds_dwordx4 v[220:221], off
	s_mov_b32 m0, s47
	s_nop 0
	global_load_lds_dwordx4 v[222:223], off
	s_waitcnt vmcnt(8)
	s_waitcnt lgkmcnt(0)
	s_barrier
	s_setprio 1
	v_mfma_f32_16x16x32_bf16 v[62:65], v[152:155], v[184:187], 0
	v_mfma_f32_16x16x32_bf16 v[58:61], v[160:163], v[184:187], 0
	v_mfma_f32_16x16x32_bf16 v[46:49], v[152:155], v[196:199], 0
	v_mfma_f32_16x16x32_bf16 v[42:45], v[160:163], v[196:199], 0
	v_mfma_f32_16x16x32_bf16 v[30:33], v[152:155], v[204:207], 0
	v_mfma_f32_16x16x32_bf16 v[26:29], v[160:163], v[204:207], 0
	v_mfma_f32_16x16x32_bf16 v[14:17], v[152:155], v[212:215], 0
	v_mfma_f32_16x16x32_bf16 v[10:13], v[160:163], v[212:215], 0
	v_mfma_f32_16x16x32_bf16 v[62:65], v[156:159], v[188:191], v[62:65]
	v_mfma_f32_16x16x32_bf16 v[58:61], v[164:167], v[188:191], v[58:61]
	v_mfma_f32_16x16x32_bf16 v[46:49], v[156:159], v[200:203], v[46:49]
	v_mfma_f32_16x16x32_bf16 v[42:45], v[164:167], v[200:203], v[42:45]
	v_mfma_f32_16x16x32_bf16 v[30:33], v[156:159], v[208:211], v[30:33]
	v_mfma_f32_16x16x32_bf16 v[26:29], v[164:167], v[208:211], v[26:29]
	v_mfma_f32_16x16x32_bf16 v[14:17], v[156:159], v[216:219], v[14:17]
	v_mfma_f32_16x16x32_bf16 v[10:13], v[164:167], v[216:219], v[10:13]
	s_setprio 0
	s_setprio 1
	v_mfma_f32_16x16x32_bf16 v[54:57], v[168:171], v[184:187], 0
	v_mfma_f32_16x16x32_bf16 v[50:53], v[176:179], v[184:187], 0
	v_mfma_f32_16x16x32_bf16 v[38:41], v[168:171], v[196:199], 0
	v_mfma_f32_16x16x32_bf16 v[34:37], v[176:179], v[196:199], 0
	v_mfma_f32_16x16x32_bf16 v[22:25], v[168:171], v[204:207], 0
	v_mfma_f32_16x16x32_bf16 v[18:21], v[176:179], v[204:207], 0
	v_mfma_f32_16x16x32_bf16 v[6:9], v[168:171], v[212:215], 0
	v_mfma_f32_16x16x32_bf16 v[2:5], v[176:179], v[212:215], 0
	v_mfma_f32_16x16x32_bf16 v[54:57], v[172:175], v[188:191], v[54:57]
	v_mfma_f32_16x16x32_bf16 v[50:53], v[180:183], v[188:191], v[50:53]
	v_mfma_f32_16x16x32_bf16 v[38:41], v[172:175], v[200:203], v[38:41]
	v_mfma_f32_16x16x32_bf16 v[34:37], v[180:183], v[200:203], v[34:37]
	v_mfma_f32_16x16x32_bf16 v[22:25], v[172:175], v[208:211], v[22:25]
	v_mfma_f32_16x16x32_bf16 v[18:21], v[180:183], v[208:211], v[18:21]
	v_mfma_f32_16x16x32_bf16 v[6:9], v[172:175], v[216:219], v[6:9]
	v_mfma_f32_16x16x32_bf16 v[2:5], v[180:183], v[216:219], v[2:5]
	s_setprio 0
	s_barrier
	s_add_i32 s25, 0, 0x18000
	s_add_i32 s44, 0, 0x1c000
	v_add_u32_e32 v164, s25, v147
	v_add_u32_e32 v180, s44, v147
	ds_read_b128 v[152:155], v164
	ds_read_b128 v[156:159], v164 offset:1024
	ds_read_b128 v[160:163], v164 offset:2048
	ds_read_b128 v[164:167], v164 offset:3072
	ds_read_b128 v[168:171], v180
	ds_read_b128 v[172:175], v180 offset:1024
	ds_read_b128 v[176:179], v180 offset:2048
	ds_read_b128 v[180:183], v180 offset:3072
	s_add_u32 s42, s42, 0x80000
	s_addc_u32 s43, s43, 0
	s_mov_b32 m0, s48
	v_lshl_add_u64 v[224:225], s[42:43], 0, v[130:131]
	ds_read_b128 v[184:187], v151 offset:32768
	ds_read_b128 v[188:191], v151 offset:33792
	ds_read_b128 v[196:199], v151 offset:34816
	ds_read_b128 v[200:203], v151 offset:35840
	ds_read_b128 v[204:207], v151 offset:36864
	ds_read_b128 v[208:211], v151 offset:37888
	ds_read_b128 v[212:215], v151 offset:38912
	ds_read_b128 v[216:219], v151 offset:39936
	global_load_lds_dwordx4 v[224:225], off
	v_lshl_add_u64 v[224:225], s[42:43], 0, v[134:135]
	s_mov_b32 m0, s49
	s_nop 0
	global_load_lds_dwordx4 v[224:225], off
	s_waitcnt vmcnt(8)
	s_waitcnt lgkmcnt(0)
	s_barrier
	s_setprio 1
	v_mfma_f32_16x16x32_bf16 v[126:129], v[152:155], v[184:187], v[126:129]
	v_mfma_f32_16x16x32_bf16 v[122:125], v[160:163], v[184:187], v[122:125]
	v_mfma_f32_16x16x32_bf16 v[110:113], v[152:155], v[196:199], v[110:113]
	v_mfma_f32_16x16x32_bf16 v[106:109], v[160:163], v[196:199], v[106:109]
	v_mfma_f32_16x16x32_bf16 v[94:97], v[152:155], v[204:207], v[94:97]
	v_mfma_f32_16x16x32_bf16 v[90:93], v[160:163], v[204:207], v[90:93]
	v_mfma_f32_16x16x32_bf16 v[78:81], v[152:155], v[212:215], v[78:81]
	v_mfma_f32_16x16x32_bf16 v[74:77], v[160:163], v[212:215], v[74:77]
	v_mfma_f32_16x16x32_bf16 v[126:129], v[156:159], v[188:191], v[126:129]
	v_mfma_f32_16x16x32_bf16 v[122:125], v[164:167], v[188:191], v[122:125]
	v_mfma_f32_16x16x32_bf16 v[110:113], v[156:159], v[200:203], v[110:113]
	v_mfma_f32_16x16x32_bf16 v[106:109], v[164:167], v[200:203], v[106:109]
	v_mfma_f32_16x16x32_bf16 v[94:97], v[156:159], v[208:211], v[94:97]
	v_mfma_f32_16x16x32_bf16 v[90:93], v[164:167], v[208:211], v[90:93]
	v_mfma_f32_16x16x32_bf16 v[78:81], v[156:159], v[216:219], v[78:81]
	v_mfma_f32_16x16x32_bf16 v[74:77], v[164:167], v[216:219], v[74:77]
	s_setprio 0
	s_setprio 1
	v_mfma_f32_16x16x32_bf16 v[118:121], v[168:171], v[184:187], v[118:121]
	v_mfma_f32_16x16x32_bf16 v[114:117], v[176:179], v[184:187], v[114:117]
	v_mfma_f32_16x16x32_bf16 v[102:105], v[168:171], v[196:199], v[102:105]
	v_mfma_f32_16x16x32_bf16 v[98:101], v[176:179], v[196:199], v[98:101]
	v_mfma_f32_16x16x32_bf16 v[86:89], v[168:171], v[204:207], v[86:89]
	v_mfma_f32_16x16x32_bf16 v[82:85], v[176:179], v[204:207], v[82:85]
	v_mfma_f32_16x16x32_bf16 v[70:73], v[168:171], v[212:215], v[70:73]
	v_mfma_f32_16x16x32_bf16 v[66:69], v[176:179], v[212:215], v[66:69]
	v_mfma_f32_16x16x32_bf16 v[118:121], v[172:175], v[188:191], v[118:121]
	v_mfma_f32_16x16x32_bf16 v[114:117], v[180:183], v[188:191], v[114:117]
	v_mfma_f32_16x16x32_bf16 v[102:105], v[172:175], v[200:203], v[102:105]
	v_mfma_f32_16x16x32_bf16 v[98:101], v[180:183], v[200:203], v[98:101]
	v_mfma_f32_16x16x32_bf16 v[86:89], v[172:175], v[208:211], v[86:89]
	v_mfma_f32_16x16x32_bf16 v[82:85], v[180:183], v[208:211], v[82:85]
	v_mfma_f32_16x16x32_bf16 v[70:73], v[172:175], v[216:219], v[70:73]
	v_mfma_f32_16x16x32_bf16 v[66:69], v[180:183], v[216:219], v[66:69]
	s_setprio 0
	s_barrier
	s_add_i32 s25, s25, s33
	v_lshl_add_u64 v[144:145], v[144:145], 0, s[16:17]
	s_mov_b32 m0, s25
	ds_read_b128 v[184:187], v151 offset:49152
	ds_read_b128 v[188:191], v151 offset:50176
	ds_read_b128 v[196:199], v151 offset:51200
	ds_read_b128 v[200:203], v151 offset:52224
	ds_read_b128 v[204:207], v151 offset:53248
	ds_read_b128 v[208:211], v151 offset:54272
	ds_read_b128 v[212:215], v151 offset:55296
	ds_read_b128 v[216:219], v151 offset:56320
	global_load_lds_dwordx4 v[144:145], off
	s_add_i32 m0, s25, 0x2000
	s_add_u32 s40, s40, 0x80080
	v_lshl_add_u64 v[144:145], v[192:193], 0, s[16:17]
	s_addc_u32 s41, s41, 0
	s_add_i32 s25, s44, s33
	global_load_lds_dwordx4 v[144:145], off
	v_lshl_add_u64 v[144:145], s[40:41], 0, v[132:133]
	s_mov_b32 m0, s25
	s_nop 0
	global_load_lds_dwordx4 v[144:145], off
	v_lshl_add_u64 v[144:145], s[40:41], 0, v[136:137]
	s_add_i32 m0, s25, 0x2000
	s_nop 0
	global_load_lds_dwordx4 v[144:145], off
	v_lshl_add_u64 v[144:145], v[220:221], 0, s[16:17]
	s_mov_b32 m0, s50
	s_nop 0
	global_load_lds_dwordx4 v[144:145], off
	v_lshl_add_u64 v[144:145], v[222:223], 0, s[16:17]
	s_mov_b32 m0, s51
	s_nop 0
	global_load_lds_dwordx4 v[144:145], off
	s_waitcnt vmcnt(8)
	s_waitcnt lgkmcnt(0)
	s_barrier
	s_setprio 1
	v_mfma_f32_16x16x32_bf16 v[62:65], v[152:155], v[184:187], v[62:65]
	v_mfma_f32_16x16x32_bf16 v[58:61], v[160:163], v[184:187], v[58:61]
	v_mfma_f32_16x16x32_bf16 v[46:49], v[152:155], v[196:199], v[46:49]
	v_mfma_f32_16x16x32_bf16 v[42:45], v[160:163], v[196:199], v[42:45]
	v_mfma_f32_16x16x32_bf16 v[30:33], v[152:155], v[204:207], v[30:33]
	v_mfma_f32_16x16x32_bf16 v[26:29], v[160:163], v[204:207], v[26:29]
	v_mfma_f32_16x16x32_bf16 v[14:17], v[152:155], v[212:215], v[14:17]
	v_mfma_f32_16x16x32_bf16 v[10:13], v[160:163], v[212:215], v[10:13]
	v_mfma_f32_16x16x32_bf16 v[62:65], v[156:159], v[188:191], v[62:65]
	v_mfma_f32_16x16x32_bf16 v[58:61], v[164:167], v[188:191], v[58:61]
	v_mfma_f32_16x16x32_bf16 v[46:49], v[156:159], v[200:203], v[46:49]
	v_mfma_f32_16x16x32_bf16 v[42:45], v[164:167], v[200:203], v[42:45]
	v_mfma_f32_16x16x32_bf16 v[30:33], v[156:159], v[208:211], v[30:33]
	v_mfma_f32_16x16x32_bf16 v[26:29], v[164:167], v[208:211], v[26:29]
	v_mfma_f32_16x16x32_bf16 v[14:17], v[156:159], v[216:219], v[14:17]
	v_mfma_f32_16x16x32_bf16 v[10:13], v[164:167], v[216:219], v[10:13]
	s_setprio 0
	s_setprio 1
	v_mfma_f32_16x16x32_bf16 v[54:57], v[168:171], v[184:187], v[54:57]
	v_mfma_f32_16x16x32_bf16 v[50:53], v[176:179], v[184:187], v[50:53]
	v_mfma_f32_16x16x32_bf16 v[38:41], v[168:171], v[196:199], v[38:41]
	v_mfma_f32_16x16x32_bf16 v[34:37], v[176:179], v[196:199], v[34:37]
	v_mfma_f32_16x16x32_bf16 v[22:25], v[168:171], v[204:207], v[22:25]
	v_mfma_f32_16x16x32_bf16 v[18:21], v[176:179], v[204:207], v[18:21]
	v_mfma_f32_16x16x32_bf16 v[6:9], v[168:171], v[212:215], v[6:9]
	v_mfma_f32_16x16x32_bf16 v[2:5], v[176:179], v[212:215], v[2:5]
	v_mfma_f32_16x16x32_bf16 v[54:57], v[172:175], v[188:191], v[54:57]
	v_mfma_f32_16x16x32_bf16 v[50:53], v[180:183], v[188:191], v[50:53]
	v_mfma_f32_16x16x32_bf16 v[38:41], v[172:175], v[200:203], v[38:41]
	v_mfma_f32_16x16x32_bf16 v[34:37], v[180:183], v[200:203], v[34:37]
	v_mfma_f32_16x16x32_bf16 v[22:25], v[172:175], v[208:211], v[22:25]
	v_mfma_f32_16x16x32_bf16 v[18:21], v[180:183], v[208:211], v[18:21]
	v_mfma_f32_16x16x32_bf16 v[6:9], v[172:175], v[216:219], v[6:9]
	v_mfma_f32_16x16x32_bf16 v[2:5], v[180:183], v[216:219], v[2:5]
	s_setprio 0
	s_barrier
	s_add_u32 s38, s38, 0x100
	s_addc_u32 s39, s39, 0
	s_add_u32 s21, s21, 0x100
	s_addc_u32 s23, s23, 0
	s_cmp_ge_i32 s37, s62
	s_mov_b32 s25, s37
	s_cbranch_scc0 .LBB0_221
	s_branch .Lpeeldone_13
.LBB0_221:
	ds_read_b128 v[152:155], v149
	ds_read_b128 v[156:159], v149 offset:1024
	ds_read_b128 v[160:163], v149 offset:2048
	ds_read_b128 v[164:167], v149 offset:3072
	ds_read_b128 v[168:171], v150
	ds_read_b128 v[172:175], v150 offset:1024
	ds_read_b128 v[176:179], v150 offset:2048
	ds_read_b128 v[180:183], v150 offset:3072
	s_add_i32 s37, s25, 2
	s_add_u32 s40, s38, 0xfff80080
	s_addc_u32 s41, s39, -1
	s_cmp_eq_u32 s36, s25
	s_cselect_b32 s43, s27, s41
	s_cselect_b32 s42, s26, s40
	s_cselect_b32 s41, s29, s23
	s_cselect_b32 s40, s28, s21
	v_lshl_add_u64 v[144:145], s[38:39], 0, v[140:141]
	s_add_i32 m0, s35, 0xc000
	ds_read_b128 v[184:187], v151
	ds_read_b128 v[188:191], v151 offset:1024
	ds_read_b128 v[196:199], v151 offset:2048
	ds_read_b128 v[200:203], v151 offset:3072
	ds_read_b128 v[204:207], v151 offset:4096
	ds_read_b128 v[208:211], v151 offset:5120
	ds_read_b128 v[212:215], v151 offset:6144
	ds_read_b128 v[216:219], v151 offset:7168
	global_load_lds_dwordx4 v[144:145], off
	v_lshl_add_u64 v[144:145], s[38:39], 0, v[142:143]
	s_add_i32 m0, s35, 0xe000
	s_nop 0
	global_load_lds_dwordx4 v[144:145], off
	s_waitcnt vmcnt(8)
	s_waitcnt lgkmcnt(0)
	s_barrier
	s_setprio 1
	v_mfma_f32_16x16x32_bf16 v[126:129], v[152:155], v[184:187], v[126:129]
	v_mfma_f32_16x16x32_bf16 v[122:125], v[160:163], v[184:187], v[122:125]
	v_mfma_f32_16x16x32_bf16 v[110:113], v[152:155], v[196:199], v[110:113]
	v_mfma_f32_16x16x32_bf16 v[106:109], v[160:163], v[196:199], v[106:109]
	v_mfma_f32_16x16x32_bf16 v[94:97], v[152:155], v[204:207], v[94:97]
	v_mfma_f32_16x16x32_bf16 v[90:93], v[160:163], v[204:207], v[90:93]
	v_mfma_f32_16x16x32_bf16 v[78:81], v[152:155], v[212:215], v[78:81]
	v_mfma_f32_16x16x32_bf16 v[74:77], v[160:163], v[212:215], v[74:77]
	v_mfma_f32_16x16x32_bf16 v[126:129], v[156:159], v[188:191], v[126:129]
	v_mfma_f32_16x16x32_bf16 v[122:125], v[164:167], v[188:191], v[122:125]
	v_mfma_f32_16x16x32_bf16 v[110:113], v[156:159], v[200:203], v[110:113]
	v_mfma_f32_16x16x32_bf16 v[106:109], v[164:167], v[200:203], v[106:109]
	v_mfma_f32_16x16x32_bf16 v[94:97], v[156:159], v[208:211], v[94:97]
	v_mfma_f32_16x16x32_bf16 v[90:93], v[164:167], v[208:211], v[90:93]
	v_mfma_f32_16x16x32_bf16 v[78:81], v[156:159], v[216:219], v[78:81]
	v_mfma_f32_16x16x32_bf16 v[74:77], v[164:167], v[216:219], v[74:77]
	s_setprio 0
	s_setprio 1
	v_mfma_f32_16x16x32_bf16 v[118:121], v[168:171], v[184:187], v[118:121]
	v_mfma_f32_16x16x32_bf16 v[114:117], v[176:179], v[184:187], v[114:117]
	v_mfma_f32_16x16x32_bf16 v[102:105], v[168:171], v[196:199], v[102:105]
	v_mfma_f32_16x16x32_bf16 v[98:101], v[176:179], v[196:199], v[98:101]
	v_mfma_f32_16x16x32_bf16 v[86:89], v[168:171], v[204:207], v[86:89]
	v_mfma_f32_16x16x32_bf16 v[82:85], v[176:179], v[204:207], v[82:85]
	v_mfma_f32_16x16x32_bf16 v[70:73], v[168:171], v[212:215], v[70:73]
	v_mfma_f32_16x16x32_bf16 v[66:69], v[176:179], v[212:215], v[66:69]
	v_mfma_f32_16x16x32_bf16 v[118:121], v[172:175], v[188:191], v[118:121]
	v_mfma_f32_16x16x32_bf16 v[114:117], v[180:183], v[188:191], v[114:117]
	v_mfma_f32_16x16x32_bf16 v[102:105], v[172:175], v[200:203], v[102:105]
	v_mfma_f32_16x16x32_bf16 v[98:101], v[180:183], v[200:203], v[98:101]
	v_mfma_f32_16x16x32_bf16 v[86:89], v[172:175], v[208:211], v[86:89]
	v_mfma_f32_16x16x32_bf16 v[82:85], v[180:183], v[208:211], v[82:85]
	v_mfma_f32_16x16x32_bf16 v[70:73], v[172:175], v[216:219], v[70:73]
	v_mfma_f32_16x16x32_bf16 v[66:69], v[180:183], v[216:219], v[66:69]
	s_setprio 0
	s_barrier
	s_add_i32 s25, s54, s33
	v_lshl_add_u64 v[144:145], s[40:41], 0, v[132:133]
	s_mov_b32 m0, s25
	ds_read_b128 v[184:187], v151 offset:16384
	ds_read_b128 v[188:191], v151 offset:17408
	ds_read_b128 v[196:199], v151 offset:18432
	ds_read_b128 v[200:203], v151 offset:19456
	ds_read_b128 v[204:207], v151 offset:20480
	ds_read_b128 v[208:211], v151 offset:21504
	ds_read_b128 v[212:215], v151 offset:22528
	ds_read_b128 v[216:219], v151 offset:23552
	global_load_lds_dwordx4 v[144:145], off
	s_add_i32 m0, s25, 0x2000
	s_add_u32 s44, s40, 0x80000
	v_lshl_add_u64 v[192:193], s[40:41], 0, v[136:137]
	s_addc_u32 s45, s41, 0
	s_add_i32 s25, s55, s33
	global_load_lds_dwordx4 v[192:193], off
	v_lshl_add_u64 v[220:221], s[44:45], 0, v[132:133]
	s_mov_b32 m0, s25
	v_lshl_add_u64 v[222:223], s[42:43], 0, v[134:135]
	global_load_lds_dwordx4 v[220:221], off
	v_lshl_add_u64 v[220:221], s[44:45], 0, v[136:137]
	s_add_i32 m0, s25, 0x2000
	s_nop 0
	global_load_lds_dwordx4 v[220:221], off
	v_lshl_add_u64 v[220:221], s[42:43], 0, v[130:131]
	s_mov_b32 m0, s35
	s_nop 0
	global_load_lds_dwordx4 v[220:221], off
	s_mov_b32 m0, s47
	s_nop 0
	global_load_lds_dwordx4 v[222:223], off
	s_waitcnt vmcnt(8)
	s_waitcnt lgkmcnt(0)
	s_barrier
	s_setprio 1
	v_mfma_f32_16x16x32_bf16 v[62:65], v[152:155], v[184:187], v[62:65]
	v_mfma_f32_16x16x32_bf16 v[58:61], v[160:163], v[184:187], v[58:61]
	v_mfma_f32_16x16x32_bf16 v[46:49], v[152:155], v[196:199], v[46:49]
	v_mfma_f32_16x16x32_bf16 v[42:45], v[160:163], v[196:199], v[42:45]
	v_mfma_f32_16x16x32_bf16 v[30:33], v[152:155], v[204:207], v[30:33]
	v_mfma_f32_16x16x32_bf16 v[26:29], v[160:163], v[204:207], v[26:29]
	v_mfma_f32_16x16x32_bf16 v[14:17], v[152:155], v[212:215], v[14:17]
	v_mfma_f32_16x16x32_bf16 v[10:13], v[160:163], v[212:215], v[10:13]
	v_mfma_f32_16x16x32_bf16 v[62:65], v[156:159], v[188:191], v[62:65]
	v_mfma_f32_16x16x32_bf16 v[58:61], v[164:167], v[188:191], v[58:61]
	v_mfma_f32_16x16x32_bf16 v[46:49], v[156:159], v[200:203], v[46:49]
	v_mfma_f32_16x16x32_bf16 v[42:45], v[164:167], v[200:203], v[42:45]
	v_mfma_f32_16x16x32_bf16 v[30:33], v[156:159], v[208:211], v[30:33]
	v_mfma_f32_16x16x32_bf16 v[26:29], v[164:167], v[208:211], v[26:29]
	v_mfma_f32_16x16x32_bf16 v[14:17], v[156:159], v[216:219], v[14:17]
	v_mfma_f32_16x16x32_bf16 v[10:13], v[164:167], v[216:219], v[10:13]
	s_setprio 0
	s_setprio 1
	v_mfma_f32_16x16x32_bf16 v[54:57], v[168:171], v[184:187], v[54:57]
	v_mfma_f32_16x16x32_bf16 v[50:53], v[176:179], v[184:187], v[50:53]
	v_mfma_f32_16x16x32_bf16 v[38:41], v[168:171], v[196:199], v[38:41]
	v_mfma_f32_16x16x32_bf16 v[34:37], v[176:179], v[196:199], v[34:37]
	v_mfma_f32_16x16x32_bf16 v[22:25], v[168:171], v[204:207], v[22:25]
	v_mfma_f32_16x16x32_bf16 v[18:21], v[176:179], v[204:207], v[18:21]
	v_mfma_f32_16x16x32_bf16 v[6:9], v[168:171], v[212:215], v[6:9]
	v_mfma_f32_16x16x32_bf16 v[2:5], v[176:179], v[212:215], v[2:5]
	v_mfma_f32_16x16x32_bf16 v[54:57], v[172:175], v[188:191], v[54:57]
	v_mfma_f32_16x16x32_bf16 v[50:53], v[180:183], v[188:191], v[50:53]
	v_mfma_f32_16x16x32_bf16 v[38:41], v[172:175], v[200:203], v[38:41]
	v_mfma_f32_16x16x32_bf16 v[34:37], v[180:183], v[200:203], v[34:37]
	v_mfma_f32_16x16x32_bf16 v[22:25], v[172:175], v[208:211], v[22:25]
	v_mfma_f32_16x16x32_bf16 v[18:21], v[180:183], v[208:211], v[18:21]
	v_mfma_f32_16x16x32_bf16 v[6:9], v[172:175], v[216:219], v[6:9]
	v_mfma_f32_16x16x32_bf16 v[2:5], v[180:183], v[216:219], v[2:5]
	s_setprio 0
	s_barrier
	s_add_i32 s25, 0, 0x18000
	s_add_i32 s44, 0, 0x1c000
	v_add_u32_e32 v164, s25, v147
	v_add_u32_e32 v180, s44, v147
	ds_read_b128 v[152:155], v164
	ds_read_b128 v[156:159], v164 offset:1024
	ds_read_b128 v[160:163], v164 offset:2048
	ds_read_b128 v[164:167], v164 offset:3072
	ds_read_b128 v[168:171], v180
	ds_read_b128 v[172:175], v180 offset:1024
	ds_read_b128 v[176:179], v180 offset:2048
	ds_read_b128 v[180:183], v180 offset:3072
	s_add_u32 s42, s42, 0x80000
	s_addc_u32 s43, s43, 0
	s_mov_b32 m0, s48
	v_lshl_add_u64 v[224:225], s[42:43], 0, v[130:131]
	ds_read_b128 v[184:187], v151 offset:32768
	ds_read_b128 v[188:191], v151 offset:33792
	ds_read_b128 v[196:199], v151 offset:34816
	ds_read_b128 v[200:203], v151 offset:35840
	ds_read_b128 v[204:207], v151 offset:36864
	ds_read_b128 v[208:211], v151 offset:37888
	ds_read_b128 v[212:215], v151 offset:38912
	ds_read_b128 v[216:219], v151 offset:39936
	global_load_lds_dwordx4 v[224:225], off
	v_lshl_add_u64 v[224:225], s[42:43], 0, v[134:135]
	s_mov_b32 m0, s49
	s_nop 0
	global_load_lds_dwordx4 v[224:225], off
	s_waitcnt vmcnt(8)
	s_waitcnt lgkmcnt(0)
	s_barrier
	s_setprio 1
	v_mfma_f32_16x16x32_bf16 v[126:129], v[152:155], v[184:187], v[126:129]
	v_mfma_f32_16x16x32_bf16 v[122:125], v[160:163], v[184:187], v[122:125]
	v_mfma_f32_16x16x32_bf16 v[110:113], v[152:155], v[196:199], v[110:113]
	v_mfma_f32_16x16x32_bf16 v[106:109], v[160:163], v[196:199], v[106:109]
	v_mfma_f32_16x16x32_bf16 v[94:97], v[152:155], v[204:207], v[94:97]
	v_mfma_f32_16x16x32_bf16 v[90:93], v[160:163], v[204:207], v[90:93]
	v_mfma_f32_16x16x32_bf16 v[78:81], v[152:155], v[212:215], v[78:81]
	v_mfma_f32_16x16x32_bf16 v[74:77], v[160:163], v[212:215], v[74:77]
	v_mfma_f32_16x16x32_bf16 v[126:129], v[156:159], v[188:191], v[126:129]
	v_mfma_f32_16x16x32_bf16 v[122:125], v[164:167], v[188:191], v[122:125]
	v_mfma_f32_16x16x32_bf16 v[110:113], v[156:159], v[200:203], v[110:113]
	v_mfma_f32_16x16x32_bf16 v[106:109], v[164:167], v[200:203], v[106:109]
	v_mfma_f32_16x16x32_bf16 v[94:97], v[156:159], v[208:211], v[94:97]
	v_mfma_f32_16x16x32_bf16 v[90:93], v[164:167], v[208:211], v[90:93]
	v_mfma_f32_16x16x32_bf16 v[78:81], v[156:159], v[216:219], v[78:81]
	v_mfma_f32_16x16x32_bf16 v[74:77], v[164:167], v[216:219], v[74:77]
	s_setprio 0
	s_setprio 1
	v_mfma_f32_16x16x32_bf16 v[118:121], v[168:171], v[184:187], v[118:121]
	v_mfma_f32_16x16x32_bf16 v[114:117], v[176:179], v[184:187], v[114:117]
	v_mfma_f32_16x16x32_bf16 v[102:105], v[168:171], v[196:199], v[102:105]
	v_mfma_f32_16x16x32_bf16 v[98:101], v[176:179], v[196:199], v[98:101]
	v_mfma_f32_16x16x32_bf16 v[86:89], v[168:171], v[204:207], v[86:89]
	v_mfma_f32_16x16x32_bf16 v[82:85], v[176:179], v[204:207], v[82:85]
	v_mfma_f32_16x16x32_bf16 v[70:73], v[168:171], v[212:215], v[70:73]
	v_mfma_f32_16x16x32_bf16 v[66:69], v[176:179], v[212:215], v[66:69]
	v_mfma_f32_16x16x32_bf16 v[118:121], v[172:175], v[188:191], v[118:121]
	v_mfma_f32_16x16x32_bf16 v[114:117], v[180:183], v[188:191], v[114:117]
	v_mfma_f32_16x16x32_bf16 v[102:105], v[172:175], v[200:203], v[102:105]
	v_mfma_f32_16x16x32_bf16 v[98:101], v[180:183], v[200:203], v[98:101]
	v_mfma_f32_16x16x32_bf16 v[86:89], v[172:175], v[208:211], v[86:89]
	v_mfma_f32_16x16x32_bf16 v[82:85], v[180:183], v[208:211], v[82:85]
	v_mfma_f32_16x16x32_bf16 v[70:73], v[172:175], v[216:219], v[70:73]
	v_mfma_f32_16x16x32_bf16 v[66:69], v[180:183], v[216:219], v[66:69]
	s_setprio 0
	s_barrier
	s_add_i32 s25, s25, s33
	v_lshl_add_u64 v[144:145], v[144:145], 0, s[16:17]
	s_mov_b32 m0, s25
	ds_read_b128 v[184:187], v151 offset:49152
	ds_read_b128 v[188:191], v151 offset:50176
	ds_read_b128 v[196:199], v151 offset:51200
	ds_read_b128 v[200:203], v151 offset:52224
	ds_read_b128 v[204:207], v151 offset:53248
	ds_read_b128 v[208:211], v151 offset:54272
	ds_read_b128 v[212:215], v151 offset:55296
	ds_read_b128 v[216:219], v151 offset:56320
	global_load_lds_dwordx4 v[144:145], off
	s_add_i32 m0, s25, 0x2000
	s_add_u32 s40, s40, 0x80080
	v_lshl_add_u64 v[144:145], v[192:193], 0, s[16:17]
	s_addc_u32 s41, s41, 0
	s_add_i32 s25, s44, s33
	global_load_lds_dwordx4 v[144:145], off
	v_lshl_add_u64 v[144:145], s[40:41], 0, v[132:133]
	s_mov_b32 m0, s25
	s_nop 0
	global_load_lds_dwordx4 v[144:145], off
	v_lshl_add_u64 v[144:145], s[40:41], 0, v[136:137]
	s_add_i32 m0, s25, 0x2000
	s_nop 0
	global_load_lds_dwordx4 v[144:145], off
	v_lshl_add_u64 v[144:145], v[220:221], 0, s[16:17]
	s_mov_b32 m0, s50
	s_nop 0
	global_load_lds_dwordx4 v[144:145], off
	v_lshl_add_u64 v[144:145], v[222:223], 0, s[16:17]
	s_mov_b32 m0, s51
	s_nop 0
	global_load_lds_dwordx4 v[144:145], off
	s_waitcnt vmcnt(8)
	s_waitcnt lgkmcnt(0)
	s_barrier
	s_setprio 1
	v_mfma_f32_16x16x32_bf16 v[62:65], v[152:155], v[184:187], v[62:65]
	v_mfma_f32_16x16x32_bf16 v[58:61], v[160:163], v[184:187], v[58:61]
	v_mfma_f32_16x16x32_bf16 v[46:49], v[152:155], v[196:199], v[46:49]
	v_mfma_f32_16x16x32_bf16 v[42:45], v[160:163], v[196:199], v[42:45]
	v_mfma_f32_16x16x32_bf16 v[30:33], v[152:155], v[204:207], v[30:33]
	v_mfma_f32_16x16x32_bf16 v[26:29], v[160:163], v[204:207], v[26:29]
	v_mfma_f32_16x16x32_bf16 v[14:17], v[152:155], v[212:215], v[14:17]
	v_mfma_f32_16x16x32_bf16 v[10:13], v[160:163], v[212:215], v[10:13]
	v_mfma_f32_16x16x32_bf16 v[62:65], v[156:159], v[188:191], v[62:65]
	v_mfma_f32_16x16x32_bf16 v[58:61], v[164:167], v[188:191], v[58:61]
	v_mfma_f32_16x16x32_bf16 v[46:49], v[156:159], v[200:203], v[46:49]
	v_mfma_f32_16x16x32_bf16 v[42:45], v[164:167], v[200:203], v[42:45]
	v_mfma_f32_16x16x32_bf16 v[30:33], v[156:159], v[208:211], v[30:33]
	v_mfma_f32_16x16x32_bf16 v[26:29], v[164:167], v[208:211], v[26:29]
	v_mfma_f32_16x16x32_bf16 v[14:17], v[156:159], v[216:219], v[14:17]
	v_mfma_f32_16x16x32_bf16 v[10:13], v[164:167], v[216:219], v[10:13]
	s_setprio 0
	s_setprio 1
	v_mfma_f32_16x16x32_bf16 v[54:57], v[168:171], v[184:187], v[54:57]
	v_mfma_f32_16x16x32_bf16 v[50:53], v[176:179], v[184:187], v[50:53]
	v_mfma_f32_16x16x32_bf16 v[38:41], v[168:171], v[196:199], v[38:41]
	v_mfma_f32_16x16x32_bf16 v[34:37], v[176:179], v[196:199], v[34:37]
	v_mfma_f32_16x16x32_bf16 v[22:25], v[168:171], v[204:207], v[22:25]
	v_mfma_f32_16x16x32_bf16 v[18:21], v[176:179], v[204:207], v[18:21]
	v_mfma_f32_16x16x32_bf16 v[6:9], v[168:171], v[212:215], v[6:9]
	v_mfma_f32_16x16x32_bf16 v[2:5], v[176:179], v[212:215], v[2:5]
	v_mfma_f32_16x16x32_bf16 v[54:57], v[172:175], v[188:191], v[54:57]
	v_mfma_f32_16x16x32_bf16 v[50:53], v[180:183], v[188:191], v[50:53]
	v_mfma_f32_16x16x32_bf16 v[38:41], v[172:175], v[200:203], v[38:41]
	v_mfma_f32_16x16x32_bf16 v[34:37], v[180:183], v[200:203], v[34:37]
	v_mfma_f32_16x16x32_bf16 v[22:25], v[172:175], v[208:211], v[22:25]
	v_mfma_f32_16x16x32_bf16 v[18:21], v[180:183], v[208:211], v[18:21]
	v_mfma_f32_16x16x32_bf16 v[6:9], v[172:175], v[216:219], v[6:9]
	v_mfma_f32_16x16x32_bf16 v[2:5], v[180:183], v[216:219], v[2:5]
	s_setprio 0
	s_barrier
	s_add_u32 s38, s38, 0x100
	s_addc_u32 s39, s39, 0
	s_add_u32 s21, s21, 0x100
	s_addc_u32 s23, s23, 0
	s_cmp_ge_i32 s37, s62
	s_mov_b32 s25, s37
	s_cbranch_scc0 .LBB0_221

.Lpeel_12:
	ds_read_b128 v[130:133], v215
	ds_read_b128 v[134:137], v215 offset:1024
	ds_read_b128 v[138:141], v215 offset:2048
	ds_read_b128 v[142:145], v215 offset:3072
	ds_read_b128 v[146:149], v216
	ds_read_b128 v[150:153], v216 offset:1024
	ds_read_b128 v[154:157], v216 offset:2048
	ds_read_b128 v[158:161], v216 offset:3072
	s_add_i32 s38, s34, 2
	s_add_u32 s35, s30, 0xffea0080
	s_addc_u32 s36, s31, -1
	s_cmp_eq_u32 s28, s34
	s_cselect_b32 s34, s26, s23
	s_cselect_b32 s37, s25, s36
	s_cselect_b32 s36, s24, s35
	s_cselect_b32 s35, s27, s29
	v_lshl_add_u64 v[192:193], s[30:31], 0, v[188:189]
	s_add_i32 m0, s40, 0xc000
	ds_read_b128 v[162:165], v217
	ds_read_b128 v[166:169], v217 offset:1024
	ds_read_b128 v[170:173], v217 offset:2048
	ds_read_b128 v[174:177], v217 offset:3072
	ds_read_b128 v[196:199], v217 offset:4096
	ds_read_b128 v[200:203], v217 offset:5120
	ds_read_b128 v[204:207], v217 offset:6144
	ds_read_b128 v[208:211], v217 offset:7168
	global_load_lds_dwordx4 v[192:193], off
	v_lshl_add_u64 v[192:193], s[30:31], 0, v[190:191]
	s_add_i32 m0, s40, 0xe000
	s_nop 0
	global_load_lds_dwordx4 v[192:193], off
	s_waitcnt vmcnt(8)
	s_waitcnt lgkmcnt(0)
	s_barrier
	s_setprio 1
	v_mfma_f32_16x16x32_bf16 v[126:129], v[130:133], v[162:165], 0
	v_mfma_f32_16x16x32_bf16 v[122:125], v[138:141], v[162:165], 0
	v_mfma_f32_16x16x32_bf16 v[118:121], v[130:133], v[170:173], 0
	v_mfma_f32_16x16x32_bf16 v[114:117], v[138:141], v[170:173], 0
	v_mfma_f32_16x16x32_bf16 v[94:97], v[130:133], v[196:199], 0
	v_mfma_f32_16x16x32_bf16 v[90:93], v[138:141], v[196:199], 0
	v_mfma_f32_16x16x32_bf16 v[86:89], v[130:133], v[204:207], 0
	v_mfma_f32_16x16x32_bf16 v[82:85], v[138:141], v[204:207], 0
	v_mfma_f32_16x16x32_bf16 v[126:129], v[134:137], v[166:169], v[126:129]
	v_mfma_f32_16x16x32_bf16 v[122:125], v[142:145], v[166:169], v[122:125]
	v_mfma_f32_16x16x32_bf16 v[118:121], v[134:137], v[174:177], v[118:121]
	v_mfma_f32_16x16x32_bf16 v[114:117], v[142:145], v[174:177], v[114:117]
	v_mfma_f32_16x16x32_bf16 v[94:97], v[134:137], v[200:203], v[94:97]
	v_mfma_f32_16x16x32_bf16 v[90:93], v[142:145], v[200:203], v[90:93]
	v_mfma_f32_16x16x32_bf16 v[86:89], v[134:137], v[208:211], v[86:89]
	v_mfma_f32_16x16x32_bf16 v[82:85], v[142:145], v[208:211], v[82:85]
	s_setprio 0
	s_setprio 1
	v_mfma_f32_16x16x32_bf16 v[110:113], v[146:149], v[162:165], 0
	v_mfma_f32_16x16x32_bf16 v[106:109], v[154:157], v[162:165], 0
	v_mfma_f32_16x16x32_bf16 v[102:105], v[146:149], v[170:173], 0
	v_mfma_f32_16x16x32_bf16 v[98:101], v[154:157], v[170:173], 0
	v_mfma_f32_16x16x32_bf16 v[78:81], v[146:149], v[196:199], 0
	v_mfma_f32_16x16x32_bf16 v[74:77], v[154:157], v[196:199], 0
	v_mfma_f32_16x16x32_bf16 v[70:73], v[146:149], v[204:207], 0
	v_mfma_f32_16x16x32_bf16 v[66:69], v[154:157], v[204:207], 0
	v_mfma_f32_16x16x32_bf16 v[110:113], v[150:153], v[166:169], v[110:113]
	v_mfma_f32_16x16x32_bf16 v[106:109], v[158:161], v[166:169], v[106:109]
	v_mfma_f32_16x16x32_bf16 v[102:105], v[150:153], v[174:177], v[102:105]
	v_mfma_f32_16x16x32_bf16 v[98:101], v[158:161], v[174:177], v[98:101]
	v_mfma_f32_16x16x32_bf16 v[78:81], v[150:153], v[200:203], v[78:81]
	v_mfma_f32_16x16x32_bf16 v[74:77], v[158:161], v[200:203], v[74:77]
	v_mfma_f32_16x16x32_bf16 v[70:73], v[150:153], v[208:211], v[70:73]
	v_mfma_f32_16x16x32_bf16 v[66:69], v[158:161], v[208:211], v[66:69]
	s_setprio 0
	s_barrier
	s_add_i32 s39, s53, s33
	v_lshl_add_u64 v[192:193], s[34:35], 0, v[180:181]
	s_mov_b32 m0, s39
	ds_read_b128 v[162:165], v217 offset:16384
	ds_read_b128 v[166:169], v217 offset:17408
	ds_read_b128 v[170:173], v217 offset:18432
	ds_read_b128 v[174:177], v217 offset:19456
	ds_read_b128 v[196:199], v217 offset:20480
	ds_read_b128 v[200:203], v217 offset:21504
	ds_read_b128 v[204:207], v217 offset:22528
	ds_read_b128 v[208:211], v217 offset:23552
	global_load_lds_dwordx4 v[192:193], off
	s_add_i32 m0, s39, 0x2000
	s_add_u32 s62, s34, 0x160000
	v_lshl_add_u64 v[218:219], s[34:35], 0, v[184:185]
	s_addc_u32 s63, s35, 0
	s_add_i32 s39, s54, s33
	global_load_lds_dwordx4 v[218:219], off
	v_lshl_add_u64 v[220:221], s[62:63], 0, v[180:181]
	s_mov_b32 m0, s39
	v_lshl_add_u64 v[222:223], s[36:37], 0, v[182:183]
	global_load_lds_dwordx4 v[220:221], off
	v_lshl_add_u64 v[220:221], s[62:63], 0, v[184:185]
	s_add_i32 m0, s39, 0x2000
	s_nop 0
	global_load_lds_dwordx4 v[220:221], off
	v_lshl_add_u64 v[220:221], s[36:37], 0, v[178:179]
	s_mov_b32 m0, s40
	s_nop 0
	global_load_lds_dwordx4 v[220:221], off
	s_mov_b32 m0, s41
	s_nop 0
	global_load_lds_dwordx4 v[222:223], off
	s_waitcnt vmcnt(8)
	s_waitcnt lgkmcnt(0)
	s_barrier
	s_setprio 1
	v_mfma_f32_16x16x32_bf16 v[62:65], v[130:133], v[162:165], 0
	v_mfma_f32_16x16x32_bf16 v[58:61], v[138:141], v[162:165], 0
	v_mfma_f32_16x16x32_bf16 v[54:57], v[130:133], v[170:173], 0
	v_mfma_f32_16x16x32_bf16 v[50:53], v[138:141], v[170:173], 0
	v_mfma_f32_16x16x32_bf16 v[30:33], v[130:133], v[196:199], 0
	v_mfma_f32_16x16x32_bf16 v[26:29], v[138:141], v[196:199], 0
	v_mfma_f32_16x16x32_bf16 v[22:25], v[130:133], v[204:207], 0
	v_mfma_f32_16x16x32_bf16 v[18:21], v[138:141], v[204:207], 0
	v_mfma_f32_16x16x32_bf16 v[62:65], v[134:137], v[166:169], v[62:65]
	v_mfma_f32_16x16x32_bf16 v[58:61], v[142:145], v[166:169], v[58:61]
	v_mfma_f32_16x16x32_bf16 v[54:57], v[134:137], v[174:177], v[54:57]
	v_mfma_f32_16x16x32_bf16 v[50:53], v[142:145], v[174:177], v[50:53]
	v_mfma_f32_16x16x32_bf16 v[30:33], v[134:137], v[200:203], v[30:33]
	v_mfma_f32_16x16x32_bf16 v[26:29], v[142:145], v[200:203], v[26:29]
	v_mfma_f32_16x16x32_bf16 v[22:25], v[134:137], v[208:211], v[22:25]
	v_mfma_f32_16x16x32_bf16 v[18:21], v[142:145], v[208:211], v[18:21]
	s_setprio 0
	s_setprio 1
	v_mfma_f32_16x16x32_bf16 v[46:49], v[146:149], v[162:165], 0
	v_mfma_f32_16x16x32_bf16 v[42:45], v[154:157], v[162:165], 0
	v_mfma_f32_16x16x32_bf16 v[38:41], v[146:149], v[170:173], 0
	v_mfma_f32_16x16x32_bf16 v[34:37], v[154:157], v[170:173], 0
	v_mfma_f32_16x16x32_bf16 v[14:17], v[146:149], v[196:199], 0
	v_mfma_f32_16x16x32_bf16 v[10:13], v[154:157], v[196:199], 0
	v_mfma_f32_16x16x32_bf16 v[6:9], v[146:149], v[204:207], 0
	v_mfma_f32_16x16x32_bf16 v[2:5], v[154:157], v[204:207], 0
	v_mfma_f32_16x16x32_bf16 v[46:49], v[150:153], v[166:169], v[46:49]
	v_mfma_f32_16x16x32_bf16 v[42:45], v[158:161], v[166:169], v[42:45]
	v_mfma_f32_16x16x32_bf16 v[38:41], v[150:153], v[174:177], v[38:41]
	v_mfma_f32_16x16x32_bf16 v[34:37], v[158:161], v[174:177], v[34:37]
	v_mfma_f32_16x16x32_bf16 v[14:17], v[150:153], v[200:203], v[14:17]
	v_mfma_f32_16x16x32_bf16 v[10:13], v[158:161], v[200:203], v[10:13]
	v_mfma_f32_16x16x32_bf16 v[6:9], v[150:153], v[208:211], v[6:9]
	v_mfma_f32_16x16x32_bf16 v[2:5], v[158:161], v[208:211], v[2:5]
	s_setprio 0
	s_barrier
	s_add_i32 s39, 0, 0x18000
	s_add_i32 s62, 0, 0x1c000
	v_add_u32_e32 v142, s39, v213
	v_add_u32_e32 v158, s62, v213
	ds_read_b128 v[130:133], v142
	ds_read_b128 v[134:137], v142 offset:1024
	ds_read_b128 v[138:141], v142 offset:2048
	ds_read_b128 v[142:145], v142 offset:3072
	ds_read_b128 v[146:149], v158
	ds_read_b128 v[150:153], v158 offset:1024
	ds_read_b128 v[154:157], v158 offset:2048
	ds_read_b128 v[158:161], v158 offset:3072
	s_add_u32 s36, s36, 0x160000
	s_addc_u32 s37, s37, 0
	s_mov_b32 m0, s42
	v_lshl_add_u64 v[224:225], s[36:37], 0, v[178:179]
	ds_read_b128 v[162:165], v217 offset:32768
	ds_read_b128 v[166:169], v217 offset:33792
	ds_read_b128 v[170:173], v217 offset:34816
	ds_read_b128 v[174:177], v217 offset:35840
	ds_read_b128 v[196:199], v217 offset:36864
	ds_read_b128 v[200:203], v217 offset:37888
	ds_read_b128 v[204:207], v217 offset:38912
	ds_read_b128 v[208:211], v217 offset:39936
	global_load_lds_dwordx4 v[224:225], off
	v_lshl_add_u64 v[224:225], s[36:37], 0, v[182:183]
	s_mov_b32 m0, s43
	s_nop 0
	global_load_lds_dwordx4 v[224:225], off
	s_waitcnt vmcnt(8)
	s_waitcnt lgkmcnt(0)
	s_barrier
	s_setprio 1
	v_mfma_f32_16x16x32_bf16 v[126:129], v[130:133], v[162:165], v[126:129]
	v_mfma_f32_16x16x32_bf16 v[122:125], v[138:141], v[162:165], v[122:125]
	v_mfma_f32_16x16x32_bf16 v[118:121], v[130:133], v[170:173], v[118:121]
	v_mfma_f32_16x16x32_bf16 v[114:117], v[138:141], v[170:173], v[114:117]
	v_mfma_f32_16x16x32_bf16 v[94:97], v[130:133], v[196:199], v[94:97]
	v_mfma_f32_16x16x32_bf16 v[90:93], v[138:141], v[196:199], v[90:93]
	v_mfma_f32_16x16x32_bf16 v[86:89], v[130:133], v[204:207], v[86:89]
	v_mfma_f32_16x16x32_bf16 v[82:85], v[138:141], v[204:207], v[82:85]
	v_mfma_f32_16x16x32_bf16 v[126:129], v[134:137], v[166:169], v[126:129]
	v_mfma_f32_16x16x32_bf16 v[122:125], v[142:145], v[166:169], v[122:125]
	v_mfma_f32_16x16x32_bf16 v[118:121], v[134:137], v[174:177], v[118:121]
	v_mfma_f32_16x16x32_bf16 v[114:117], v[142:145], v[174:177], v[114:117]
	v_mfma_f32_16x16x32_bf16 v[94:97], v[134:137], v[200:203], v[94:97]
	v_mfma_f32_16x16x32_bf16 v[90:93], v[142:145], v[200:203], v[90:93]
	v_mfma_f32_16x16x32_bf16 v[86:89], v[134:137], v[208:211], v[86:89]
	v_mfma_f32_16x16x32_bf16 v[82:85], v[142:145], v[208:211], v[82:85]
	s_setprio 0
	s_setprio 1
	v_mfma_f32_16x16x32_bf16 v[110:113], v[146:149], v[162:165], v[110:113]
	v_mfma_f32_16x16x32_bf16 v[106:109], v[154:157], v[162:165], v[106:109]
	v_mfma_f32_16x16x32_bf16 v[102:105], v[146:149], v[170:173], v[102:105]
	v_mfma_f32_16x16x32_bf16 v[98:101], v[154:157], v[170:173], v[98:101]
	v_mfma_f32_16x16x32_bf16 v[78:81], v[146:149], v[196:199], v[78:81]
	v_mfma_f32_16x16x32_bf16 v[74:77], v[154:157], v[196:199], v[74:77]
	v_mfma_f32_16x16x32_bf16 v[70:73], v[146:149], v[204:207], v[70:73]
	v_mfma_f32_16x16x32_bf16 v[66:69], v[154:157], v[204:207], v[66:69]
	v_mfma_f32_16x16x32_bf16 v[110:113], v[150:153], v[166:169], v[110:113]
	v_mfma_f32_16x16x32_bf16 v[106:109], v[158:161], v[166:169], v[106:109]
	v_mfma_f32_16x16x32_bf16 v[102:105], v[150:153], v[174:177], v[102:105]
	v_mfma_f32_16x16x32_bf16 v[98:101], v[158:161], v[174:177], v[98:101]
	v_mfma_f32_16x16x32_bf16 v[78:81], v[150:153], v[200:203], v[78:81]
	v_mfma_f32_16x16x32_bf16 v[74:77], v[158:161], v[200:203], v[74:77]
	v_mfma_f32_16x16x32_bf16 v[70:73], v[150:153], v[208:211], v[70:73]
	v_mfma_f32_16x16x32_bf16 v[66:69], v[158:161], v[208:211], v[66:69]
	s_setprio 0
	s_barrier
	s_add_i32 s36, s39, s33
	v_lshl_add_u64 v[192:193], v[192:193], 0, s[18:19]
	s_mov_b32 m0, s36
	ds_read_b128 v[162:165], v217 offset:49152
	ds_read_b128 v[166:169], v217 offset:50176
	ds_read_b128 v[170:173], v217 offset:51200
	ds_read_b128 v[174:177], v217 offset:52224
	ds_read_b128 v[196:199], v217 offset:53248
	ds_read_b128 v[200:203], v217 offset:54272
	ds_read_b128 v[204:207], v217 offset:55296
	ds_read_b128 v[208:211], v217 offset:56320
	global_load_lds_dwordx4 v[192:193], off
	s_add_i32 m0, s36, 0x2000
	s_add_u32 s34, s34, 0x160080
	v_lshl_add_u64 v[192:193], v[218:219], 0, s[18:19]
	s_addc_u32 s35, s35, 0
	s_add_i32 s36, s62, s33
	global_load_lds_dwordx4 v[192:193], off
	v_lshl_add_u64 v[192:193], s[34:35], 0, v[180:181]
	s_mov_b32 m0, s36
	s_nop 0
	global_load_lds_dwordx4 v[192:193], off
	v_lshl_add_u64 v[192:193], s[34:35], 0, v[184:185]
	s_add_i32 m0, s36, 0x2000
	s_nop 0
	global_load_lds_dwordx4 v[192:193], off
	v_lshl_add_u64 v[192:193], v[220:221], 0, s[18:19]
	s_mov_b32 m0, s46
	s_nop 0
	global_load_lds_dwordx4 v[192:193], off
	v_lshl_add_u64 v[192:193], v[222:223], 0, s[18:19]
	s_mov_b32 m0, s47
	s_nop 0
	global_load_lds_dwordx4 v[192:193], off
	s_waitcnt vmcnt(8)
	s_waitcnt lgkmcnt(0)
	s_barrier
	s_setprio 1
	v_mfma_f32_16x16x32_bf16 v[62:65], v[130:133], v[162:165], v[62:65]
	v_mfma_f32_16x16x32_bf16 v[58:61], v[138:141], v[162:165], v[58:61]
	v_mfma_f32_16x16x32_bf16 v[54:57], v[130:133], v[170:173], v[54:57]
	v_mfma_f32_16x16x32_bf16 v[50:53], v[138:141], v[170:173], v[50:53]
	v_mfma_f32_16x16x32_bf16 v[30:33], v[130:133], v[196:199], v[30:33]
	v_mfma_f32_16x16x32_bf16 v[26:29], v[138:141], v[196:199], v[26:29]
	v_mfma_f32_16x16x32_bf16 v[22:25], v[130:133], v[204:207], v[22:25]
	v_mfma_f32_16x16x32_bf16 v[18:21], v[138:141], v[204:207], v[18:21]
	v_mfma_f32_16x16x32_bf16 v[62:65], v[134:137], v[166:169], v[62:65]
	v_mfma_f32_16x16x32_bf16 v[58:61], v[142:145], v[166:169], v[58:61]
	v_mfma_f32_16x16x32_bf16 v[54:57], v[134:137], v[174:177], v[54:57]
	v_mfma_f32_16x16x32_bf16 v[50:53], v[142:145], v[174:177], v[50:53]
	v_mfma_f32_16x16x32_bf16 v[30:33], v[134:137], v[200:203], v[30:33]
	v_mfma_f32_16x16x32_bf16 v[26:29], v[142:145], v[200:203], v[26:29]
	v_mfma_f32_16x16x32_bf16 v[22:25], v[134:137], v[208:211], v[22:25]
	v_mfma_f32_16x16x32_bf16 v[18:21], v[142:145], v[208:211], v[18:21]
	s_setprio 0
	s_setprio 1
	v_mfma_f32_16x16x32_bf16 v[46:49], v[146:149], v[162:165], v[46:49]
	v_mfma_f32_16x16x32_bf16 v[42:45], v[154:157], v[162:165], v[42:45]
	v_mfma_f32_16x16x32_bf16 v[38:41], v[146:149], v[170:173], v[38:41]
	v_mfma_f32_16x16x32_bf16 v[34:37], v[154:157], v[170:173], v[34:37]
	v_mfma_f32_16x16x32_bf16 v[14:17], v[146:149], v[196:199], v[14:17]
	v_mfma_f32_16x16x32_bf16 v[10:13], v[154:157], v[196:199], v[10:13]
	v_mfma_f32_16x16x32_bf16 v[6:9], v[146:149], v[204:207], v[6:9]
	v_mfma_f32_16x16x32_bf16 v[2:5], v[154:157], v[204:207], v[2:5]
	v_mfma_f32_16x16x32_bf16 v[46:49], v[150:153], v[166:169], v[46:49]
	v_mfma_f32_16x16x32_bf16 v[42:45], v[158:161], v[166:169], v[42:45]
	v_mfma_f32_16x16x32_bf16 v[38:41], v[150:153], v[174:177], v[38:41]
	v_mfma_f32_16x16x32_bf16 v[34:37], v[158:161], v[174:177], v[34:37]
	v_mfma_f32_16x16x32_bf16 v[14:17], v[150:153], v[200:203], v[14:17]
	v_mfma_f32_16x16x32_bf16 v[10:13], v[158:161], v[200:203], v[10:13]
	v_mfma_f32_16x16x32_bf16 v[6:9], v[150:153], v[208:211], v[6:9]
	v_mfma_f32_16x16x32_bf16 v[2:5], v[158:161], v[208:211], v[2:5]
	s_setprio 0
	s_barrier
	s_add_u32 s30, s30, 0x100
	s_addc_u32 s31, s31, 0
	s_add_u32 s23, s23, 0x100
	s_addc_u32 s29, s29, 0
	s_cmp_ge_i32 s38, s61
	s_mov_b32 s34, s38
	s_cbranch_scc0 .LBB0_357
	s_branch .Lpeeldone_12
.LBB0_357:
	ds_read_b128 v[130:133], v215
	ds_read_b128 v[134:137], v215 offset:1024
	ds_read_b128 v[138:141], v215 offset:2048
	ds_read_b128 v[142:145], v215 offset:3072
	ds_read_b128 v[146:149], v216
	ds_read_b128 v[150:153], v216 offset:1024
	ds_read_b128 v[154:157], v216 offset:2048
	ds_read_b128 v[158:161], v216 offset:3072
	s_add_i32 s38, s34, 2
	s_add_u32 s35, s30, 0xffea0080
	s_addc_u32 s36, s31, -1
	s_cmp_eq_u32 s28, s34
	s_cselect_b32 s34, s26, s23
	s_cselect_b32 s37, s25, s36
	s_cselect_b32 s36, s24, s35
	s_cselect_b32 s35, s27, s29
	v_lshl_add_u64 v[192:193], s[30:31], 0, v[188:189]
	s_add_i32 m0, s40, 0xc000
	ds_read_b128 v[162:165], v217
	ds_read_b128 v[166:169], v217 offset:1024
	ds_read_b128 v[170:173], v217 offset:2048
	ds_read_b128 v[174:177], v217 offset:3072
	ds_read_b128 v[196:199], v217 offset:4096
	ds_read_b128 v[200:203], v217 offset:5120
	ds_read_b128 v[204:207], v217 offset:6144
	ds_read_b128 v[208:211], v217 offset:7168
	global_load_lds_dwordx4 v[192:193], off
	v_lshl_add_u64 v[192:193], s[30:31], 0, v[190:191]
	s_add_i32 m0, s40, 0xe000
	s_nop 0
	global_load_lds_dwordx4 v[192:193], off
	s_waitcnt vmcnt(8)
	s_waitcnt lgkmcnt(0)
	s_barrier
	s_setprio 1
	v_mfma_f32_16x16x32_bf16 v[126:129], v[130:133], v[162:165], v[126:129]
	v_mfma_f32_16x16x32_bf16 v[122:125], v[138:141], v[162:165], v[122:125]
	v_mfma_f32_16x16x32_bf16 v[118:121], v[130:133], v[170:173], v[118:121]
	v_mfma_f32_16x16x32_bf16 v[114:117], v[138:141], v[170:173], v[114:117]
	v_mfma_f32_16x16x32_bf16 v[94:97], v[130:133], v[196:199], v[94:97]
	v_mfma_f32_16x16x32_bf16 v[90:93], v[138:141], v[196:199], v[90:93]
	v_mfma_f32_16x16x32_bf16 v[86:89], v[130:133], v[204:207], v[86:89]
	v_mfma_f32_16x16x32_bf16 v[82:85], v[138:141], v[204:207], v[82:85]
	v_mfma_f32_16x16x32_bf16 v[126:129], v[134:137], v[166:169], v[126:129]
	v_mfma_f32_16x16x32_bf16 v[122:125], v[142:145], v[166:169], v[122:125]
	v_mfma_f32_16x16x32_bf16 v[118:121], v[134:137], v[174:177], v[118:121]
	v_mfma_f32_16x16x32_bf16 v[114:117], v[142:145], v[174:177], v[114:117]
	v_mfma_f32_16x16x32_bf16 v[94:97], v[134:137], v[200:203], v[94:97]
	v_mfma_f32_16x16x32_bf16 v[90:93], v[142:145], v[200:203], v[90:93]
	v_mfma_f32_16x16x32_bf16 v[86:89], v[134:137], v[208:211], v[86:89]
	v_mfma_f32_16x16x32_bf16 v[82:85], v[142:145], v[208:211], v[82:85]
	s_setprio 0
	s_setprio 1
	v_mfma_f32_16x16x32_bf16 v[110:113], v[146:149], v[162:165], v[110:113]
	v_mfma_f32_16x16x32_bf16 v[106:109], v[154:157], v[162:165], v[106:109]
	v_mfma_f32_16x16x32_bf16 v[102:105], v[146:149], v[170:173], v[102:105]
	v_mfma_f32_16x16x32_bf16 v[98:101], v[154:157], v[170:173], v[98:101]
	v_mfma_f32_16x16x32_bf16 v[78:81], v[146:149], v[196:199], v[78:81]
	v_mfma_f32_16x16x32_bf16 v[74:77], v[154:157], v[196:199], v[74:77]
	v_mfma_f32_16x16x32_bf16 v[70:73], v[146:149], v[204:207], v[70:73]
	v_mfma_f32_16x16x32_bf16 v[66:69], v[154:157], v[204:207], v[66:69]
	v_mfma_f32_16x16x32_bf16 v[110:113], v[150:153], v[166:169], v[110:113]
	v_mfma_f32_16x16x32_bf16 v[106:109], v[158:161], v[166:169], v[106:109]
	v_mfma_f32_16x16x32_bf16 v[102:105], v[150:153], v[174:177], v[102:105]
	v_mfma_f32_16x16x32_bf16 v[98:101], v[158:161], v[174:177], v[98:101]
	v_mfma_f32_16x16x32_bf16 v[78:81], v[150:153], v[200:203], v[78:81]
	v_mfma_f32_16x16x32_bf16 v[74:77], v[158:161], v[200:203], v[74:77]
	v_mfma_f32_16x16x32_bf16 v[70:73], v[150:153], v[208:211], v[70:73]
	v_mfma_f32_16x16x32_bf16 v[66:69], v[158:161], v[208:211], v[66:69]
	s_setprio 0
	s_barrier
	s_add_i32 s39, s53, s33
	v_lshl_add_u64 v[192:193], s[34:35], 0, v[180:181]
	s_mov_b32 m0, s39
	ds_read_b128 v[162:165], v217 offset:16384
	ds_read_b128 v[166:169], v217 offset:17408
	ds_read_b128 v[170:173], v217 offset:18432
	ds_read_b128 v[174:177], v217 offset:19456
	ds_read_b128 v[196:199], v217 offset:20480
	ds_read_b128 v[200:203], v217 offset:21504
	ds_read_b128 v[204:207], v217 offset:22528
	ds_read_b128 v[208:211], v217 offset:23552
	global_load_lds_dwordx4 v[192:193], off
	s_add_i32 m0, s39, 0x2000
	s_add_u32 s62, s34, 0x160000
	v_lshl_add_u64 v[218:219], s[34:35], 0, v[184:185]
	s_addc_u32 s63, s35, 0
	s_add_i32 s39, s54, s33
	global_load_lds_dwordx4 v[218:219], off
	v_lshl_add_u64 v[220:221], s[62:63], 0, v[180:181]
	s_mov_b32 m0, s39
	v_lshl_add_u64 v[222:223], s[36:37], 0, v[182:183]
	global_load_lds_dwordx4 v[220:221], off
	v_lshl_add_u64 v[220:221], s[62:63], 0, v[184:185]
	s_add_i32 m0, s39, 0x2000
	s_nop 0
	global_load_lds_dwordx4 v[220:221], off
	v_lshl_add_u64 v[220:221], s[36:37], 0, v[178:179]
	s_mov_b32 m0, s40
	s_nop 0
	global_load_lds_dwordx4 v[220:221], off
	s_mov_b32 m0, s41
	s_nop 0
	global_load_lds_dwordx4 v[222:223], off
	s_waitcnt vmcnt(8)
	s_waitcnt lgkmcnt(0)
	s_barrier
	s_setprio 1
	v_mfma_f32_16x16x32_bf16 v[62:65], v[130:133], v[162:165], v[62:65]
	v_mfma_f32_16x16x32_bf16 v[58:61], v[138:141], v[162:165], v[58:61]
	v_mfma_f32_16x16x32_bf16 v[54:57], v[130:133], v[170:173], v[54:57]
	v_mfma_f32_16x16x32_bf16 v[50:53], v[138:141], v[170:173], v[50:53]
	v_mfma_f32_16x16x32_bf16 v[30:33], v[130:133], v[196:199], v[30:33]
	v_mfma_f32_16x16x32_bf16 v[26:29], v[138:141], v[196:199], v[26:29]
	v_mfma_f32_16x16x32_bf16 v[22:25], v[130:133], v[204:207], v[22:25]
	v_mfma_f32_16x16x32_bf16 v[18:21], v[138:141], v[204:207], v[18:21]
	v_mfma_f32_16x16x32_bf16 v[62:65], v[134:137], v[166:169], v[62:65]
	v_mfma_f32_16x16x32_bf16 v[58:61], v[142:145], v[166:169], v[58:61]
	v_mfma_f32_16x16x32_bf16 v[54:57], v[134:137], v[174:177], v[54:57]
	v_mfma_f32_16x16x32_bf16 v[50:53], v[142:145], v[174:177], v[50:53]
	v_mfma_f32_16x16x32_bf16 v[30:33], v[134:137], v[200:203], v[30:33]
	v_mfma_f32_16x16x32_bf16 v[26:29], v[142:145], v[200:203], v[26:29]
	v_mfma_f32_16x16x32_bf16 v[22:25], v[134:137], v[208:211], v[22:25]
	v_mfma_f32_16x16x32_bf16 v[18:21], v[142:145], v[208:211], v[18:21]
	s_setprio 0
	s_setprio 1
	v_mfma_f32_16x16x32_bf16 v[46:49], v[146:149], v[162:165], v[46:49]
	v_mfma_f32_16x16x32_bf16 v[42:45], v[154:157], v[162:165], v[42:45]
	v_mfma_f32_16x16x32_bf16 v[38:41], v[146:149], v[170:173], v[38:41]
	v_mfma_f32_16x16x32_bf16 v[34:37], v[154:157], v[170:173], v[34:37]
	v_mfma_f32_16x16x32_bf16 v[14:17], v[146:149], v[196:199], v[14:17]
	v_mfma_f32_16x16x32_bf16 v[10:13], v[154:157], v[196:199], v[10:13]
	v_mfma_f32_16x16x32_bf16 v[6:9], v[146:149], v[204:207], v[6:9]
	v_mfma_f32_16x16x32_bf16 v[2:5], v[154:157], v[204:207], v[2:5]
	v_mfma_f32_16x16x32_bf16 v[46:49], v[150:153], v[166:169], v[46:49]
	v_mfma_f32_16x16x32_bf16 v[42:45], v[158:161], v[166:169], v[42:45]
	v_mfma_f32_16x16x32_bf16 v[38:41], v[150:153], v[174:177], v[38:41]
	v_mfma_f32_16x16x32_bf16 v[34:37], v[158:161], v[174:177], v[34:37]
	v_mfma_f32_16x16x32_bf16 v[14:17], v[150:153], v[200:203], v[14:17]
	v_mfma_f32_16x16x32_bf16 v[10:13], v[158:161], v[200:203], v[10:13]
	v_mfma_f32_16x16x32_bf16 v[6:9], v[150:153], v[208:211], v[6:9]
	v_mfma_f32_16x16x32_bf16 v[2:5], v[158:161], v[208:211], v[2:5]
	s_setprio 0
	s_barrier
	s_add_i32 s39, 0, 0x18000
	s_add_i32 s62, 0, 0x1c000
	v_add_u32_e32 v142, s39, v213
	v_add_u32_e32 v158, s62, v213
	ds_read_b128 v[130:133], v142
	ds_read_b128 v[134:137], v142 offset:1024
	ds_read_b128 v[138:141], v142 offset:2048
	ds_read_b128 v[142:145], v142 offset:3072
	ds_read_b128 v[146:149], v158
	ds_read_b128 v[150:153], v158 offset:1024
	ds_read_b128 v[154:157], v158 offset:2048
	ds_read_b128 v[158:161], v158 offset:3072
	s_add_u32 s36, s36, 0x160000
	s_addc_u32 s37, s37, 0
	s_mov_b32 m0, s42
	v_lshl_add_u64 v[224:225], s[36:37], 0, v[178:179]
	ds_read_b128 v[162:165], v217 offset:32768
	ds_read_b128 v[166:169], v217 offset:33792
	ds_read_b128 v[170:173], v217 offset:34816
	ds_read_b128 v[174:177], v217 offset:35840
	ds_read_b128 v[196:199], v217 offset:36864
	ds_read_b128 v[200:203], v217 offset:37888
	ds_read_b128 v[204:207], v217 offset:38912
	ds_read_b128 v[208:211], v217 offset:39936
	global_load_lds_dwordx4 v[224:225], off
	v_lshl_add_u64 v[224:225], s[36:37], 0, v[182:183]
	s_mov_b32 m0, s43
	s_nop 0
	global_load_lds_dwordx4 v[224:225], off
	s_waitcnt vmcnt(8)
	s_waitcnt lgkmcnt(0)
	s_barrier
	s_setprio 1
	v_mfma_f32_16x16x32_bf16 v[126:129], v[130:133], v[162:165], v[126:129]
	v_mfma_f32_16x16x32_bf16 v[122:125], v[138:141], v[162:165], v[122:125]
	v_mfma_f32_16x16x32_bf16 v[118:121], v[130:133], v[170:173], v[118:121]
	v_mfma_f32_16x16x32_bf16 v[114:117], v[138:141], v[170:173], v[114:117]
	v_mfma_f32_16x16x32_bf16 v[94:97], v[130:133], v[196:199], v[94:97]
	v_mfma_f32_16x16x32_bf16 v[90:93], v[138:141], v[196:199], v[90:93]
	v_mfma_f32_16x16x32_bf16 v[86:89], v[130:133], v[204:207], v[86:89]
	v_mfma_f32_16x16x32_bf16 v[82:85], v[138:141], v[204:207], v[82:85]
	v_mfma_f32_16x16x32_bf16 v[126:129], v[134:137], v[166:169], v[126:129]
	v_mfma_f32_16x16x32_bf16 v[122:125], v[142:145], v[166:169], v[122:125]
	v_mfma_f32_16x16x32_bf16 v[118:121], v[134:137], v[174:177], v[118:121]
	v_mfma_f32_16x16x32_bf16 v[114:117], v[142:145], v[174:177], v[114:117]
	v_mfma_f32_16x16x32_bf16 v[94:97], v[134:137], v[200:203], v[94:97]
	v_mfma_f32_16x16x32_bf16 v[90:93], v[142:145], v[200:203], v[90:93]
	v_mfma_f32_16x16x32_bf16 v[86:89], v[134:137], v[208:211], v[86:89]
	v_mfma_f32_16x16x32_bf16 v[82:85], v[142:145], v[208:211], v[82:85]
	s_setprio 0
	s_setprio 1
	v_mfma_f32_16x16x32_bf16 v[110:113], v[146:149], v[162:165], v[110:113]
	v_mfma_f32_16x16x32_bf16 v[106:109], v[154:157], v[162:165], v[106:109]
	v_mfma_f32_16x16x32_bf16 v[102:105], v[146:149], v[170:173], v[102:105]
	v_mfma_f32_16x16x32_bf16 v[98:101], v[154:157], v[170:173], v[98:101]
	v_mfma_f32_16x16x32_bf16 v[78:81], v[146:149], v[196:199], v[78:81]
	v_mfma_f32_16x16x32_bf16 v[74:77], v[154:157], v[196:199], v[74:77]
	v_mfma_f32_16x16x32_bf16 v[70:73], v[146:149], v[204:207], v[70:73]
	v_mfma_f32_16x16x32_bf16 v[66:69], v[154:157], v[204:207], v[66:69]
	v_mfma_f32_16x16x32_bf16 v[110:113], v[150:153], v[166:169], v[110:113]
	v_mfma_f32_16x16x32_bf16 v[106:109], v[158:161], v[166:169], v[106:109]
	v_mfma_f32_16x16x32_bf16 v[102:105], v[150:153], v[174:177], v[102:105]
	v_mfma_f32_16x16x32_bf16 v[98:101], v[158:161], v[174:177], v[98:101]
	v_mfma_f32_16x16x32_bf16 v[78:81], v[150:153], v[200:203], v[78:81]
	v_mfma_f32_16x16x32_bf16 v[74:77], v[158:161], v[200:203], v[74:77]
	v_mfma_f32_16x16x32_bf16 v[70:73], v[150:153], v[208:211], v[70:73]
	v_mfma_f32_16x16x32_bf16 v[66:69], v[158:161], v[208:211], v[66:69]
	s_setprio 0
	s_barrier
	s_add_i32 s36, s39, s33
	v_lshl_add_u64 v[192:193], v[192:193], 0, s[18:19]
	s_mov_b32 m0, s36
	ds_read_b128 v[162:165], v217 offset:49152
	ds_read_b128 v[166:169], v217 offset:50176
	ds_read_b128 v[170:173], v217 offset:51200
	ds_read_b128 v[174:177], v217 offset:52224
	ds_read_b128 v[196:199], v217 offset:53248
	ds_read_b128 v[200:203], v217 offset:54272
	ds_read_b128 v[204:207], v217 offset:55296
	ds_read_b128 v[208:211], v217 offset:56320
	global_load_lds_dwordx4 v[192:193], off
	s_add_i32 m0, s36, 0x2000
	s_add_u32 s34, s34, 0x160080
	v_lshl_add_u64 v[192:193], v[218:219], 0, s[18:19]
	s_addc_u32 s35, s35, 0
	s_add_i32 s36, s62, s33
	global_load_lds_dwordx4 v[192:193], off
	v_lshl_add_u64 v[192:193], s[34:35], 0, v[180:181]
	s_mov_b32 m0, s36
	s_nop 0
	global_load_lds_dwordx4 v[192:193], off
	v_lshl_add_u64 v[192:193], s[34:35], 0, v[184:185]
	s_add_i32 m0, s36, 0x2000
	s_nop 0
	global_load_lds_dwordx4 v[192:193], off
	v_lshl_add_u64 v[192:193], v[220:221], 0, s[18:19]
	s_mov_b32 m0, s46
	s_nop 0
	global_load_lds_dwordx4 v[192:193], off
	v_lshl_add_u64 v[192:193], v[222:223], 0, s[18:19]
	s_mov_b32 m0, s47
	s_nop 0
	global_load_lds_dwordx4 v[192:193], off
	s_waitcnt vmcnt(8)
	s_waitcnt lgkmcnt(0)
	s_barrier
	s_setprio 1
	v_mfma_f32_16x16x32_bf16 v[62:65], v[130:133], v[162:165], v[62:65]
	v_mfma_f32_16x16x32_bf16 v[58:61], v[138:141], v[162:165], v[58:61]
	v_mfma_f32_16x16x32_bf16 v[54:57], v[130:133], v[170:173], v[54:57]
	v_mfma_f32_16x16x32_bf16 v[50:53], v[138:141], v[170:173], v[50:53]
	v_mfma_f32_16x16x32_bf16 v[30:33], v[130:133], v[196:199], v[30:33]
	v_mfma_f32_16x16x32_bf16 v[26:29], v[138:141], v[196:199], v[26:29]
	v_mfma_f32_16x16x32_bf16 v[22:25], v[130:133], v[204:207], v[22:25]
	v_mfma_f32_16x16x32_bf16 v[18:21], v[138:141], v[204:207], v[18:21]
	v_mfma_f32_16x16x32_bf16 v[62:65], v[134:137], v[166:169], v[62:65]
	v_mfma_f32_16x16x32_bf16 v[58:61], v[142:145], v[166:169], v[58:61]
	v_mfma_f32_16x16x32_bf16 v[54:57], v[134:137], v[174:177], v[54:57]
	v_mfma_f32_16x16x32_bf16 v[50:53], v[142:145], v[174:177], v[50:53]
	v_mfma_f32_16x16x32_bf16 v[30:33], v[134:137], v[200:203], v[30:33]
	v_mfma_f32_16x16x32_bf16 v[26:29], v[142:145], v[200:203], v[26:29]
	v_mfma_f32_16x16x32_bf16 v[22:25], v[134:137], v[208:211], v[22:25]
	v_mfma_f32_16x16x32_bf16 v[18:21], v[142:145], v[208:211], v[18:21]
	s_setprio 0
	s_setprio 1
	v_mfma_f32_16x16x32_bf16 v[46:49], v[146:149], v[162:165], v[46:49]
	v_mfma_f32_16x16x32_bf16 v[42:45], v[154:157], v[162:165], v[42:45]
	v_mfma_f32_16x16x32_bf16 v[38:41], v[146:149], v[170:173], v[38:41]
	v_mfma_f32_16x16x32_bf16 v[34:37], v[154:157], v[170:173], v[34:37]
	v_mfma_f32_16x16x32_bf16 v[14:17], v[146:149], v[196:199], v[14:17]
	v_mfma_f32_16x16x32_bf16 v[10:13], v[154:157], v[196:199], v[10:13]
	v_mfma_f32_16x16x32_bf16 v[6:9], v[146:149], v[204:207], v[6:9]
	v_mfma_f32_16x16x32_bf16 v[2:5], v[154:157], v[204:207], v[2:5]
	v_mfma_f32_16x16x32_bf16 v[46:49], v[150:153], v[166:169], v[46:49]
	v_mfma_f32_16x16x32_bf16 v[42:45], v[158:161], v[166:169], v[42:45]
	v_mfma_f32_16x16x32_bf16 v[38:41], v[150:153], v[174:177], v[38:41]
	v_mfma_f32_16x16x32_bf16 v[34:37], v[158:161], v[174:177], v[34:37]
	v_mfma_f32_16x16x32_bf16 v[14:17], v[150:153], v[200:203], v[14:17]
	v_mfma_f32_16x16x32_bf16 v[10:13], v[158:161], v[200:203], v[10:13]
	v_mfma_f32_16x16x32_bf16 v[6:9], v[150:153], v[208:211], v[6:9]
	v_mfma_f32_16x16x32_bf16 v[2:5], v[158:161], v[208:211], v[2:5]
	s_setprio 0
	s_barrier
	s_add_u32 s30, s30, 0x100
	s_addc_u32 s31, s31, 0
	s_add_u32 s23, s23, 0x100
	s_addc_u32 s29, s29, 0
	s_cmp_ge_i32 s38, s61
	s_mov_b32 s34, s38
	s_cbranch_scc0 .LBB0_357

.Lpeel_11:
	ds_read_b128 v[148:151], v145
	ds_read_b128 v[152:155], v145 offset:1024
	s_add_u32 s36, s34, 0xfff80080
	s_addc_u32 s37, s35, -1
	s_cmp_eq_u32 s58, 28
	s_cselect_b32 s39, s21, s37
	s_cselect_b32 s38, s54, s36
	s_cselect_b32 s37, s23, s57
	s_cselect_b32 s36, s55, s56
	v_lshl_add_u64 v[192:193], s[34:35], 0, v[138:139]
	s_add_i32 m0, s27, 0xc000
	global_load_lds_dwordx4 v[192:193], off
	v_lshl_add_u64 v[192:193], s[34:35], 0, v[140:141]
	s_add_i32 m0, s27, 0xe000
	s_nop 0
	global_load_lds_dwordx4 v[192:193], off
	s_waitcnt vmcnt(8)
	s_waitcnt lgkmcnt(0)
	s_barrier
	s_setprio 1
	v_mfma_f32_16x16x32_bf16 v[126:129], v[148:151], v[180:183], 0
	v_mfma_f32_16x16x32_bf16 v[122:125], v[156:159], v[180:183], 0
	v_mfma_f32_16x16x32_bf16 v[118:121], v[148:151], v[188:191], 0
	v_mfma_f32_16x16x32_bf16 v[114:117], v[156:159], v[188:191], 0
	v_mfma_f32_16x16x32_bf16 v[102:105], v[148:151], v[200:203], 0
	v_mfma_f32_16x16x32_bf16 v[98:101], v[156:159], v[200:203], 0
	v_mfma_f32_16x16x32_bf16 v[86:89], v[148:151], v[208:211], 0
	v_mfma_f32_16x16x32_bf16 v[82:85], v[156:159], v[208:211], 0
	v_mfma_f32_16x16x32_bf16 v[126:129], v[152:155], v[184:187], v[126:129]
	v_mfma_f32_16x16x32_bf16 v[122:125], v[160:163], v[184:187], v[122:125]
	v_mfma_f32_16x16x32_bf16 v[118:121], v[152:155], v[196:199], v[118:121]
	v_mfma_f32_16x16x32_bf16 v[114:117], v[160:163], v[196:199], v[114:117]
	v_mfma_f32_16x16x32_bf16 v[102:105], v[152:155], v[204:207], v[102:105]
	v_mfma_f32_16x16x32_bf16 v[98:101], v[160:163], v[204:207], v[98:101]
	v_mfma_f32_16x16x32_bf16 v[86:89], v[152:155], v[212:215], v[86:89]
	v_mfma_f32_16x16x32_bf16 v[82:85], v[160:163], v[212:215], v[82:85]
	s_setprio 0
	s_setprio 1
	v_mfma_f32_16x16x32_bf16 v[110:113], v[164:167], v[180:183], 0
	v_mfma_f32_16x16x32_bf16 v[106:109], v[172:175], v[180:183], 0
	v_mfma_f32_16x16x32_bf16 v[94:97], v[164:167], v[188:191], 0
	v_mfma_f32_16x16x32_bf16 v[90:93], v[172:175], v[188:191], 0
	v_mfma_f32_16x16x32_bf16 v[78:81], v[164:167], v[200:203], 0
	v_mfma_f32_16x16x32_bf16 v[74:77], v[172:175], v[200:203], 0
	v_mfma_f32_16x16x32_bf16 v[70:73], v[164:167], v[208:211], 0
	v_mfma_f32_16x16x32_bf16 v[66:69], v[172:175], v[208:211], 0
	v_mfma_f32_16x16x32_bf16 v[110:113], v[168:171], v[184:187], v[110:113]
	v_mfma_f32_16x16x32_bf16 v[106:109], v[176:179], v[184:187], v[106:109]
	v_mfma_f32_16x16x32_bf16 v[94:97], v[168:171], v[196:199], v[94:97]
	v_mfma_f32_16x16x32_bf16 v[90:93], v[176:179], v[196:199], v[90:93]
	v_mfma_f32_16x16x32_bf16 v[78:81], v[168:171], v[204:207], v[78:81]
	v_mfma_f32_16x16x32_bf16 v[74:77], v[176:179], v[204:207], v[74:77]
	v_mfma_f32_16x16x32_bf16 v[70:73], v[168:171], v[212:215], v[70:73]
	v_mfma_f32_16x16x32_bf16 v[66:69], v[176:179], v[212:215], v[66:69]
	s_setprio 0
	s_barrier
	s_add_i32 s59, s47, s33
	v_lshl_add_u64 v[192:193], s[36:37], 0, v[134:135]
	s_mov_b32 m0, s59
	ds_read_b128 v[180:183], v147 offset:16384
	ds_read_b128 v[184:187], v147 offset:17408
	ds_read_b128 v[188:191], v147 offset:18432
	ds_read_b128 v[196:199], v147 offset:19456
	ds_read_b128 v[200:203], v147 offset:20480
	ds_read_b128 v[204:207], v147 offset:21504
	ds_read_b128 v[208:211], v147 offset:22528
	ds_read_b128 v[212:215], v147 offset:23552
	global_load_lds_dwordx4 v[192:193], off
	s_add_i32 m0, s59, 0x2000
	s_add_u32 s60, s36, 0x80000
	v_lshl_add_u64 v[216:217], s[36:37], 0, v[130:131]
	s_addc_u32 s61, s37, 0
	s_add_i32 s59, s48, s33
	global_load_lds_dwordx4 v[216:217], off
	v_lshl_add_u64 v[218:219], s[60:61], 0, v[134:135]
	s_mov_b32 m0, s59
	v_lshl_add_u64 v[220:221], s[38:39], 0, v[132:133]
	global_load_lds_dwordx4 v[218:219], off
	v_lshl_add_u64 v[218:219], s[60:61], 0, v[130:131]
	s_add_i32 m0, s59, 0x2000
	s_nop 0
	global_load_lds_dwordx4 v[218:219], off
	v_lshl_add_u64 v[218:219], s[38:39], 0, v[136:137]
	s_mov_b32 m0, s27
	s_nop 0
	global_load_lds_dwordx4 v[218:219], off
	s_mov_b32 m0, s41
	s_nop 0
	global_load_lds_dwordx4 v[220:221], off
	s_waitcnt vmcnt(8)
	s_waitcnt lgkmcnt(0)
	s_barrier
	s_setprio 1
	v_mfma_f32_16x16x32_bf16 v[62:65], v[148:151], v[180:183], 0
	v_mfma_f32_16x16x32_bf16 v[58:61], v[156:159], v[180:183], 0
	v_mfma_f32_16x16x32_bf16 v[54:57], v[148:151], v[188:191], 0
	v_mfma_f32_16x16x32_bf16 v[50:53], v[156:159], v[188:191], 0
	v_mfma_f32_16x16x32_bf16 v[38:41], v[148:151], v[200:203], 0
	v_mfma_f32_16x16x32_bf16 v[34:37], v[156:159], v[200:203], 0
	v_mfma_f32_16x16x32_bf16 v[22:25], v[148:151], v[208:211], 0
	v_mfma_f32_16x16x32_bf16 v[18:21], v[156:159], v[208:211], 0
	v_mfma_f32_16x16x32_bf16 v[62:65], v[152:155], v[184:187], v[62:65]
	v_mfma_f32_16x16x32_bf16 v[58:61], v[160:163], v[184:187], v[58:61]
	v_mfma_f32_16x16x32_bf16 v[54:57], v[152:155], v[196:199], v[54:57]
	v_mfma_f32_16x16x32_bf16 v[50:53], v[160:163], v[196:199], v[50:53]
	v_mfma_f32_16x16x32_bf16 v[38:41], v[152:155], v[204:207], v[38:41]
	v_mfma_f32_16x16x32_bf16 v[34:37], v[160:163], v[204:207], v[34:37]
	v_mfma_f32_16x16x32_bf16 v[22:25], v[152:155], v[212:215], v[22:25]
	v_mfma_f32_16x16x32_bf16 v[18:21], v[160:163], v[212:215], v[18:21]
	s_setprio 0
	s_setprio 1
	v_mfma_f32_16x16x32_bf16 v[46:49], v[164:167], v[180:183], 0
	v_mfma_f32_16x16x32_bf16 v[42:45], v[172:175], v[180:183], 0
	v_mfma_f32_16x16x32_bf16 v[30:33], v[164:167], v[188:191], 0
	v_mfma_f32_16x16x32_bf16 v[26:29], v[172:175], v[188:191], 0
	v_mfma_f32_16x16x32_bf16 v[14:17], v[164:167], v[200:203], 0
	v_mfma_f32_16x16x32_bf16 v[10:13], v[172:175], v[200:203], 0
	v_mfma_f32_16x16x32_bf16 v[6:9], v[164:167], v[208:211], 0
	v_mfma_f32_16x16x32_bf16 v[2:5], v[172:175], v[208:211], 0
	v_mfma_f32_16x16x32_bf16 v[46:49], v[168:171], v[184:187], v[46:49]
	v_mfma_f32_16x16x32_bf16 v[42:45], v[176:179], v[184:187], v[42:45]
	v_mfma_f32_16x16x32_bf16 v[30:33], v[168:171], v[196:199], v[30:33]
	v_mfma_f32_16x16x32_bf16 v[26:29], v[176:179], v[196:199], v[26:29]
	v_mfma_f32_16x16x32_bf16 v[14:17], v[168:171], v[204:207], v[14:17]
	v_mfma_f32_16x16x32_bf16 v[10:13], v[176:179], v[204:207], v[10:13]
	v_mfma_f32_16x16x32_bf16 v[6:9], v[168:171], v[212:215], v[6:9]
	v_mfma_f32_16x16x32_bf16 v[2:5], v[176:179], v[212:215], v[2:5]
	s_setprio 0
	s_barrier
	s_add_i32 s59, 0, 0x18000
	s_add_i32 s60, 0, 0x1c000
	v_add_u32_e32 v160, s59, v143
	v_add_u32_e32 v176, s60, v143
	ds_read_b128 v[148:151], v160
	ds_read_b128 v[152:155], v160 offset:1024
	ds_read_b128 v[156:159], v160 offset:2048
	ds_read_b128 v[160:163], v160 offset:3072
	ds_read_b128 v[164:167], v176
	ds_read_b128 v[168:171], v176 offset:1024
	ds_read_b128 v[172:175], v176 offset:2048
	ds_read_b128 v[176:179], v176 offset:3072
	s_add_u32 s38, s38, 0x80000
	s_addc_u32 s39, s39, 0
	s_mov_b32 m0, s42
	v_lshl_add_u64 v[222:223], s[38:39], 0, v[136:137]
	ds_read_b128 v[180:183], v147 offset:32768
	ds_read_b128 v[184:187], v147 offset:33792
	ds_read_b128 v[188:191], v147 offset:34816
	ds_read_b128 v[196:199], v147 offset:35840
	ds_read_b128 v[200:203], v147 offset:36864
	ds_read_b128 v[204:207], v147 offset:37888
	ds_read_b128 v[208:211], v147 offset:38912
	ds_read_b128 v[212:215], v147 offset:39936
	global_load_lds_dwordx4 v[222:223], off
	v_lshl_add_u64 v[222:223], s[38:39], 0, v[132:133]
	s_mov_b32 m0, s43
	s_nop 0
	global_load_lds_dwordx4 v[222:223], off
	s_waitcnt vmcnt(8)
	s_waitcnt lgkmcnt(0)
	s_barrier
	s_setprio 1
	v_mfma_f32_16x16x32_bf16 v[126:129], v[148:151], v[180:183], v[126:129]
	v_mfma_f32_16x16x32_bf16 v[122:125], v[156:159], v[180:183], v[122:125]
	v_mfma_f32_16x16x32_bf16 v[118:121], v[148:151], v[188:191], v[118:121]
	v_mfma_f32_16x16x32_bf16 v[114:117], v[156:159], v[188:191], v[114:117]
	v_mfma_f32_16x16x32_bf16 v[102:105], v[148:151], v[200:203], v[102:105]
	v_mfma_f32_16x16x32_bf16 v[98:101], v[156:159], v[200:203], v[98:101]
	v_mfma_f32_16x16x32_bf16 v[86:89], v[148:151], v[208:211], v[86:89]
	v_mfma_f32_16x16x32_bf16 v[82:85], v[156:159], v[208:211], v[82:85]
	v_mfma_f32_16x16x32_bf16 v[126:129], v[152:155], v[184:187], v[126:129]
	v_mfma_f32_16x16x32_bf16 v[122:125], v[160:163], v[184:187], v[122:125]
	v_mfma_f32_16x16x32_bf16 v[118:121], v[152:155], v[196:199], v[118:121]
	v_mfma_f32_16x16x32_bf16 v[114:117], v[160:163], v[196:199], v[114:117]
	v_mfma_f32_16x16x32_bf16 v[102:105], v[152:155], v[204:207], v[102:105]
	v_mfma_f32_16x16x32_bf16 v[98:101], v[160:163], v[204:207], v[98:101]
	v_mfma_f32_16x16x32_bf16 v[86:89], v[152:155], v[212:215], v[86:89]
	v_mfma_f32_16x16x32_bf16 v[82:85], v[160:163], v[212:215], v[82:85]
	s_setprio 0
	s_setprio 1
	v_mfma_f32_16x16x32_bf16 v[110:113], v[164:167], v[180:183], v[110:113]
	v_mfma_f32_16x16x32_bf16 v[106:109], v[172:175], v[180:183], v[106:109]
	v_mfma_f32_16x16x32_bf16 v[94:97], v[164:167], v[188:191], v[94:97]
	v_mfma_f32_16x16x32_bf16 v[90:93], v[172:175], v[188:191], v[90:93]
	v_mfma_f32_16x16x32_bf16 v[78:81], v[164:167], v[200:203], v[78:81]
	v_mfma_f32_16x16x32_bf16 v[74:77], v[172:175], v[200:203], v[74:77]
	v_mfma_f32_16x16x32_bf16 v[70:73], v[164:167], v[208:211], v[70:73]
	v_mfma_f32_16x16x32_bf16 v[66:69], v[172:175], v[208:211], v[66:69]
	v_mfma_f32_16x16x32_bf16 v[110:113], v[168:171], v[184:187], v[110:113]
	v_mfma_f32_16x16x32_bf16 v[106:109], v[176:179], v[184:187], v[106:109]
	v_mfma_f32_16x16x32_bf16 v[94:97], v[168:171], v[196:199], v[94:97]
	v_mfma_f32_16x16x32_bf16 v[90:93], v[176:179], v[196:199], v[90:93]
	v_mfma_f32_16x16x32_bf16 v[78:81], v[168:171], v[204:207], v[78:81]
	v_mfma_f32_16x16x32_bf16 v[74:77], v[176:179], v[204:207], v[74:77]
	v_mfma_f32_16x16x32_bf16 v[70:73], v[168:171], v[212:215], v[70:73]
	v_mfma_f32_16x16x32_bf16 v[66:69], v[176:179], v[212:215], v[66:69]
	s_setprio 0
	s_barrier
	s_add_i32 s38, s59, s33
	v_lshl_add_u64 v[192:193], v[192:193], 0, s[6:7]
	s_mov_b32 m0, s38
	ds_read_b128 v[180:183], v147 offset:49152
	ds_read_b128 v[184:187], v147 offset:50176
	ds_read_b128 v[188:191], v147 offset:51200
	ds_read_b128 v[196:199], v147 offset:52224
	ds_read_b128 v[200:203], v147 offset:53248
	ds_read_b128 v[204:207], v147 offset:54272
	ds_read_b128 v[208:211], v147 offset:55296
	ds_read_b128 v[212:215], v147 offset:56320
	global_load_lds_dwordx4 v[192:193], off
	s_add_i32 m0, s38, 0x2000
	s_add_u32 s36, s36, 0x80080
	v_lshl_add_u64 v[192:193], v[216:217], 0, s[6:7]
	s_addc_u32 s37, s37, 0
	s_add_i32 s38, s60, s33
	global_load_lds_dwordx4 v[192:193], off
	v_lshl_add_u64 v[192:193], s[36:37], 0, v[134:135]
	s_mov_b32 m0, s38
	s_nop 0
	global_load_lds_dwordx4 v[192:193], off
	v_lshl_add_u64 v[192:193], s[36:37], 0, v[130:131]
	s_add_i32 m0, s38, 0x2000
	s_nop 0
	global_load_lds_dwordx4 v[192:193], off
	v_lshl_add_u64 v[192:193], v[218:219], 0, s[6:7]
	s_mov_b32 m0, s45
	s_nop 0
	global_load_lds_dwordx4 v[192:193], off
	v_lshl_add_u64 v[192:193], v[220:221], 0, s[6:7]
	s_mov_b32 m0, s46
	s_nop 0
	global_load_lds_dwordx4 v[192:193], off
	s_waitcnt vmcnt(8)
	s_waitcnt lgkmcnt(0)
	s_barrier
	s_setprio 1
	v_mfma_f32_16x16x32_bf16 v[62:65], v[148:151], v[180:183], v[62:65]
	v_mfma_f32_16x16x32_bf16 v[58:61], v[156:159], v[180:183], v[58:61]
	v_mfma_f32_16x16x32_bf16 v[54:57], v[148:151], v[188:191], v[54:57]
	v_mfma_f32_16x16x32_bf16 v[50:53], v[156:159], v[188:191], v[50:53]
	v_mfma_f32_16x16x32_bf16 v[38:41], v[148:151], v[200:203], v[38:41]
	v_mfma_f32_16x16x32_bf16 v[34:37], v[156:159], v[200:203], v[34:37]
	v_mfma_f32_16x16x32_bf16 v[22:25], v[148:151], v[208:211], v[22:25]
	v_mfma_f32_16x16x32_bf16 v[18:21], v[156:159], v[208:211], v[18:21]
	v_mfma_f32_16x16x32_bf16 v[62:65], v[152:155], v[184:187], v[62:65]
	v_mfma_f32_16x16x32_bf16 v[58:61], v[160:163], v[184:187], v[58:61]
	v_mfma_f32_16x16x32_bf16 v[54:57], v[152:155], v[196:199], v[54:57]
	v_mfma_f32_16x16x32_bf16 v[50:53], v[160:163], v[196:199], v[50:53]
	v_mfma_f32_16x16x32_bf16 v[38:41], v[152:155], v[204:207], v[38:41]
	v_mfma_f32_16x16x32_bf16 v[34:37], v[160:163], v[204:207], v[34:37]
	v_mfma_f32_16x16x32_bf16 v[22:25], v[152:155], v[212:215], v[22:25]
	v_mfma_f32_16x16x32_bf16 v[18:21], v[160:163], v[212:215], v[18:21]
	s_setprio 0
	s_setprio 1
	v_mfma_f32_16x16x32_bf16 v[46:49], v[164:167], v[180:183], v[46:49]
	v_mfma_f32_16x16x32_bf16 v[42:45], v[172:175], v[180:183], v[42:45]
	v_mfma_f32_16x16x32_bf16 v[30:33], v[164:167], v[188:191], v[30:33]
	v_mfma_f32_16x16x32_bf16 v[26:29], v[172:175], v[188:191], v[26:29]
	v_mfma_f32_16x16x32_bf16 v[14:17], v[164:167], v[200:203], v[14:17]
	v_mfma_f32_16x16x32_bf16 v[10:13], v[172:175], v[200:203], v[10:13]
	v_mfma_f32_16x16x32_bf16 v[6:9], v[164:167], v[208:211], v[6:9]
	v_mfma_f32_16x16x32_bf16 v[2:5], v[172:175], v[208:211], v[2:5]
	v_mfma_f32_16x16x32_bf16 v[46:49], v[168:171], v[184:187], v[46:49]
	v_mfma_f32_16x16x32_bf16 v[42:45], v[176:179], v[184:187], v[42:45]
	v_mfma_f32_16x16x32_bf16 v[30:33], v[168:171], v[196:199], v[30:33]
	v_mfma_f32_16x16x32_bf16 v[26:29], v[176:179], v[196:199], v[26:29]
	v_mfma_f32_16x16x32_bf16 v[14:17], v[168:171], v[204:207], v[14:17]
	v_mfma_f32_16x16x32_bf16 v[10:13], v[176:179], v[204:207], v[10:13]
	v_mfma_f32_16x16x32_bf16 v[6:9], v[168:171], v[212:215], v[6:9]
	v_mfma_f32_16x16x32_bf16 v[2:5], v[176:179], v[212:215], v[2:5]
	s_setprio 0
	s_barrier
	s_add_i32 s58, s58, 2
	s_add_u32 s34, s34, 0x100
	s_addc_u32 s35, s35, 0
	s_add_u32 s56, s56, 0x100
	s_addc_u32 s57, s57, 0
	s_cmp_gt_u32 s58, 29
	s_cbranch_scc0 .LBB0_541
	s_branch .Lpeeldone_11
.LBB0_541:
	ds_read_b128 v[148:151], v145
	ds_read_b128 v[152:155], v145 offset:1024
	ds_read_b128 v[156:159], v145 offset:2048
	ds_read_b128 v[160:163], v145 offset:3072
	ds_read_b128 v[164:167], v146
	ds_read_b128 v[168:171], v146 offset:1024
	ds_read_b128 v[172:175], v146 offset:2048
	ds_read_b128 v[176:179], v146 offset:3072
	s_add_u32 s36, s34, 0xfff80080
	s_addc_u32 s37, s35, -1
	s_cmp_eq_u32 s58, 28
	s_cselect_b32 s39, s21, s37
	s_cselect_b32 s38, s54, s36
	s_cselect_b32 s37, s23, s57
	s_cselect_b32 s36, s55, s56
	v_lshl_add_u64 v[192:193], s[34:35], 0, v[138:139]
	s_add_i32 m0, s27, 0xc000
	ds_read_b128 v[180:183], v147
	ds_read_b128 v[184:187], v147 offset:1024
	ds_read_b128 v[188:191], v147 offset:2048
	ds_read_b128 v[196:199], v147 offset:3072
	ds_read_b128 v[200:203], v147 offset:4096
	ds_read_b128 v[204:207], v147 offset:5120
	ds_read_b128 v[208:211], v147 offset:6144
	ds_read_b128 v[212:215], v147 offset:7168
	global_load_lds_dwordx4 v[192:193], off
	v_lshl_add_u64 v[192:193], s[34:35], 0, v[140:141]
	s_add_i32 m0, s27, 0xe000
	s_nop 0
	global_load_lds_dwordx4 v[192:193], off
	s_waitcnt vmcnt(8)
	s_waitcnt lgkmcnt(0)
	s_barrier
	s_setprio 1
	v_mfma_f32_16x16x32_bf16 v[126:129], v[148:151], v[180:183], v[126:129]
	v_mfma_f32_16x16x32_bf16 v[122:125], v[156:159], v[180:183], v[122:125]
	v_mfma_f32_16x16x32_bf16 v[118:121], v[148:151], v[188:191], v[118:121]
	v_mfma_f32_16x16x32_bf16 v[114:117], v[156:159], v[188:191], v[114:117]
	v_mfma_f32_16x16x32_bf16 v[102:105], v[148:151], v[200:203], v[102:105]
	v_mfma_f32_16x16x32_bf16 v[98:101], v[156:159], v[200:203], v[98:101]
	v_mfma_f32_16x16x32_bf16 v[86:89], v[148:151], v[208:211], v[86:89]
	v_mfma_f32_16x16x32_bf16 v[82:85], v[156:159], v[208:211], v[82:85]
	v_mfma_f32_16x16x32_bf16 v[126:129], v[152:155], v[184:187], v[126:129]
	v_mfma_f32_16x16x32_bf16 v[122:125], v[160:163], v[184:187], v[122:125]
	v_mfma_f32_16x16x32_bf16 v[118:121], v[152:155], v[196:199], v[118:121]
	v_mfma_f32_16x16x32_bf16 v[114:117], v[160:163], v[196:199], v[114:117]
	v_mfma_f32_16x16x32_bf16 v[102:105], v[152:155], v[204:207], v[102:105]
	v_mfma_f32_16x16x32_bf16 v[98:101], v[160:163], v[204:207], v[98:101]
	v_mfma_f32_16x16x32_bf16 v[86:89], v[152:155], v[212:215], v[86:89]
	v_mfma_f32_16x16x32_bf16 v[82:85], v[160:163], v[212:215], v[82:85]
	s_setprio 0
	s_setprio 1
	v_mfma_f32_16x16x32_bf16 v[110:113], v[164:167], v[180:183], v[110:113]
	v_mfma_f32_16x16x32_bf16 v[106:109], v[172:175], v[180:183], v[106:109]
	v_mfma_f32_16x16x32_bf16 v[94:97], v[164:167], v[188:191], v[94:97]
	v_mfma_f32_16x16x32_bf16 v[90:93], v[172:175], v[188:191], v[90:93]
	v_mfma_f32_16x16x32_bf16 v[78:81], v[164:167], v[200:203], v[78:81]
	v_mfma_f32_16x16x32_bf16 v[74:77], v[172:175], v[200:203], v[74:77]
	v_mfma_f32_16x16x32_bf16 v[70:73], v[164:167], v[208:211], v[70:73]
	v_mfma_f32_16x16x32_bf16 v[66:69], v[172:175], v[208:211], v[66:69]
	v_mfma_f32_16x16x32_bf16 v[110:113], v[168:171], v[184:187], v[110:113]
	v_mfma_f32_16x16x32_bf16 v[106:109], v[176:179], v[184:187], v[106:109]
	v_mfma_f32_16x16x32_bf16 v[94:97], v[168:171], v[196:199], v[94:97]
	v_mfma_f32_16x16x32_bf16 v[90:93], v[176:179], v[196:199], v[90:93]
	v_mfma_f32_16x16x32_bf16 v[78:81], v[168:171], v[204:207], v[78:81]
	v_mfma_f32_16x16x32_bf16 v[74:77], v[176:179], v[204:207], v[74:77]
	v_mfma_f32_16x16x32_bf16 v[70:73], v[168:171], v[212:215], v[70:73]
	v_mfma_f32_16x16x32_bf16 v[66:69], v[176:179], v[212:215], v[66:69]
	s_setprio 0
	s_barrier
	s_add_i32 s59, s47, s33
	v_lshl_add_u64 v[192:193], s[36:37], 0, v[134:135]
	s_mov_b32 m0, s59
	ds_read_b128 v[180:183], v147 offset:16384
	ds_read_b128 v[184:187], v147 offset:17408
	ds_read_b128 v[188:191], v147 offset:18432
	ds_read_b128 v[196:199], v147 offset:19456
	ds_read_b128 v[200:203], v147 offset:20480
	ds_read_b128 v[204:207], v147 offset:21504
	ds_read_b128 v[208:211], v147 offset:22528
	ds_read_b128 v[212:215], v147 offset:23552
	global_load_lds_dwordx4 v[192:193], off
	s_add_i32 m0, s59, 0x2000
	s_add_u32 s60, s36, 0x80000
	v_lshl_add_u64 v[216:217], s[36:37], 0, v[130:131]
	s_addc_u32 s61, s37, 0
	s_add_i32 s59, s48, s33
	global_load_lds_dwordx4 v[216:217], off
	v_lshl_add_u64 v[218:219], s[60:61], 0, v[134:135]
	s_mov_b32 m0, s59
	v_lshl_add_u64 v[220:221], s[38:39], 0, v[132:133]
	global_load_lds_dwordx4 v[218:219], off
	v_lshl_add_u64 v[218:219], s[60:61], 0, v[130:131]
	s_add_i32 m0, s59, 0x2000
	s_nop 0
	global_load_lds_dwordx4 v[218:219], off
	v_lshl_add_u64 v[218:219], s[38:39], 0, v[136:137]
	s_mov_b32 m0, s27
	s_nop 0
	global_load_lds_dwordx4 v[218:219], off
	s_mov_b32 m0, s41
	s_nop 0
	global_load_lds_dwordx4 v[220:221], off
	s_waitcnt vmcnt(8)
	s_waitcnt lgkmcnt(0)
	s_barrier
	s_setprio 1
	v_mfma_f32_16x16x32_bf16 v[62:65], v[148:151], v[180:183], v[62:65]
	v_mfma_f32_16x16x32_bf16 v[58:61], v[156:159], v[180:183], v[58:61]
	v_mfma_f32_16x16x32_bf16 v[54:57], v[148:151], v[188:191], v[54:57]
	v_mfma_f32_16x16x32_bf16 v[50:53], v[156:159], v[188:191], v[50:53]
	v_mfma_f32_16x16x32_bf16 v[38:41], v[148:151], v[200:203], v[38:41]
	v_mfma_f32_16x16x32_bf16 v[34:37], v[156:159], v[200:203], v[34:37]
	v_mfma_f32_16x16x32_bf16 v[22:25], v[148:151], v[208:211], v[22:25]
	v_mfma_f32_16x16x32_bf16 v[18:21], v[156:159], v[208:211], v[18:21]
	v_mfma_f32_16x16x32_bf16 v[62:65], v[152:155], v[184:187], v[62:65]
	v_mfma_f32_16x16x32_bf16 v[58:61], v[160:163], v[184:187], v[58:61]
	v_mfma_f32_16x16x32_bf16 v[54:57], v[152:155], v[196:199], v[54:57]
	v_mfma_f32_16x16x32_bf16 v[50:53], v[160:163], v[196:199], v[50:53]
	v_mfma_f32_16x16x32_bf16 v[38:41], v[152:155], v[204:207], v[38:41]
	v_mfma_f32_16x16x32_bf16 v[34:37], v[160:163], v[204:207], v[34:37]
	v_mfma_f32_16x16x32_bf16 v[22:25], v[152:155], v[212:215], v[22:25]
	v_mfma_f32_16x16x32_bf16 v[18:21], v[160:163], v[212:215], v[18:21]
	s_setprio 0
	s_setprio 1
	v_mfma_f32_16x16x32_bf16 v[46:49], v[164:167], v[180:183], v[46:49]
	v_mfma_f32_16x16x32_bf16 v[42:45], v[172:175], v[180:183], v[42:45]
	v_mfma_f32_16x16x32_bf16 v[30:33], v[164:167], v[188:191], v[30:33]
	v_mfma_f32_16x16x32_bf16 v[26:29], v[172:175], v[188:191], v[26:29]
	v_mfma_f32_16x16x32_bf16 v[14:17], v[164:167], v[200:203], v[14:17]
	v_mfma_f32_16x16x32_bf16 v[10:13], v[172:175], v[200:203], v[10:13]
	v_mfma_f32_16x16x32_bf16 v[6:9], v[164:167], v[208:211], v[6:9]
	v_mfma_f32_16x16x32_bf16 v[2:5], v[172:175], v[208:211], v[2:5]
	v_mfma_f32_16x16x32_bf16 v[46:49], v[168:171], v[184:187], v[46:49]
	v_mfma_f32_16x16x32_bf16 v[42:45], v[176:179], v[184:187], v[42:45]
	v_mfma_f32_16x16x32_bf16 v[30:33], v[168:171], v[196:199], v[30:33]
	v_mfma_f32_16x16x32_bf16 v[26:29], v[176:179], v[196:199], v[26:29]
	v_mfma_f32_16x16x32_bf16 v[14:17], v[168:171], v[204:207], v[14:17]
	v_mfma_f32_16x16x32_bf16 v[10:13], v[176:179], v[204:207], v[10:13]
	v_mfma_f32_16x16x32_bf16 v[6:9], v[168:171], v[212:215], v[6:9]
	v_mfma_f32_16x16x32_bf16 v[2:5], v[176:179], v[212:215], v[2:5]
	s_setprio 0
	s_barrier
	s_add_i32 s59, 0, 0x18000
	s_add_i32 s60, 0, 0x1c000
	v_add_u32_e32 v160, s59, v143
	v_add_u32_e32 v176, s60, v143
	ds_read_b128 v[148:151], v160
	ds_read_b128 v[152:155], v160 offset:1024
	ds_read_b128 v[156:159], v160 offset:2048
	ds_read_b128 v[160:163], v160 offset:3072
	ds_read_b128 v[164:167], v176
	ds_read_b128 v[168:171], v176 offset:1024
	ds_read_b128 v[172:175], v176 offset:2048
	ds_read_b128 v[176:179], v176 offset:3072
	s_add_u32 s38, s38, 0x80000
	s_addc_u32 s39, s39, 0
	s_mov_b32 m0, s42
	v_lshl_add_u64 v[222:223], s[38:39], 0, v[136:137]
	ds_read_b128 v[180:183], v147 offset:32768
	ds_read_b128 v[184:187], v147 offset:33792
	ds_read_b128 v[188:191], v147 offset:34816
	ds_read_b128 v[196:199], v147 offset:35840
	ds_read_b128 v[200:203], v147 offset:36864
	ds_read_b128 v[204:207], v147 offset:37888
	ds_read_b128 v[208:211], v147 offset:38912
	ds_read_b128 v[212:215], v147 offset:39936
	global_load_lds_dwordx4 v[222:223], off
	v_lshl_add_u64 v[222:223], s[38:39], 0, v[132:133]
	s_mov_b32 m0, s43
	s_nop 0
	global_load_lds_dwordx4 v[222:223], off
	s_waitcnt vmcnt(8)
	s_waitcnt lgkmcnt(0)
	s_barrier
	s_setprio 1
	v_mfma_f32_16x16x32_bf16 v[126:129], v[148:151], v[180:183], v[126:129]
	v_mfma_f32_16x16x32_bf16 v[122:125], v[156:159], v[180:183], v[122:125]
	v_mfma_f32_16x16x32_bf16 v[118:121], v[148:151], v[188:191], v[118:121]
	v_mfma_f32_16x16x32_bf16 v[114:117], v[156:159], v[188:191], v[114:117]
	v_mfma_f32_16x16x32_bf16 v[102:105], v[148:151], v[200:203], v[102:105]
	v_mfma_f32_16x16x32_bf16 v[98:101], v[156:159], v[200:203], v[98:101]
	v_mfma_f32_16x16x32_bf16 v[86:89], v[148:151], v[208:211], v[86:89]
	v_mfma_f32_16x16x32_bf16 v[82:85], v[156:159], v[208:211], v[82:85]
	v_mfma_f32_16x16x32_bf16 v[126:129], v[152:155], v[184:187], v[126:129]
	v_mfma_f32_16x16x32_bf16 v[122:125], v[160:163], v[184:187], v[122:125]
	v_mfma_f32_16x16x32_bf16 v[118:121], v[152:155], v[196:199], v[118:121]
	v_mfma_f32_16x16x32_bf16 v[114:117], v[160:163], v[196:199], v[114:117]
	v_mfma_f32_16x16x32_bf16 v[102:105], v[152:155], v[204:207], v[102:105]
	v_mfma_f32_16x16x32_bf16 v[98:101], v[160:163], v[204:207], v[98:101]
	v_mfma_f32_16x16x32_bf16 v[86:89], v[152:155], v[212:215], v[86:89]
	v_mfma_f32_16x16x32_bf16 v[82:85], v[160:163], v[212:215], v[82:85]
	s_setprio 0
	s_setprio 1
	v_mfma_f32_16x16x32_bf16 v[110:113], v[164:167], v[180:183], v[110:113]
	v_mfma_f32_16x16x32_bf16 v[106:109], v[172:175], v[180:183], v[106:109]
	v_mfma_f32_16x16x32_bf16 v[94:97], v[164:167], v[188:191], v[94:97]
	v_mfma_f32_16x16x32_bf16 v[90:93], v[172:175], v[188:191], v[90:93]
	v_mfma_f32_16x16x32_bf16 v[78:81], v[164:167], v[200:203], v[78:81]
	v_mfma_f32_16x16x32_bf16 v[74:77], v[172:175], v[200:203], v[74:77]
	v_mfma_f32_16x16x32_bf16 v[70:73], v[164:167], v[208:211], v[70:73]
	v_mfma_f32_16x16x32_bf16 v[66:69], v[172:175], v[208:211], v[66:69]
	v_mfma_f32_16x16x32_bf16 v[110:113], v[168:171], v[184:187], v[110:113]
	v_mfma_f32_16x16x32_bf16 v[106:109], v[176:179], v[184:187], v[106:109]
	v_mfma_f32_16x16x32_bf16 v[94:97], v[168:171], v[196:199], v[94:97]
	v_mfma_f32_16x16x32_bf16 v[90:93], v[176:179], v[196:199], v[90:93]
	v_mfma_f32_16x16x32_bf16 v[78:81], v[168:171], v[204:207], v[78:81]
	v_mfma_f32_16x16x32_bf16 v[74:77], v[176:179], v[204:207], v[74:77]
	v_mfma_f32_16x16x32_bf16 v[70:73], v[168:171], v[212:215], v[70:73]
	v_mfma_f32_16x16x32_bf16 v[66:69], v[176:179], v[212:215], v[66:69]
	s_setprio 0
	s_barrier
	s_add_i32 s38, s59, s33
	v_lshl_add_u64 v[192:193], v[192:193], 0, s[6:7]
	s_mov_b32 m0, s38
	ds_read_b128 v[180:183], v147 offset:49152
	ds_read_b128 v[184:187], v147 offset:50176
	ds_read_b128 v[188:191], v147 offset:51200
	ds_read_b128 v[196:199], v147 offset:52224
	ds_read_b128 v[200:203], v147 offset:53248
	ds_read_b128 v[204:207], v147 offset:54272
	ds_read_b128 v[208:211], v147 offset:55296
	ds_read_b128 v[212:215], v147 offset:56320
	global_load_lds_dwordx4 v[192:193], off
	s_add_i32 m0, s38, 0x2000
	s_add_u32 s36, s36, 0x80080
	v_lshl_add_u64 v[192:193], v[216:217], 0, s[6:7]
	s_addc_u32 s37, s37, 0
	s_add_i32 s38, s60, s33
	global_load_lds_dwordx4 v[192:193], off
	v_lshl_add_u64 v[192:193], s[36:37], 0, v[134:135]
	s_mov_b32 m0, s38
	s_nop 0
	global_load_lds_dwordx4 v[192:193], off
	v_lshl_add_u64 v[192:193], s[36:37], 0, v[130:131]
	s_add_i32 m0, s38, 0x2000
	s_nop 0
	global_load_lds_dwordx4 v[192:193], off
	v_lshl_add_u64 v[192:193], v[218:219], 0, s[6:7]
	s_mov_b32 m0, s45
	s_nop 0
	global_load_lds_dwordx4 v[192:193], off
	v_lshl_add_u64 v[192:193], v[220:221], 0, s[6:7]
	s_mov_b32 m0, s46
	s_nop 0
	global_load_lds_dwordx4 v[192:193], off
	s_waitcnt vmcnt(8)
	s_waitcnt lgkmcnt(0)
	s_barrier
	s_setprio 1
	v_mfma_f32_16x16x32_bf16 v[62:65], v[148:151], v[180:183], v[62:65]
	v_mfma_f32_16x16x32_bf16 v[58:61], v[156:159], v[180:183], v[58:61]
	v_mfma_f32_16x16x32_bf16 v[54:57], v[148:151], v[188:191], v[54:57]
	v_mfma_f32_16x16x32_bf16 v[50:53], v[156:159], v[188:191], v[50:53]
	v_mfma_f32_16x16x32_bf16 v[38:41], v[148:151], v[200:203], v[38:41]
	v_mfma_f32_16x16x32_bf16 v[34:37], v[156:159], v[200:203], v[34:37]
	v_mfma_f32_16x16x32_bf16 v[22:25], v[148:151], v[208:211], v[22:25]
	v_mfma_f32_16x16x32_bf16 v[18:21], v[156:159], v[208:211], v[18:21]
	v_mfma_f32_16x16x32_bf16 v[62:65], v[152:155], v[184:187], v[62:65]
	v_mfma_f32_16x16x32_bf16 v[58:61], v[160:163], v[184:187], v[58:61]
	v_mfma_f32_16x16x32_bf16 v[54:57], v[152:155], v[196:199], v[54:57]
	v_mfma_f32_16x16x32_bf16 v[50:53], v[160:163], v[196:199], v[50:53]
	v_mfma_f32_16x16x32_bf16 v[38:41], v[152:155], v[204:207], v[38:41]
	v_mfma_f32_16x16x32_bf16 v[34:37], v[160:163], v[204:207], v[34:37]
	v_mfma_f32_16x16x32_bf16 v[22:25], v[152:155], v[212:215], v[22:25]
	v_mfma_f32_16x16x32_bf16 v[18:21], v[160:163], v[212:215], v[18:21]
	s_setprio 0
	s_setprio 1
	v_mfma_f32_16x16x32_bf16 v[46:49], v[164:167], v[180:183], v[46:49]
	v_mfma_f32_16x16x32_bf16 v[42:45], v[172:175], v[180:183], v[42:45]
	v_mfma_f32_16x16x32_bf16 v[30:33], v[164:167], v[188:191], v[30:33]
	v_mfma_f32_16x16x32_bf16 v[26:29], v[172:175], v[188:191], v[26:29]
	v_mfma_f32_16x16x32_bf16 v[14:17], v[164:167], v[200:203], v[14:17]
	v_mfma_f32_16x16x32_bf16 v[10:13], v[172:175], v[200:203], v[10:13]
	v_mfma_f32_16x16x32_bf16 v[6:9], v[164:167], v[208:211], v[6:9]
	v_mfma_f32_16x16x32_bf16 v[2:5], v[172:175], v[208:211], v[2:5]
	v_mfma_f32_16x16x32_bf16 v[46:49], v[168:171], v[184:187], v[46:49]
	v_mfma_f32_16x16x32_bf16 v[42:45], v[176:179], v[184:187], v[42:45]
	v_mfma_f32_16x16x32_bf16 v[30:33], v[168:171], v[196:199], v[30:33]
	v_mfma_f32_16x16x32_bf16 v[26:29], v[176:179], v[196:199], v[26:29]
	v_mfma_f32_16x16x32_bf16 v[14:17], v[168:171], v[204:207], v[14:17]
	v_mfma_f32_16x16x32_bf16 v[10:13], v[176:179], v[204:207], v[10:13]
	v_mfma_f32_16x16x32_bf16 v[6:9], v[168:171], v[212:215], v[6:9]
	v_mfma_f32_16x16x32_bf16 v[2:5], v[176:179], v[212:215], v[2:5]
	s_setprio 0
	s_barrier
	s_add_i32 s58, s58, 2
	s_add_u32 s34, s34, 0x100
	s_addc_u32 s35, s35, 0
	s_add_u32 s56, s56, 0x100
	s_addc_u32 s57, s57, 0
	s_cmp_gt_u32 s58, 29
	s_cbranch_scc0 .LBB0_541

.Lpeel_10:
	ds_read_b128 v[150:153], v147
	ds_read_b128 v[154:157], v147 offset:1024
	s_add_u32 s28, s26, 0xfffe0080
	s_addc_u32 s29, s27, -1
	s_cmp_eq_u32 s50, 4
	s_cselect_b32 s31, s13, s29
	s_cselect_b32 s30, s46, s28
	s_cselect_b32 s29, s17, s49
	s_cselect_b32 s28, s47, s48
	v_lshl_add_u64 v[202:203], s[26:27], 0, v[138:139]
	s_add_i32 m0, s36, 0xc000
	global_load_lds_dwordx4 v[202:203], off
	v_lshl_add_u64 v[202:203], s[26:27], 0, v[140:141]
	s_add_i32 m0, s36, 0xe000
	s_nop 0
	global_load_lds_dwordx4 v[202:203], off
	s_waitcnt vmcnt(8)
	s_waitcnt lgkmcnt(0)
	s_barrier
	s_setprio 1
	v_mfma_f32_16x16x32_bf16 v[126:129], v[150:153], v[182:185], 0
	v_mfma_f32_16x16x32_bf16 v[122:125], v[158:161], v[182:185], 0
	v_mfma_f32_16x16x32_bf16 v[118:121], v[150:153], v[190:193], 0
	v_mfma_f32_16x16x32_bf16 v[114:117], v[158:161], v[190:193], 0
	v_mfma_f32_16x16x32_bf16 v[102:105], v[150:153], v[210:213], 0
	v_mfma_f32_16x16x32_bf16 v[98:101], v[158:161], v[210:213], 0
	v_mfma_f32_16x16x32_bf16 v[86:89], v[150:153], v[218:221], 0
	v_mfma_f32_16x16x32_bf16 v[82:85], v[158:161], v[218:221], 0
	v_mfma_f32_16x16x32_bf16 v[126:129], v[154:157], v[186:189], v[126:129]
	v_mfma_f32_16x16x32_bf16 v[122:125], v[162:165], v[186:189], v[122:125]
	v_mfma_f32_16x16x32_bf16 v[118:121], v[154:157], v[198:201], v[118:121]
	v_mfma_f32_16x16x32_bf16 v[114:117], v[162:165], v[198:201], v[114:117]
	v_mfma_f32_16x16x32_bf16 v[102:105], v[154:157], v[214:217], v[102:105]
	v_mfma_f32_16x16x32_bf16 v[98:101], v[162:165], v[214:217], v[98:101]
	v_mfma_f32_16x16x32_bf16 v[86:89], v[154:157], v[222:225], v[86:89]
	v_mfma_f32_16x16x32_bf16 v[82:85], v[162:165], v[222:225], v[82:85]
	s_setprio 0
	s_setprio 1
	v_mfma_f32_16x16x32_bf16 v[110:113], v[166:169], v[182:185], 0
	v_mfma_f32_16x16x32_bf16 v[106:109], v[174:177], v[182:185], 0
	v_mfma_f32_16x16x32_bf16 v[94:97], v[166:169], v[190:193], 0
	v_mfma_f32_16x16x32_bf16 v[90:93], v[174:177], v[190:193], 0
	v_mfma_f32_16x16x32_bf16 v[78:81], v[166:169], v[210:213], 0
	v_mfma_f32_16x16x32_bf16 v[74:77], v[174:177], v[210:213], 0
	v_mfma_f32_16x16x32_bf16 v[70:73], v[166:169], v[218:221], 0
	v_mfma_f32_16x16x32_bf16 v[66:69], v[174:177], v[218:221], 0
	v_mfma_f32_16x16x32_bf16 v[110:113], v[170:173], v[186:189], v[110:113]
	v_mfma_f32_16x16x32_bf16 v[106:109], v[178:181], v[186:189], v[106:109]
	v_mfma_f32_16x16x32_bf16 v[94:97], v[170:173], v[198:201], v[94:97]
	v_mfma_f32_16x16x32_bf16 v[90:93], v[178:181], v[198:201], v[90:93]
	v_mfma_f32_16x16x32_bf16 v[78:81], v[170:173], v[214:217], v[78:81]
	v_mfma_f32_16x16x32_bf16 v[74:77], v[178:181], v[214:217], v[74:77]
	v_mfma_f32_16x16x32_bf16 v[70:73], v[170:173], v[222:225], v[70:73]
	v_mfma_f32_16x16x32_bf16 v[66:69], v[178:181], v[222:225], v[66:69]
	s_setprio 0
	s_barrier
	s_add_i32 s51, s43, s35
	v_lshl_add_u64 v[202:203], s[28:29], 0, v[132:133]
	s_mov_b32 m0, s51
	ds_read_b128 v[182:185], v149 offset:16384
	ds_read_b128 v[186:189], v149 offset:17408
	ds_read_b128 v[190:193], v149 offset:18432
	ds_read_b128 v[198:201], v149 offset:19456
	ds_read_b128 v[210:213], v149 offset:20480
	ds_read_b128 v[214:217], v149 offset:21504
	ds_read_b128 v[218:221], v149 offset:22528
	ds_read_b128 v[222:225], v149 offset:23552
	global_load_lds_dwordx4 v[202:203], off
	s_add_i32 m0, s51, 0x2000
	s_add_u32 s52, s28, 0x20000
	v_lshl_add_u64 v[206:207], s[28:29], 0, v[134:135]
	s_addc_u32 s53, s29, 0
	s_add_i32 s51, s44, s35
	global_load_lds_dwordx4 v[206:207], off
	v_lshl_add_u64 v[226:227], s[52:53], 0, v[132:133]
	s_mov_b32 m0, s51
	v_lshl_add_u64 v[228:229], s[30:31], 0, v[136:137]
	global_load_lds_dwordx4 v[226:227], off
	v_lshl_add_u64 v[226:227], s[52:53], 0, v[134:135]
	s_add_i32 m0, s51, 0x2000
	s_nop 0
	global_load_lds_dwordx4 v[226:227], off
	v_lshl_add_u64 v[226:227], s[30:31], 0, v[130:131]
	s_mov_b32 m0, s36
	s_nop 0
	global_load_lds_dwordx4 v[226:227], off
	s_mov_b32 m0, s37
	s_nop 0
	global_load_lds_dwordx4 v[228:229], off
	s_waitcnt vmcnt(8)
	s_waitcnt lgkmcnt(0)
	s_barrier
	s_setprio 1
	v_mfma_f32_16x16x32_bf16 v[62:65], v[150:153], v[182:185], 0
	v_mfma_f32_16x16x32_bf16 v[58:61], v[158:161], v[182:185], 0
	v_mfma_f32_16x16x32_bf16 v[54:57], v[150:153], v[190:193], 0
	v_mfma_f32_16x16x32_bf16 v[50:53], v[158:161], v[190:193], 0
	v_mfma_f32_16x16x32_bf16 v[38:41], v[150:153], v[210:213], 0
	v_mfma_f32_16x16x32_bf16 v[34:37], v[158:161], v[210:213], 0
	v_mfma_f32_16x16x32_bf16 v[22:25], v[150:153], v[218:221], 0
	v_mfma_f32_16x16x32_bf16 v[18:21], v[158:161], v[218:221], 0
	v_mfma_f32_16x16x32_bf16 v[62:65], v[154:157], v[186:189], v[62:65]
	v_mfma_f32_16x16x32_bf16 v[58:61], v[162:165], v[186:189], v[58:61]
	v_mfma_f32_16x16x32_bf16 v[54:57], v[154:157], v[198:201], v[54:57]
	v_mfma_f32_16x16x32_bf16 v[50:53], v[162:165], v[198:201], v[50:53]
	v_mfma_f32_16x16x32_bf16 v[38:41], v[154:157], v[214:217], v[38:41]
	v_mfma_f32_16x16x32_bf16 v[34:37], v[162:165], v[214:217], v[34:37]
	v_mfma_f32_16x16x32_bf16 v[22:25], v[154:157], v[222:225], v[22:25]
	v_mfma_f32_16x16x32_bf16 v[18:21], v[162:165], v[222:225], v[18:21]
	s_setprio 0
	s_setprio 1
	v_mfma_f32_16x16x32_bf16 v[46:49], v[166:169], v[182:185], 0
	v_mfma_f32_16x16x32_bf16 v[42:45], v[174:177], v[182:185], 0
	v_mfma_f32_16x16x32_bf16 v[30:33], v[166:169], v[190:193], 0
	v_mfma_f32_16x16x32_bf16 v[26:29], v[174:177], v[190:193], 0
	v_mfma_f32_16x16x32_bf16 v[14:17], v[166:169], v[210:213], 0
	v_mfma_f32_16x16x32_bf16 v[10:13], v[174:177], v[210:213], 0
	v_mfma_f32_16x16x32_bf16 v[6:9], v[166:169], v[218:221], 0
	v_mfma_f32_16x16x32_bf16 v[2:5], v[174:177], v[218:221], 0
	v_mfma_f32_16x16x32_bf16 v[46:49], v[170:173], v[186:189], v[46:49]
	v_mfma_f32_16x16x32_bf16 v[42:45], v[178:181], v[186:189], v[42:45]
	v_mfma_f32_16x16x32_bf16 v[30:33], v[170:173], v[198:201], v[30:33]
	v_mfma_f32_16x16x32_bf16 v[26:29], v[178:181], v[198:201], v[26:29]
	v_mfma_f32_16x16x32_bf16 v[14:17], v[170:173], v[214:217], v[14:17]
	v_mfma_f32_16x16x32_bf16 v[10:13], v[178:181], v[214:217], v[10:13]
	v_mfma_f32_16x16x32_bf16 v[6:9], v[170:173], v[222:225], v[6:9]
	v_mfma_f32_16x16x32_bf16 v[2:5], v[178:181], v[222:225], v[2:5]
	s_setprio 0
	s_barrier
	s_add_i32 s51, 0, 0x18000
	s_add_i32 s52, 0, 0x1c000
	v_add_u32_e32 v162, s51, v145
	v_add_u32_e32 v178, s52, v145
	ds_read_b128 v[150:153], v162
	ds_read_b128 v[154:157], v162 offset:1024
	ds_read_b128 v[158:161], v162 offset:2048
	ds_read_b128 v[162:165], v162 offset:3072
	ds_read_b128 v[166:169], v178
	ds_read_b128 v[170:173], v178 offset:1024
	ds_read_b128 v[174:177], v178 offset:2048
	ds_read_b128 v[178:181], v178 offset:3072
	s_add_u32 s30, s30, 0x20000
	s_addc_u32 s31, s31, 0
	s_mov_b32 m0, s38
	v_lshl_add_u64 v[230:231], s[30:31], 0, v[130:131]
	ds_read_b128 v[182:185], v149 offset:32768
	ds_read_b128 v[186:189], v149 offset:33792
	ds_read_b128 v[190:193], v149 offset:34816
	ds_read_b128 v[198:201], v149 offset:35840
	ds_read_b128 v[210:213], v149 offset:36864
	ds_read_b128 v[214:217], v149 offset:37888
	ds_read_b128 v[218:221], v149 offset:38912
	ds_read_b128 v[222:225], v149 offset:39936
	global_load_lds_dwordx4 v[230:231], off
	v_lshl_add_u64 v[230:231], s[30:31], 0, v[136:137]
	s_mov_b32 m0, s39
	s_nop 0
	global_load_lds_dwordx4 v[230:231], off
	s_waitcnt vmcnt(8)
	s_waitcnt lgkmcnt(0)
	s_barrier
	s_setprio 1
	v_mfma_f32_16x16x32_bf16 v[126:129], v[150:153], v[182:185], v[126:129]
	v_mfma_f32_16x16x32_bf16 v[122:125], v[158:161], v[182:185], v[122:125]
	v_mfma_f32_16x16x32_bf16 v[118:121], v[150:153], v[190:193], v[118:121]
	v_mfma_f32_16x16x32_bf16 v[114:117], v[158:161], v[190:193], v[114:117]
	v_mfma_f32_16x16x32_bf16 v[102:105], v[150:153], v[210:213], v[102:105]
	v_mfma_f32_16x16x32_bf16 v[98:101], v[158:161], v[210:213], v[98:101]
	v_mfma_f32_16x16x32_bf16 v[86:89], v[150:153], v[218:221], v[86:89]
	v_mfma_f32_16x16x32_bf16 v[82:85], v[158:161], v[218:221], v[82:85]
	v_mfma_f32_16x16x32_bf16 v[126:129], v[154:157], v[186:189], v[126:129]
	v_mfma_f32_16x16x32_bf16 v[122:125], v[162:165], v[186:189], v[122:125]
	v_mfma_f32_16x16x32_bf16 v[118:121], v[154:157], v[198:201], v[118:121]
	v_mfma_f32_16x16x32_bf16 v[114:117], v[162:165], v[198:201], v[114:117]
	v_mfma_f32_16x16x32_bf16 v[102:105], v[154:157], v[214:217], v[102:105]
	v_mfma_f32_16x16x32_bf16 v[98:101], v[162:165], v[214:217], v[98:101]
	v_mfma_f32_16x16x32_bf16 v[86:89], v[154:157], v[222:225], v[86:89]
	v_mfma_f32_16x16x32_bf16 v[82:85], v[162:165], v[222:225], v[82:85]
	s_setprio 0
	s_setprio 1
	v_mfma_f32_16x16x32_bf16 v[110:113], v[166:169], v[182:185], v[110:113]
	v_mfma_f32_16x16x32_bf16 v[106:109], v[174:177], v[182:185], v[106:109]
	v_mfma_f32_16x16x32_bf16 v[94:97], v[166:169], v[190:193], v[94:97]
	v_mfma_f32_16x16x32_bf16 v[90:93], v[174:177], v[190:193], v[90:93]
	v_mfma_f32_16x16x32_bf16 v[78:81], v[166:169], v[210:213], v[78:81]
	v_mfma_f32_16x16x32_bf16 v[74:77], v[174:177], v[210:213], v[74:77]
	v_mfma_f32_16x16x32_bf16 v[70:73], v[166:169], v[218:221], v[70:73]
	v_mfma_f32_16x16x32_bf16 v[66:69], v[174:177], v[218:221], v[66:69]
	v_mfma_f32_16x16x32_bf16 v[110:113], v[170:173], v[186:189], v[110:113]
	v_mfma_f32_16x16x32_bf16 v[106:109], v[178:181], v[186:189], v[106:109]
	v_mfma_f32_16x16x32_bf16 v[94:97], v[170:173], v[198:201], v[94:97]
	v_mfma_f32_16x16x32_bf16 v[90:93], v[178:181], v[198:201], v[90:93]
	v_mfma_f32_16x16x32_bf16 v[78:81], v[170:173], v[214:217], v[78:81]
	v_mfma_f32_16x16x32_bf16 v[74:77], v[178:181], v[214:217], v[74:77]
	v_mfma_f32_16x16x32_bf16 v[70:73], v[170:173], v[222:225], v[70:73]
	v_mfma_f32_16x16x32_bf16 v[66:69], v[178:181], v[222:225], v[66:69]
	s_setprio 0
	s_barrier
	s_add_i32 s30, s51, s35
	v_lshl_add_u64 v[202:203], v[202:203], 0, s[8:9]
	s_mov_b32 m0, s30
	ds_read_b128 v[182:185], v149 offset:49152
	ds_read_b128 v[186:189], v149 offset:50176
	ds_read_b128 v[190:193], v149 offset:51200
	ds_read_b128 v[198:201], v149 offset:52224
	ds_read_b128 v[210:213], v149 offset:53248
	ds_read_b128 v[214:217], v149 offset:54272
	ds_read_b128 v[218:221], v149 offset:55296
	ds_read_b128 v[222:225], v149 offset:56320
	global_load_lds_dwordx4 v[202:203], off
	s_add_i32 m0, s30, 0x2000
	s_add_u32 s28, s28, 0x20080
	v_lshl_add_u64 v[202:203], v[206:207], 0, s[8:9]
	s_addc_u32 s29, s29, 0
	s_add_i32 s30, s52, s35
	global_load_lds_dwordx4 v[202:203], off
	v_lshl_add_u64 v[202:203], s[28:29], 0, v[132:133]
	s_mov_b32 m0, s30
	s_nop 0
	global_load_lds_dwordx4 v[202:203], off
	v_lshl_add_u64 v[202:203], s[28:29], 0, v[134:135]
	s_add_i32 m0, s30, 0x2000
	s_nop 0
	global_load_lds_dwordx4 v[202:203], off
	v_lshl_add_u64 v[202:203], v[226:227], 0, s[8:9]
	s_mov_b32 m0, s41
	s_nop 0
	global_load_lds_dwordx4 v[202:203], off
	v_lshl_add_u64 v[202:203], v[228:229], 0, s[8:9]
	s_mov_b32 m0, s42
	s_nop 0
	global_load_lds_dwordx4 v[202:203], off
	s_waitcnt vmcnt(8)
	s_waitcnt lgkmcnt(0)
	s_barrier
	s_setprio 1
	v_mfma_f32_16x16x32_bf16 v[62:65], v[150:153], v[182:185], v[62:65]
	v_mfma_f32_16x16x32_bf16 v[58:61], v[158:161], v[182:185], v[58:61]
	v_mfma_f32_16x16x32_bf16 v[54:57], v[150:153], v[190:193], v[54:57]
	v_mfma_f32_16x16x32_bf16 v[50:53], v[158:161], v[190:193], v[50:53]
	v_mfma_f32_16x16x32_bf16 v[38:41], v[150:153], v[210:213], v[38:41]
	v_mfma_f32_16x16x32_bf16 v[34:37], v[158:161], v[210:213], v[34:37]
	v_mfma_f32_16x16x32_bf16 v[22:25], v[150:153], v[218:221], v[22:25]
	v_mfma_f32_16x16x32_bf16 v[18:21], v[158:161], v[218:221], v[18:21]
	v_mfma_f32_16x16x32_bf16 v[62:65], v[154:157], v[186:189], v[62:65]
	v_mfma_f32_16x16x32_bf16 v[58:61], v[162:165], v[186:189], v[58:61]
	v_mfma_f32_16x16x32_bf16 v[54:57], v[154:157], v[198:201], v[54:57]
	v_mfma_f32_16x16x32_bf16 v[50:53], v[162:165], v[198:201], v[50:53]
	v_mfma_f32_16x16x32_bf16 v[38:41], v[154:157], v[214:217], v[38:41]
	v_mfma_f32_16x16x32_bf16 v[34:37], v[162:165], v[214:217], v[34:37]
	v_mfma_f32_16x16x32_bf16 v[22:25], v[154:157], v[222:225], v[22:25]
	v_mfma_f32_16x16x32_bf16 v[18:21], v[162:165], v[222:225], v[18:21]
	s_setprio 0
	s_setprio 1
	v_mfma_f32_16x16x32_bf16 v[46:49], v[166:169], v[182:185], v[46:49]
	v_mfma_f32_16x16x32_bf16 v[42:45], v[174:177], v[182:185], v[42:45]
	v_mfma_f32_16x16x32_bf16 v[30:33], v[166:169], v[190:193], v[30:33]
	v_mfma_f32_16x16x32_bf16 v[26:29], v[174:177], v[190:193], v[26:29]
	v_mfma_f32_16x16x32_bf16 v[14:17], v[166:169], v[210:213], v[14:17]
	v_mfma_f32_16x16x32_bf16 v[10:13], v[174:177], v[210:213], v[10:13]
	v_mfma_f32_16x16x32_bf16 v[6:9], v[166:169], v[218:221], v[6:9]
	v_mfma_f32_16x16x32_bf16 v[2:5], v[174:177], v[218:221], v[2:5]
	v_mfma_f32_16x16x32_bf16 v[46:49], v[170:173], v[186:189], v[46:49]
	v_mfma_f32_16x16x32_bf16 v[42:45], v[178:181], v[186:189], v[42:45]
	v_mfma_f32_16x16x32_bf16 v[30:33], v[170:173], v[198:201], v[30:33]
	v_mfma_f32_16x16x32_bf16 v[26:29], v[178:181], v[198:201], v[26:29]
	v_mfma_f32_16x16x32_bf16 v[14:17], v[170:173], v[214:217], v[14:17]
	v_mfma_f32_16x16x32_bf16 v[10:13], v[178:181], v[214:217], v[10:13]
	v_mfma_f32_16x16x32_bf16 v[6:9], v[170:173], v[222:225], v[6:9]
	v_mfma_f32_16x16x32_bf16 v[2:5], v[178:181], v[222:225], v[2:5]
	s_setprio 0
	s_barrier
	s_add_i32 s50, s50, 2
	s_add_u32 s26, s26, 0x100
	s_addc_u32 s27, s27, 0
	s_add_u32 s48, s48, 0x100
	s_addc_u32 s49, s49, 0
	s_cmp_gt_u32 s50, 5
	s_cbranch_scc0 .LBB0_690
	s_branch .Lpeeldone_10
.LBB0_690:
	ds_read_b128 v[150:153], v147
	ds_read_b128 v[154:157], v147 offset:1024
	ds_read_b128 v[158:161], v147 offset:2048
	ds_read_b128 v[162:165], v147 offset:3072
	ds_read_b128 v[166:169], v148
	ds_read_b128 v[170:173], v148 offset:1024
	ds_read_b128 v[174:177], v148 offset:2048
	ds_read_b128 v[178:181], v148 offset:3072
	s_add_u32 s28, s26, 0xfffe0080
	s_addc_u32 s29, s27, -1
	s_cmp_eq_u32 s50, 4
	s_cselect_b32 s31, s13, s29
	s_cselect_b32 s30, s46, s28
	s_cselect_b32 s29, s17, s49
	s_cselect_b32 s28, s47, s48
	v_lshl_add_u64 v[202:203], s[26:27], 0, v[138:139]
	s_add_i32 m0, s36, 0xc000
	ds_read_b128 v[182:185], v149
	ds_read_b128 v[186:189], v149 offset:1024
	ds_read_b128 v[190:193], v149 offset:2048
	ds_read_b128 v[198:201], v149 offset:3072
	ds_read_b128 v[210:213], v149 offset:4096
	ds_read_b128 v[214:217], v149 offset:5120
	ds_read_b128 v[218:221], v149 offset:6144
	ds_read_b128 v[222:225], v149 offset:7168
	global_load_lds_dwordx4 v[202:203], off
	v_lshl_add_u64 v[202:203], s[26:27], 0, v[140:141]
	s_add_i32 m0, s36, 0xe000
	s_nop 0
	global_load_lds_dwordx4 v[202:203], off
	s_waitcnt vmcnt(8)
	s_waitcnt lgkmcnt(0)
	s_barrier
	s_setprio 1
	v_mfma_f32_16x16x32_bf16 v[126:129], v[150:153], v[182:185], v[126:129]
	v_mfma_f32_16x16x32_bf16 v[122:125], v[158:161], v[182:185], v[122:125]
	v_mfma_f32_16x16x32_bf16 v[118:121], v[150:153], v[190:193], v[118:121]
	v_mfma_f32_16x16x32_bf16 v[114:117], v[158:161], v[190:193], v[114:117]
	v_mfma_f32_16x16x32_bf16 v[102:105], v[150:153], v[210:213], v[102:105]
	v_mfma_f32_16x16x32_bf16 v[98:101], v[158:161], v[210:213], v[98:101]
	v_mfma_f32_16x16x32_bf16 v[86:89], v[150:153], v[218:221], v[86:89]
	v_mfma_f32_16x16x32_bf16 v[82:85], v[158:161], v[218:221], v[82:85]
	v_mfma_f32_16x16x32_bf16 v[126:129], v[154:157], v[186:189], v[126:129]
	v_mfma_f32_16x16x32_bf16 v[122:125], v[162:165], v[186:189], v[122:125]
	v_mfma_f32_16x16x32_bf16 v[118:121], v[154:157], v[198:201], v[118:121]
	v_mfma_f32_16x16x32_bf16 v[114:117], v[162:165], v[198:201], v[114:117]
	v_mfma_f32_16x16x32_bf16 v[102:105], v[154:157], v[214:217], v[102:105]
	v_mfma_f32_16x16x32_bf16 v[98:101], v[162:165], v[214:217], v[98:101]
	v_mfma_f32_16x16x32_bf16 v[86:89], v[154:157], v[222:225], v[86:89]
	v_mfma_f32_16x16x32_bf16 v[82:85], v[162:165], v[222:225], v[82:85]
	s_setprio 0
	s_setprio 1
	v_mfma_f32_16x16x32_bf16 v[110:113], v[166:169], v[182:185], v[110:113]
	v_mfma_f32_16x16x32_bf16 v[106:109], v[174:177], v[182:185], v[106:109]
	v_mfma_f32_16x16x32_bf16 v[94:97], v[166:169], v[190:193], v[94:97]
	v_mfma_f32_16x16x32_bf16 v[90:93], v[174:177], v[190:193], v[90:93]
	v_mfma_f32_16x16x32_bf16 v[78:81], v[166:169], v[210:213], v[78:81]
	v_mfma_f32_16x16x32_bf16 v[74:77], v[174:177], v[210:213], v[74:77]
	v_mfma_f32_16x16x32_bf16 v[70:73], v[166:169], v[218:221], v[70:73]
	v_mfma_f32_16x16x32_bf16 v[66:69], v[174:177], v[218:221], v[66:69]
	v_mfma_f32_16x16x32_bf16 v[110:113], v[170:173], v[186:189], v[110:113]
	v_mfma_f32_16x16x32_bf16 v[106:109], v[178:181], v[186:189], v[106:109]
	v_mfma_f32_16x16x32_bf16 v[94:97], v[170:173], v[198:201], v[94:97]
	v_mfma_f32_16x16x32_bf16 v[90:93], v[178:181], v[198:201], v[90:93]
	v_mfma_f32_16x16x32_bf16 v[78:81], v[170:173], v[214:217], v[78:81]
	v_mfma_f32_16x16x32_bf16 v[74:77], v[178:181], v[214:217], v[74:77]
	v_mfma_f32_16x16x32_bf16 v[70:73], v[170:173], v[222:225], v[70:73]
	v_mfma_f32_16x16x32_bf16 v[66:69], v[178:181], v[222:225], v[66:69]
	s_setprio 0
	s_barrier
	s_add_i32 s51, s43, s35
	v_lshl_add_u64 v[202:203], s[28:29], 0, v[132:133]
	s_mov_b32 m0, s51
	ds_read_b128 v[182:185], v149 offset:16384
	ds_read_b128 v[186:189], v149 offset:17408
	ds_read_b128 v[190:193], v149 offset:18432
	ds_read_b128 v[198:201], v149 offset:19456
	ds_read_b128 v[210:213], v149 offset:20480
	ds_read_b128 v[214:217], v149 offset:21504
	ds_read_b128 v[218:221], v149 offset:22528
	ds_read_b128 v[222:225], v149 offset:23552
	global_load_lds_dwordx4 v[202:203], off
	s_add_i32 m0, s51, 0x2000
	s_add_u32 s52, s28, 0x20000
	v_lshl_add_u64 v[206:207], s[28:29], 0, v[134:135]
	s_addc_u32 s53, s29, 0
	s_add_i32 s51, s44, s35
	global_load_lds_dwordx4 v[206:207], off
	v_lshl_add_u64 v[226:227], s[52:53], 0, v[132:133]
	s_mov_b32 m0, s51
	v_lshl_add_u64 v[228:229], s[30:31], 0, v[136:137]
	global_load_lds_dwordx4 v[226:227], off
	v_lshl_add_u64 v[226:227], s[52:53], 0, v[134:135]
	s_add_i32 m0, s51, 0x2000
	s_nop 0
	global_load_lds_dwordx4 v[226:227], off
	v_lshl_add_u64 v[226:227], s[30:31], 0, v[130:131]
	s_mov_b32 m0, s36
	s_nop 0
	global_load_lds_dwordx4 v[226:227], off
	s_mov_b32 m0, s37
	s_nop 0
	global_load_lds_dwordx4 v[228:229], off
	s_waitcnt vmcnt(8)
	s_waitcnt lgkmcnt(0)
	s_barrier
	s_setprio 1
	v_mfma_f32_16x16x32_bf16 v[62:65], v[150:153], v[182:185], v[62:65]
	v_mfma_f32_16x16x32_bf16 v[58:61], v[158:161], v[182:185], v[58:61]
	v_mfma_f32_16x16x32_bf16 v[54:57], v[150:153], v[190:193], v[54:57]
	v_mfma_f32_16x16x32_bf16 v[50:53], v[158:161], v[190:193], v[50:53]
	v_mfma_f32_16x16x32_bf16 v[38:41], v[150:153], v[210:213], v[38:41]
	v_mfma_f32_16x16x32_bf16 v[34:37], v[158:161], v[210:213], v[34:37]
	v_mfma_f32_16x16x32_bf16 v[22:25], v[150:153], v[218:221], v[22:25]
	v_mfma_f32_16x16x32_bf16 v[18:21], v[158:161], v[218:221], v[18:21]
	v_mfma_f32_16x16x32_bf16 v[62:65], v[154:157], v[186:189], v[62:65]
	v_mfma_f32_16x16x32_bf16 v[58:61], v[162:165], v[186:189], v[58:61]
	v_mfma_f32_16x16x32_bf16 v[54:57], v[154:157], v[198:201], v[54:57]
	v_mfma_f32_16x16x32_bf16 v[50:53], v[162:165], v[198:201], v[50:53]
	v_mfma_f32_16x16x32_bf16 v[38:41], v[154:157], v[214:217], v[38:41]
	v_mfma_f32_16x16x32_bf16 v[34:37], v[162:165], v[214:217], v[34:37]
	v_mfma_f32_16x16x32_bf16 v[22:25], v[154:157], v[222:225], v[22:25]
	v_mfma_f32_16x16x32_bf16 v[18:21], v[162:165], v[222:225], v[18:21]
	s_setprio 0
	s_setprio 1
	v_mfma_f32_16x16x32_bf16 v[46:49], v[166:169], v[182:185], v[46:49]
	v_mfma_f32_16x16x32_bf16 v[42:45], v[174:177], v[182:185], v[42:45]
	v_mfma_f32_16x16x32_bf16 v[30:33], v[166:169], v[190:193], v[30:33]
	v_mfma_f32_16x16x32_bf16 v[26:29], v[174:177], v[190:193], v[26:29]
	v_mfma_f32_16x16x32_bf16 v[14:17], v[166:169], v[210:213], v[14:17]
	v_mfma_f32_16x16x32_bf16 v[10:13], v[174:177], v[210:213], v[10:13]
	v_mfma_f32_16x16x32_bf16 v[6:9], v[166:169], v[218:221], v[6:9]
	v_mfma_f32_16x16x32_bf16 v[2:5], v[174:177], v[218:221], v[2:5]
	v_mfma_f32_16x16x32_bf16 v[46:49], v[170:173], v[186:189], v[46:49]
	v_mfma_f32_16x16x32_bf16 v[42:45], v[178:181], v[186:189], v[42:45]
	v_mfma_f32_16x16x32_bf16 v[30:33], v[170:173], v[198:201], v[30:33]
	v_mfma_f32_16x16x32_bf16 v[26:29], v[178:181], v[198:201], v[26:29]
	v_mfma_f32_16x16x32_bf16 v[14:17], v[170:173], v[214:217], v[14:17]
	v_mfma_f32_16x16x32_bf16 v[10:13], v[178:181], v[214:217], v[10:13]
	v_mfma_f32_16x16x32_bf16 v[6:9], v[170:173], v[222:225], v[6:9]
	v_mfma_f32_16x16x32_bf16 v[2:5], v[178:181], v[222:225], v[2:5]
	s_setprio 0
	s_barrier
	s_add_i32 s51, 0, 0x18000
	s_add_i32 s52, 0, 0x1c000
	v_add_u32_e32 v162, s51, v145
	v_add_u32_e32 v178, s52, v145
	ds_read_b128 v[150:153], v162
	ds_read_b128 v[154:157], v162 offset:1024
	ds_read_b128 v[158:161], v162 offset:2048
	ds_read_b128 v[162:165], v162 offset:3072
	ds_read_b128 v[166:169], v178
	ds_read_b128 v[170:173], v178 offset:1024
	ds_read_b128 v[174:177], v178 offset:2048
	ds_read_b128 v[178:181], v178 offset:3072
	s_add_u32 s30, s30, 0x20000
	s_addc_u32 s31, s31, 0
	s_mov_b32 m0, s38
	v_lshl_add_u64 v[230:231], s[30:31], 0, v[130:131]
	ds_read_b128 v[182:185], v149 offset:32768
	ds_read_b128 v[186:189], v149 offset:33792
	ds_read_b128 v[190:193], v149 offset:34816
	ds_read_b128 v[198:201], v149 offset:35840
	ds_read_b128 v[210:213], v149 offset:36864
	ds_read_b128 v[214:217], v149 offset:37888
	ds_read_b128 v[218:221], v149 offset:38912
	ds_read_b128 v[222:225], v149 offset:39936
	global_load_lds_dwordx4 v[230:231], off
	v_lshl_add_u64 v[230:231], s[30:31], 0, v[136:137]
	s_mov_b32 m0, s39
	s_nop 0
	global_load_lds_dwordx4 v[230:231], off
	s_waitcnt vmcnt(8)
	s_waitcnt lgkmcnt(0)
	s_barrier
	s_setprio 1
	v_mfma_f32_16x16x32_bf16 v[126:129], v[150:153], v[182:185], v[126:129]
	v_mfma_f32_16x16x32_bf16 v[122:125], v[158:161], v[182:185], v[122:125]
	v_mfma_f32_16x16x32_bf16 v[118:121], v[150:153], v[190:193], v[118:121]
	v_mfma_f32_16x16x32_bf16 v[114:117], v[158:161], v[190:193], v[114:117]
	v_mfma_f32_16x16x32_bf16 v[102:105], v[150:153], v[210:213], v[102:105]
	v_mfma_f32_16x16x32_bf16 v[98:101], v[158:161], v[210:213], v[98:101]
	v_mfma_f32_16x16x32_bf16 v[86:89], v[150:153], v[218:221], v[86:89]
	v_mfma_f32_16x16x32_bf16 v[82:85], v[158:161], v[218:221], v[82:85]
	v_mfma_f32_16x16x32_bf16 v[126:129], v[154:157], v[186:189], v[126:129]
	v_mfma_f32_16x16x32_bf16 v[122:125], v[162:165], v[186:189], v[122:125]
	v_mfma_f32_16x16x32_bf16 v[118:121], v[154:157], v[198:201], v[118:121]
	v_mfma_f32_16x16x32_bf16 v[114:117], v[162:165], v[198:201], v[114:117]
	v_mfma_f32_16x16x32_bf16 v[102:105], v[154:157], v[214:217], v[102:105]
	v_mfma_f32_16x16x32_bf16 v[98:101], v[162:165], v[214:217], v[98:101]
	v_mfma_f32_16x16x32_bf16 v[86:89], v[154:157], v[222:225], v[86:89]
	v_mfma_f32_16x16x32_bf16 v[82:85], v[162:165], v[222:225], v[82:85]
	s_setprio 0
	s_setprio 1
	v_mfma_f32_16x16x32_bf16 v[110:113], v[166:169], v[182:185], v[110:113]
	v_mfma_f32_16x16x32_bf16 v[106:109], v[174:177], v[182:185], v[106:109]
	v_mfma_f32_16x16x32_bf16 v[94:97], v[166:169], v[190:193], v[94:97]
	v_mfma_f32_16x16x32_bf16 v[90:93], v[174:177], v[190:193], v[90:93]
	v_mfma_f32_16x16x32_bf16 v[78:81], v[166:169], v[210:213], v[78:81]
	v_mfma_f32_16x16x32_bf16 v[74:77], v[174:177], v[210:213], v[74:77]
	v_mfma_f32_16x16x32_bf16 v[70:73], v[166:169], v[218:221], v[70:73]
	v_mfma_f32_16x16x32_bf16 v[66:69], v[174:177], v[218:221], v[66:69]
	v_mfma_f32_16x16x32_bf16 v[110:113], v[170:173], v[186:189], v[110:113]
	v_mfma_f32_16x16x32_bf16 v[106:109], v[178:181], v[186:189], v[106:109]
	v_mfma_f32_16x16x32_bf16 v[94:97], v[170:173], v[198:201], v[94:97]
	v_mfma_f32_16x16x32_bf16 v[90:93], v[178:181], v[198:201], v[90:93]
	v_mfma_f32_16x16x32_bf16 v[78:81], v[170:173], v[214:217], v[78:81]
	v_mfma_f32_16x16x32_bf16 v[74:77], v[178:181], v[214:217], v[74:77]
	v_mfma_f32_16x16x32_bf16 v[70:73], v[170:173], v[222:225], v[70:73]
	v_mfma_f32_16x16x32_bf16 v[66:69], v[178:181], v[222:225], v[66:69]
	s_setprio 0
	s_barrier
	s_add_i32 s30, s51, s35
	v_lshl_add_u64 v[202:203], v[202:203], 0, s[8:9]
	s_mov_b32 m0, s30
	ds_read_b128 v[182:185], v149 offset:49152
	ds_read_b128 v[186:189], v149 offset:50176
	ds_read_b128 v[190:193], v149 offset:51200
	ds_read_b128 v[198:201], v149 offset:52224
	ds_read_b128 v[210:213], v149 offset:53248
	ds_read_b128 v[214:217], v149 offset:54272
	ds_read_b128 v[218:221], v149 offset:55296
	ds_read_b128 v[222:225], v149 offset:56320
	global_load_lds_dwordx4 v[202:203], off
	s_add_i32 m0, s30, 0x2000
	s_add_u32 s28, s28, 0x20080
	v_lshl_add_u64 v[202:203], v[206:207], 0, s[8:9]
	s_addc_u32 s29, s29, 0
	s_add_i32 s30, s52, s35
	global_load_lds_dwordx4 v[202:203], off
	v_lshl_add_u64 v[202:203], s[28:29], 0, v[132:133]
	s_mov_b32 m0, s30
	s_nop 0
	global_load_lds_dwordx4 v[202:203], off
	v_lshl_add_u64 v[202:203], s[28:29], 0, v[134:135]
	s_add_i32 m0, s30, 0x2000
	s_nop 0
	global_load_lds_dwordx4 v[202:203], off
	v_lshl_add_u64 v[202:203], v[226:227], 0, s[8:9]
	s_mov_b32 m0, s41
	s_nop 0
	global_load_lds_dwordx4 v[202:203], off
	v_lshl_add_u64 v[202:203], v[228:229], 0, s[8:9]
	s_mov_b32 m0, s42
	s_nop 0
	global_load_lds_dwordx4 v[202:203], off
	s_waitcnt vmcnt(8)
	s_waitcnt lgkmcnt(0)
	s_barrier
	s_setprio 1
	v_mfma_f32_16x16x32_bf16 v[62:65], v[150:153], v[182:185], v[62:65]
	v_mfma_f32_16x16x32_bf16 v[58:61], v[158:161], v[182:185], v[58:61]
	v_mfma_f32_16x16x32_bf16 v[54:57], v[150:153], v[190:193], v[54:57]
	v_mfma_f32_16x16x32_bf16 v[50:53], v[158:161], v[190:193], v[50:53]
	v_mfma_f32_16x16x32_bf16 v[38:41], v[150:153], v[210:213], v[38:41]
	v_mfma_f32_16x16x32_bf16 v[34:37], v[158:161], v[210:213], v[34:37]
	v_mfma_f32_16x16x32_bf16 v[22:25], v[150:153], v[218:221], v[22:25]
	v_mfma_f32_16x16x32_bf16 v[18:21], v[158:161], v[218:221], v[18:21]
	v_mfma_f32_16x16x32_bf16 v[62:65], v[154:157], v[186:189], v[62:65]
	v_mfma_f32_16x16x32_bf16 v[58:61], v[162:165], v[186:189], v[58:61]
	v_mfma_f32_16x16x32_bf16 v[54:57], v[154:157], v[198:201], v[54:57]
	v_mfma_f32_16x16x32_bf16 v[50:53], v[162:165], v[198:201], v[50:53]
	v_mfma_f32_16x16x32_bf16 v[38:41], v[154:157], v[214:217], v[38:41]
	v_mfma_f32_16x16x32_bf16 v[34:37], v[162:165], v[214:217], v[34:37]
	v_mfma_f32_16x16x32_bf16 v[22:25], v[154:157], v[222:225], v[22:25]
	v_mfma_f32_16x16x32_bf16 v[18:21], v[162:165], v[222:225], v[18:21]
	s_setprio 0
	s_setprio 1
	v_mfma_f32_16x16x32_bf16 v[46:49], v[166:169], v[182:185], v[46:49]
	v_mfma_f32_16x16x32_bf16 v[42:45], v[174:177], v[182:185], v[42:45]
	v_mfma_f32_16x16x32_bf16 v[30:33], v[166:169], v[190:193], v[30:33]
	v_mfma_f32_16x16x32_bf16 v[26:29], v[174:177], v[190:193], v[26:29]
	v_mfma_f32_16x16x32_bf16 v[14:17], v[166:169], v[210:213], v[14:17]
	v_mfma_f32_16x16x32_bf16 v[10:13], v[174:177], v[210:213], v[10:13]
	v_mfma_f32_16x16x32_bf16 v[6:9], v[166:169], v[218:221], v[6:9]
	v_mfma_f32_16x16x32_bf16 v[2:5], v[174:177], v[218:221], v[2:5]
	v_mfma_f32_16x16x32_bf16 v[46:49], v[170:173], v[186:189], v[46:49]
	v_mfma_f32_16x16x32_bf16 v[42:45], v[178:181], v[186:189], v[42:45]
	v_mfma_f32_16x16x32_bf16 v[30:33], v[170:173], v[198:201], v[30:33]
	v_mfma_f32_16x16x32_bf16 v[26:29], v[178:181], v[198:201], v[26:29]
	v_mfma_f32_16x16x32_bf16 v[14:17], v[170:173], v[214:217], v[14:17]
	v_mfma_f32_16x16x32_bf16 v[10:13], v[178:181], v[214:217], v[10:13]
	v_mfma_f32_16x16x32_bf16 v[6:9], v[170:173], v[222:225], v[6:9]
	v_mfma_f32_16x16x32_bf16 v[2:5], v[178:181], v[222:225], v[2:5]
	s_setprio 0
	s_barrier
	s_add_i32 s50, s50, 2
	s_add_u32 s26, s26, 0x100
	s_addc_u32 s27, s27, 0
	s_add_u32 s48, s48, 0x100
	s_addc_u32 s49, s49, 0
	s_cmp_gt_u32 s50, 5
	s_cbranch_scc0 .LBB0_690

.Lpeel_9:
	ds_read_b128 v[144:147], v140
	ds_read_b128 v[148:151], v140 offset:1024
	s_add_u32 s36, s34, 0xfffe0080
	s_addc_u32 s37, s35, -1
	s_cmp_eq_u32 s59, 4
	s_cselect_b32 s39, s21, s37
	s_cselect_b32 s38, s55, s36
	s_cselect_b32 s37, s25, s58
	s_cselect_b32 s36, s56, s57
	v_lshl_add_u64 v[192:193], s[34:35], 0, v[130:131]
	s_add_i32 m0, s27, 0xc000
	global_load_lds_dwordx4 v[192:193], off
	v_lshl_add_u64 v[192:193], s[34:35], 0, v[136:137]
	s_add_i32 m0, s27, 0xe000
	s_nop 0
	global_load_lds_dwordx4 v[192:193], off
	s_waitcnt vmcnt(8)
	s_waitcnt lgkmcnt(0)
	s_barrier
	s_setprio 1
	v_mfma_f32_16x16x32_bf16 v[126:129], v[144:147], v[176:179], 0
	v_mfma_f32_16x16x32_bf16 v[122:125], v[152:155], v[176:179], 0
	v_mfma_f32_16x16x32_bf16 v[118:121], v[144:147], v[184:187], 0
	v_mfma_f32_16x16x32_bf16 v[114:117], v[152:155], v[184:187], 0
	v_mfma_f32_16x16x32_bf16 v[102:105], v[144:147], v[198:201], 0
	v_mfma_f32_16x16x32_bf16 v[98:101], v[152:155], v[198:201], 0
	v_mfma_f32_16x16x32_bf16 v[86:89], v[144:147], v[214:217], 0
	v_mfma_f32_16x16x32_bf16 v[82:85], v[152:155], v[214:217], 0
	v_mfma_f32_16x16x32_bf16 v[126:129], v[148:151], v[180:183], v[126:129]
	v_mfma_f32_16x16x32_bf16 v[122:125], v[156:159], v[180:183], v[122:125]
	v_mfma_f32_16x16x32_bf16 v[118:121], v[148:151], v[188:191], v[118:121]
	v_mfma_f32_16x16x32_bf16 v[114:117], v[156:159], v[188:191], v[114:117]
	v_mfma_f32_16x16x32_bf16 v[102:105], v[148:151], v[210:213], v[102:105]
	v_mfma_f32_16x16x32_bf16 v[98:101], v[156:159], v[210:213], v[98:101]
	v_mfma_f32_16x16x32_bf16 v[86:89], v[148:151], v[218:221], v[86:89]
	v_mfma_f32_16x16x32_bf16 v[82:85], v[156:159], v[218:221], v[82:85]
	s_setprio 0
	s_setprio 1
	v_mfma_f32_16x16x32_bf16 v[110:113], v[160:163], v[176:179], 0
	v_mfma_f32_16x16x32_bf16 v[106:109], v[168:171], v[176:179], 0
	v_mfma_f32_16x16x32_bf16 v[94:97], v[160:163], v[184:187], 0
	v_mfma_f32_16x16x32_bf16 v[90:93], v[168:171], v[184:187], 0
	v_mfma_f32_16x16x32_bf16 v[78:81], v[160:163], v[198:201], 0
	v_mfma_f32_16x16x32_bf16 v[74:77], v[168:171], v[198:201], 0
	v_mfma_f32_16x16x32_bf16 v[70:73], v[160:163], v[214:217], 0
	v_mfma_f32_16x16x32_bf16 v[66:69], v[168:171], v[214:217], 0
	v_mfma_f32_16x16x32_bf16 v[110:113], v[164:167], v[180:183], v[110:113]
	v_mfma_f32_16x16x32_bf16 v[106:109], v[172:175], v[180:183], v[106:109]
	v_mfma_f32_16x16x32_bf16 v[94:97], v[164:167], v[188:191], v[94:97]
	v_mfma_f32_16x16x32_bf16 v[90:93], v[172:175], v[188:191], v[90:93]
	v_mfma_f32_16x16x32_bf16 v[78:81], v[164:167], v[210:213], v[78:81]
	v_mfma_f32_16x16x32_bf16 v[74:77], v[172:175], v[210:213], v[74:77]
	v_mfma_f32_16x16x32_bf16 v[70:73], v[164:167], v[218:221], v[70:73]
	v_mfma_f32_16x16x32_bf16 v[66:69], v[172:175], v[218:221], v[66:69]
	s_setprio 0
	s_barrier
	s_add_i32 s60, s48, s41
	v_lshl_add_u64 v[192:193], s[36:37], 0, v[132:133]
	s_mov_b32 m0, s60
	ds_read_b128 v[176:179], v142 offset:16384
	ds_read_b128 v[180:183], v142 offset:17408
	ds_read_b128 v[184:187], v142 offset:18432
	ds_read_b128 v[188:191], v142 offset:19456
	ds_read_b128 v[198:201], v142 offset:20480
	ds_read_b128 v[210:213], v142 offset:21504
	ds_read_b128 v[214:217], v142 offset:22528
	ds_read_b128 v[218:221], v142 offset:23552
	global_load_lds_dwordx4 v[192:193], off
	s_add_i32 m0, s60, 0x2000
	s_add_u32 s60, s36, 0x20000
	v_lshl_add_u64 v[202:203], s[36:37], 0, v[134:135]
	s_addc_u32 s61, s37, 0
	s_add_i32 s62, s49, s41
	global_load_lds_dwordx4 v[202:203], off
	v_lshl_add_u64 v[206:207], s[60:61], 0, v[132:133]
	s_mov_b32 m0, s62
	v_lshl_add_u64 v[222:223], s[38:39], 0, v[136:137]
	global_load_lds_dwordx4 v[206:207], off
	v_lshl_add_u64 v[206:207], s[60:61], 0, v[134:135]
	s_add_i32 m0, s62, 0x2000
	s_nop 0
	global_load_lds_dwordx4 v[206:207], off
	v_lshl_add_u64 v[206:207], s[38:39], 0, v[130:131]
	s_mov_b32 m0, s27
	s_nop 0
	global_load_lds_dwordx4 v[206:207], off
	s_mov_b32 m0, s42
	s_nop 0
	global_load_lds_dwordx4 v[222:223], off
	s_waitcnt vmcnt(8)
	s_waitcnt lgkmcnt(0)
	s_barrier
	s_setprio 1
	v_mfma_f32_16x16x32_bf16 v[62:65], v[144:147], v[176:179], 0
	v_mfma_f32_16x16x32_bf16 v[58:61], v[152:155], v[176:179], 0
	v_mfma_f32_16x16x32_bf16 v[54:57], v[144:147], v[184:187], 0
	v_mfma_f32_16x16x32_bf16 v[50:53], v[152:155], v[184:187], 0
	v_mfma_f32_16x16x32_bf16 v[38:41], v[144:147], v[198:201], 0
	v_mfma_f32_16x16x32_bf16 v[34:37], v[152:155], v[198:201], 0
	v_mfma_f32_16x16x32_bf16 v[22:25], v[144:147], v[214:217], 0
	v_mfma_f32_16x16x32_bf16 v[18:21], v[152:155], v[214:217], 0
	v_mfma_f32_16x16x32_bf16 v[62:65], v[148:151], v[180:183], v[62:65]
	v_mfma_f32_16x16x32_bf16 v[58:61], v[156:159], v[180:183], v[58:61]
	v_mfma_f32_16x16x32_bf16 v[54:57], v[148:151], v[188:191], v[54:57]
	v_mfma_f32_16x16x32_bf16 v[50:53], v[156:159], v[188:191], v[50:53]
	v_mfma_f32_16x16x32_bf16 v[38:41], v[148:151], v[210:213], v[38:41]
	v_mfma_f32_16x16x32_bf16 v[34:37], v[156:159], v[210:213], v[34:37]
	v_mfma_f32_16x16x32_bf16 v[22:25], v[148:151], v[218:221], v[22:25]
	v_mfma_f32_16x16x32_bf16 v[18:21], v[156:159], v[218:221], v[18:21]
	s_setprio 0
	s_setprio 1
	v_mfma_f32_16x16x32_bf16 v[46:49], v[160:163], v[176:179], 0
	v_mfma_f32_16x16x32_bf16 v[42:45], v[168:171], v[176:179], 0
	v_mfma_f32_16x16x32_bf16 v[30:33], v[160:163], v[184:187], 0
	v_mfma_f32_16x16x32_bf16 v[26:29], v[168:171], v[184:187], 0
	v_mfma_f32_16x16x32_bf16 v[14:17], v[160:163], v[198:201], 0
	v_mfma_f32_16x16x32_bf16 v[10:13], v[168:171], v[198:201], 0
	v_mfma_f32_16x16x32_bf16 v[6:9], v[160:163], v[214:217], 0
	v_mfma_f32_16x16x32_bf16 v[2:5], v[168:171], v[214:217], 0
	v_mfma_f32_16x16x32_bf16 v[46:49], v[164:167], v[180:183], v[46:49]
	v_mfma_f32_16x16x32_bf16 v[42:45], v[172:175], v[180:183], v[42:45]
	v_mfma_f32_16x16x32_bf16 v[30:33], v[164:167], v[188:191], v[30:33]
	v_mfma_f32_16x16x32_bf16 v[26:29], v[172:175], v[188:191], v[26:29]
	v_mfma_f32_16x16x32_bf16 v[14:17], v[164:167], v[210:213], v[14:17]
	v_mfma_f32_16x16x32_bf16 v[10:13], v[172:175], v[210:213], v[10:13]
	v_mfma_f32_16x16x32_bf16 v[6:9], v[164:167], v[218:221], v[6:9]
	v_mfma_f32_16x16x32_bf16 v[2:5], v[172:175], v[218:221], v[2:5]
	s_setprio 0
	s_barrier
	s_add_i32 s60, 0, 0x18000
	v_add_u32_e32 v143, s60, v139
	s_add_i32 s61, 0, 0x1c000
	ds_read_b128 v[144:147], v143
	ds_read_b128 v[148:151], v143 offset:1024
	ds_read_b128 v[152:155], v143 offset:2048
	ds_read_b128 v[156:159], v143 offset:3072
	v_add_u32_e32 v143, s61, v139
	ds_read_b128 v[160:163], v143
	ds_read_b128 v[164:167], v143 offset:1024
	ds_read_b128 v[168:171], v143 offset:2048
	ds_read_b128 v[172:175], v143 offset:3072
	s_add_u32 s38, s38, 0x20000
	s_addc_u32 s39, s39, 0
	s_mov_b32 m0, s43
	v_lshl_add_u64 v[224:225], s[38:39], 0, v[130:131]
	ds_read_b128 v[176:179], v142 offset:32768
	ds_read_b128 v[180:183], v142 offset:33792
	ds_read_b128 v[184:187], v142 offset:34816
	ds_read_b128 v[188:191], v142 offset:35840
	ds_read_b128 v[198:201], v142 offset:36864
	ds_read_b128 v[210:213], v142 offset:37888
	ds_read_b128 v[214:217], v142 offset:38912
	ds_read_b128 v[218:221], v142 offset:39936
	global_load_lds_dwordx4 v[224:225], off
	v_lshl_add_u64 v[224:225], s[38:39], 0, v[136:137]
	s_mov_b32 m0, s44
	s_nop 0
	global_load_lds_dwordx4 v[224:225], off
	s_waitcnt vmcnt(8)
	s_waitcnt lgkmcnt(0)
	s_barrier
	s_setprio 1
	v_mfma_f32_16x16x32_bf16 v[126:129], v[144:147], v[176:179], v[126:129]
	v_mfma_f32_16x16x32_bf16 v[122:125], v[152:155], v[176:179], v[122:125]
	v_mfma_f32_16x16x32_bf16 v[118:121], v[144:147], v[184:187], v[118:121]
	v_mfma_f32_16x16x32_bf16 v[114:117], v[152:155], v[184:187], v[114:117]
	v_mfma_f32_16x16x32_bf16 v[102:105], v[144:147], v[198:201], v[102:105]
	v_mfma_f32_16x16x32_bf16 v[98:101], v[152:155], v[198:201], v[98:101]
	v_mfma_f32_16x16x32_bf16 v[86:89], v[144:147], v[214:217], v[86:89]
	v_mfma_f32_16x16x32_bf16 v[82:85], v[152:155], v[214:217], v[82:85]
	v_mfma_f32_16x16x32_bf16 v[126:129], v[148:151], v[180:183], v[126:129]
	v_mfma_f32_16x16x32_bf16 v[122:125], v[156:159], v[180:183], v[122:125]
	v_mfma_f32_16x16x32_bf16 v[118:121], v[148:151], v[188:191], v[118:121]
	v_mfma_f32_16x16x32_bf16 v[114:117], v[156:159], v[188:191], v[114:117]
	v_mfma_f32_16x16x32_bf16 v[102:105], v[148:151], v[210:213], v[102:105]
	v_mfma_f32_16x16x32_bf16 v[98:101], v[156:159], v[210:213], v[98:101]
	v_mfma_f32_16x16x32_bf16 v[86:89], v[148:151], v[218:221], v[86:89]
	v_mfma_f32_16x16x32_bf16 v[82:85], v[156:159], v[218:221], v[82:85]
	s_setprio 0
	s_setprio 1
	v_mfma_f32_16x16x32_bf16 v[110:113], v[160:163], v[176:179], v[110:113]
	v_mfma_f32_16x16x32_bf16 v[106:109], v[168:171], v[176:179], v[106:109]
	v_mfma_f32_16x16x32_bf16 v[94:97], v[160:163], v[184:187], v[94:97]
	v_mfma_f32_16x16x32_bf16 v[90:93], v[168:171], v[184:187], v[90:93]
	v_mfma_f32_16x16x32_bf16 v[78:81], v[160:163], v[198:201], v[78:81]
	v_mfma_f32_16x16x32_bf16 v[74:77], v[168:171], v[198:201], v[74:77]
	v_mfma_f32_16x16x32_bf16 v[70:73], v[160:163], v[214:217], v[70:73]
	v_mfma_f32_16x16x32_bf16 v[66:69], v[168:171], v[214:217], v[66:69]
	v_mfma_f32_16x16x32_bf16 v[110:113], v[164:167], v[180:183], v[110:113]
	v_mfma_f32_16x16x32_bf16 v[106:109], v[172:175], v[180:183], v[106:109]
	v_mfma_f32_16x16x32_bf16 v[94:97], v[164:167], v[188:191], v[94:97]
	v_mfma_f32_16x16x32_bf16 v[90:93], v[172:175], v[188:191], v[90:93]
	v_mfma_f32_16x16x32_bf16 v[78:81], v[164:167], v[210:213], v[78:81]
	v_mfma_f32_16x16x32_bf16 v[74:77], v[172:175], v[210:213], v[74:77]
	v_mfma_f32_16x16x32_bf16 v[70:73], v[164:167], v[218:221], v[70:73]
	v_mfma_f32_16x16x32_bf16 v[66:69], v[172:175], v[218:221], v[66:69]
	s_setprio 0
	s_barrier
	s_add_i32 s38, s60, s41
	v_lshl_add_u64 v[192:193], v[192:193], 0, s[6:7]
	s_mov_b32 m0, s38
	ds_read_b128 v[176:179], v142 offset:49152
	ds_read_b128 v[180:183], v142 offset:50176
	ds_read_b128 v[184:187], v142 offset:51200
	ds_read_b128 v[188:191], v142 offset:52224
	ds_read_b128 v[198:201], v142 offset:53248
	ds_read_b128 v[210:213], v142 offset:54272
	ds_read_b128 v[214:217], v142 offset:55296
	ds_read_b128 v[218:221], v142 offset:56320
	global_load_lds_dwordx4 v[192:193], off
	s_add_i32 m0, s38, 0x2000
	s_add_u32 s36, s36, 0x20080
	v_lshl_add_u64 v[192:193], v[202:203], 0, s[6:7]
	s_addc_u32 s37, s37, 0
	s_add_i32 s38, s61, s41
	global_load_lds_dwordx4 v[192:193], off
	v_lshl_add_u64 v[192:193], s[36:37], 0, v[132:133]
	s_mov_b32 m0, s38
	s_nop 0
	global_load_lds_dwordx4 v[192:193], off
	v_lshl_add_u64 v[192:193], s[36:37], 0, v[134:135]
	s_add_i32 m0, s38, 0x2000
	s_nop 0
	global_load_lds_dwordx4 v[192:193], off
	v_lshl_add_u64 v[192:193], v[206:207], 0, s[6:7]
	s_mov_b32 m0, s46
	s_nop 0
	global_load_lds_dwordx4 v[192:193], off
	v_lshl_add_u64 v[192:193], v[222:223], 0, s[6:7]
	s_mov_b32 m0, s47
	s_nop 0
	global_load_lds_dwordx4 v[192:193], off
	s_waitcnt vmcnt(8)
	s_waitcnt lgkmcnt(0)
	s_barrier
	s_setprio 1
	v_mfma_f32_16x16x32_bf16 v[62:65], v[144:147], v[176:179], v[62:65]
	v_mfma_f32_16x16x32_bf16 v[58:61], v[152:155], v[176:179], v[58:61]
	v_mfma_f32_16x16x32_bf16 v[54:57], v[144:147], v[184:187], v[54:57]
	v_mfma_f32_16x16x32_bf16 v[50:53], v[152:155], v[184:187], v[50:53]
	v_mfma_f32_16x16x32_bf16 v[38:41], v[144:147], v[198:201], v[38:41]
	v_mfma_f32_16x16x32_bf16 v[34:37], v[152:155], v[198:201], v[34:37]
	v_mfma_f32_16x16x32_bf16 v[22:25], v[144:147], v[214:217], v[22:25]
	v_mfma_f32_16x16x32_bf16 v[18:21], v[152:155], v[214:217], v[18:21]
	v_mfma_f32_16x16x32_bf16 v[62:65], v[148:151], v[180:183], v[62:65]
	v_mfma_f32_16x16x32_bf16 v[58:61], v[156:159], v[180:183], v[58:61]
	v_mfma_f32_16x16x32_bf16 v[54:57], v[148:151], v[188:191], v[54:57]
	v_mfma_f32_16x16x32_bf16 v[50:53], v[156:159], v[188:191], v[50:53]
	v_mfma_f32_16x16x32_bf16 v[38:41], v[148:151], v[210:213], v[38:41]
	v_mfma_f32_16x16x32_bf16 v[34:37], v[156:159], v[210:213], v[34:37]
	v_mfma_f32_16x16x32_bf16 v[22:25], v[148:151], v[218:221], v[22:25]
	v_mfma_f32_16x16x32_bf16 v[18:21], v[156:159], v[218:221], v[18:21]
	s_setprio 0
	s_setprio 1
	v_mfma_f32_16x16x32_bf16 v[46:49], v[160:163], v[176:179], v[46:49]
	v_mfma_f32_16x16x32_bf16 v[42:45], v[168:171], v[176:179], v[42:45]
	v_mfma_f32_16x16x32_bf16 v[30:33], v[160:163], v[184:187], v[30:33]
	v_mfma_f32_16x16x32_bf16 v[26:29], v[168:171], v[184:187], v[26:29]
	v_mfma_f32_16x16x32_bf16 v[14:17], v[160:163], v[198:201], v[14:17]
	v_mfma_f32_16x16x32_bf16 v[10:13], v[168:171], v[198:201], v[10:13]
	v_mfma_f32_16x16x32_bf16 v[6:9], v[160:163], v[214:217], v[6:9]
	v_mfma_f32_16x16x32_bf16 v[2:5], v[168:171], v[214:217], v[2:5]
	v_mfma_f32_16x16x32_bf16 v[46:49], v[164:167], v[180:183], v[46:49]
	v_mfma_f32_16x16x32_bf16 v[42:45], v[172:175], v[180:183], v[42:45]
	v_mfma_f32_16x16x32_bf16 v[30:33], v[164:167], v[188:191], v[30:33]
	v_mfma_f32_16x16x32_bf16 v[26:29], v[172:175], v[188:191], v[26:29]
	v_mfma_f32_16x16x32_bf16 v[14:17], v[164:167], v[210:213], v[14:17]
	v_mfma_f32_16x16x32_bf16 v[10:13], v[172:175], v[210:213], v[10:13]
	v_mfma_f32_16x16x32_bf16 v[6:9], v[164:167], v[218:221], v[6:9]
	v_mfma_f32_16x16x32_bf16 v[2:5], v[172:175], v[218:221], v[2:5]
	s_setprio 0
	s_barrier
	s_add_i32 s59, s59, 2
	s_add_u32 s34, s34, 0x100
	s_addc_u32 s35, s35, 0
	s_add_u32 s57, s57, 0x100
	s_addc_u32 s58, s58, 0
	s_cmp_gt_u32 s59, 5
	s_cbranch_scc0 .LBB0_714
	s_branch .Lpeeldone_9
.LBB0_714:
	ds_read_b128 v[144:147], v140
	ds_read_b128 v[148:151], v140 offset:1024
	ds_read_b128 v[152:155], v140 offset:2048
	ds_read_b128 v[156:159], v140 offset:3072
	ds_read_b128 v[160:163], v141
	ds_read_b128 v[164:167], v141 offset:1024
	ds_read_b128 v[168:171], v141 offset:2048
	ds_read_b128 v[172:175], v141 offset:3072
	s_add_u32 s36, s34, 0xfffe0080
	s_addc_u32 s37, s35, -1
	s_cmp_eq_u32 s59, 4
	s_cselect_b32 s39, s21, s37
	s_cselect_b32 s38, s55, s36
	s_cselect_b32 s37, s25, s58
	s_cselect_b32 s36, s56, s57
	v_lshl_add_u64 v[192:193], s[34:35], 0, v[130:131]
	s_add_i32 m0, s27, 0xc000
	ds_read_b128 v[176:179], v142
	ds_read_b128 v[180:183], v142 offset:1024
	ds_read_b128 v[184:187], v142 offset:2048
	ds_read_b128 v[188:191], v142 offset:3072
	ds_read_b128 v[198:201], v142 offset:4096
	ds_read_b128 v[210:213], v142 offset:5120
	ds_read_b128 v[214:217], v142 offset:6144
	ds_read_b128 v[218:221], v142 offset:7168
	global_load_lds_dwordx4 v[192:193], off
	v_lshl_add_u64 v[192:193], s[34:35], 0, v[136:137]
	s_add_i32 m0, s27, 0xe000
	s_nop 0
	global_load_lds_dwordx4 v[192:193], off
	s_waitcnt vmcnt(8)
	s_waitcnt lgkmcnt(0)
	s_barrier
	s_setprio 1
	v_mfma_f32_16x16x32_bf16 v[126:129], v[144:147], v[176:179], v[126:129]
	v_mfma_f32_16x16x32_bf16 v[122:125], v[152:155], v[176:179], v[122:125]
	v_mfma_f32_16x16x32_bf16 v[118:121], v[144:147], v[184:187], v[118:121]
	v_mfma_f32_16x16x32_bf16 v[114:117], v[152:155], v[184:187], v[114:117]
	v_mfma_f32_16x16x32_bf16 v[102:105], v[144:147], v[198:201], v[102:105]
	v_mfma_f32_16x16x32_bf16 v[98:101], v[152:155], v[198:201], v[98:101]
	v_mfma_f32_16x16x32_bf16 v[86:89], v[144:147], v[214:217], v[86:89]
	v_mfma_f32_16x16x32_bf16 v[82:85], v[152:155], v[214:217], v[82:85]
	v_mfma_f32_16x16x32_bf16 v[126:129], v[148:151], v[180:183], v[126:129]
	v_mfma_f32_16x16x32_bf16 v[122:125], v[156:159], v[180:183], v[122:125]
	v_mfma_f32_16x16x32_bf16 v[118:121], v[148:151], v[188:191], v[118:121]
	v_mfma_f32_16x16x32_bf16 v[114:117], v[156:159], v[188:191], v[114:117]
	v_mfma_f32_16x16x32_bf16 v[102:105], v[148:151], v[210:213], v[102:105]
	v_mfma_f32_16x16x32_bf16 v[98:101], v[156:159], v[210:213], v[98:101]
	v_mfma_f32_16x16x32_bf16 v[86:89], v[148:151], v[218:221], v[86:89]
	v_mfma_f32_16x16x32_bf16 v[82:85], v[156:159], v[218:221], v[82:85]
	s_setprio 0
	s_setprio 1
	v_mfma_f32_16x16x32_bf16 v[110:113], v[160:163], v[176:179], v[110:113]
	v_mfma_f32_16x16x32_bf16 v[106:109], v[168:171], v[176:179], v[106:109]
	v_mfma_f32_16x16x32_bf16 v[94:97], v[160:163], v[184:187], v[94:97]
	v_mfma_f32_16x16x32_bf16 v[90:93], v[168:171], v[184:187], v[90:93]
	v_mfma_f32_16x16x32_bf16 v[78:81], v[160:163], v[198:201], v[78:81]
	v_mfma_f32_16x16x32_bf16 v[74:77], v[168:171], v[198:201], v[74:77]
	v_mfma_f32_16x16x32_bf16 v[70:73], v[160:163], v[214:217], v[70:73]
	v_mfma_f32_16x16x32_bf16 v[66:69], v[168:171], v[214:217], v[66:69]
	v_mfma_f32_16x16x32_bf16 v[110:113], v[164:167], v[180:183], v[110:113]
	v_mfma_f32_16x16x32_bf16 v[106:109], v[172:175], v[180:183], v[106:109]
	v_mfma_f32_16x16x32_bf16 v[94:97], v[164:167], v[188:191], v[94:97]
	v_mfma_f32_16x16x32_bf16 v[90:93], v[172:175], v[188:191], v[90:93]
	v_mfma_f32_16x16x32_bf16 v[78:81], v[164:167], v[210:213], v[78:81]
	v_mfma_f32_16x16x32_bf16 v[74:77], v[172:175], v[210:213], v[74:77]
	v_mfma_f32_16x16x32_bf16 v[70:73], v[164:167], v[218:221], v[70:73]
	v_mfma_f32_16x16x32_bf16 v[66:69], v[172:175], v[218:221], v[66:69]
	s_setprio 0
	s_barrier
	s_add_i32 s60, s48, s41
	v_lshl_add_u64 v[192:193], s[36:37], 0, v[132:133]
	s_mov_b32 m0, s60
	ds_read_b128 v[176:179], v142 offset:16384
	ds_read_b128 v[180:183], v142 offset:17408
	ds_read_b128 v[184:187], v142 offset:18432
	ds_read_b128 v[188:191], v142 offset:19456
	ds_read_b128 v[198:201], v142 offset:20480
	ds_read_b128 v[210:213], v142 offset:21504
	ds_read_b128 v[214:217], v142 offset:22528
	ds_read_b128 v[218:221], v142 offset:23552
	global_load_lds_dwordx4 v[192:193], off
	s_add_i32 m0, s60, 0x2000
	s_add_u32 s60, s36, 0x20000
	v_lshl_add_u64 v[202:203], s[36:37], 0, v[134:135]
	s_addc_u32 s61, s37, 0
	s_add_i32 s62, s49, s41
	global_load_lds_dwordx4 v[202:203], off
	v_lshl_add_u64 v[206:207], s[60:61], 0, v[132:133]
	s_mov_b32 m0, s62
	v_lshl_add_u64 v[222:223], s[38:39], 0, v[136:137]
	global_load_lds_dwordx4 v[206:207], off
	v_lshl_add_u64 v[206:207], s[60:61], 0, v[134:135]
	s_add_i32 m0, s62, 0x2000
	s_nop 0
	global_load_lds_dwordx4 v[206:207], off
	v_lshl_add_u64 v[206:207], s[38:39], 0, v[130:131]
	s_mov_b32 m0, s27
	s_nop 0
	global_load_lds_dwordx4 v[206:207], off
	s_mov_b32 m0, s42
	s_nop 0
	global_load_lds_dwordx4 v[222:223], off
	s_waitcnt vmcnt(8)
	s_waitcnt lgkmcnt(0)
	s_barrier
	s_setprio 1
	v_mfma_f32_16x16x32_bf16 v[62:65], v[144:147], v[176:179], v[62:65]
	v_mfma_f32_16x16x32_bf16 v[58:61], v[152:155], v[176:179], v[58:61]
	v_mfma_f32_16x16x32_bf16 v[54:57], v[144:147], v[184:187], v[54:57]
	v_mfma_f32_16x16x32_bf16 v[50:53], v[152:155], v[184:187], v[50:53]
	v_mfma_f32_16x16x32_bf16 v[38:41], v[144:147], v[198:201], v[38:41]
	v_mfma_f32_16x16x32_bf16 v[34:37], v[152:155], v[198:201], v[34:37]
	v_mfma_f32_16x16x32_bf16 v[22:25], v[144:147], v[214:217], v[22:25]
	v_mfma_f32_16x16x32_bf16 v[18:21], v[152:155], v[214:217], v[18:21]
	v_mfma_f32_16x16x32_bf16 v[62:65], v[148:151], v[180:183], v[62:65]
	v_mfma_f32_16x16x32_bf16 v[58:61], v[156:159], v[180:183], v[58:61]
	v_mfma_f32_16x16x32_bf16 v[54:57], v[148:151], v[188:191], v[54:57]
	v_mfma_f32_16x16x32_bf16 v[50:53], v[156:159], v[188:191], v[50:53]
	v_mfma_f32_16x16x32_bf16 v[38:41], v[148:151], v[210:213], v[38:41]
	v_mfma_f32_16x16x32_bf16 v[34:37], v[156:159], v[210:213], v[34:37]
	v_mfma_f32_16x16x32_bf16 v[22:25], v[148:151], v[218:221], v[22:25]
	v_mfma_f32_16x16x32_bf16 v[18:21], v[156:159], v[218:221], v[18:21]
	s_setprio 0
	s_setprio 1
	v_mfma_f32_16x16x32_bf16 v[46:49], v[160:163], v[176:179], v[46:49]
	v_mfma_f32_16x16x32_bf16 v[42:45], v[168:171], v[176:179], v[42:45]
	v_mfma_f32_16x16x32_bf16 v[30:33], v[160:163], v[184:187], v[30:33]
	v_mfma_f32_16x16x32_bf16 v[26:29], v[168:171], v[184:187], v[26:29]
	v_mfma_f32_16x16x32_bf16 v[14:17], v[160:163], v[198:201], v[14:17]
	v_mfma_f32_16x16x32_bf16 v[10:13], v[168:171], v[198:201], v[10:13]
	v_mfma_f32_16x16x32_bf16 v[6:9], v[160:163], v[214:217], v[6:9]
	v_mfma_f32_16x16x32_bf16 v[2:5], v[168:171], v[214:217], v[2:5]
	v_mfma_f32_16x16x32_bf16 v[46:49], v[164:167], v[180:183], v[46:49]
	v_mfma_f32_16x16x32_bf16 v[42:45], v[172:175], v[180:183], v[42:45]
	v_mfma_f32_16x16x32_bf16 v[30:33], v[164:167], v[188:191], v[30:33]
	v_mfma_f32_16x16x32_bf16 v[26:29], v[172:175], v[188:191], v[26:29]
	v_mfma_f32_16x16x32_bf16 v[14:17], v[164:167], v[210:213], v[14:17]
	v_mfma_f32_16x16x32_bf16 v[10:13], v[172:175], v[210:213], v[10:13]
	v_mfma_f32_16x16x32_bf16 v[6:9], v[164:167], v[218:221], v[6:9]
	v_mfma_f32_16x16x32_bf16 v[2:5], v[172:175], v[218:221], v[2:5]
	s_setprio 0
	s_barrier
	s_add_i32 s60, 0, 0x18000
	v_add_u32_e32 v143, s60, v139
	s_add_i32 s61, 0, 0x1c000
	ds_read_b128 v[144:147], v143
	ds_read_b128 v[148:151], v143 offset:1024
	ds_read_b128 v[152:155], v143 offset:2048
	ds_read_b128 v[156:159], v143 offset:3072
	v_add_u32_e32 v143, s61, v139
	ds_read_b128 v[160:163], v143
	ds_read_b128 v[164:167], v143 offset:1024
	ds_read_b128 v[168:171], v143 offset:2048
	ds_read_b128 v[172:175], v143 offset:3072
	s_add_u32 s38, s38, 0x20000
	s_addc_u32 s39, s39, 0
	s_mov_b32 m0, s43
	v_lshl_add_u64 v[224:225], s[38:39], 0, v[130:131]
	ds_read_b128 v[176:179], v142 offset:32768
	ds_read_b128 v[180:183], v142 offset:33792
	ds_read_b128 v[184:187], v142 offset:34816
	ds_read_b128 v[188:191], v142 offset:35840
	ds_read_b128 v[198:201], v142 offset:36864
	ds_read_b128 v[210:213], v142 offset:37888
	ds_read_b128 v[214:217], v142 offset:38912
	ds_read_b128 v[218:221], v142 offset:39936
	global_load_lds_dwordx4 v[224:225], off
	v_lshl_add_u64 v[224:225], s[38:39], 0, v[136:137]
	s_mov_b32 m0, s44
	s_nop 0
	global_load_lds_dwordx4 v[224:225], off
	s_waitcnt vmcnt(8)
	s_waitcnt lgkmcnt(0)
	s_barrier
	s_setprio 1
	v_mfma_f32_16x16x32_bf16 v[126:129], v[144:147], v[176:179], v[126:129]
	v_mfma_f32_16x16x32_bf16 v[122:125], v[152:155], v[176:179], v[122:125]
	v_mfma_f32_16x16x32_bf16 v[118:121], v[144:147], v[184:187], v[118:121]
	v_mfma_f32_16x16x32_bf16 v[114:117], v[152:155], v[184:187], v[114:117]
	v_mfma_f32_16x16x32_bf16 v[102:105], v[144:147], v[198:201], v[102:105]
	v_mfma_f32_16x16x32_bf16 v[98:101], v[152:155], v[198:201], v[98:101]
	v_mfma_f32_16x16x32_bf16 v[86:89], v[144:147], v[214:217], v[86:89]
	v_mfma_f32_16x16x32_bf16 v[82:85], v[152:155], v[214:217], v[82:85]
	v_mfma_f32_16x16x32_bf16 v[126:129], v[148:151], v[180:183], v[126:129]
	v_mfma_f32_16x16x32_bf16 v[122:125], v[156:159], v[180:183], v[122:125]
	v_mfma_f32_16x16x32_bf16 v[118:121], v[148:151], v[188:191], v[118:121]
	v_mfma_f32_16x16x32_bf16 v[114:117], v[156:159], v[188:191], v[114:117]
	v_mfma_f32_16x16x32_bf16 v[102:105], v[148:151], v[210:213], v[102:105]
	v_mfma_f32_16x16x32_bf16 v[98:101], v[156:159], v[210:213], v[98:101]
	v_mfma_f32_16x16x32_bf16 v[86:89], v[148:151], v[218:221], v[86:89]
	v_mfma_f32_16x16x32_bf16 v[82:85], v[156:159], v[218:221], v[82:85]
	s_setprio 0
	s_setprio 1
	v_mfma_f32_16x16x32_bf16 v[110:113], v[160:163], v[176:179], v[110:113]
	v_mfma_f32_16x16x32_bf16 v[106:109], v[168:171], v[176:179], v[106:109]
	v_mfma_f32_16x16x32_bf16 v[94:97], v[160:163], v[184:187], v[94:97]
	v_mfma_f32_16x16x32_bf16 v[90:93], v[168:171], v[184:187], v[90:93]
	v_mfma_f32_16x16x32_bf16 v[78:81], v[160:163], v[198:201], v[78:81]
	v_mfma_f32_16x16x32_bf16 v[74:77], v[168:171], v[198:201], v[74:77]
	v_mfma_f32_16x16x32_bf16 v[70:73], v[160:163], v[214:217], v[70:73]
	v_mfma_f32_16x16x32_bf16 v[66:69], v[168:171], v[214:217], v[66:69]
	v_mfma_f32_16x16x32_bf16 v[110:113], v[164:167], v[180:183], v[110:113]
	v_mfma_f32_16x16x32_bf16 v[106:109], v[172:175], v[180:183], v[106:109]
	v_mfma_f32_16x16x32_bf16 v[94:97], v[164:167], v[188:191], v[94:97]
	v_mfma_f32_16x16x32_bf16 v[90:93], v[172:175], v[188:191], v[90:93]
	v_mfma_f32_16x16x32_bf16 v[78:81], v[164:167], v[210:213], v[78:81]
	v_mfma_f32_16x16x32_bf16 v[74:77], v[172:175], v[210:213], v[74:77]
	v_mfma_f32_16x16x32_bf16 v[70:73], v[164:167], v[218:221], v[70:73]
	v_mfma_f32_16x16x32_bf16 v[66:69], v[172:175], v[218:221], v[66:69]
	s_setprio 0
	s_barrier
	s_add_i32 s38, s60, s41
	v_lshl_add_u64 v[192:193], v[192:193], 0, s[6:7]
	s_mov_b32 m0, s38
	ds_read_b128 v[176:179], v142 offset:49152
	ds_read_b128 v[180:183], v142 offset:50176
	ds_read_b128 v[184:187], v142 offset:51200
	ds_read_b128 v[188:191], v142 offset:52224
	ds_read_b128 v[198:201], v142 offset:53248
	ds_read_b128 v[210:213], v142 offset:54272
	ds_read_b128 v[214:217], v142 offset:55296
	ds_read_b128 v[218:221], v142 offset:56320
	global_load_lds_dwordx4 v[192:193], off
	s_add_i32 m0, s38, 0x2000
	s_add_u32 s36, s36, 0x20080
	v_lshl_add_u64 v[192:193], v[202:203], 0, s[6:7]
	s_addc_u32 s37, s37, 0
	s_add_i32 s38, s61, s41
	global_load_lds_dwordx4 v[192:193], off
	v_lshl_add_u64 v[192:193], s[36:37], 0, v[132:133]
	s_mov_b32 m0, s38
	s_nop 0
	global_load_lds_dwordx4 v[192:193], off
	v_lshl_add_u64 v[192:193], s[36:37], 0, v[134:135]
	s_add_i32 m0, s38, 0x2000
	s_nop 0
	global_load_lds_dwordx4 v[192:193], off
	v_lshl_add_u64 v[192:193], v[206:207], 0, s[6:7]
	s_mov_b32 m0, s46
	s_nop 0
	global_load_lds_dwordx4 v[192:193], off
	v_lshl_add_u64 v[192:193], v[222:223], 0, s[6:7]
	s_mov_b32 m0, s47
	s_nop 0
	global_load_lds_dwordx4 v[192:193], off
	s_waitcnt vmcnt(8)
	s_waitcnt lgkmcnt(0)
	s_barrier
	s_setprio 1
	v_mfma_f32_16x16x32_bf16 v[62:65], v[144:147], v[176:179], v[62:65]
	v_mfma_f32_16x16x32_bf16 v[58:61], v[152:155], v[176:179], v[58:61]
	v_mfma_f32_16x16x32_bf16 v[54:57], v[144:147], v[184:187], v[54:57]
	v_mfma_f32_16x16x32_bf16 v[50:53], v[152:155], v[184:187], v[50:53]
	v_mfma_f32_16x16x32_bf16 v[38:41], v[144:147], v[198:201], v[38:41]
	v_mfma_f32_16x16x32_bf16 v[34:37], v[152:155], v[198:201], v[34:37]
	v_mfma_f32_16x16x32_bf16 v[22:25], v[144:147], v[214:217], v[22:25]
	v_mfma_f32_16x16x32_bf16 v[18:21], v[152:155], v[214:217], v[18:21]
	v_mfma_f32_16x16x32_bf16 v[62:65], v[148:151], v[180:183], v[62:65]
	v_mfma_f32_16x16x32_bf16 v[58:61], v[156:159], v[180:183], v[58:61]
	v_mfma_f32_16x16x32_bf16 v[54:57], v[148:151], v[188:191], v[54:57]
	v_mfma_f32_16x16x32_bf16 v[50:53], v[156:159], v[188:191], v[50:53]
	v_mfma_f32_16x16x32_bf16 v[38:41], v[148:151], v[210:213], v[38:41]
	v_mfma_f32_16x16x32_bf16 v[34:37], v[156:159], v[210:213], v[34:37]
	v_mfma_f32_16x16x32_bf16 v[22:25], v[148:151], v[218:221], v[22:25]
	v_mfma_f32_16x16x32_bf16 v[18:21], v[156:159], v[218:221], v[18:21]
	s_setprio 0
	s_setprio 1
	v_mfma_f32_16x16x32_bf16 v[46:49], v[160:163], v[176:179], v[46:49]
	v_mfma_f32_16x16x32_bf16 v[42:45], v[168:171], v[176:179], v[42:45]
	v_mfma_f32_16x16x32_bf16 v[30:33], v[160:163], v[184:187], v[30:33]
	v_mfma_f32_16x16x32_bf16 v[26:29], v[168:171], v[184:187], v[26:29]
	v_mfma_f32_16x16x32_bf16 v[14:17], v[160:163], v[198:201], v[14:17]
	v_mfma_f32_16x16x32_bf16 v[10:13], v[168:171], v[198:201], v[10:13]
	v_mfma_f32_16x16x32_bf16 v[6:9], v[160:163], v[214:217], v[6:9]
	v_mfma_f32_16x16x32_bf16 v[2:5], v[168:171], v[214:217], v[2:5]
	v_mfma_f32_16x16x32_bf16 v[46:49], v[164:167], v[180:183], v[46:49]
	v_mfma_f32_16x16x32_bf16 v[42:45], v[172:175], v[180:183], v[42:45]
	v_mfma_f32_16x16x32_bf16 v[30:33], v[164:167], v[188:191], v[30:33]
	v_mfma_f32_16x16x32_bf16 v[26:29], v[172:175], v[188:191], v[26:29]
	v_mfma_f32_16x16x32_bf16 v[14:17], v[164:167], v[210:213], v[14:17]
	v_mfma_f32_16x16x32_bf16 v[10:13], v[172:175], v[210:213], v[10:13]
	v_mfma_f32_16x16x32_bf16 v[6:9], v[164:167], v[218:221], v[6:9]
	v_mfma_f32_16x16x32_bf16 v[2:5], v[172:175], v[218:221], v[2:5]
	s_setprio 0
	s_barrier
	s_add_i32 s59, s59, 2
	s_add_u32 s34, s34, 0x100
	s_addc_u32 s35, s35, 0
	s_add_u32 s57, s57, 0x100
	s_addc_u32 s58, s58, 0
	s_cmp_gt_u32 s59, 5
	s_cbranch_scc0 .LBB0_714

.Lpeel_8:
	ds_read_b128 v[130:133], v170
	ds_read_b128 v[134:137], v170 offset:1024
	ds_read_b128 v[138:141], v170 offset:2048
	ds_read_b128 v[142:145], v170 offset:3072
	ds_read_b128 v[160:163], v171
	ds_read_b128 v[164:167], v171 offset:1024
	ds_read_b128 v[174:177], v171 offset:2048
	ds_read_b128 v[178:181], v171 offset:3072
	s_add_i32 s31, s21, 2
	s_add_u32 s36, s34, 0xfff80080
	s_addc_u32 s37, s35, -1
	s_cmp_eq_u32 s30, s21
	s_cselect_b32 s39, s23, s37
	s_cselect_b32 s38, s22, s36
	s_cselect_b32 s37, s25, s19
	s_cselect_b32 s36, s24, s17
	v_lshl_add_u64 v[202:203], s[34:35], 0, v[156:157]
	s_add_i32 m0, s27, 0xc000
	ds_read_b128 v[182:185], v172
	ds_read_b128 v[186:189], v172 offset:1024
	ds_read_b128 v[190:193], v172 offset:2048
	ds_read_b128 v[198:201], v172 offset:3072
	ds_read_b128 v[210:213], v172 offset:4096
	ds_read_b128 v[214:217], v172 offset:5120
	global_load_lds_dwordx4 v[202:203], off
	v_lshl_add_u64 v[202:203], s[34:35], 0, v[158:159]
	s_add_i32 m0, s27, 0xe000
	s_nop 0
	global_load_lds_dwordx4 v[202:203], off
	s_waitcnt vmcnt(8)
	s_waitcnt lgkmcnt(0)
	s_barrier
	s_setprio 1
	v_mfma_f32_16x16x32_bf16 v[126:129], v[130:133], v[182:185], 0
	v_mfma_f32_16x16x32_bf16 v[122:125], v[138:141], v[182:185], 0
	v_mfma_f32_16x16x32_bf16 v[118:121], v[130:133], v[190:193], 0
	v_mfma_f32_16x16x32_bf16 v[110:113], v[138:141], v[190:193], 0
	v_mfma_f32_16x16x32_bf16 v[94:97], v[130:133], v[210:213], 0
	v_mfma_f32_16x16x32_bf16 v[90:93], v[138:141], v[210:213], 0
	v_mfma_f32_16x16x32_bf16 v[78:81], v[130:133], v[218:221], 0
	v_mfma_f32_16x16x32_bf16 v[74:77], v[138:141], v[218:221], 0
	v_mfma_f32_16x16x32_bf16 v[126:129], v[134:137], v[186:189], v[126:129]
	v_mfma_f32_16x16x32_bf16 v[122:125], v[142:145], v[186:189], v[122:125]
	v_mfma_f32_16x16x32_bf16 v[118:121], v[134:137], v[198:201], v[118:121]
	v_mfma_f32_16x16x32_bf16 v[110:113], v[142:145], v[198:201], v[110:113]
	v_mfma_f32_16x16x32_bf16 v[94:97], v[134:137], v[214:217], v[94:97]
	v_mfma_f32_16x16x32_bf16 v[90:93], v[142:145], v[214:217], v[90:93]
	v_mfma_f32_16x16x32_bf16 v[78:81], v[134:137], v[222:225], v[78:81]
	v_mfma_f32_16x16x32_bf16 v[74:77], v[142:145], v[222:225], v[74:77]
	s_setprio 0
	s_setprio 1
	v_mfma_f32_16x16x32_bf16 v[114:117], v[160:163], v[182:185], 0
	v_mfma_f32_16x16x32_bf16 v[106:109], v[174:177], v[182:185], 0
	v_mfma_f32_16x16x32_bf16 v[102:105], v[160:163], v[190:193], 0
	v_mfma_f32_16x16x32_bf16 v[98:101], v[174:177], v[190:193], 0
	v_mfma_f32_16x16x32_bf16 v[86:89], v[160:163], v[210:213], 0
	v_mfma_f32_16x16x32_bf16 v[82:85], v[174:177], v[210:213], 0
	v_mfma_f32_16x16x32_bf16 v[70:73], v[160:163], v[218:221], 0
	v_mfma_f32_16x16x32_bf16 v[66:69], v[174:177], v[218:221], 0
	v_mfma_f32_16x16x32_bf16 v[114:117], v[164:167], v[186:189], v[114:117]
	v_mfma_f32_16x16x32_bf16 v[106:109], v[178:181], v[186:189], v[106:109]
	v_mfma_f32_16x16x32_bf16 v[102:105], v[164:167], v[198:201], v[102:105]
	v_mfma_f32_16x16x32_bf16 v[98:101], v[178:181], v[198:201], v[98:101]
	v_mfma_f32_16x16x32_bf16 v[86:89], v[164:167], v[214:217], v[86:89]
	v_mfma_f32_16x16x32_bf16 v[82:85], v[178:181], v[214:217], v[82:85]
	v_mfma_f32_16x16x32_bf16 v[70:73], v[164:167], v[222:225], v[70:73]
	v_mfma_f32_16x16x32_bf16 v[66:69], v[178:181], v[222:225], v[66:69]
	s_setprio 0
	s_barrier
	s_add_i32 s21, s63, s33
	v_lshl_add_u64 v[202:203], s[36:37], 0, v[148:149]
	s_mov_b32 m0, s21
	ds_read_b128 v[182:185], v172 offset:16384
	ds_read_b128 v[186:189], v172 offset:17408
	ds_read_b128 v[190:193], v172 offset:18432
	ds_read_b128 v[198:201], v172 offset:19456
	ds_read_b128 v[210:213], v172 offset:20480
	ds_read_b128 v[214:217], v172 offset:21504
	ds_read_b128 v[218:221], v172 offset:22528
	ds_read_b128 v[222:225], v172 offset:23552
	global_load_lds_dwordx4 v[202:203], off
	s_add_i32 m0, s21, 0x2000
	s_add_u32 s40, s36, 0x80000
	v_lshl_add_u64 v[206:207], s[36:37], 0, v[152:153]
	s_addc_u32 s41, s37, 0
	s_add_i32 s21, s64, s33
	global_load_lds_dwordx4 v[206:207], off
	v_lshl_add_u64 v[226:227], s[40:41], 0, v[148:149]
	s_mov_b32 m0, s21
	v_lshl_add_u64 v[228:229], s[38:39], 0, v[150:151]
	global_load_lds_dwordx4 v[226:227], off
	v_lshl_add_u64 v[226:227], s[40:41], 0, v[152:153]
	s_add_i32 m0, s21, 0x2000
	s_nop 0
	global_load_lds_dwordx4 v[226:227], off
	v_lshl_add_u64 v[226:227], s[38:39], 0, v[146:147]
	s_mov_b32 m0, s27
	s_nop 0
	global_load_lds_dwordx4 v[226:227], off
	s_mov_b32 m0, s29
	s_nop 0
	global_load_lds_dwordx4 v[228:229], off
	s_waitcnt vmcnt(8)
	s_waitcnt lgkmcnt(0)
	s_barrier
	s_setprio 1
	v_mfma_f32_16x16x32_bf16 v[62:65], v[130:133], v[182:185], 0
	v_mfma_f32_16x16x32_bf16 v[58:61], v[138:141], v[182:185], 0
	v_mfma_f32_16x16x32_bf16 v[46:49], v[130:133], v[190:193], 0
	v_mfma_f32_16x16x32_bf16 v[42:45], v[138:141], v[190:193], 0
	v_mfma_f32_16x16x32_bf16 v[30:33], v[130:133], v[210:213], 0
	v_mfma_f32_16x16x32_bf16 v[26:29], v[138:141], v[210:213], 0
	v_mfma_f32_16x16x32_bf16 v[14:17], v[130:133], v[218:221], 0
	v_mfma_f32_16x16x32_bf16 v[10:13], v[138:141], v[218:221], 0
	v_mfma_f32_16x16x32_bf16 v[62:65], v[134:137], v[186:189], v[62:65]
	v_mfma_f32_16x16x32_bf16 v[58:61], v[142:145], v[186:189], v[58:61]
	v_mfma_f32_16x16x32_bf16 v[46:49], v[134:137], v[198:201], v[46:49]
	v_mfma_f32_16x16x32_bf16 v[42:45], v[142:145], v[198:201], v[42:45]
	v_mfma_f32_16x16x32_bf16 v[30:33], v[134:137], v[214:217], v[30:33]
	v_mfma_f32_16x16x32_bf16 v[26:29], v[142:145], v[214:217], v[26:29]
	v_mfma_f32_16x16x32_bf16 v[14:17], v[134:137], v[222:225], v[14:17]
	v_mfma_f32_16x16x32_bf16 v[10:13], v[142:145], v[222:225], v[10:13]
	s_setprio 0
	s_setprio 1
	v_mfma_f32_16x16x32_bf16 v[54:57], v[160:163], v[182:185], 0
	v_mfma_f32_16x16x32_bf16 v[50:53], v[174:177], v[182:185], 0
	v_mfma_f32_16x16x32_bf16 v[38:41], v[160:163], v[190:193], 0
	v_mfma_f32_16x16x32_bf16 v[34:37], v[174:177], v[190:193], 0
	v_mfma_f32_16x16x32_bf16 v[22:25], v[160:163], v[210:213], 0
	v_mfma_f32_16x16x32_bf16 v[18:21], v[174:177], v[210:213], 0
	v_mfma_f32_16x16x32_bf16 v[6:9], v[160:163], v[218:221], 0
	v_mfma_f32_16x16x32_bf16 v[2:5], v[174:177], v[218:221], 0
	v_mfma_f32_16x16x32_bf16 v[54:57], v[164:167], v[186:189], v[54:57]
	v_mfma_f32_16x16x32_bf16 v[50:53], v[178:181], v[186:189], v[50:53]
	v_mfma_f32_16x16x32_bf16 v[38:41], v[164:167], v[198:201], v[38:41]
	v_mfma_f32_16x16x32_bf16 v[34:37], v[178:181], v[198:201], v[34:37]
	v_mfma_f32_16x16x32_bf16 v[22:25], v[164:167], v[214:217], v[22:25]
	v_mfma_f32_16x16x32_bf16 v[18:21], v[178:181], v[214:217], v[18:21]
	v_mfma_f32_16x16x32_bf16 v[6:9], v[164:167], v[222:225], v[6:9]
	v_mfma_f32_16x16x32_bf16 v[2:5], v[178:181], v[222:225], v[2:5]
	s_setprio 0
	s_barrier
	s_add_i32 s21, 0, 0x18000
	s_add_i32 s40, 0, 0x1c000
	v_add_u32_e32 v142, s21, v168
	v_add_u32_e32 v173, s40, v168
	ds_read_b128 v[130:133], v142
	ds_read_b128 v[134:137], v142 offset:1024
	ds_read_b128 v[138:141], v142 offset:2048
	ds_read_b128 v[142:145], v142 offset:3072
	ds_read_b128 v[160:163], v173
	ds_read_b128 v[164:167], v173 offset:1024
	ds_read_b128 v[174:177], v173 offset:2048
	ds_read_b128 v[178:181], v173 offset:3072
	s_add_u32 s38, s38, 0x80000
	s_addc_u32 s39, s39, 0
	s_mov_b32 m0, s42
	v_lshl_add_u64 v[230:231], s[38:39], 0, v[146:147]
	ds_read_b128 v[182:185], v172 offset:32768
	ds_read_b128 v[186:189], v172 offset:33792
	ds_read_b128 v[190:193], v172 offset:34816
	ds_read_b128 v[198:201], v172 offset:35840
	ds_read_b128 v[210:213], v172 offset:36864
	ds_read_b128 v[214:217], v172 offset:37888
	ds_read_b128 v[218:221], v172 offset:38912
	ds_read_b128 v[222:225], v172 offset:39936
	global_load_lds_dwordx4 v[230:231], off
	v_lshl_add_u64 v[230:231], s[38:39], 0, v[150:151]
	s_mov_b32 m0, s43
	s_nop 0
	global_load_lds_dwordx4 v[230:231], off
	s_waitcnt vmcnt(8)
	s_waitcnt lgkmcnt(0)
	s_barrier
	s_setprio 1
	v_mfma_f32_16x16x32_bf16 v[126:129], v[130:133], v[182:185], v[126:129]
	v_mfma_f32_16x16x32_bf16 v[122:125], v[138:141], v[182:185], v[122:125]
	v_mfma_f32_16x16x32_bf16 v[118:121], v[130:133], v[190:193], v[118:121]
	v_mfma_f32_16x16x32_bf16 v[110:113], v[138:141], v[190:193], v[110:113]
	v_mfma_f32_16x16x32_bf16 v[94:97], v[130:133], v[210:213], v[94:97]
	v_mfma_f32_16x16x32_bf16 v[90:93], v[138:141], v[210:213], v[90:93]
	v_mfma_f32_16x16x32_bf16 v[78:81], v[130:133], v[218:221], v[78:81]
	v_mfma_f32_16x16x32_bf16 v[74:77], v[138:141], v[218:221], v[74:77]
	v_mfma_f32_16x16x32_bf16 v[126:129], v[134:137], v[186:189], v[126:129]
	v_mfma_f32_16x16x32_bf16 v[122:125], v[142:145], v[186:189], v[122:125]
	v_mfma_f32_16x16x32_bf16 v[118:121], v[134:137], v[198:201], v[118:121]
	v_mfma_f32_16x16x32_bf16 v[110:113], v[142:145], v[198:201], v[110:113]
	v_mfma_f32_16x16x32_bf16 v[94:97], v[134:137], v[214:217], v[94:97]
	v_mfma_f32_16x16x32_bf16 v[90:93], v[142:145], v[214:217], v[90:93]
	v_mfma_f32_16x16x32_bf16 v[78:81], v[134:137], v[222:225], v[78:81]
	v_mfma_f32_16x16x32_bf16 v[74:77], v[142:145], v[222:225], v[74:77]
	s_setprio 0
	s_setprio 1
	v_mfma_f32_16x16x32_bf16 v[114:117], v[160:163], v[182:185], v[114:117]
	v_mfma_f32_16x16x32_bf16 v[106:109], v[174:177], v[182:185], v[106:109]
	v_mfma_f32_16x16x32_bf16 v[102:105], v[160:163], v[190:193], v[102:105]
	v_mfma_f32_16x16x32_bf16 v[98:101], v[174:177], v[190:193], v[98:101]
	v_mfma_f32_16x16x32_bf16 v[86:89], v[160:163], v[210:213], v[86:89]
	v_mfma_f32_16x16x32_bf16 v[82:85], v[174:177], v[210:213], v[82:85]
	v_mfma_f32_16x16x32_bf16 v[70:73], v[160:163], v[218:221], v[70:73]
	v_mfma_f32_16x16x32_bf16 v[66:69], v[174:177], v[218:221], v[66:69]
	v_mfma_f32_16x16x32_bf16 v[114:117], v[164:167], v[186:189], v[114:117]
	v_mfma_f32_16x16x32_bf16 v[106:109], v[178:181], v[186:189], v[106:109]
	v_mfma_f32_16x16x32_bf16 v[102:105], v[164:167], v[198:201], v[102:105]
	v_mfma_f32_16x16x32_bf16 v[98:101], v[178:181], v[198:201], v[98:101]
	v_mfma_f32_16x16x32_bf16 v[86:89], v[164:167], v[214:217], v[86:89]
	v_mfma_f32_16x16x32_bf16 v[82:85], v[178:181], v[214:217], v[82:85]
	v_mfma_f32_16x16x32_bf16 v[70:73], v[164:167], v[222:225], v[70:73]
	v_mfma_f32_16x16x32_bf16 v[66:69], v[178:181], v[222:225], v[66:69]
	s_setprio 0
	s_barrier
	s_add_i32 s21, s21, s33
	v_lshl_add_u64 v[202:203], v[202:203], 0, s[12:13]
	s_mov_b32 m0, s21
	ds_read_b128 v[182:185], v172 offset:49152
	ds_read_b128 v[186:189], v172 offset:50176
	ds_read_b128 v[190:193], v172 offset:51200
	ds_read_b128 v[198:201], v172 offset:52224
	ds_read_b128 v[210:213], v172 offset:53248
	ds_read_b128 v[214:217], v172 offset:54272
	ds_read_b128 v[218:221], v172 offset:55296
	ds_read_b128 v[222:225], v172 offset:56320
	global_load_lds_dwordx4 v[202:203], off
	s_add_i32 m0, s21, 0x2000
	s_add_u32 s36, s36, 0x80080
	v_lshl_add_u64 v[202:203], v[206:207], 0, s[12:13]
	s_addc_u32 s37, s37, 0
	s_add_i32 s21, s40, s33
	global_load_lds_dwordx4 v[202:203], off
	v_lshl_add_u64 v[202:203], s[36:37], 0, v[148:149]
	s_mov_b32 m0, s21
	s_nop 0
	global_load_lds_dwordx4 v[202:203], off
	v_lshl_add_u64 v[202:203], s[36:37], 0, v[152:153]
	s_add_i32 m0, s21, 0x2000
	s_nop 0
	global_load_lds_dwordx4 v[202:203], off
	v_lshl_add_u64 v[202:203], v[226:227], 0, s[12:13]
	s_mov_b32 m0, s53
	s_nop 0
	global_load_lds_dwordx4 v[202:203], off
	v_lshl_add_u64 v[202:203], v[228:229], 0, s[12:13]
	s_mov_b32 m0, s54
	s_nop 0
	global_load_lds_dwordx4 v[202:203], off
	s_waitcnt vmcnt(8)
	s_waitcnt lgkmcnt(0)
	s_barrier
	s_setprio 1
	v_mfma_f32_16x16x32_bf16 v[62:65], v[130:133], v[182:185], v[62:65]
	v_mfma_f32_16x16x32_bf16 v[58:61], v[138:141], v[182:185], v[58:61]
	v_mfma_f32_16x16x32_bf16 v[46:49], v[130:133], v[190:193], v[46:49]
	v_mfma_f32_16x16x32_bf16 v[42:45], v[138:141], v[190:193], v[42:45]
	v_mfma_f32_16x16x32_bf16 v[30:33], v[130:133], v[210:213], v[30:33]
	v_mfma_f32_16x16x32_bf16 v[26:29], v[138:141], v[210:213], v[26:29]
	v_mfma_f32_16x16x32_bf16 v[14:17], v[130:133], v[218:221], v[14:17]
	v_mfma_f32_16x16x32_bf16 v[10:13], v[138:141], v[218:221], v[10:13]
	v_mfma_f32_16x16x32_bf16 v[62:65], v[134:137], v[186:189], v[62:65]
	v_mfma_f32_16x16x32_bf16 v[58:61], v[142:145], v[186:189], v[58:61]
	v_mfma_f32_16x16x32_bf16 v[46:49], v[134:137], v[198:201], v[46:49]
	v_mfma_f32_16x16x32_bf16 v[42:45], v[142:145], v[198:201], v[42:45]
	v_mfma_f32_16x16x32_bf16 v[30:33], v[134:137], v[214:217], v[30:33]
	v_mfma_f32_16x16x32_bf16 v[26:29], v[142:145], v[214:217], v[26:29]
	v_mfma_f32_16x16x32_bf16 v[14:17], v[134:137], v[222:225], v[14:17]
	v_mfma_f32_16x16x32_bf16 v[10:13], v[142:145], v[222:225], v[10:13]
	s_setprio 0
	s_setprio 1
	v_mfma_f32_16x16x32_bf16 v[54:57], v[160:163], v[182:185], v[54:57]
	v_mfma_f32_16x16x32_bf16 v[50:53], v[174:177], v[182:185], v[50:53]
	v_mfma_f32_16x16x32_bf16 v[38:41], v[160:163], v[190:193], v[38:41]
	v_mfma_f32_16x16x32_bf16 v[34:37], v[174:177], v[190:193], v[34:37]
	v_mfma_f32_16x16x32_bf16 v[22:25], v[160:163], v[210:213], v[22:25]
	v_mfma_f32_16x16x32_bf16 v[18:21], v[174:177], v[210:213], v[18:21]
	v_mfma_f32_16x16x32_bf16 v[6:9], v[160:163], v[218:221], v[6:9]
	v_mfma_f32_16x16x32_bf16 v[2:5], v[174:177], v[218:221], v[2:5]
	v_mfma_f32_16x16x32_bf16 v[54:57], v[164:167], v[186:189], v[54:57]
	v_mfma_f32_16x16x32_bf16 v[50:53], v[178:181], v[186:189], v[50:53]
	v_mfma_f32_16x16x32_bf16 v[38:41], v[164:167], v[198:201], v[38:41]
	v_mfma_f32_16x16x32_bf16 v[34:37], v[178:181], v[198:201], v[34:37]
	v_mfma_f32_16x16x32_bf16 v[22:25], v[164:167], v[214:217], v[22:25]
	v_mfma_f32_16x16x32_bf16 v[18:21], v[178:181], v[214:217], v[18:21]
	v_mfma_f32_16x16x32_bf16 v[6:9], v[164:167], v[222:225], v[6:9]
	v_mfma_f32_16x16x32_bf16 v[2:5], v[178:181], v[222:225], v[2:5]
	s_setprio 0
	s_barrier
	s_add_u32 s34, s34, 0x100
	s_addc_u32 s35, s35, 0
	s_add_u32 s17, s17, 0x100
	s_addc_u32 s19, s19, 0
	s_cmp_ge_i32 s31, s69
	s_mov_b32 s21, s31
	s_cbranch_scc0 .LBB0_1122
	s_branch .Lpeeldone_8
.LBB0_1122:
	ds_read_b128 v[130:133], v170
	ds_read_b128 v[134:137], v170 offset:1024
	ds_read_b128 v[138:141], v170 offset:2048
	ds_read_b128 v[142:145], v170 offset:3072
	ds_read_b128 v[160:163], v171
	ds_read_b128 v[164:167], v171 offset:1024
	ds_read_b128 v[174:177], v171 offset:2048
	ds_read_b128 v[178:181], v171 offset:3072
	s_add_i32 s31, s21, 2
	s_add_u32 s36, s34, 0xfff80080
	s_addc_u32 s37, s35, -1
	s_cmp_eq_u32 s30, s21
	s_cselect_b32 s39, s23, s37
	s_cselect_b32 s38, s22, s36
	s_cselect_b32 s37, s25, s19
	s_cselect_b32 s36, s24, s17
	v_lshl_add_u64 v[202:203], s[34:35], 0, v[156:157]
	s_add_i32 m0, s27, 0xc000
	ds_read_b128 v[182:185], v172
	ds_read_b128 v[186:189], v172 offset:1024
	ds_read_b128 v[190:193], v172 offset:2048
	ds_read_b128 v[198:201], v172 offset:3072
	ds_read_b128 v[210:213], v172 offset:4096
	ds_read_b128 v[214:217], v172 offset:5120
	ds_read_b128 v[218:221], v172 offset:6144
	ds_read_b128 v[222:225], v172 offset:7168
	global_load_lds_dwordx4 v[202:203], off
	v_lshl_add_u64 v[202:203], s[34:35], 0, v[158:159]
	s_add_i32 m0, s27, 0xe000
	s_nop 0
	global_load_lds_dwordx4 v[202:203], off
	s_waitcnt vmcnt(8)
	s_waitcnt lgkmcnt(0)
	s_barrier
	s_setprio 1
	v_mfma_f32_16x16x32_bf16 v[126:129], v[130:133], v[182:185], v[126:129]
	v_mfma_f32_16x16x32_bf16 v[122:125], v[138:141], v[182:185], v[122:125]
	v_mfma_f32_16x16x32_bf16 v[118:121], v[130:133], v[190:193], v[118:121]
	v_mfma_f32_16x16x32_bf16 v[110:113], v[138:141], v[190:193], v[110:113]
	v_mfma_f32_16x16x32_bf16 v[94:97], v[130:133], v[210:213], v[94:97]
	v_mfma_f32_16x16x32_bf16 v[90:93], v[138:141], v[210:213], v[90:93]
	v_mfma_f32_16x16x32_bf16 v[78:81], v[130:133], v[218:221], v[78:81]
	v_mfma_f32_16x16x32_bf16 v[74:77], v[138:141], v[218:221], v[74:77]
	v_mfma_f32_16x16x32_bf16 v[126:129], v[134:137], v[186:189], v[126:129]
	v_mfma_f32_16x16x32_bf16 v[122:125], v[142:145], v[186:189], v[122:125]
	v_mfma_f32_16x16x32_bf16 v[118:121], v[134:137], v[198:201], v[118:121]
	v_mfma_f32_16x16x32_bf16 v[110:113], v[142:145], v[198:201], v[110:113]
	v_mfma_f32_16x16x32_bf16 v[94:97], v[134:137], v[214:217], v[94:97]
	v_mfma_f32_16x16x32_bf16 v[90:93], v[142:145], v[214:217], v[90:93]
	v_mfma_f32_16x16x32_bf16 v[78:81], v[134:137], v[222:225], v[78:81]
	v_mfma_f32_16x16x32_bf16 v[74:77], v[142:145], v[222:225], v[74:77]
	s_setprio 0
	s_setprio 1
	v_mfma_f32_16x16x32_bf16 v[114:117], v[160:163], v[182:185], v[114:117]
	v_mfma_f32_16x16x32_bf16 v[106:109], v[174:177], v[182:185], v[106:109]
	v_mfma_f32_16x16x32_bf16 v[102:105], v[160:163], v[190:193], v[102:105]
	v_mfma_f32_16x16x32_bf16 v[98:101], v[174:177], v[190:193], v[98:101]
	v_mfma_f32_16x16x32_bf16 v[86:89], v[160:163], v[210:213], v[86:89]
	v_mfma_f32_16x16x32_bf16 v[82:85], v[174:177], v[210:213], v[82:85]
	v_mfma_f32_16x16x32_bf16 v[70:73], v[160:163], v[218:221], v[70:73]
	v_mfma_f32_16x16x32_bf16 v[66:69], v[174:177], v[218:221], v[66:69]
	v_mfma_f32_16x16x32_bf16 v[114:117], v[164:167], v[186:189], v[114:117]
	v_mfma_f32_16x16x32_bf16 v[106:109], v[178:181], v[186:189], v[106:109]
	v_mfma_f32_16x16x32_bf16 v[102:105], v[164:167], v[198:201], v[102:105]
	v_mfma_f32_16x16x32_bf16 v[98:101], v[178:181], v[198:201], v[98:101]
	v_mfma_f32_16x16x32_bf16 v[86:89], v[164:167], v[214:217], v[86:89]
	v_mfma_f32_16x16x32_bf16 v[82:85], v[178:181], v[214:217], v[82:85]
	v_mfma_f32_16x16x32_bf16 v[70:73], v[164:167], v[222:225], v[70:73]
	v_mfma_f32_16x16x32_bf16 v[66:69], v[178:181], v[222:225], v[66:69]
	s_setprio 0
	s_barrier
	s_add_i32 s21, s63, s33
	v_lshl_add_u64 v[202:203], s[36:37], 0, v[148:149]
	s_mov_b32 m0, s21
	ds_read_b128 v[182:185], v172 offset:16384
	ds_read_b128 v[186:189], v172 offset:17408
	ds_read_b128 v[190:193], v172 offset:18432
	ds_read_b128 v[198:201], v172 offset:19456
	ds_read_b128 v[210:213], v172 offset:20480
	ds_read_b128 v[214:217], v172 offset:21504
	ds_read_b128 v[218:221], v172 offset:22528
	ds_read_b128 v[222:225], v172 offset:23552
	global_load_lds_dwordx4 v[202:203], off
	s_add_i32 m0, s21, 0x2000
	s_add_u32 s40, s36, 0x80000
	v_lshl_add_u64 v[206:207], s[36:37], 0, v[152:153]
	s_addc_u32 s41, s37, 0
	s_add_i32 s21, s64, s33
	global_load_lds_dwordx4 v[206:207], off
	v_lshl_add_u64 v[226:227], s[40:41], 0, v[148:149]
	s_mov_b32 m0, s21
	v_lshl_add_u64 v[228:229], s[38:39], 0, v[150:151]
	global_load_lds_dwordx4 v[226:227], off
	v_lshl_add_u64 v[226:227], s[40:41], 0, v[152:153]
	s_add_i32 m0, s21, 0x2000
	s_nop 0
	global_load_lds_dwordx4 v[226:227], off
	v_lshl_add_u64 v[226:227], s[38:39], 0, v[146:147]
	s_mov_b32 m0, s27
	s_nop 0
	global_load_lds_dwordx4 v[226:227], off
	s_mov_b32 m0, s29
	s_nop 0
	global_load_lds_dwordx4 v[228:229], off
	s_waitcnt vmcnt(8)
	s_waitcnt lgkmcnt(0)
	s_barrier
	s_setprio 1
	v_mfma_f32_16x16x32_bf16 v[62:65], v[130:133], v[182:185], v[62:65]
	v_mfma_f32_16x16x32_bf16 v[58:61], v[138:141], v[182:185], v[58:61]
	v_mfma_f32_16x16x32_bf16 v[46:49], v[130:133], v[190:193], v[46:49]
	v_mfma_f32_16x16x32_bf16 v[42:45], v[138:141], v[190:193], v[42:45]
	v_mfma_f32_16x16x32_bf16 v[30:33], v[130:133], v[210:213], v[30:33]
	v_mfma_f32_16x16x32_bf16 v[26:29], v[138:141], v[210:213], v[26:29]
	v_mfma_f32_16x16x32_bf16 v[14:17], v[130:133], v[218:221], v[14:17]
	v_mfma_f32_16x16x32_bf16 v[10:13], v[138:141], v[218:221], v[10:13]
	v_mfma_f32_16x16x32_bf16 v[62:65], v[134:137], v[186:189], v[62:65]
	v_mfma_f32_16x16x32_bf16 v[58:61], v[142:145], v[186:189], v[58:61]
	v_mfma_f32_16x16x32_bf16 v[46:49], v[134:137], v[198:201], v[46:49]
	v_mfma_f32_16x16x32_bf16 v[42:45], v[142:145], v[198:201], v[42:45]
	v_mfma_f32_16x16x32_bf16 v[30:33], v[134:137], v[214:217], v[30:33]
	v_mfma_f32_16x16x32_bf16 v[26:29], v[142:145], v[214:217], v[26:29]
	v_mfma_f32_16x16x32_bf16 v[14:17], v[134:137], v[222:225], v[14:17]
	v_mfma_f32_16x16x32_bf16 v[10:13], v[142:145], v[222:225], v[10:13]
	s_setprio 0
	s_setprio 1
	v_mfma_f32_16x16x32_bf16 v[54:57], v[160:163], v[182:185], v[54:57]
	v_mfma_f32_16x16x32_bf16 v[50:53], v[174:177], v[182:185], v[50:53]
	v_mfma_f32_16x16x32_bf16 v[38:41], v[160:163], v[190:193], v[38:41]
	v_mfma_f32_16x16x32_bf16 v[34:37], v[174:177], v[190:193], v[34:37]
	v_mfma_f32_16x16x32_bf16 v[22:25], v[160:163], v[210:213], v[22:25]
	v_mfma_f32_16x16x32_bf16 v[18:21], v[174:177], v[210:213], v[18:21]
	v_mfma_f32_16x16x32_bf16 v[6:9], v[160:163], v[218:221], v[6:9]
	v_mfma_f32_16x16x32_bf16 v[2:5], v[174:177], v[218:221], v[2:5]
	v_mfma_f32_16x16x32_bf16 v[54:57], v[164:167], v[186:189], v[54:57]
	v_mfma_f32_16x16x32_bf16 v[50:53], v[178:181], v[186:189], v[50:53]
	v_mfma_f32_16x16x32_bf16 v[38:41], v[164:167], v[198:201], v[38:41]
	v_mfma_f32_16x16x32_bf16 v[34:37], v[178:181], v[198:201], v[34:37]
	v_mfma_f32_16x16x32_bf16 v[22:25], v[164:167], v[214:217], v[22:25]
	v_mfma_f32_16x16x32_bf16 v[18:21], v[178:181], v[214:217], v[18:21]
	v_mfma_f32_16x16x32_bf16 v[6:9], v[164:167], v[222:225], v[6:9]
	v_mfma_f32_16x16x32_bf16 v[2:5], v[178:181], v[222:225], v[2:5]
	s_setprio 0
	s_barrier
	s_add_i32 s21, 0, 0x18000
	s_add_i32 s40, 0, 0x1c000
	v_add_u32_e32 v142, s21, v168
	v_add_u32_e32 v173, s40, v168
	ds_read_b128 v[130:133], v142
	ds_read_b128 v[134:137], v142 offset:1024
	ds_read_b128 v[138:141], v142 offset:2048
	ds_read_b128 v[142:145], v142 offset:3072
	ds_read_b128 v[160:163], v173
	ds_read_b128 v[164:167], v173 offset:1024
	ds_read_b128 v[174:177], v173 offset:2048
	ds_read_b128 v[178:181], v173 offset:3072
	s_add_u32 s38, s38, 0x80000
	s_addc_u32 s39, s39, 0
	s_mov_b32 m0, s42
	v_lshl_add_u64 v[230:231], s[38:39], 0, v[146:147]
	ds_read_b128 v[182:185], v172 offset:32768
	ds_read_b128 v[186:189], v172 offset:33792
	ds_read_b128 v[190:193], v172 offset:34816
	ds_read_b128 v[198:201], v172 offset:35840
	ds_read_b128 v[210:213], v172 offset:36864
	ds_read_b128 v[214:217], v172 offset:37888
	ds_read_b128 v[218:221], v172 offset:38912
	ds_read_b128 v[222:225], v172 offset:39936
	global_load_lds_dwordx4 v[230:231], off
	v_lshl_add_u64 v[230:231], s[38:39], 0, v[150:151]
	s_mov_b32 m0, s43
	s_nop 0
	global_load_lds_dwordx4 v[230:231], off
	s_waitcnt vmcnt(8)
	s_waitcnt lgkmcnt(0)
	s_barrier
	s_setprio 1
	v_mfma_f32_16x16x32_bf16 v[126:129], v[130:133], v[182:185], v[126:129]
	v_mfma_f32_16x16x32_bf16 v[122:125], v[138:141], v[182:185], v[122:125]
	v_mfma_f32_16x16x32_bf16 v[118:121], v[130:133], v[190:193], v[118:121]
	v_mfma_f32_16x16x32_bf16 v[110:113], v[138:141], v[190:193], v[110:113]
	v_mfma_f32_16x16x32_bf16 v[94:97], v[130:133], v[210:213], v[94:97]
	v_mfma_f32_16x16x32_bf16 v[90:93], v[138:141], v[210:213], v[90:93]
	v_mfma_f32_16x16x32_bf16 v[78:81], v[130:133], v[218:221], v[78:81]
	v_mfma_f32_16x16x32_bf16 v[74:77], v[138:141], v[218:221], v[74:77]
	v_mfma_f32_16x16x32_bf16 v[126:129], v[134:137], v[186:189], v[126:129]
	v_mfma_f32_16x16x32_bf16 v[122:125], v[142:145], v[186:189], v[122:125]
	v_mfma_f32_16x16x32_bf16 v[118:121], v[134:137], v[198:201], v[118:121]
	v_mfma_f32_16x16x32_bf16 v[110:113], v[142:145], v[198:201], v[110:113]
	v_mfma_f32_16x16x32_bf16 v[94:97], v[134:137], v[214:217], v[94:97]
	v_mfma_f32_16x16x32_bf16 v[90:93], v[142:145], v[214:217], v[90:93]
	v_mfma_f32_16x16x32_bf16 v[78:81], v[134:137], v[222:225], v[78:81]
	v_mfma_f32_16x16x32_bf16 v[74:77], v[142:145], v[222:225], v[74:77]
	s_setprio 0
	s_setprio 1
	v_mfma_f32_16x16x32_bf16 v[114:117], v[160:163], v[182:185], v[114:117]
	v_mfma_f32_16x16x32_bf16 v[106:109], v[174:177], v[182:185], v[106:109]
	v_mfma_f32_16x16x32_bf16 v[102:105], v[160:163], v[190:193], v[102:105]
	v_mfma_f32_16x16x32_bf16 v[98:101], v[174:177], v[190:193], v[98:101]
	v_mfma_f32_16x16x32_bf16 v[86:89], v[160:163], v[210:213], v[86:89]
	v_mfma_f32_16x16x32_bf16 v[82:85], v[174:177], v[210:213], v[82:85]
	v_mfma_f32_16x16x32_bf16 v[70:73], v[160:163], v[218:221], v[70:73]
	v_mfma_f32_16x16x32_bf16 v[66:69], v[174:177], v[218:221], v[66:69]
	v_mfma_f32_16x16x32_bf16 v[114:117], v[164:167], v[186:189], v[114:117]
	v_mfma_f32_16x16x32_bf16 v[106:109], v[178:181], v[186:189], v[106:109]
	v_mfma_f32_16x16x32_bf16 v[102:105], v[164:167], v[198:201], v[102:105]
	v_mfma_f32_16x16x32_bf16 v[98:101], v[178:181], v[198:201], v[98:101]
	v_mfma_f32_16x16x32_bf16 v[86:89], v[164:167], v[214:217], v[86:89]
	v_mfma_f32_16x16x32_bf16 v[82:85], v[178:181], v[214:217], v[82:85]
	v_mfma_f32_16x16x32_bf16 v[70:73], v[164:167], v[222:225], v[70:73]
	v_mfma_f32_16x16x32_bf16 v[66:69], v[178:181], v[222:225], v[66:69]
	s_setprio 0
	s_barrier
	s_add_i32 s21, s21, s33
	v_lshl_add_u64 v[202:203], v[202:203], 0, s[12:13]
	s_mov_b32 m0, s21
	ds_read_b128 v[182:185], v172 offset:49152
	ds_read_b128 v[186:189], v172 offset:50176
	ds_read_b128 v[190:193], v172 offset:51200
	ds_read_b128 v[198:201], v172 offset:52224
	ds_read_b128 v[210:213], v172 offset:53248
	ds_read_b128 v[214:217], v172 offset:54272
	ds_read_b128 v[218:221], v172 offset:55296
	ds_read_b128 v[222:225], v172 offset:56320
	global_load_lds_dwordx4 v[202:203], off
	s_add_i32 m0, s21, 0x2000
	s_add_u32 s36, s36, 0x80080
	v_lshl_add_u64 v[202:203], v[206:207], 0, s[12:13]
	s_addc_u32 s37, s37, 0
	s_add_i32 s21, s40, s33
	global_load_lds_dwordx4 v[202:203], off
	v_lshl_add_u64 v[202:203], s[36:37], 0, v[148:149]
	s_mov_b32 m0, s21
	s_nop 0
	global_load_lds_dwordx4 v[202:203], off
	v_lshl_add_u64 v[202:203], s[36:37], 0, v[152:153]
	s_add_i32 m0, s21, 0x2000
	s_nop 0
	global_load_lds_dwordx4 v[202:203], off
	v_lshl_add_u64 v[202:203], v[226:227], 0, s[12:13]
	s_mov_b32 m0, s53
	s_nop 0
	global_load_lds_dwordx4 v[202:203], off
	v_lshl_add_u64 v[202:203], v[228:229], 0, s[12:13]
	s_mov_b32 m0, s54
	s_nop 0
	global_load_lds_dwordx4 v[202:203], off
	s_waitcnt vmcnt(8)
	s_waitcnt lgkmcnt(0)
	s_barrier
	s_setprio 1
	v_mfma_f32_16x16x32_bf16 v[62:65], v[130:133], v[182:185], v[62:65]
	v_mfma_f32_16x16x32_bf16 v[58:61], v[138:141], v[182:185], v[58:61]
	v_mfma_f32_16x16x32_bf16 v[46:49], v[130:133], v[190:193], v[46:49]
	v_mfma_f32_16x16x32_bf16 v[42:45], v[138:141], v[190:193], v[42:45]
	v_mfma_f32_16x16x32_bf16 v[30:33], v[130:133], v[210:213], v[30:33]
	v_mfma_f32_16x16x32_bf16 v[26:29], v[138:141], v[210:213], v[26:29]
	v_mfma_f32_16x16x32_bf16 v[14:17], v[130:133], v[218:221], v[14:17]
	v_mfma_f32_16x16x32_bf16 v[10:13], v[138:141], v[218:221], v[10:13]
	v_mfma_f32_16x16x32_bf16 v[62:65], v[134:137], v[186:189], v[62:65]
	v_mfma_f32_16x16x32_bf16 v[58:61], v[142:145], v[186:189], v[58:61]
	v_mfma_f32_16x16x32_bf16 v[46:49], v[134:137], v[198:201], v[46:49]
	v_mfma_f32_16x16x32_bf16 v[42:45], v[142:145], v[198:201], v[42:45]
	v_mfma_f32_16x16x32_bf16 v[30:33], v[134:137], v[214:217], v[30:33]
	v_mfma_f32_16x16x32_bf16 v[26:29], v[142:145], v[214:217], v[26:29]
	v_mfma_f32_16x16x32_bf16 v[14:17], v[134:137], v[222:225], v[14:17]
	v_mfma_f32_16x16x32_bf16 v[10:13], v[142:145], v[222:225], v[10:13]
	s_setprio 0
	s_setprio 1
	v_mfma_f32_16x16x32_bf16 v[54:57], v[160:163], v[182:185], v[54:57]
	v_mfma_f32_16x16x32_bf16 v[50:53], v[174:177], v[182:185], v[50:53]
	v_mfma_f32_16x16x32_bf16 v[38:41], v[160:163], v[190:193], v[38:41]
	v_mfma_f32_16x16x32_bf16 v[34:37], v[174:177], v[190:193], v[34:37]
	v_mfma_f32_16x16x32_bf16 v[22:25], v[160:163], v[210:213], v[22:25]
	v_mfma_f32_16x16x32_bf16 v[18:21], v[174:177], v[210:213], v[18:21]
	v_mfma_f32_16x16x32_bf16 v[6:9], v[160:163], v[218:221], v[6:9]
	v_mfma_f32_16x16x32_bf16 v[2:5], v[174:177], v[218:221], v[2:5]
	v_mfma_f32_16x16x32_bf16 v[54:57], v[164:167], v[186:189], v[54:57]
	v_mfma_f32_16x16x32_bf16 v[50:53], v[178:181], v[186:189], v[50:53]
	v_mfma_f32_16x16x32_bf16 v[38:41], v[164:167], v[198:201], v[38:41]
	v_mfma_f32_16x16x32_bf16 v[34:37], v[178:181], v[198:201], v[34:37]
	v_mfma_f32_16x16x32_bf16 v[22:25], v[164:167], v[214:217], v[22:25]
	v_mfma_f32_16x16x32_bf16 v[18:21], v[178:181], v[214:217], v[18:21]
	v_mfma_f32_16x16x32_bf16 v[6:9], v[164:167], v[222:225], v[6:9]
	v_mfma_f32_16x16x32_bf16 v[2:5], v[178:181], v[222:225], v[2:5]
	s_setprio 0
	s_barrier
	s_add_u32 s34, s34, 0x100
	s_addc_u32 s35, s35, 0
	s_add_u32 s17, s17, 0x100
	s_addc_u32 s19, s19, 0
	s_cmp_ge_i32 s31, s69
	s_mov_b32 s21, s31
	s_cbranch_scc0 .LBB0_1122

.Lpeel_7:
	ds_read_b128 v[152:155], v148
	ds_read_b128 v[156:159], v148 offset:1024
	s_add_i32 s29, s19, 2
	s_add_u32 s34, s30, 0xfff80080
	s_addc_u32 s35, s31, -1
	s_cmp_eq_u32 s28, s19
	s_cselect_b32 s37, s21, s35
	s_cselect_b32 s36, s20, s34
	s_cselect_b32 s35, s23, s17
	s_cselect_b32 s34, s22, s15
	v_lshl_add_u64 v[144:145], s[30:31], 0, v[140:141]
	s_add_i32 m0, s27, 0xc000
	global_load_lds_dwordx4 v[144:145], off
	v_lshl_add_u64 v[144:145], s[30:31], 0, v[142:143]
	s_add_i32 m0, s27, 0xe000
	s_nop 0
	global_load_lds_dwordx4 v[144:145], off
	s_waitcnt vmcnt(8)
	s_waitcnt lgkmcnt(0)
	s_barrier
	s_setprio 1
	v_mfma_f32_16x16x32_bf16 v[126:129], v[152:155], v[184:187], 0
	v_mfma_f32_16x16x32_bf16 v[122:125], v[160:163], v[184:187], 0
	v_mfma_f32_16x16x32_bf16 v[110:113], v[152:155], v[198:201], 0
	v_mfma_f32_16x16x32_bf16 v[106:109], v[160:163], v[198:201], 0
	v_mfma_f32_16x16x32_bf16 v[94:97], v[152:155], v[214:217], 0
	v_mfma_f32_16x16x32_bf16 v[90:93], v[160:163], v[214:217], 0
	v_mfma_f32_16x16x32_bf16 v[78:81], v[152:155], v[222:225], 0
	v_mfma_f32_16x16x32_bf16 v[74:77], v[160:163], v[222:225], 0
	v_mfma_f32_16x16x32_bf16 v[126:129], v[156:159], v[188:191], v[126:129]
	v_mfma_f32_16x16x32_bf16 v[122:125], v[164:167], v[188:191], v[122:125]
	v_mfma_f32_16x16x32_bf16 v[110:113], v[156:159], v[210:213], v[110:113]
	v_mfma_f32_16x16x32_bf16 v[106:109], v[164:167], v[210:213], v[106:109]
	v_mfma_f32_16x16x32_bf16 v[94:97], v[156:159], v[218:221], v[94:97]
	v_mfma_f32_16x16x32_bf16 v[90:93], v[164:167], v[218:221], v[90:93]
	v_mfma_f32_16x16x32_bf16 v[78:81], v[156:159], v[226:229], v[78:81]
	v_mfma_f32_16x16x32_bf16 v[74:77], v[164:167], v[226:229], v[74:77]
	s_setprio 0
	s_setprio 1
	v_mfma_f32_16x16x32_bf16 v[118:121], v[168:171], v[184:187], 0
	v_mfma_f32_16x16x32_bf16 v[114:117], v[176:179], v[184:187], 0
	v_mfma_f32_16x16x32_bf16 v[102:105], v[168:171], v[198:201], 0
	v_mfma_f32_16x16x32_bf16 v[98:101], v[176:179], v[198:201], 0
	v_mfma_f32_16x16x32_bf16 v[86:89], v[168:171], v[214:217], 0
	v_mfma_f32_16x16x32_bf16 v[82:85], v[176:179], v[214:217], 0
	v_mfma_f32_16x16x32_bf16 v[70:73], v[168:171], v[222:225], 0
	v_mfma_f32_16x16x32_bf16 v[66:69], v[176:179], v[222:225], 0
	v_mfma_f32_16x16x32_bf16 v[118:121], v[172:175], v[188:191], v[118:121]
	v_mfma_f32_16x16x32_bf16 v[114:117], v[180:183], v[188:191], v[114:117]
	v_mfma_f32_16x16x32_bf16 v[102:105], v[172:175], v[210:213], v[102:105]
	v_mfma_f32_16x16x32_bf16 v[98:101], v[180:183], v[210:213], v[98:101]
	v_mfma_f32_16x16x32_bf16 v[86:89], v[172:175], v[218:221], v[86:89]
	v_mfma_f32_16x16x32_bf16 v[82:85], v[180:183], v[218:221], v[82:85]
	v_mfma_f32_16x16x32_bf16 v[70:73], v[172:175], v[226:229], v[70:73]
	v_mfma_f32_16x16x32_bf16 v[66:69], v[180:183], v[226:229], v[66:69]
	s_setprio 0
	s_barrier
	s_add_i32 s19, s60, s33
	v_lshl_add_u64 v[144:145], s[34:35], 0, v[132:133]
	s_mov_b32 m0, s19
	ds_read_b128 v[184:187], v150 offset:16384
	ds_read_b128 v[188:191], v150 offset:17408
	ds_read_b128 v[198:201], v150 offset:18432
	ds_read_b128 v[210:213], v150 offset:19456
	ds_read_b128 v[214:217], v150 offset:20480
	ds_read_b128 v[218:221], v150 offset:21504
	ds_read_b128 v[222:225], v150 offset:22528
	ds_read_b128 v[226:229], v150 offset:23552
	global_load_lds_dwordx4 v[144:145], off
	s_add_i32 m0, s19, 0x2000
	s_add_u32 s38, s34, 0x80000
	v_lshl_add_u64 v[192:193], s[34:35], 0, v[136:137]
	s_addc_u32 s39, s35, 0
	s_add_i32 s19, s61, s33
	global_load_lds_dwordx4 v[192:193], off
	v_lshl_add_u64 v[202:203], s[38:39], 0, v[132:133]
	s_mov_b32 m0, s19
	v_lshl_add_u64 v[206:207], s[36:37], 0, v[134:135]
	global_load_lds_dwordx4 v[202:203], off
	v_lshl_add_u64 v[202:203], s[38:39], 0, v[136:137]
	s_add_i32 m0, s19, 0x2000
	s_nop 0
	global_load_lds_dwordx4 v[202:203], off
	v_lshl_add_u64 v[202:203], s[36:37], 0, v[130:131]
	s_mov_b32 m0, s27
	s_nop 0
	global_load_lds_dwordx4 v[202:203], off
	s_mov_b32 m0, s41
	s_nop 0
	global_load_lds_dwordx4 v[206:207], off
	s_waitcnt vmcnt(8)
	s_waitcnt lgkmcnt(0)
	s_barrier
	s_setprio 1
	v_mfma_f32_16x16x32_bf16 v[62:65], v[152:155], v[184:187], 0
	v_mfma_f32_16x16x32_bf16 v[58:61], v[160:163], v[184:187], 0
	v_mfma_f32_16x16x32_bf16 v[46:49], v[152:155], v[198:201], 0
	v_mfma_f32_16x16x32_bf16 v[42:45], v[160:163], v[198:201], 0
	v_mfma_f32_16x16x32_bf16 v[30:33], v[152:155], v[214:217], 0
	v_mfma_f32_16x16x32_bf16 v[26:29], v[160:163], v[214:217], 0
	v_mfma_f32_16x16x32_bf16 v[14:17], v[152:155], v[222:225], 0
	v_mfma_f32_16x16x32_bf16 v[10:13], v[160:163], v[222:225], 0
	v_mfma_f32_16x16x32_bf16 v[62:65], v[156:159], v[188:191], v[62:65]
	v_mfma_f32_16x16x32_bf16 v[58:61], v[164:167], v[188:191], v[58:61]
	v_mfma_f32_16x16x32_bf16 v[46:49], v[156:159], v[210:213], v[46:49]
	v_mfma_f32_16x16x32_bf16 v[42:45], v[164:167], v[210:213], v[42:45]
	v_mfma_f32_16x16x32_bf16 v[30:33], v[156:159], v[218:221], v[30:33]
	v_mfma_f32_16x16x32_bf16 v[26:29], v[164:167], v[218:221], v[26:29]
	v_mfma_f32_16x16x32_bf16 v[14:17], v[156:159], v[226:229], v[14:17]
	v_mfma_f32_16x16x32_bf16 v[10:13], v[164:167], v[226:229], v[10:13]
	s_setprio 0
	s_setprio 1
	v_mfma_f32_16x16x32_bf16 v[54:57], v[168:171], v[184:187], 0
	v_mfma_f32_16x16x32_bf16 v[50:53], v[176:179], v[184:187], 0
	v_mfma_f32_16x16x32_bf16 v[38:41], v[168:171], v[198:201], 0
	v_mfma_f32_16x16x32_bf16 v[34:37], v[176:179], v[198:201], 0
	v_mfma_f32_16x16x32_bf16 v[22:25], v[168:171], v[214:217], 0
	v_mfma_f32_16x16x32_bf16 v[18:21], v[176:179], v[214:217], 0
	v_mfma_f32_16x16x32_bf16 v[6:9], v[168:171], v[222:225], 0
	v_mfma_f32_16x16x32_bf16 v[2:5], v[176:179], v[222:225], 0
	v_mfma_f32_16x16x32_bf16 v[54:57], v[172:175], v[188:191], v[54:57]
	v_mfma_f32_16x16x32_bf16 v[50:53], v[180:183], v[188:191], v[50:53]
	v_mfma_f32_16x16x32_bf16 v[38:41], v[172:175], v[210:213], v[38:41]
	v_mfma_f32_16x16x32_bf16 v[34:37], v[180:183], v[210:213], v[34:37]
	v_mfma_f32_16x16x32_bf16 v[22:25], v[172:175], v[218:221], v[22:25]
	v_mfma_f32_16x16x32_bf16 v[18:21], v[180:183], v[218:221], v[18:21]
	v_mfma_f32_16x16x32_bf16 v[6:9], v[172:175], v[226:229], v[6:9]
	v_mfma_f32_16x16x32_bf16 v[2:5], v[180:183], v[226:229], v[2:5]
	s_setprio 0
	s_barrier
	s_add_i32 s19, 0, 0x18000
	v_add_u32_e32 v151, s19, v146
	s_add_i32 s38, 0, 0x1c000
	ds_read_b128 v[152:155], v151
	ds_read_b128 v[156:159], v151 offset:1024
	ds_read_b128 v[160:163], v151 offset:2048
	ds_read_b128 v[164:167], v151 offset:3072
	v_add_u32_e32 v151, s38, v146
	ds_read_b128 v[168:171], v151
	ds_read_b128 v[172:175], v151 offset:1024
	ds_read_b128 v[176:179], v151 offset:2048
	ds_read_b128 v[180:183], v151 offset:3072
	s_add_u32 s36, s36, 0x80000
	s_addc_u32 s37, s37, 0
	s_mov_b32 m0, s42
	v_lshl_add_u64 v[230:231], s[36:37], 0, v[130:131]
	ds_read_b128 v[184:187], v150 offset:32768
	ds_read_b128 v[188:191], v150 offset:33792
	ds_read_b128 v[198:201], v150 offset:34816
	ds_read_b128 v[210:213], v150 offset:35840
	ds_read_b128 v[214:217], v150 offset:36864
	ds_read_b128 v[218:221], v150 offset:37888
	ds_read_b128 v[222:225], v150 offset:38912
	ds_read_b128 v[226:229], v150 offset:39936
	global_load_lds_dwordx4 v[230:231], off
	v_lshl_add_u64 v[230:231], s[36:37], 0, v[134:135]
	s_mov_b32 m0, s43
	s_nop 0
	global_load_lds_dwordx4 v[230:231], off
	s_waitcnt vmcnt(8)
	s_waitcnt lgkmcnt(0)
	s_barrier
	s_setprio 1
	v_mfma_f32_16x16x32_bf16 v[126:129], v[152:155], v[184:187], v[126:129]
	v_mfma_f32_16x16x32_bf16 v[122:125], v[160:163], v[184:187], v[122:125]
	v_mfma_f32_16x16x32_bf16 v[110:113], v[152:155], v[198:201], v[110:113]
	v_mfma_f32_16x16x32_bf16 v[106:109], v[160:163], v[198:201], v[106:109]
	v_mfma_f32_16x16x32_bf16 v[94:97], v[152:155], v[214:217], v[94:97]
	v_mfma_f32_16x16x32_bf16 v[90:93], v[160:163], v[214:217], v[90:93]
	v_mfma_f32_16x16x32_bf16 v[78:81], v[152:155], v[222:225], v[78:81]
	v_mfma_f32_16x16x32_bf16 v[74:77], v[160:163], v[222:225], v[74:77]
	v_mfma_f32_16x16x32_bf16 v[126:129], v[156:159], v[188:191], v[126:129]
	v_mfma_f32_16x16x32_bf16 v[122:125], v[164:167], v[188:191], v[122:125]
	v_mfma_f32_16x16x32_bf16 v[110:113], v[156:159], v[210:213], v[110:113]
	v_mfma_f32_16x16x32_bf16 v[106:109], v[164:167], v[210:213], v[106:109]
	v_mfma_f32_16x16x32_bf16 v[94:97], v[156:159], v[218:221], v[94:97]
	v_mfma_f32_16x16x32_bf16 v[90:93], v[164:167], v[218:221], v[90:93]
	v_mfma_f32_16x16x32_bf16 v[78:81], v[156:159], v[226:229], v[78:81]
	v_mfma_f32_16x16x32_bf16 v[74:77], v[164:167], v[226:229], v[74:77]
	s_setprio 0
	s_setprio 1
	v_mfma_f32_16x16x32_bf16 v[118:121], v[168:171], v[184:187], v[118:121]
	v_mfma_f32_16x16x32_bf16 v[114:117], v[176:179], v[184:187], v[114:117]
	v_mfma_f32_16x16x32_bf16 v[102:105], v[168:171], v[198:201], v[102:105]
	v_mfma_f32_16x16x32_bf16 v[98:101], v[176:179], v[198:201], v[98:101]
	v_mfma_f32_16x16x32_bf16 v[86:89], v[168:171], v[214:217], v[86:89]
	v_mfma_f32_16x16x32_bf16 v[82:85], v[176:179], v[214:217], v[82:85]
	v_mfma_f32_16x16x32_bf16 v[70:73], v[168:171], v[222:225], v[70:73]
	v_mfma_f32_16x16x32_bf16 v[66:69], v[176:179], v[222:225], v[66:69]
	v_mfma_f32_16x16x32_bf16 v[118:121], v[172:175], v[188:191], v[118:121]
	v_mfma_f32_16x16x32_bf16 v[114:117], v[180:183], v[188:191], v[114:117]
	v_mfma_f32_16x16x32_bf16 v[102:105], v[172:175], v[210:213], v[102:105]
	v_mfma_f32_16x16x32_bf16 v[98:101], v[180:183], v[210:213], v[98:101]
	v_mfma_f32_16x16x32_bf16 v[86:89], v[172:175], v[218:221], v[86:89]
	v_mfma_f32_16x16x32_bf16 v[82:85], v[180:183], v[218:221], v[82:85]
	v_mfma_f32_16x16x32_bf16 v[70:73], v[172:175], v[226:229], v[70:73]
	v_mfma_f32_16x16x32_bf16 v[66:69], v[180:183], v[226:229], v[66:69]
	s_setprio 0
	s_barrier
	s_add_i32 s19, s19, s33
	v_lshl_add_u64 v[144:145], v[144:145], 0, s[10:11]
	s_mov_b32 m0, s19
	ds_read_b128 v[184:187], v150 offset:49152
	ds_read_b128 v[188:191], v150 offset:50176
	ds_read_b128 v[198:201], v150 offset:51200
	ds_read_b128 v[210:213], v150 offset:52224
	ds_read_b128 v[214:217], v150 offset:53248
	ds_read_b128 v[218:221], v150 offset:54272
	ds_read_b128 v[222:225], v150 offset:55296
	ds_read_b128 v[226:229], v150 offset:56320
	global_load_lds_dwordx4 v[144:145], off
	s_add_i32 m0, s19, 0x2000
	s_add_u32 s34, s34, 0x80080
	v_lshl_add_u64 v[144:145], v[192:193], 0, s[10:11]
	s_addc_u32 s35, s35, 0
	s_add_i32 s19, s38, s33
	global_load_lds_dwordx4 v[144:145], off
	v_lshl_add_u64 v[144:145], s[34:35], 0, v[132:133]
	s_mov_b32 m0, s19
	s_nop 0
	global_load_lds_dwordx4 v[144:145], off
	v_lshl_add_u64 v[144:145], s[34:35], 0, v[136:137]
	s_add_i32 m0, s19, 0x2000
	s_nop 0
	global_load_lds_dwordx4 v[144:145], off
	v_lshl_add_u64 v[144:145], v[202:203], 0, s[10:11]
	s_mov_b32 m0, s51
	s_nop 0
	global_load_lds_dwordx4 v[144:145], off
	v_lshl_add_u64 v[144:145], v[206:207], 0, s[10:11]
	s_mov_b32 m0, s52
	s_nop 0
	global_load_lds_dwordx4 v[144:145], off
	s_waitcnt vmcnt(8)
	s_waitcnt lgkmcnt(0)
	s_barrier
	s_setprio 1
	v_mfma_f32_16x16x32_bf16 v[62:65], v[152:155], v[184:187], v[62:65]
	v_mfma_f32_16x16x32_bf16 v[58:61], v[160:163], v[184:187], v[58:61]
	v_mfma_f32_16x16x32_bf16 v[46:49], v[152:155], v[198:201], v[46:49]
	v_mfma_f32_16x16x32_bf16 v[42:45], v[160:163], v[198:201], v[42:45]
	v_mfma_f32_16x16x32_bf16 v[30:33], v[152:155], v[214:217], v[30:33]
	v_mfma_f32_16x16x32_bf16 v[26:29], v[160:163], v[214:217], v[26:29]
	v_mfma_f32_16x16x32_bf16 v[14:17], v[152:155], v[222:225], v[14:17]
	v_mfma_f32_16x16x32_bf16 v[10:13], v[160:163], v[222:225], v[10:13]
	v_mfma_f32_16x16x32_bf16 v[62:65], v[156:159], v[188:191], v[62:65]
	v_mfma_f32_16x16x32_bf16 v[58:61], v[164:167], v[188:191], v[58:61]
	v_mfma_f32_16x16x32_bf16 v[46:49], v[156:159], v[210:213], v[46:49]
	v_mfma_f32_16x16x32_bf16 v[42:45], v[164:167], v[210:213], v[42:45]
	v_mfma_f32_16x16x32_bf16 v[30:33], v[156:159], v[218:221], v[30:33]
	v_mfma_f32_16x16x32_bf16 v[26:29], v[164:167], v[218:221], v[26:29]
	v_mfma_f32_16x16x32_bf16 v[14:17], v[156:159], v[226:229], v[14:17]
	v_mfma_f32_16x16x32_bf16 v[10:13], v[164:167], v[226:229], v[10:13]
	s_setprio 0
	s_setprio 1
	v_mfma_f32_16x16x32_bf16 v[54:57], v[168:171], v[184:187], v[54:57]
	v_mfma_f32_16x16x32_bf16 v[50:53], v[176:179], v[184:187], v[50:53]
	v_mfma_f32_16x16x32_bf16 v[38:41], v[168:171], v[198:201], v[38:41]
	v_mfma_f32_16x16x32_bf16 v[34:37], v[176:179], v[198:201], v[34:37]
	v_mfma_f32_16x16x32_bf16 v[22:25], v[168:171], v[214:217], v[22:25]
	v_mfma_f32_16x16x32_bf16 v[18:21], v[176:179], v[214:217], v[18:21]
	v_mfma_f32_16x16x32_bf16 v[6:9], v[168:171], v[222:225], v[6:9]
	v_mfma_f32_16x16x32_bf16 v[2:5], v[176:179], v[222:225], v[2:5]
	v_mfma_f32_16x16x32_bf16 v[54:57], v[172:175], v[188:191], v[54:57]
	v_mfma_f32_16x16x32_bf16 v[50:53], v[180:183], v[188:191], v[50:53]
	v_mfma_f32_16x16x32_bf16 v[38:41], v[172:175], v[210:213], v[38:41]
	v_mfma_f32_16x16x32_bf16 v[34:37], v[180:183], v[210:213], v[34:37]
	v_mfma_f32_16x16x32_bf16 v[22:25], v[172:175], v[218:221], v[22:25]
	v_mfma_f32_16x16x32_bf16 v[18:21], v[180:183], v[218:221], v[18:21]
	v_mfma_f32_16x16x32_bf16 v[6:9], v[172:175], v[226:229], v[6:9]
	v_mfma_f32_16x16x32_bf16 v[2:5], v[180:183], v[226:229], v[2:5]
	s_setprio 0
	s_barrier
	s_add_u32 s30, s30, 0x100
	s_addc_u32 s31, s31, 0
	s_add_u32 s15, s15, 0x100
	s_addc_u32 s17, s17, 0
	s_cmp_ge_i32 s29, s68
	s_mov_b32 s19, s29
	s_cbranch_scc0 .LBB0_1315
	s_branch .Lpeeldone_7
.LBB0_1315:
	ds_read_b128 v[152:155], v148
	ds_read_b128 v[156:159], v148 offset:1024
	ds_read_b128 v[160:163], v148 offset:2048
	ds_read_b128 v[164:167], v148 offset:3072
	ds_read_b128 v[168:171], v149
	ds_read_b128 v[172:175], v149 offset:1024
	ds_read_b128 v[176:179], v149 offset:2048
	ds_read_b128 v[180:183], v149 offset:3072
	s_add_i32 s29, s19, 2
	s_add_u32 s34, s30, 0xfff80080
	s_addc_u32 s35, s31, -1
	s_cmp_eq_u32 s28, s19
	s_cselect_b32 s37, s21, s35
	s_cselect_b32 s36, s20, s34
	s_cselect_b32 s35, s23, s17
	s_cselect_b32 s34, s22, s15
	v_lshl_add_u64 v[144:145], s[30:31], 0, v[140:141]
	s_add_i32 m0, s27, 0xc000
	ds_read_b128 v[184:187], v150
	ds_read_b128 v[188:191], v150 offset:1024
	ds_read_b128 v[198:201], v150 offset:2048
	ds_read_b128 v[210:213], v150 offset:3072
	ds_read_b128 v[214:217], v150 offset:4096
	ds_read_b128 v[218:221], v150 offset:5120
	ds_read_b128 v[222:225], v150 offset:6144
	ds_read_b128 v[226:229], v150 offset:7168
	global_load_lds_dwordx4 v[144:145], off
	v_lshl_add_u64 v[144:145], s[30:31], 0, v[142:143]
	s_add_i32 m0, s27, 0xe000
	s_nop 0
	global_load_lds_dwordx4 v[144:145], off
	s_waitcnt vmcnt(8)
	s_waitcnt lgkmcnt(0)
	s_barrier
	s_setprio 1
	v_mfma_f32_16x16x32_bf16 v[126:129], v[152:155], v[184:187], v[126:129]
	v_mfma_f32_16x16x32_bf16 v[122:125], v[160:163], v[184:187], v[122:125]
	v_mfma_f32_16x16x32_bf16 v[110:113], v[152:155], v[198:201], v[110:113]
	v_mfma_f32_16x16x32_bf16 v[106:109], v[160:163], v[198:201], v[106:109]
	v_mfma_f32_16x16x32_bf16 v[94:97], v[152:155], v[214:217], v[94:97]
	v_mfma_f32_16x16x32_bf16 v[90:93], v[160:163], v[214:217], v[90:93]
	v_mfma_f32_16x16x32_bf16 v[78:81], v[152:155], v[222:225], v[78:81]
	v_mfma_f32_16x16x32_bf16 v[74:77], v[160:163], v[222:225], v[74:77]
	v_mfma_f32_16x16x32_bf16 v[126:129], v[156:159], v[188:191], v[126:129]
	v_mfma_f32_16x16x32_bf16 v[122:125], v[164:167], v[188:191], v[122:125]
	v_mfma_f32_16x16x32_bf16 v[110:113], v[156:159], v[210:213], v[110:113]
	v_mfma_f32_16x16x32_bf16 v[106:109], v[164:167], v[210:213], v[106:109]
	v_mfma_f32_16x16x32_bf16 v[94:97], v[156:159], v[218:221], v[94:97]
	v_mfma_f32_16x16x32_bf16 v[90:93], v[164:167], v[218:221], v[90:93]
	v_mfma_f32_16x16x32_bf16 v[78:81], v[156:159], v[226:229], v[78:81]
	v_mfma_f32_16x16x32_bf16 v[74:77], v[164:167], v[226:229], v[74:77]
	s_setprio 0
	s_setprio 1
	v_mfma_f32_16x16x32_bf16 v[118:121], v[168:171], v[184:187], v[118:121]
	v_mfma_f32_16x16x32_bf16 v[114:117], v[176:179], v[184:187], v[114:117]
	v_mfma_f32_16x16x32_bf16 v[102:105], v[168:171], v[198:201], v[102:105]
	v_mfma_f32_16x16x32_bf16 v[98:101], v[176:179], v[198:201], v[98:101]
	v_mfma_f32_16x16x32_bf16 v[86:89], v[168:171], v[214:217], v[86:89]
	v_mfma_f32_16x16x32_bf16 v[82:85], v[176:179], v[214:217], v[82:85]
	v_mfma_f32_16x16x32_bf16 v[70:73], v[168:171], v[222:225], v[70:73]
	v_mfma_f32_16x16x32_bf16 v[66:69], v[176:179], v[222:225], v[66:69]
	v_mfma_f32_16x16x32_bf16 v[118:121], v[172:175], v[188:191], v[118:121]
	v_mfma_f32_16x16x32_bf16 v[114:117], v[180:183], v[188:191], v[114:117]
	v_mfma_f32_16x16x32_bf16 v[102:105], v[172:175], v[210:213], v[102:105]
	v_mfma_f32_16x16x32_bf16 v[98:101], v[180:183], v[210:213], v[98:101]
	v_mfma_f32_16x16x32_bf16 v[86:89], v[172:175], v[218:221], v[86:89]
	v_mfma_f32_16x16x32_bf16 v[82:85], v[180:183], v[218:221], v[82:85]
	v_mfma_f32_16x16x32_bf16 v[70:73], v[172:175], v[226:229], v[70:73]
	v_mfma_f32_16x16x32_bf16 v[66:69], v[180:183], v[226:229], v[66:69]
	s_setprio 0
	s_barrier
	s_add_i32 s19, s60, s33
	v_lshl_add_u64 v[144:145], s[34:35], 0, v[132:133]
	s_mov_b32 m0, s19
	ds_read_b128 v[184:187], v150 offset:16384
	ds_read_b128 v[188:191], v150 offset:17408
	ds_read_b128 v[198:201], v150 offset:18432
	ds_read_b128 v[210:213], v150 offset:19456
	ds_read_b128 v[214:217], v150 offset:20480
	ds_read_b128 v[218:221], v150 offset:21504
	ds_read_b128 v[222:225], v150 offset:22528
	ds_read_b128 v[226:229], v150 offset:23552
	global_load_lds_dwordx4 v[144:145], off
	s_add_i32 m0, s19, 0x2000
	s_add_u32 s38, s34, 0x80000
	v_lshl_add_u64 v[192:193], s[34:35], 0, v[136:137]
	s_addc_u32 s39, s35, 0
	s_add_i32 s19, s61, s33
	global_load_lds_dwordx4 v[192:193], off
	v_lshl_add_u64 v[202:203], s[38:39], 0, v[132:133]
	s_mov_b32 m0, s19
	v_lshl_add_u64 v[206:207], s[36:37], 0, v[134:135]
	global_load_lds_dwordx4 v[202:203], off
	v_lshl_add_u64 v[202:203], s[38:39], 0, v[136:137]
	s_add_i32 m0, s19, 0x2000
	s_nop 0
	global_load_lds_dwordx4 v[202:203], off
	v_lshl_add_u64 v[202:203], s[36:37], 0, v[130:131]
	s_mov_b32 m0, s27
	s_nop 0
	global_load_lds_dwordx4 v[202:203], off
	s_mov_b32 m0, s41
	s_nop 0
	global_load_lds_dwordx4 v[206:207], off
	s_waitcnt vmcnt(8)
	s_waitcnt lgkmcnt(0)
	s_barrier
	s_setprio 1
	v_mfma_f32_16x16x32_bf16 v[62:65], v[152:155], v[184:187], v[62:65]
	v_mfma_f32_16x16x32_bf16 v[58:61], v[160:163], v[184:187], v[58:61]
	v_mfma_f32_16x16x32_bf16 v[46:49], v[152:155], v[198:201], v[46:49]
	v_mfma_f32_16x16x32_bf16 v[42:45], v[160:163], v[198:201], v[42:45]
	v_mfma_f32_16x16x32_bf16 v[30:33], v[152:155], v[214:217], v[30:33]
	v_mfma_f32_16x16x32_bf16 v[26:29], v[160:163], v[214:217], v[26:29]
	v_mfma_f32_16x16x32_bf16 v[14:17], v[152:155], v[222:225], v[14:17]
	v_mfma_f32_16x16x32_bf16 v[10:13], v[160:163], v[222:225], v[10:13]
	v_mfma_f32_16x16x32_bf16 v[62:65], v[156:159], v[188:191], v[62:65]
	v_mfma_f32_16x16x32_bf16 v[58:61], v[164:167], v[188:191], v[58:61]
	v_mfma_f32_16x16x32_bf16 v[46:49], v[156:159], v[210:213], v[46:49]
	v_mfma_f32_16x16x32_bf16 v[42:45], v[164:167], v[210:213], v[42:45]
	v_mfma_f32_16x16x32_bf16 v[30:33], v[156:159], v[218:221], v[30:33]
	v_mfma_f32_16x16x32_bf16 v[26:29], v[164:167], v[218:221], v[26:29]
	v_mfma_f32_16x16x32_bf16 v[14:17], v[156:159], v[226:229], v[14:17]
	v_mfma_f32_16x16x32_bf16 v[10:13], v[164:167], v[226:229], v[10:13]
	s_setprio 0
	s_setprio 1
	v_mfma_f32_16x16x32_bf16 v[54:57], v[168:171], v[184:187], v[54:57]
	v_mfma_f32_16x16x32_bf16 v[50:53], v[176:179], v[184:187], v[50:53]
	v_mfma_f32_16x16x32_bf16 v[38:41], v[168:171], v[198:201], v[38:41]
	v_mfma_f32_16x16x32_bf16 v[34:37], v[176:179], v[198:201], v[34:37]
	v_mfma_f32_16x16x32_bf16 v[22:25], v[168:171], v[214:217], v[22:25]
	v_mfma_f32_16x16x32_bf16 v[18:21], v[176:179], v[214:217], v[18:21]
	v_mfma_f32_16x16x32_bf16 v[6:9], v[168:171], v[222:225], v[6:9]
	v_mfma_f32_16x16x32_bf16 v[2:5], v[176:179], v[222:225], v[2:5]
	v_mfma_f32_16x16x32_bf16 v[54:57], v[172:175], v[188:191], v[54:57]
	v_mfma_f32_16x16x32_bf16 v[50:53], v[180:183], v[188:191], v[50:53]
	v_mfma_f32_16x16x32_bf16 v[38:41], v[172:175], v[210:213], v[38:41]
	v_mfma_f32_16x16x32_bf16 v[34:37], v[180:183], v[210:213], v[34:37]
	v_mfma_f32_16x16x32_bf16 v[22:25], v[172:175], v[218:221], v[22:25]
	v_mfma_f32_16x16x32_bf16 v[18:21], v[180:183], v[218:221], v[18:21]
	v_mfma_f32_16x16x32_bf16 v[6:9], v[172:175], v[226:229], v[6:9]
	v_mfma_f32_16x16x32_bf16 v[2:5], v[180:183], v[226:229], v[2:5]
	s_setprio 0
	s_barrier
	s_add_i32 s19, 0, 0x18000
	v_add_u32_e32 v151, s19, v146
	s_add_i32 s38, 0, 0x1c000
	ds_read_b128 v[152:155], v151
	ds_read_b128 v[156:159], v151 offset:1024
	ds_read_b128 v[160:163], v151 offset:2048
	ds_read_b128 v[164:167], v151 offset:3072
	v_add_u32_e32 v151, s38, v146
	ds_read_b128 v[168:171], v151
	ds_read_b128 v[172:175], v151 offset:1024
	ds_read_b128 v[176:179], v151 offset:2048
	ds_read_b128 v[180:183], v151 offset:3072
	s_add_u32 s36, s36, 0x80000
	s_addc_u32 s37, s37, 0
	s_mov_b32 m0, s42
	v_lshl_add_u64 v[230:231], s[36:37], 0, v[130:131]
	ds_read_b128 v[184:187], v150 offset:32768
	ds_read_b128 v[188:191], v150 offset:33792
	ds_read_b128 v[198:201], v150 offset:34816
	ds_read_b128 v[210:213], v150 offset:35840
	ds_read_b128 v[214:217], v150 offset:36864
	ds_read_b128 v[218:221], v150 offset:37888
	ds_read_b128 v[222:225], v150 offset:38912
	ds_read_b128 v[226:229], v150 offset:39936
	global_load_lds_dwordx4 v[230:231], off
	v_lshl_add_u64 v[230:231], s[36:37], 0, v[134:135]
	s_mov_b32 m0, s43
	s_nop 0
	global_load_lds_dwordx4 v[230:231], off
	s_waitcnt vmcnt(8)
	s_waitcnt lgkmcnt(0)
	s_barrier
	s_setprio 1
	v_mfma_f32_16x16x32_bf16 v[126:129], v[152:155], v[184:187], v[126:129]
	v_mfma_f32_16x16x32_bf16 v[122:125], v[160:163], v[184:187], v[122:125]
	v_mfma_f32_16x16x32_bf16 v[110:113], v[152:155], v[198:201], v[110:113]
	v_mfma_f32_16x16x32_bf16 v[106:109], v[160:163], v[198:201], v[106:109]
	v_mfma_f32_16x16x32_bf16 v[94:97], v[152:155], v[214:217], v[94:97]
	v_mfma_f32_16x16x32_bf16 v[90:93], v[160:163], v[214:217], v[90:93]
	v_mfma_f32_16x16x32_bf16 v[78:81], v[152:155], v[222:225], v[78:81]
	v_mfma_f32_16x16x32_bf16 v[74:77], v[160:163], v[222:225], v[74:77]
	v_mfma_f32_16x16x32_bf16 v[126:129], v[156:159], v[188:191], v[126:129]
	v_mfma_f32_16x16x32_bf16 v[122:125], v[164:167], v[188:191], v[122:125]
	v_mfma_f32_16x16x32_bf16 v[110:113], v[156:159], v[210:213], v[110:113]
	v_mfma_f32_16x16x32_bf16 v[106:109], v[164:167], v[210:213], v[106:109]
	v_mfma_f32_16x16x32_bf16 v[94:97], v[156:159], v[218:221], v[94:97]
	v_mfma_f32_16x16x32_bf16 v[90:93], v[164:167], v[218:221], v[90:93]
	v_mfma_f32_16x16x32_bf16 v[78:81], v[156:159], v[226:229], v[78:81]
	v_mfma_f32_16x16x32_bf16 v[74:77], v[164:167], v[226:229], v[74:77]
	s_setprio 0
	s_setprio 1
	v_mfma_f32_16x16x32_bf16 v[118:121], v[168:171], v[184:187], v[118:121]
	v_mfma_f32_16x16x32_bf16 v[114:117], v[176:179], v[184:187], v[114:117]
	v_mfma_f32_16x16x32_bf16 v[102:105], v[168:171], v[198:201], v[102:105]
	v_mfma_f32_16x16x32_bf16 v[98:101], v[176:179], v[198:201], v[98:101]
	v_mfma_f32_16x16x32_bf16 v[86:89], v[168:171], v[214:217], v[86:89]
	v_mfma_f32_16x16x32_bf16 v[82:85], v[176:179], v[214:217], v[82:85]
	v_mfma_f32_16x16x32_bf16 v[70:73], v[168:171], v[222:225], v[70:73]
	v_mfma_f32_16x16x32_bf16 v[66:69], v[176:179], v[222:225], v[66:69]
	v_mfma_f32_16x16x32_bf16 v[118:121], v[172:175], v[188:191], v[118:121]
	v_mfma_f32_16x16x32_bf16 v[114:117], v[180:183], v[188:191], v[114:117]
	v_mfma_f32_16x16x32_bf16 v[102:105], v[172:175], v[210:213], v[102:105]
	v_mfma_f32_16x16x32_bf16 v[98:101], v[180:183], v[210:213], v[98:101]
	v_mfma_f32_16x16x32_bf16 v[86:89], v[172:175], v[218:221], v[86:89]
	v_mfma_f32_16x16x32_bf16 v[82:85], v[180:183], v[218:221], v[82:85]
	v_mfma_f32_16x16x32_bf16 v[70:73], v[172:175], v[226:229], v[70:73]
	v_mfma_f32_16x16x32_bf16 v[66:69], v[180:183], v[226:229], v[66:69]
	s_setprio 0
	s_barrier
	s_add_i32 s19, s19, s33
	v_lshl_add_u64 v[144:145], v[144:145], 0, s[10:11]
	s_mov_b32 m0, s19
	ds_read_b128 v[184:187], v150 offset:49152
	ds_read_b128 v[188:191], v150 offset:50176
	ds_read_b128 v[198:201], v150 offset:51200
	ds_read_b128 v[210:213], v150 offset:52224
	ds_read_b128 v[214:217], v150 offset:53248
	ds_read_b128 v[218:221], v150 offset:54272
	ds_read_b128 v[222:225], v150 offset:55296
	ds_read_b128 v[226:229], v150 offset:56320
	global_load_lds_dwordx4 v[144:145], off
	s_add_i32 m0, s19, 0x2000
	s_add_u32 s34, s34, 0x80080
	v_lshl_add_u64 v[144:145], v[192:193], 0, s[10:11]
	s_addc_u32 s35, s35, 0
	s_add_i32 s19, s38, s33
	global_load_lds_dwordx4 v[144:145], off
	v_lshl_add_u64 v[144:145], s[34:35], 0, v[132:133]
	s_mov_b32 m0, s19
	s_nop 0
	global_load_lds_dwordx4 v[144:145], off
	v_lshl_add_u64 v[144:145], s[34:35], 0, v[136:137]
	s_add_i32 m0, s19, 0x2000
	s_nop 0
	global_load_lds_dwordx4 v[144:145], off
	v_lshl_add_u64 v[144:145], v[202:203], 0, s[10:11]
	s_mov_b32 m0, s51
	s_nop 0
	global_load_lds_dwordx4 v[144:145], off
	v_lshl_add_u64 v[144:145], v[206:207], 0, s[10:11]
	s_mov_b32 m0, s52
	s_nop 0
	global_load_lds_dwordx4 v[144:145], off
	s_waitcnt vmcnt(8)
	s_waitcnt lgkmcnt(0)
	s_barrier
	s_setprio 1
	v_mfma_f32_16x16x32_bf16 v[62:65], v[152:155], v[184:187], v[62:65]
	v_mfma_f32_16x16x32_bf16 v[58:61], v[160:163], v[184:187], v[58:61]
	v_mfma_f32_16x16x32_bf16 v[46:49], v[152:155], v[198:201], v[46:49]
	v_mfma_f32_16x16x32_bf16 v[42:45], v[160:163], v[198:201], v[42:45]
	v_mfma_f32_16x16x32_bf16 v[30:33], v[152:155], v[214:217], v[30:33]
	v_mfma_f32_16x16x32_bf16 v[26:29], v[160:163], v[214:217], v[26:29]
	v_mfma_f32_16x16x32_bf16 v[14:17], v[152:155], v[222:225], v[14:17]
	v_mfma_f32_16x16x32_bf16 v[10:13], v[160:163], v[222:225], v[10:13]
	v_mfma_f32_16x16x32_bf16 v[62:65], v[156:159], v[188:191], v[62:65]
	v_mfma_f32_16x16x32_bf16 v[58:61], v[164:167], v[188:191], v[58:61]
	v_mfma_f32_16x16x32_bf16 v[46:49], v[156:159], v[210:213], v[46:49]
	v_mfma_f32_16x16x32_bf16 v[42:45], v[164:167], v[210:213], v[42:45]
	v_mfma_f32_16x16x32_bf16 v[30:33], v[156:159], v[218:221], v[30:33]
	v_mfma_f32_16x16x32_bf16 v[26:29], v[164:167], v[218:221], v[26:29]
	v_mfma_f32_16x16x32_bf16 v[14:17], v[156:159], v[226:229], v[14:17]
	v_mfma_f32_16x16x32_bf16 v[10:13], v[164:167], v[226:229], v[10:13]
	s_setprio 0
	s_setprio 1
	v_mfma_f32_16x16x32_bf16 v[54:57], v[168:171], v[184:187], v[54:57]
	v_mfma_f32_16x16x32_bf16 v[50:53], v[176:179], v[184:187], v[50:53]
	v_mfma_f32_16x16x32_bf16 v[38:41], v[168:171], v[198:201], v[38:41]
	v_mfma_f32_16x16x32_bf16 v[34:37], v[176:179], v[198:201], v[34:37]
	v_mfma_f32_16x16x32_bf16 v[22:25], v[168:171], v[214:217], v[22:25]
	v_mfma_f32_16x16x32_bf16 v[18:21], v[176:179], v[214:217], v[18:21]
	v_mfma_f32_16x16x32_bf16 v[6:9], v[168:171], v[222:225], v[6:9]
	v_mfma_f32_16x16x32_bf16 v[2:5], v[176:179], v[222:225], v[2:5]
	v_mfma_f32_16x16x32_bf16 v[54:57], v[172:175], v[188:191], v[54:57]
	v_mfma_f32_16x16x32_bf16 v[50:53], v[180:183], v[188:191], v[50:53]
	v_mfma_f32_16x16x32_bf16 v[38:41], v[172:175], v[210:213], v[38:41]
	v_mfma_f32_16x16x32_bf16 v[34:37], v[180:183], v[210:213], v[34:37]
	v_mfma_f32_16x16x32_bf16 v[22:25], v[172:175], v[218:221], v[22:25]
	v_mfma_f32_16x16x32_bf16 v[18:21], v[180:183], v[218:221], v[18:21]
	v_mfma_f32_16x16x32_bf16 v[6:9], v[172:175], v[226:229], v[6:9]
	v_mfma_f32_16x16x32_bf16 v[2:5], v[180:183], v[226:229], v[2:5]
	s_setprio 0
	s_barrier
	s_add_u32 s30, s30, 0x100
	s_addc_u32 s31, s31, 0
	s_add_u32 s15, s15, 0x100
	s_addc_u32 s17, s17, 0
	s_cmp_ge_i32 s29, s68
	s_mov_b32 s19, s29
	s_cbranch_scc0 .LBB0_1315

.Lpeel_6:
	ds_read_b128 v[144:147], v166
	ds_read_b128 v[148:151], v166 offset:1024
	ds_read_b128 v[152:155], v166 offset:2048
	ds_read_b128 v[156:159], v166 offset:3072
	ds_read_b128 v[160:163], v167
	ds_read_b128 v[170:173], v167 offset:1024
	ds_read_b128 v[174:177], v167 offset:2048
	ds_read_b128 v[178:181], v167 offset:3072
	s_add_i32 s30, s26, 2
	s_add_u32 s27, s24, 0xffea0080
	s_addc_u32 s28, s25, -1
	s_cmp_eq_u32 s22, s26
	s_cselect_b32 s26, s20, s17
	s_cselect_b32 s29, s19, s28
	s_cselect_b32 s28, s18, s27
	s_cselect_b32 s27, s21, s23
	v_lshl_add_u64 v[202:203], s[24:25], 0, v[140:141]
	s_add_i32 m0, s34, 0xc000
	ds_read_b128 v[182:185], v168
	ds_read_b128 v[186:189], v168 offset:1024
	ds_read_b128 v[190:193], v168 offset:2048
	ds_read_b128 v[198:201], v168 offset:3072
	ds_read_b128 v[210:213], v168 offset:4096
	ds_read_b128 v[214:217], v168 offset:5120
	ds_read_b128 v[218:221], v168 offset:6144
	ds_read_b128 v[222:225], v168 offset:7168
	global_load_lds_dwordx4 v[202:203], off
	v_lshl_add_u64 v[202:203], s[24:25], 0, v[142:143]
	s_add_i32 m0, s34, 0xe000
	s_nop 0
	global_load_lds_dwordx4 v[202:203], off
	s_waitcnt vmcnt(8)
	s_waitcnt lgkmcnt(0)
	s_barrier
	s_setprio 1
	v_mfma_f32_16x16x32_bf16 v[126:129], v[144:147], v[182:185], 0
	v_mfma_f32_16x16x32_bf16 v[122:125], v[152:155], v[182:185], 0
	v_mfma_f32_16x16x32_bf16 v[114:117], v[144:147], v[190:193], 0
	v_mfma_f32_16x16x32_bf16 v[106:109], v[152:155], v[190:193], 0
	v_mfma_f32_16x16x32_bf16 v[94:97], v[144:147], v[210:213], 0
	v_mfma_f32_16x16x32_bf16 v[90:93], v[152:155], v[210:213], 0
	v_mfma_f32_16x16x32_bf16 v[78:81], v[144:147], v[218:221], 0
	v_mfma_f32_16x16x32_bf16 v[74:77], v[152:155], v[218:221], 0
	v_mfma_f32_16x16x32_bf16 v[126:129], v[148:151], v[186:189], v[126:129]
	v_mfma_f32_16x16x32_bf16 v[122:125], v[156:159], v[186:189], v[122:125]
	v_mfma_f32_16x16x32_bf16 v[114:117], v[148:151], v[198:201], v[114:117]
	v_mfma_f32_16x16x32_bf16 v[106:109], v[156:159], v[198:201], v[106:109]
	v_mfma_f32_16x16x32_bf16 v[94:97], v[148:151], v[214:217], v[94:97]
	v_mfma_f32_16x16x32_bf16 v[90:93], v[156:159], v[214:217], v[90:93]
	v_mfma_f32_16x16x32_bf16 v[78:81], v[148:151], v[222:225], v[78:81]
	v_mfma_f32_16x16x32_bf16 v[74:77], v[156:159], v[222:225], v[74:77]
	s_setprio 0
	s_setprio 1
	v_mfma_f32_16x16x32_bf16 v[118:121], v[160:163], v[182:185], 0
	v_mfma_f32_16x16x32_bf16 v[110:113], v[174:177], v[182:185], 0
	v_mfma_f32_16x16x32_bf16 v[102:105], v[160:163], v[190:193], 0
	v_mfma_f32_16x16x32_bf16 v[98:101], v[174:177], v[190:193], 0
	v_mfma_f32_16x16x32_bf16 v[86:89], v[160:163], v[210:213], 0
	v_mfma_f32_16x16x32_bf16 v[82:85], v[174:177], v[210:213], 0
	v_mfma_f32_16x16x32_bf16 v[70:73], v[160:163], v[218:221], 0
	v_mfma_f32_16x16x32_bf16 v[66:69], v[174:177], v[218:221], 0
	v_mfma_f32_16x16x32_bf16 v[118:121], v[170:173], v[186:189], v[118:121]
	v_mfma_f32_16x16x32_bf16 v[110:113], v[178:181], v[186:189], v[110:113]
	v_mfma_f32_16x16x32_bf16 v[102:105], v[170:173], v[198:201], v[102:105]
	v_mfma_f32_16x16x32_bf16 v[98:101], v[178:181], v[198:201], v[98:101]
	v_mfma_f32_16x16x32_bf16 v[86:89], v[170:173], v[214:217], v[86:89]
	v_mfma_f32_16x16x32_bf16 v[82:85], v[178:181], v[214:217], v[82:85]
	v_mfma_f32_16x16x32_bf16 v[70:73], v[170:173], v[222:225], v[70:73]
	v_mfma_f32_16x16x32_bf16 v[66:69], v[178:181], v[222:225], v[66:69]
	s_setprio 0
	s_barrier
	s_add_i32 s31, s57, s33
	v_lshl_add_u64 v[202:203], s[26:27], 0, v[132:133]
	s_mov_b32 m0, s31
	ds_read_b128 v[182:185], v168 offset:16384
	ds_read_b128 v[186:189], v168 offset:17408
	ds_read_b128 v[190:193], v168 offset:18432
	ds_read_b128 v[198:201], v168 offset:19456
	ds_read_b128 v[210:213], v168 offset:20480
	ds_read_b128 v[214:217], v168 offset:21504
	ds_read_b128 v[218:221], v168 offset:22528
	ds_read_b128 v[222:225], v168 offset:23552
	global_load_lds_dwordx4 v[202:203], off
	s_add_i32 m0, s31, 0x2000
	s_add_u32 s68, s26, 0x160000
	v_lshl_add_u64 v[206:207], s[26:27], 0, v[136:137]
	s_addc_u32 s69, s27, 0
	s_add_i32 s31, s58, s33
	global_load_lds_dwordx4 v[206:207], off
	v_lshl_add_u64 v[226:227], s[68:69], 0, v[132:133]
	s_mov_b32 m0, s31
	v_lshl_add_u64 v[228:229], s[28:29], 0, v[134:135]
	global_load_lds_dwordx4 v[226:227], off
	v_lshl_add_u64 v[226:227], s[68:69], 0, v[136:137]
	s_add_i32 m0, s31, 0x2000
	s_nop 0
	global_load_lds_dwordx4 v[226:227], off
	v_lshl_add_u64 v[226:227], s[28:29], 0, v[130:131]
	s_mov_b32 m0, s34
	s_nop 0
	global_load_lds_dwordx4 v[226:227], off
	s_mov_b32 m0, s35
	s_nop 0
	global_load_lds_dwordx4 v[228:229], off
	s_waitcnt vmcnt(8)
	s_waitcnt lgkmcnt(0)
	s_barrier
	s_setprio 1
	v_mfma_f32_16x16x32_bf16 v[62:65], v[144:147], v[182:185], 0
	v_mfma_f32_16x16x32_bf16 v[58:61], v[152:155], v[182:185], 0
	v_mfma_f32_16x16x32_bf16 v[46:49], v[144:147], v[190:193], 0
	v_mfma_f32_16x16x32_bf16 v[42:45], v[152:155], v[190:193], 0
	v_mfma_f32_16x16x32_bf16 v[30:33], v[144:147], v[210:213], 0
	v_mfma_f32_16x16x32_bf16 v[26:29], v[152:155], v[210:213], 0
	v_mfma_f32_16x16x32_bf16 v[14:17], v[144:147], v[218:221], 0
	v_mfma_f32_16x16x32_bf16 v[10:13], v[152:155], v[218:221], 0
	v_mfma_f32_16x16x32_bf16 v[62:65], v[148:151], v[186:189], v[62:65]
	v_mfma_f32_16x16x32_bf16 v[58:61], v[156:159], v[186:189], v[58:61]
	v_mfma_f32_16x16x32_bf16 v[46:49], v[148:151], v[198:201], v[46:49]
	v_mfma_f32_16x16x32_bf16 v[42:45], v[156:159], v[198:201], v[42:45]
	v_mfma_f32_16x16x32_bf16 v[30:33], v[148:151], v[214:217], v[30:33]
	v_mfma_f32_16x16x32_bf16 v[26:29], v[156:159], v[214:217], v[26:29]
	v_mfma_f32_16x16x32_bf16 v[14:17], v[148:151], v[222:225], v[14:17]
	v_mfma_f32_16x16x32_bf16 v[10:13], v[156:159], v[222:225], v[10:13]
	s_setprio 0
	s_setprio 1
	v_mfma_f32_16x16x32_bf16 v[54:57], v[160:163], v[182:185], 0
	v_mfma_f32_16x16x32_bf16 v[50:53], v[174:177], v[182:185], 0
	v_mfma_f32_16x16x32_bf16 v[38:41], v[160:163], v[190:193], 0
	v_mfma_f32_16x16x32_bf16 v[34:37], v[174:177], v[190:193], 0
	v_mfma_f32_16x16x32_bf16 v[22:25], v[160:163], v[210:213], 0
	v_mfma_f32_16x16x32_bf16 v[18:21], v[174:177], v[210:213], 0
	v_mfma_f32_16x16x32_bf16 v[6:9], v[160:163], v[218:221], 0
	v_mfma_f32_16x16x32_bf16 v[2:5], v[174:177], v[218:221], 0
	v_mfma_f32_16x16x32_bf16 v[54:57], v[170:173], v[186:189], v[54:57]
	v_mfma_f32_16x16x32_bf16 v[50:53], v[178:181], v[186:189], v[50:53]
	v_mfma_f32_16x16x32_bf16 v[38:41], v[170:173], v[198:201], v[38:41]
	v_mfma_f32_16x16x32_bf16 v[34:37], v[178:181], v[198:201], v[34:37]
	v_mfma_f32_16x16x32_bf16 v[22:25], v[170:173], v[214:217], v[22:25]
	v_mfma_f32_16x16x32_bf16 v[18:21], v[178:181], v[214:217], v[18:21]
	v_mfma_f32_16x16x32_bf16 v[6:9], v[170:173], v[222:225], v[6:9]
	v_mfma_f32_16x16x32_bf16 v[2:5], v[178:181], v[222:225], v[2:5]
	s_setprio 0
	s_barrier
	s_add_i32 s31, 0, 0x18000
	s_add_i32 s68, 0, 0x1c000
	v_add_u32_e32 v156, s31, v164
	v_add_u32_e32 v169, s68, v164
	ds_read_b128 v[144:147], v156
	ds_read_b128 v[148:151], v156 offset:1024
	ds_read_b128 v[152:155], v156 offset:2048
	ds_read_b128 v[156:159], v156 offset:3072
	ds_read_b128 v[160:163], v169
	ds_read_b128 v[170:173], v169 offset:1024
	ds_read_b128 v[174:177], v169 offset:2048
	ds_read_b128 v[178:181], v169 offset:3072
	s_add_u32 s28, s28, 0x160000
	s_addc_u32 s29, s29, 0
	s_mov_b32 m0, s36
	v_lshl_add_u64 v[230:231], s[28:29], 0, v[130:131]
	ds_read_b128 v[182:185], v168 offset:32768
	ds_read_b128 v[186:189], v168 offset:33792
	ds_read_b128 v[190:193], v168 offset:34816
	ds_read_b128 v[198:201], v168 offset:35840
	ds_read_b128 v[210:213], v168 offset:36864
	ds_read_b128 v[214:217], v168 offset:37888
	ds_read_b128 v[218:221], v168 offset:38912
	ds_read_b128 v[222:225], v168 offset:39936
	global_load_lds_dwordx4 v[230:231], off
	v_lshl_add_u64 v[230:231], s[28:29], 0, v[134:135]
	s_mov_b32 m0, s37
	s_nop 0
	global_load_lds_dwordx4 v[230:231], off
	s_waitcnt vmcnt(8)
	s_waitcnt lgkmcnt(0)
	s_barrier
	s_setprio 1
	v_mfma_f32_16x16x32_bf16 v[126:129], v[144:147], v[182:185], v[126:129]
	v_mfma_f32_16x16x32_bf16 v[122:125], v[152:155], v[182:185], v[122:125]
	v_mfma_f32_16x16x32_bf16 v[114:117], v[144:147], v[190:193], v[114:117]
	v_mfma_f32_16x16x32_bf16 v[106:109], v[152:155], v[190:193], v[106:109]
	v_mfma_f32_16x16x32_bf16 v[94:97], v[144:147], v[210:213], v[94:97]
	v_mfma_f32_16x16x32_bf16 v[90:93], v[152:155], v[210:213], v[90:93]
	v_mfma_f32_16x16x32_bf16 v[78:81], v[144:147], v[218:221], v[78:81]
	v_mfma_f32_16x16x32_bf16 v[74:77], v[152:155], v[218:221], v[74:77]
	v_mfma_f32_16x16x32_bf16 v[126:129], v[148:151], v[186:189], v[126:129]
	v_mfma_f32_16x16x32_bf16 v[122:125], v[156:159], v[186:189], v[122:125]
	v_mfma_f32_16x16x32_bf16 v[114:117], v[148:151], v[198:201], v[114:117]
	v_mfma_f32_16x16x32_bf16 v[106:109], v[156:159], v[198:201], v[106:109]
	v_mfma_f32_16x16x32_bf16 v[94:97], v[148:151], v[214:217], v[94:97]
	v_mfma_f32_16x16x32_bf16 v[90:93], v[156:159], v[214:217], v[90:93]
	v_mfma_f32_16x16x32_bf16 v[78:81], v[148:151], v[222:225], v[78:81]
	v_mfma_f32_16x16x32_bf16 v[74:77], v[156:159], v[222:225], v[74:77]
	s_setprio 0
	s_setprio 1
	v_mfma_f32_16x16x32_bf16 v[118:121], v[160:163], v[182:185], v[118:121]
	v_mfma_f32_16x16x32_bf16 v[110:113], v[174:177], v[182:185], v[110:113]
	v_mfma_f32_16x16x32_bf16 v[102:105], v[160:163], v[190:193], v[102:105]
	v_mfma_f32_16x16x32_bf16 v[98:101], v[174:177], v[190:193], v[98:101]
	v_mfma_f32_16x16x32_bf16 v[86:89], v[160:163], v[210:213], v[86:89]
	v_mfma_f32_16x16x32_bf16 v[82:85], v[174:177], v[210:213], v[82:85]
	v_mfma_f32_16x16x32_bf16 v[70:73], v[160:163], v[218:221], v[70:73]
	v_mfma_f32_16x16x32_bf16 v[66:69], v[174:177], v[218:221], v[66:69]
	v_mfma_f32_16x16x32_bf16 v[118:121], v[170:173], v[186:189], v[118:121]
	v_mfma_f32_16x16x32_bf16 v[110:113], v[178:181], v[186:189], v[110:113]
	v_mfma_f32_16x16x32_bf16 v[102:105], v[170:173], v[198:201], v[102:105]
	v_mfma_f32_16x16x32_bf16 v[98:101], v[178:181], v[198:201], v[98:101]
	v_mfma_f32_16x16x32_bf16 v[86:89], v[170:173], v[214:217], v[86:89]
	v_mfma_f32_16x16x32_bf16 v[82:85], v[178:181], v[214:217], v[82:85]
	v_mfma_f32_16x16x32_bf16 v[70:73], v[170:173], v[222:225], v[70:73]
	v_mfma_f32_16x16x32_bf16 v[66:69], v[178:181], v[222:225], v[66:69]
	s_setprio 0
	s_barrier
	s_add_i32 s28, s31, s33
	v_lshl_add_u64 v[202:203], v[202:203], 0, s[12:13]
	s_mov_b32 m0, s28
	ds_read_b128 v[182:185], v168 offset:49152
	ds_read_b128 v[186:189], v168 offset:50176
	ds_read_b128 v[190:193], v168 offset:51200
	ds_read_b128 v[198:201], v168 offset:52224
	ds_read_b128 v[210:213], v168 offset:53248
	ds_read_b128 v[214:217], v168 offset:54272
	ds_read_b128 v[218:221], v168 offset:55296
	ds_read_b128 v[222:225], v168 offset:56320
	global_load_lds_dwordx4 v[202:203], off
	s_add_i32 m0, s28, 0x2000
	s_add_u32 s26, s26, 0x160080
	v_lshl_add_u64 v[202:203], v[206:207], 0, s[12:13]
	s_addc_u32 s27, s27, 0
	s_add_i32 s28, s68, s33
	global_load_lds_dwordx4 v[202:203], off
	v_lshl_add_u64 v[202:203], s[26:27], 0, v[132:133]
	s_mov_b32 m0, s28
	s_nop 0
	global_load_lds_dwordx4 v[202:203], off
	v_lshl_add_u64 v[202:203], s[26:27], 0, v[136:137]
	s_add_i32 m0, s28, 0x2000
	s_nop 0
	global_load_lds_dwordx4 v[202:203], off
	v_lshl_add_u64 v[202:203], v[226:227], 0, s[12:13]
	s_mov_b32 m0, s47
	s_nop 0
	global_load_lds_dwordx4 v[202:203], off
	v_lshl_add_u64 v[202:203], v[228:229], 0, s[12:13]
	s_mov_b32 m0, s48
	s_nop 0
	global_load_lds_dwordx4 v[202:203], off
	s_waitcnt vmcnt(8)
	s_waitcnt lgkmcnt(0)
	s_barrier
	s_setprio 1
	v_mfma_f32_16x16x32_bf16 v[62:65], v[144:147], v[182:185], v[62:65]
	v_mfma_f32_16x16x32_bf16 v[58:61], v[152:155], v[182:185], v[58:61]
	v_mfma_f32_16x16x32_bf16 v[46:49], v[144:147], v[190:193], v[46:49]
	v_mfma_f32_16x16x32_bf16 v[42:45], v[152:155], v[190:193], v[42:45]
	v_mfma_f32_16x16x32_bf16 v[30:33], v[144:147], v[210:213], v[30:33]
	v_mfma_f32_16x16x32_bf16 v[26:29], v[152:155], v[210:213], v[26:29]
	v_mfma_f32_16x16x32_bf16 v[14:17], v[144:147], v[218:221], v[14:17]
	v_mfma_f32_16x16x32_bf16 v[10:13], v[152:155], v[218:221], v[10:13]
	v_mfma_f32_16x16x32_bf16 v[62:65], v[148:151], v[186:189], v[62:65]
	v_mfma_f32_16x16x32_bf16 v[58:61], v[156:159], v[186:189], v[58:61]
	v_mfma_f32_16x16x32_bf16 v[46:49], v[148:151], v[198:201], v[46:49]
	v_mfma_f32_16x16x32_bf16 v[42:45], v[156:159], v[198:201], v[42:45]
	v_mfma_f32_16x16x32_bf16 v[30:33], v[148:151], v[214:217], v[30:33]
	v_mfma_f32_16x16x32_bf16 v[26:29], v[156:159], v[214:217], v[26:29]
	v_mfma_f32_16x16x32_bf16 v[14:17], v[148:151], v[222:225], v[14:17]
	v_mfma_f32_16x16x32_bf16 v[10:13], v[156:159], v[222:225], v[10:13]
	s_setprio 0
	s_setprio 1
	v_mfma_f32_16x16x32_bf16 v[54:57], v[160:163], v[182:185], v[54:57]
	v_mfma_f32_16x16x32_bf16 v[50:53], v[174:177], v[182:185], v[50:53]
	v_mfma_f32_16x16x32_bf16 v[38:41], v[160:163], v[190:193], v[38:41]
	v_mfma_f32_16x16x32_bf16 v[34:37], v[174:177], v[190:193], v[34:37]
	v_mfma_f32_16x16x32_bf16 v[22:25], v[160:163], v[210:213], v[22:25]
	v_mfma_f32_16x16x32_bf16 v[18:21], v[174:177], v[210:213], v[18:21]
	v_mfma_f32_16x16x32_bf16 v[6:9], v[160:163], v[218:221], v[6:9]
	v_mfma_f32_16x16x32_bf16 v[2:5], v[174:177], v[218:221], v[2:5]
	v_mfma_f32_16x16x32_bf16 v[54:57], v[170:173], v[186:189], v[54:57]
	v_mfma_f32_16x16x32_bf16 v[50:53], v[178:181], v[186:189], v[50:53]
	v_mfma_f32_16x16x32_bf16 v[38:41], v[170:173], v[198:201], v[38:41]
	v_mfma_f32_16x16x32_bf16 v[34:37], v[178:181], v[198:201], v[34:37]
	v_mfma_f32_16x16x32_bf16 v[22:25], v[170:173], v[214:217], v[22:25]
	v_mfma_f32_16x16x32_bf16 v[18:21], v[178:181], v[214:217], v[18:21]
	v_mfma_f32_16x16x32_bf16 v[6:9], v[170:173], v[222:225], v[6:9]
	v_mfma_f32_16x16x32_bf16 v[2:5], v[178:181], v[222:225], v[2:5]
	s_setprio 0
	s_barrier
	s_add_u32 s24, s24, 0x100
	s_addc_u32 s25, s25, 0
	s_add_u32 s17, s17, 0x100
	s_addc_u32 s23, s23, 0
	s_cmp_ge_i32 s30, s67
	s_mov_b32 s26, s30
	s_cbranch_scc0 .LBB0_1451
	s_branch .Lpeeldone_6
.LBB0_1451:
	ds_read_b128 v[144:147], v166
	ds_read_b128 v[148:151], v166 offset:1024
	ds_read_b128 v[152:155], v166 offset:2048
	ds_read_b128 v[156:159], v166 offset:3072
	ds_read_b128 v[160:163], v167
	ds_read_b128 v[170:173], v167 offset:1024
	ds_read_b128 v[174:177], v167 offset:2048
	ds_read_b128 v[178:181], v167 offset:3072
	s_add_i32 s30, s26, 2
	s_add_u32 s27, s24, 0xffea0080
	s_addc_u32 s28, s25, -1
	s_cmp_eq_u32 s22, s26
	s_cselect_b32 s26, s20, s17
	s_cselect_b32 s29, s19, s28
	s_cselect_b32 s28, s18, s27
	s_cselect_b32 s27, s21, s23
	v_lshl_add_u64 v[202:203], s[24:25], 0, v[140:141]
	s_add_i32 m0, s34, 0xc000
	ds_read_b128 v[182:185], v168
	ds_read_b128 v[186:189], v168 offset:1024
	ds_read_b128 v[190:193], v168 offset:2048
	ds_read_b128 v[198:201], v168 offset:3072
	ds_read_b128 v[210:213], v168 offset:4096
	ds_read_b128 v[214:217], v168 offset:5120
	ds_read_b128 v[218:221], v168 offset:6144
	ds_read_b128 v[222:225], v168 offset:7168
	global_load_lds_dwordx4 v[202:203], off
	v_lshl_add_u64 v[202:203], s[24:25], 0, v[142:143]
	s_add_i32 m0, s34, 0xe000
	s_nop 0
	global_load_lds_dwordx4 v[202:203], off
	s_waitcnt vmcnt(8)
	s_waitcnt lgkmcnt(0)
	s_barrier
	s_setprio 1
	v_mfma_f32_16x16x32_bf16 v[126:129], v[144:147], v[182:185], v[126:129]
	v_mfma_f32_16x16x32_bf16 v[122:125], v[152:155], v[182:185], v[122:125]
	v_mfma_f32_16x16x32_bf16 v[114:117], v[144:147], v[190:193], v[114:117]
	v_mfma_f32_16x16x32_bf16 v[106:109], v[152:155], v[190:193], v[106:109]
	v_mfma_f32_16x16x32_bf16 v[94:97], v[144:147], v[210:213], v[94:97]
	v_mfma_f32_16x16x32_bf16 v[90:93], v[152:155], v[210:213], v[90:93]
	v_mfma_f32_16x16x32_bf16 v[78:81], v[144:147], v[218:221], v[78:81]
	v_mfma_f32_16x16x32_bf16 v[74:77], v[152:155], v[218:221], v[74:77]
	v_mfma_f32_16x16x32_bf16 v[126:129], v[148:151], v[186:189], v[126:129]
	v_mfma_f32_16x16x32_bf16 v[122:125], v[156:159], v[186:189], v[122:125]
	v_mfma_f32_16x16x32_bf16 v[114:117], v[148:151], v[198:201], v[114:117]
	v_mfma_f32_16x16x32_bf16 v[106:109], v[156:159], v[198:201], v[106:109]
	v_mfma_f32_16x16x32_bf16 v[94:97], v[148:151], v[214:217], v[94:97]
	v_mfma_f32_16x16x32_bf16 v[90:93], v[156:159], v[214:217], v[90:93]
	v_mfma_f32_16x16x32_bf16 v[78:81], v[148:151], v[222:225], v[78:81]
	v_mfma_f32_16x16x32_bf16 v[74:77], v[156:159], v[222:225], v[74:77]
	s_setprio 0
	s_setprio 1
	v_mfma_f32_16x16x32_bf16 v[118:121], v[160:163], v[182:185], v[118:121]
	v_mfma_f32_16x16x32_bf16 v[110:113], v[174:177], v[182:185], v[110:113]
	v_mfma_f32_16x16x32_bf16 v[102:105], v[160:163], v[190:193], v[102:105]
	v_mfma_f32_16x16x32_bf16 v[98:101], v[174:177], v[190:193], v[98:101]
	v_mfma_f32_16x16x32_bf16 v[86:89], v[160:163], v[210:213], v[86:89]
	v_mfma_f32_16x16x32_bf16 v[82:85], v[174:177], v[210:213], v[82:85]
	v_mfma_f32_16x16x32_bf16 v[70:73], v[160:163], v[218:221], v[70:73]
	v_mfma_f32_16x16x32_bf16 v[66:69], v[174:177], v[218:221], v[66:69]
	v_mfma_f32_16x16x32_bf16 v[118:121], v[170:173], v[186:189], v[118:121]
	v_mfma_f32_16x16x32_bf16 v[110:113], v[178:181], v[186:189], v[110:113]
	v_mfma_f32_16x16x32_bf16 v[102:105], v[170:173], v[198:201], v[102:105]
	v_mfma_f32_16x16x32_bf16 v[98:101], v[178:181], v[198:201], v[98:101]
	v_mfma_f32_16x16x32_bf16 v[86:89], v[170:173], v[214:217], v[86:89]
	v_mfma_f32_16x16x32_bf16 v[82:85], v[178:181], v[214:217], v[82:85]
	v_mfma_f32_16x16x32_bf16 v[70:73], v[170:173], v[222:225], v[70:73]
	v_mfma_f32_16x16x32_bf16 v[66:69], v[178:181], v[222:225], v[66:69]
	s_setprio 0
	s_barrier
	s_add_i32 s31, s57, s33
	v_lshl_add_u64 v[202:203], s[26:27], 0, v[132:133]
	s_mov_b32 m0, s31
	ds_read_b128 v[182:185], v168 offset:16384
	ds_read_b128 v[186:189], v168 offset:17408
	ds_read_b128 v[190:193], v168 offset:18432
	ds_read_b128 v[198:201], v168 offset:19456
	ds_read_b128 v[210:213], v168 offset:20480
	ds_read_b128 v[214:217], v168 offset:21504
	ds_read_b128 v[218:221], v168 offset:22528
	ds_read_b128 v[222:225], v168 offset:23552
	global_load_lds_dwordx4 v[202:203], off
	s_add_i32 m0, s31, 0x2000
	s_add_u32 s68, s26, 0x160000
	v_lshl_add_u64 v[206:207], s[26:27], 0, v[136:137]
	s_addc_u32 s69, s27, 0
	s_add_i32 s31, s58, s33
	global_load_lds_dwordx4 v[206:207], off
	v_lshl_add_u64 v[226:227], s[68:69], 0, v[132:133]
	s_mov_b32 m0, s31
	v_lshl_add_u64 v[228:229], s[28:29], 0, v[134:135]
	global_load_lds_dwordx4 v[226:227], off
	v_lshl_add_u64 v[226:227], s[68:69], 0, v[136:137]
	s_add_i32 m0, s31, 0x2000
	s_nop 0
	global_load_lds_dwordx4 v[226:227], off
	v_lshl_add_u64 v[226:227], s[28:29], 0, v[130:131]
	s_mov_b32 m0, s34
	s_nop 0
	global_load_lds_dwordx4 v[226:227], off
	s_mov_b32 m0, s35
	s_nop 0
	global_load_lds_dwordx4 v[228:229], off
	s_waitcnt vmcnt(8)
	s_waitcnt lgkmcnt(0)
	s_barrier
	s_setprio 1
	v_mfma_f32_16x16x32_bf16 v[62:65], v[144:147], v[182:185], v[62:65]
	v_mfma_f32_16x16x32_bf16 v[58:61], v[152:155], v[182:185], v[58:61]
	v_mfma_f32_16x16x32_bf16 v[46:49], v[144:147], v[190:193], v[46:49]
	v_mfma_f32_16x16x32_bf16 v[42:45], v[152:155], v[190:193], v[42:45]
	v_mfma_f32_16x16x32_bf16 v[30:33], v[144:147], v[210:213], v[30:33]
	v_mfma_f32_16x16x32_bf16 v[26:29], v[152:155], v[210:213], v[26:29]
	v_mfma_f32_16x16x32_bf16 v[14:17], v[144:147], v[218:221], v[14:17]
	v_mfma_f32_16x16x32_bf16 v[10:13], v[152:155], v[218:221], v[10:13]
	v_mfma_f32_16x16x32_bf16 v[62:65], v[148:151], v[186:189], v[62:65]
	v_mfma_f32_16x16x32_bf16 v[58:61], v[156:159], v[186:189], v[58:61]
	v_mfma_f32_16x16x32_bf16 v[46:49], v[148:151], v[198:201], v[46:49]
	v_mfma_f32_16x16x32_bf16 v[42:45], v[156:159], v[198:201], v[42:45]
	v_mfma_f32_16x16x32_bf16 v[30:33], v[148:151], v[214:217], v[30:33]
	v_mfma_f32_16x16x32_bf16 v[26:29], v[156:159], v[214:217], v[26:29]
	v_mfma_f32_16x16x32_bf16 v[14:17], v[148:151], v[222:225], v[14:17]
	v_mfma_f32_16x16x32_bf16 v[10:13], v[156:159], v[222:225], v[10:13]
	s_setprio 0
	s_setprio 1
	v_mfma_f32_16x16x32_bf16 v[54:57], v[160:163], v[182:185], v[54:57]
	v_mfma_f32_16x16x32_bf16 v[50:53], v[174:177], v[182:185], v[50:53]
	v_mfma_f32_16x16x32_bf16 v[38:41], v[160:163], v[190:193], v[38:41]
	v_mfma_f32_16x16x32_bf16 v[34:37], v[174:177], v[190:193], v[34:37]
	v_mfma_f32_16x16x32_bf16 v[22:25], v[160:163], v[210:213], v[22:25]
	v_mfma_f32_16x16x32_bf16 v[18:21], v[174:177], v[210:213], v[18:21]
	v_mfma_f32_16x16x32_bf16 v[6:9], v[160:163], v[218:221], v[6:9]
	v_mfma_f32_16x16x32_bf16 v[2:5], v[174:177], v[218:221], v[2:5]
	v_mfma_f32_16x16x32_bf16 v[54:57], v[170:173], v[186:189], v[54:57]
	v_mfma_f32_16x16x32_bf16 v[50:53], v[178:181], v[186:189], v[50:53]
	v_mfma_f32_16x16x32_bf16 v[38:41], v[170:173], v[198:201], v[38:41]
	v_mfma_f32_16x16x32_bf16 v[34:37], v[178:181], v[198:201], v[34:37]
	v_mfma_f32_16x16x32_bf16 v[22:25], v[170:173], v[214:217], v[22:25]
	v_mfma_f32_16x16x32_bf16 v[18:21], v[178:181], v[214:217], v[18:21]
	v_mfma_f32_16x16x32_bf16 v[6:9], v[170:173], v[222:225], v[6:9]
	v_mfma_f32_16x16x32_bf16 v[2:5], v[178:181], v[222:225], v[2:5]
	s_setprio 0
	s_barrier
	s_add_i32 s31, 0, 0x18000
	s_add_i32 s68, 0, 0x1c000
	v_add_u32_e32 v156, s31, v164
	v_add_u32_e32 v169, s68, v164
	ds_read_b128 v[144:147], v156
	ds_read_b128 v[148:151], v156 offset:1024
	ds_read_b128 v[152:155], v156 offset:2048
	ds_read_b128 v[156:159], v156 offset:3072
	ds_read_b128 v[160:163], v169
	ds_read_b128 v[170:173], v169 offset:1024
	ds_read_b128 v[174:177], v169 offset:2048
	ds_read_b128 v[178:181], v169 offset:3072
	s_add_u32 s28, s28, 0x160000
	s_addc_u32 s29, s29, 0
	s_mov_b32 m0, s36
	v_lshl_add_u64 v[230:231], s[28:29], 0, v[130:131]
	ds_read_b128 v[182:185], v168 offset:32768
	ds_read_b128 v[186:189], v168 offset:33792
	ds_read_b128 v[190:193], v168 offset:34816
	ds_read_b128 v[198:201], v168 offset:35840
	ds_read_b128 v[210:213], v168 offset:36864
	ds_read_b128 v[214:217], v168 offset:37888
	ds_read_b128 v[218:221], v168 offset:38912
	ds_read_b128 v[222:225], v168 offset:39936
	global_load_lds_dwordx4 v[230:231], off
	v_lshl_add_u64 v[230:231], s[28:29], 0, v[134:135]
	s_mov_b32 m0, s37
	s_nop 0
	global_load_lds_dwordx4 v[230:231], off
	s_waitcnt vmcnt(8)
	s_waitcnt lgkmcnt(0)
	s_barrier
	s_setprio 1
	v_mfma_f32_16x16x32_bf16 v[126:129], v[144:147], v[182:185], v[126:129]
	v_mfma_f32_16x16x32_bf16 v[122:125], v[152:155], v[182:185], v[122:125]
	v_mfma_f32_16x16x32_bf16 v[114:117], v[144:147], v[190:193], v[114:117]
	v_mfma_f32_16x16x32_bf16 v[106:109], v[152:155], v[190:193], v[106:109]
	v_mfma_f32_16x16x32_bf16 v[94:97], v[144:147], v[210:213], v[94:97]
	v_mfma_f32_16x16x32_bf16 v[90:93], v[152:155], v[210:213], v[90:93]
	v_mfma_f32_16x16x32_bf16 v[78:81], v[144:147], v[218:221], v[78:81]
	v_mfma_f32_16x16x32_bf16 v[74:77], v[152:155], v[218:221], v[74:77]
	v_mfma_f32_16x16x32_bf16 v[126:129], v[148:151], v[186:189], v[126:129]
	v_mfma_f32_16x16x32_bf16 v[122:125], v[156:159], v[186:189], v[122:125]
	v_mfma_f32_16x16x32_bf16 v[114:117], v[148:151], v[198:201], v[114:117]
	v_mfma_f32_16x16x32_bf16 v[106:109], v[156:159], v[198:201], v[106:109]
	v_mfma_f32_16x16x32_bf16 v[94:97], v[148:151], v[214:217], v[94:97]
	v_mfma_f32_16x16x32_bf16 v[90:93], v[156:159], v[214:217], v[90:93]
	v_mfma_f32_16x16x32_bf16 v[78:81], v[148:151], v[222:225], v[78:81]
	v_mfma_f32_16x16x32_bf16 v[74:77], v[156:159], v[222:225], v[74:77]
	s_setprio 0
	s_setprio 1
	v_mfma_f32_16x16x32_bf16 v[118:121], v[160:163], v[182:185], v[118:121]
	v_mfma_f32_16x16x32_bf16 v[110:113], v[174:177], v[182:185], v[110:113]
	v_mfma_f32_16x16x32_bf16 v[102:105], v[160:163], v[190:193], v[102:105]
	v_mfma_f32_16x16x32_bf16 v[98:101], v[174:177], v[190:193], v[98:101]
	v_mfma_f32_16x16x32_bf16 v[86:89], v[160:163], v[210:213], v[86:89]
	v_mfma_f32_16x16x32_bf16 v[82:85], v[174:177], v[210:213], v[82:85]
	v_mfma_f32_16x16x32_bf16 v[70:73], v[160:163], v[218:221], v[70:73]
	v_mfma_f32_16x16x32_bf16 v[66:69], v[174:177], v[218:221], v[66:69]
	v_mfma_f32_16x16x32_bf16 v[118:121], v[170:173], v[186:189], v[118:121]
	v_mfma_f32_16x16x32_bf16 v[110:113], v[178:181], v[186:189], v[110:113]
	v_mfma_f32_16x16x32_bf16 v[102:105], v[170:173], v[198:201], v[102:105]
	v_mfma_f32_16x16x32_bf16 v[98:101], v[178:181], v[198:201], v[98:101]
	v_mfma_f32_16x16x32_bf16 v[86:89], v[170:173], v[214:217], v[86:89]
	v_mfma_f32_16x16x32_bf16 v[82:85], v[178:181], v[214:217], v[82:85]
	v_mfma_f32_16x16x32_bf16 v[70:73], v[170:173], v[222:225], v[70:73]
	v_mfma_f32_16x16x32_bf16 v[66:69], v[178:181], v[222:225], v[66:69]
	s_setprio 0
	s_barrier
	s_add_i32 s28, s31, s33
	v_lshl_add_u64 v[202:203], v[202:203], 0, s[12:13]
	s_mov_b32 m0, s28
	ds_read_b128 v[182:185], v168 offset:49152
	ds_read_b128 v[186:189], v168 offset:50176
	ds_read_b128 v[190:193], v168 offset:51200
	ds_read_b128 v[198:201], v168 offset:52224
	ds_read_b128 v[210:213], v168 offset:53248
	ds_read_b128 v[214:217], v168 offset:54272
	ds_read_b128 v[218:221], v168 offset:55296
	ds_read_b128 v[222:225], v168 offset:56320
	global_load_lds_dwordx4 v[202:203], off
	s_add_i32 m0, s28, 0x2000
	s_add_u32 s26, s26, 0x160080
	v_lshl_add_u64 v[202:203], v[206:207], 0, s[12:13]
	s_addc_u32 s27, s27, 0
	s_add_i32 s28, s68, s33
	global_load_lds_dwordx4 v[202:203], off
	v_lshl_add_u64 v[202:203], s[26:27], 0, v[132:133]
	s_mov_b32 m0, s28
	s_nop 0
	global_load_lds_dwordx4 v[202:203], off
	v_lshl_add_u64 v[202:203], s[26:27], 0, v[136:137]
	s_add_i32 m0, s28, 0x2000
	s_nop 0
	global_load_lds_dwordx4 v[202:203], off
	v_lshl_add_u64 v[202:203], v[226:227], 0, s[12:13]
	s_mov_b32 m0, s47
	s_nop 0
	global_load_lds_dwordx4 v[202:203], off
	v_lshl_add_u64 v[202:203], v[228:229], 0, s[12:13]
	s_mov_b32 m0, s48
	s_nop 0
	global_load_lds_dwordx4 v[202:203], off
	s_waitcnt vmcnt(8)
	s_waitcnt lgkmcnt(0)
	s_barrier
	s_setprio 1
	v_mfma_f32_16x16x32_bf16 v[62:65], v[144:147], v[182:185], v[62:65]
	v_mfma_f32_16x16x32_bf16 v[58:61], v[152:155], v[182:185], v[58:61]
	v_mfma_f32_16x16x32_bf16 v[46:49], v[144:147], v[190:193], v[46:49]
	v_mfma_f32_16x16x32_bf16 v[42:45], v[152:155], v[190:193], v[42:45]
	v_mfma_f32_16x16x32_bf16 v[30:33], v[144:147], v[210:213], v[30:33]
	v_mfma_f32_16x16x32_bf16 v[26:29], v[152:155], v[210:213], v[26:29]
	v_mfma_f32_16x16x32_bf16 v[14:17], v[144:147], v[218:221], v[14:17]
	v_mfma_f32_16x16x32_bf16 v[10:13], v[152:155], v[218:221], v[10:13]
	v_mfma_f32_16x16x32_bf16 v[62:65], v[148:151], v[186:189], v[62:65]
	v_mfma_f32_16x16x32_bf16 v[58:61], v[156:159], v[186:189], v[58:61]
	v_mfma_f32_16x16x32_bf16 v[46:49], v[148:151], v[198:201], v[46:49]
	v_mfma_f32_16x16x32_bf16 v[42:45], v[156:159], v[198:201], v[42:45]
	v_mfma_f32_16x16x32_bf16 v[30:33], v[148:151], v[214:217], v[30:33]
	v_mfma_f32_16x16x32_bf16 v[26:29], v[156:159], v[214:217], v[26:29]
	v_mfma_f32_16x16x32_bf16 v[14:17], v[148:151], v[222:225], v[14:17]
	v_mfma_f32_16x16x32_bf16 v[10:13], v[156:159], v[222:225], v[10:13]
	s_setprio 0
	s_setprio 1
	v_mfma_f32_16x16x32_bf16 v[54:57], v[160:163], v[182:185], v[54:57]
	v_mfma_f32_16x16x32_bf16 v[50:53], v[174:177], v[182:185], v[50:53]
	v_mfma_f32_16x16x32_bf16 v[38:41], v[160:163], v[190:193], v[38:41]
	v_mfma_f32_16x16x32_bf16 v[34:37], v[174:177], v[190:193], v[34:37]
	v_mfma_f32_16x16x32_bf16 v[22:25], v[160:163], v[210:213], v[22:25]
	v_mfma_f32_16x16x32_bf16 v[18:21], v[174:177], v[210:213], v[18:21]
	v_mfma_f32_16x16x32_bf16 v[6:9], v[160:163], v[218:221], v[6:9]
	v_mfma_f32_16x16x32_bf16 v[2:5], v[174:177], v[218:221], v[2:5]
	v_mfma_f32_16x16x32_bf16 v[54:57], v[170:173], v[186:189], v[54:57]
	v_mfma_f32_16x16x32_bf16 v[50:53], v[178:181], v[186:189], v[50:53]
	v_mfma_f32_16x16x32_bf16 v[38:41], v[170:173], v[198:201], v[38:41]
	v_mfma_f32_16x16x32_bf16 v[34:37], v[178:181], v[198:201], v[34:37]
	v_mfma_f32_16x16x32_bf16 v[22:25], v[170:173], v[214:217], v[22:25]
	v_mfma_f32_16x16x32_bf16 v[18:21], v[178:181], v[214:217], v[18:21]
	v_mfma_f32_16x16x32_bf16 v[6:9], v[170:173], v[222:225], v[6:9]
	v_mfma_f32_16x16x32_bf16 v[2:5], v[178:181], v[222:225], v[2:5]
	s_setprio 0
	s_barrier
	s_add_u32 s24, s24, 0x100
	s_addc_u32 s25, s25, 0
	s_add_u32 s17, s17, 0x100
	s_addc_u32 s23, s23, 0
	s_cmp_ge_i32 s30, s67
	s_mov_b32 s26, s30
	s_cbranch_scc0 .LBB0_1451

.Lpeel_3:
	s_add_i32 s29, s23, 2
	s_add_u32 s34, s30, 0xfff80080
	s_addc_u32 s35, s31, -1
	s_cmp_eq_u32 s28, s23
	s_cselect_b32 s37, s25, s35
	s_cselect_b32 s36, s24, s34
	s_cselect_b32 s35, s27, s21
	s_cselect_b32 s34, s26, s19
	v_lshl_add_u64 v[202:203], s[30:31], 0, v[140:141]
	s_add_i32 m0, s15, 0xc000
	global_load_lds_dwordx4 v[202:203], off
	v_lshl_add_u64 v[202:203], s[30:31], 0, v[142:143]
	s_add_i32 m0, s15, 0xe000
	s_nop 0
	global_load_lds_dwordx4 v[202:203], off
	s_waitcnt vmcnt(8)
	s_waitcnt lgkmcnt(0)
	s_barrier
	s_setprio 1
	v_mfma_f32_16x16x32_bf16 v[126:129], v[150:153], v[182:185], 0
	v_mfma_f32_16x16x32_bf16 v[122:125], v[158:161], v[182:185], 0
	v_mfma_f32_16x16x32_bf16 v[118:121], v[150:153], v[190:193], 0
	v_mfma_f32_16x16x32_bf16 v[114:117], v[158:161], v[190:193], 0
	v_mfma_f32_16x16x32_bf16 v[110:113], v[150:153], v[210:213], 0
	v_mfma_f32_16x16x32_bf16 v[106:109], v[158:161], v[210:213], 0
	v_mfma_f32_16x16x32_bf16 v[102:105], v[150:153], v[218:221], 0
	v_mfma_f32_16x16x32_bf16 v[98:101], v[158:161], v[218:221], 0
	v_mfma_f32_16x16x32_bf16 v[126:129], v[154:157], v[186:189], v[126:129]
	v_mfma_f32_16x16x32_bf16 v[122:125], v[162:165], v[186:189], v[122:125]
	v_mfma_f32_16x16x32_bf16 v[118:121], v[154:157], v[198:201], v[118:121]
	v_mfma_f32_16x16x32_bf16 v[114:117], v[162:165], v[198:201], v[114:117]
	v_mfma_f32_16x16x32_bf16 v[110:113], v[154:157], v[214:217], v[110:113]
	v_mfma_f32_16x16x32_bf16 v[106:109], v[162:165], v[214:217], v[106:109]
	v_mfma_f32_16x16x32_bf16 v[102:105], v[154:157], v[222:225], v[102:105]
	v_mfma_f32_16x16x32_bf16 v[98:101], v[162:165], v[222:225], v[98:101]
	s_setprio 0
	s_setprio 1
	v_mfma_f32_16x16x32_bf16 v[94:97], v[166:169], v[182:185], 0
	v_mfma_f32_16x16x32_bf16 v[90:93], v[174:177], v[182:185], 0
	v_mfma_f32_16x16x32_bf16 v[86:89], v[166:169], v[190:193], 0
	v_mfma_f32_16x16x32_bf16 v[82:85], v[174:177], v[190:193], 0
	v_mfma_f32_16x16x32_bf16 v[78:81], v[166:169], v[210:213], 0
	v_mfma_f32_16x16x32_bf16 v[74:77], v[174:177], v[210:213], 0
	v_mfma_f32_16x16x32_bf16 v[70:73], v[166:169], v[218:221], 0
	v_mfma_f32_16x16x32_bf16 v[66:69], v[174:177], v[218:221], 0
	v_mfma_f32_16x16x32_bf16 v[94:97], v[170:173], v[186:189], v[94:97]
	v_mfma_f32_16x16x32_bf16 v[90:93], v[178:181], v[186:189], v[90:93]
	v_mfma_f32_16x16x32_bf16 v[86:89], v[170:173], v[198:201], v[86:89]
	v_mfma_f32_16x16x32_bf16 v[82:85], v[178:181], v[198:201], v[82:85]
	v_mfma_f32_16x16x32_bf16 v[78:81], v[170:173], v[214:217], v[78:81]
	v_mfma_f32_16x16x32_bf16 v[74:77], v[178:181], v[214:217], v[74:77]
	v_mfma_f32_16x16x32_bf16 v[70:73], v[170:173], v[222:225], v[70:73]
	v_mfma_f32_16x16x32_bf16 v[66:69], v[178:181], v[222:225], v[66:69]
	s_setprio 0
	s_barrier
	s_add_i32 s23, s60, s33
	v_lshl_add_u64 v[202:203], s[34:35], 0, v[132:133]
	s_mov_b32 m0, s23
	ds_read_b128 v[182:185], v148 offset:16384
	ds_read_b128 v[186:189], v148 offset:17408
	ds_read_b128 v[190:193], v148 offset:18432
	ds_read_b128 v[198:201], v148 offset:19456
	ds_read_b128 v[210:213], v148 offset:20480
	ds_read_b128 v[214:217], v148 offset:21504
	ds_read_b128 v[218:221], v148 offset:22528
	ds_read_b128 v[222:225], v148 offset:23552
	global_load_lds_dwordx4 v[202:203], off
	s_add_i32 m0, s23, 0x2000
	s_add_u32 s38, s34, 0x80000
	v_lshl_add_u64 v[206:207], s[34:35], 0, v[136:137]
	s_addc_u32 s39, s35, 0
	s_add_i32 s23, s61, s33
	global_load_lds_dwordx4 v[206:207], off
	v_lshl_add_u64 v[226:227], s[38:39], 0, v[132:133]
	s_mov_b32 m0, s23
	v_lshl_add_u64 v[228:229], s[36:37], 0, v[134:135]
	global_load_lds_dwordx4 v[226:227], off
	v_lshl_add_u64 v[226:227], s[38:39], 0, v[136:137]
	s_add_i32 m0, s23, 0x2000
	s_nop 0
	global_load_lds_dwordx4 v[226:227], off
	v_lshl_add_u64 v[226:227], s[36:37], 0, v[130:131]
	s_mov_b32 m0, s15
	s_nop 0
	global_load_lds_dwordx4 v[226:227], off
	s_mov_b32 m0, s41
	s_nop 0
	global_load_lds_dwordx4 v[228:229], off
	s_waitcnt vmcnt(8)
	s_waitcnt lgkmcnt(0)
	s_barrier
	s_setprio 1
	v_mfma_f32_16x16x32_bf16 v[62:65], v[150:153], v[182:185], 0
	v_mfma_f32_16x16x32_bf16 v[58:61], v[158:161], v[182:185], 0
	v_mfma_f32_16x16x32_bf16 v[54:57], v[150:153], v[190:193], 0
	v_mfma_f32_16x16x32_bf16 v[50:53], v[158:161], v[190:193], 0
	v_mfma_f32_16x16x32_bf16 v[46:49], v[150:153], v[210:213], 0
	v_mfma_f32_16x16x32_bf16 v[42:45], v[158:161], v[210:213], 0
	v_mfma_f32_16x16x32_bf16 v[38:41], v[150:153], v[218:221], 0
	v_mfma_f32_16x16x32_bf16 v[34:37], v[158:161], v[218:221], 0
	v_mfma_f32_16x16x32_bf16 v[62:65], v[154:157], v[186:189], v[62:65]
	v_mfma_f32_16x16x32_bf16 v[58:61], v[162:165], v[186:189], v[58:61]
	v_mfma_f32_16x16x32_bf16 v[54:57], v[154:157], v[198:201], v[54:57]
	v_mfma_f32_16x16x32_bf16 v[50:53], v[162:165], v[198:201], v[50:53]
	v_mfma_f32_16x16x32_bf16 v[46:49], v[154:157], v[214:217], v[46:49]
	v_mfma_f32_16x16x32_bf16 v[42:45], v[162:165], v[214:217], v[42:45]
	v_mfma_f32_16x16x32_bf16 v[38:41], v[154:157], v[222:225], v[38:41]
	v_mfma_f32_16x16x32_bf16 v[34:37], v[162:165], v[222:225], v[34:37]
	s_setprio 0
	s_setprio 1
	v_mfma_f32_16x16x32_bf16 v[30:33], v[166:169], v[182:185], 0
	v_mfma_f32_16x16x32_bf16 v[26:29], v[174:177], v[182:185], 0
	v_mfma_f32_16x16x32_bf16 v[22:25], v[166:169], v[190:193], 0
	v_mfma_f32_16x16x32_bf16 v[18:21], v[174:177], v[190:193], 0
	v_mfma_f32_16x16x32_bf16 v[14:17], v[166:169], v[210:213], 0
	v_mfma_f32_16x16x32_bf16 v[10:13], v[174:177], v[210:213], 0
	v_mfma_f32_16x16x32_bf16 v[6:9], v[166:169], v[218:221], 0
	v_mfma_f32_16x16x32_bf16 v[2:5], v[174:177], v[218:221], 0
	v_mfma_f32_16x16x32_bf16 v[30:33], v[170:173], v[186:189], v[30:33]
	v_mfma_f32_16x16x32_bf16 v[26:29], v[178:181], v[186:189], v[26:29]
	v_mfma_f32_16x16x32_bf16 v[22:25], v[170:173], v[198:201], v[22:25]
	v_mfma_f32_16x16x32_bf16 v[18:21], v[178:181], v[198:201], v[18:21]
	v_mfma_f32_16x16x32_bf16 v[14:17], v[170:173], v[214:217], v[14:17]
	v_mfma_f32_16x16x32_bf16 v[10:13], v[178:181], v[214:217], v[10:13]
	v_mfma_f32_16x16x32_bf16 v[6:9], v[170:173], v[222:225], v[6:9]
	v_mfma_f32_16x16x32_bf16 v[2:5], v[178:181], v[222:225], v[2:5]
	s_setprio 0
	s_barrier
	s_add_i32 s23, 0, 0x18000
	v_add_u32_e32 v149, s23, v144
	s_add_i32 s38, 0, 0x1c000
	ds_read_b128 v[150:153], v149
	ds_read_b128 v[154:157], v149 offset:1024
	ds_read_b128 v[158:161], v149 offset:2048
	ds_read_b128 v[162:165], v149 offset:3072
	v_add_u32_e32 v149, s38, v144
	ds_read_b128 v[166:169], v149
	ds_read_b128 v[170:173], v149 offset:1024
	ds_read_b128 v[174:177], v149 offset:2048
	ds_read_b128 v[178:181], v149 offset:3072
	s_add_u32 s36, s36, 0x80000
	s_addc_u32 s37, s37, 0
	s_mov_b32 m0, s42
	v_lshl_add_u64 v[230:231], s[36:37], 0, v[130:131]
	ds_read_b128 v[182:185], v148 offset:32768
	ds_read_b128 v[186:189], v148 offset:33792
	ds_read_b128 v[190:193], v148 offset:34816
	ds_read_b128 v[198:201], v148 offset:35840
	ds_read_b128 v[210:213], v148 offset:36864
	ds_read_b128 v[214:217], v148 offset:37888
	ds_read_b128 v[218:221], v148 offset:38912
	ds_read_b128 v[222:225], v148 offset:39936
	global_load_lds_dwordx4 v[230:231], off
	v_lshl_add_u64 v[230:231], s[36:37], 0, v[134:135]
	s_mov_b32 m0, s43
	s_nop 0
	global_load_lds_dwordx4 v[230:231], off
	s_waitcnt vmcnt(8)
	s_waitcnt lgkmcnt(0)
	s_barrier
	s_setprio 1
	v_mfma_f32_16x16x32_bf16 v[126:129], v[150:153], v[182:185], v[126:129]
	v_mfma_f32_16x16x32_bf16 v[122:125], v[158:161], v[182:185], v[122:125]
	v_mfma_f32_16x16x32_bf16 v[118:121], v[150:153], v[190:193], v[118:121]
	v_mfma_f32_16x16x32_bf16 v[114:117], v[158:161], v[190:193], v[114:117]
	v_mfma_f32_16x16x32_bf16 v[110:113], v[150:153], v[210:213], v[110:113]
	v_mfma_f32_16x16x32_bf16 v[106:109], v[158:161], v[210:213], v[106:109]
	v_mfma_f32_16x16x32_bf16 v[102:105], v[150:153], v[218:221], v[102:105]
	v_mfma_f32_16x16x32_bf16 v[98:101], v[158:161], v[218:221], v[98:101]
	v_mfma_f32_16x16x32_bf16 v[126:129], v[154:157], v[186:189], v[126:129]
	v_mfma_f32_16x16x32_bf16 v[122:125], v[162:165], v[186:189], v[122:125]
	v_mfma_f32_16x16x32_bf16 v[118:121], v[154:157], v[198:201], v[118:121]
	v_mfma_f32_16x16x32_bf16 v[114:117], v[162:165], v[198:201], v[114:117]
	v_mfma_f32_16x16x32_bf16 v[110:113], v[154:157], v[214:217], v[110:113]
	v_mfma_f32_16x16x32_bf16 v[106:109], v[162:165], v[214:217], v[106:109]
	v_mfma_f32_16x16x32_bf16 v[102:105], v[154:157], v[222:225], v[102:105]
	v_mfma_f32_16x16x32_bf16 v[98:101], v[162:165], v[222:225], v[98:101]
	s_setprio 0
	s_setprio 1
	v_mfma_f32_16x16x32_bf16 v[94:97], v[166:169], v[182:185], v[94:97]
	v_mfma_f32_16x16x32_bf16 v[90:93], v[174:177], v[182:185], v[90:93]
	v_mfma_f32_16x16x32_bf16 v[86:89], v[166:169], v[190:193], v[86:89]
	v_mfma_f32_16x16x32_bf16 v[82:85], v[174:177], v[190:193], v[82:85]
	v_mfma_f32_16x16x32_bf16 v[78:81], v[166:169], v[210:213], v[78:81]
	v_mfma_f32_16x16x32_bf16 v[74:77], v[174:177], v[210:213], v[74:77]
	v_mfma_f32_16x16x32_bf16 v[70:73], v[166:169], v[218:221], v[70:73]
	v_mfma_f32_16x16x32_bf16 v[66:69], v[174:177], v[218:221], v[66:69]
	v_mfma_f32_16x16x32_bf16 v[94:97], v[170:173], v[186:189], v[94:97]
	v_mfma_f32_16x16x32_bf16 v[90:93], v[178:181], v[186:189], v[90:93]
	v_mfma_f32_16x16x32_bf16 v[86:89], v[170:173], v[198:201], v[86:89]
	v_mfma_f32_16x16x32_bf16 v[82:85], v[178:181], v[198:201], v[82:85]
	v_mfma_f32_16x16x32_bf16 v[78:81], v[170:173], v[214:217], v[78:81]
	v_mfma_f32_16x16x32_bf16 v[74:77], v[178:181], v[214:217], v[74:77]
	v_mfma_f32_16x16x32_bf16 v[70:73], v[170:173], v[222:225], v[70:73]
	v_mfma_f32_16x16x32_bf16 v[66:69], v[178:181], v[222:225], v[66:69]
	s_setprio 0
	s_barrier
	s_add_i32 s23, s23, s33
	v_lshl_add_u64 v[202:203], v[202:203], 0, s[10:11]
	s_mov_b32 m0, s23
	ds_read_b128 v[182:185], v148 offset:49152
	ds_read_b128 v[186:189], v148 offset:50176
	ds_read_b128 v[190:193], v148 offset:51200
	ds_read_b128 v[198:201], v148 offset:52224
	ds_read_b128 v[210:213], v148 offset:53248
	ds_read_b128 v[214:217], v148 offset:54272
	ds_read_b128 v[218:221], v148 offset:55296
	ds_read_b128 v[222:225], v148 offset:56320
	global_load_lds_dwordx4 v[202:203], off
	s_add_i32 m0, s23, 0x2000
	s_add_u32 s34, s34, 0x80080
	v_lshl_add_u64 v[202:203], v[206:207], 0, s[10:11]
	s_addc_u32 s35, s35, 0
	s_add_i32 s23, s38, s33
	global_load_lds_dwordx4 v[202:203], off
	v_lshl_add_u64 v[202:203], s[34:35], 0, v[132:133]
	s_mov_b32 m0, s23
	s_nop 0
	global_load_lds_dwordx4 v[202:203], off
	v_lshl_add_u64 v[202:203], s[34:35], 0, v[136:137]
	s_add_i32 m0, s23, 0x2000
	s_nop 0
	global_load_lds_dwordx4 v[202:203], off
	v_lshl_add_u64 v[202:203], v[226:227], 0, s[10:11]
	s_mov_b32 m0, s51
	s_nop 0
	global_load_lds_dwordx4 v[202:203], off
	v_lshl_add_u64 v[202:203], v[228:229], 0, s[10:11]
	s_mov_b32 m0, s52
	s_nop 0
	global_load_lds_dwordx4 v[202:203], off
	s_waitcnt vmcnt(8)
	s_waitcnt lgkmcnt(0)
	s_barrier
	s_setprio 1
	v_mfma_f32_16x16x32_bf16 v[62:65], v[150:153], v[182:185], v[62:65]
	v_mfma_f32_16x16x32_bf16 v[58:61], v[158:161], v[182:185], v[58:61]
	v_mfma_f32_16x16x32_bf16 v[54:57], v[150:153], v[190:193], v[54:57]
	v_mfma_f32_16x16x32_bf16 v[50:53], v[158:161], v[190:193], v[50:53]
	v_mfma_f32_16x16x32_bf16 v[46:49], v[150:153], v[210:213], v[46:49]
	v_mfma_f32_16x16x32_bf16 v[42:45], v[158:161], v[210:213], v[42:45]
	v_mfma_f32_16x16x32_bf16 v[38:41], v[150:153], v[218:221], v[38:41]
	v_mfma_f32_16x16x32_bf16 v[34:37], v[158:161], v[218:221], v[34:37]
	v_mfma_f32_16x16x32_bf16 v[62:65], v[154:157], v[186:189], v[62:65]
	v_mfma_f32_16x16x32_bf16 v[58:61], v[162:165], v[186:189], v[58:61]
	v_mfma_f32_16x16x32_bf16 v[54:57], v[154:157], v[198:201], v[54:57]
	v_mfma_f32_16x16x32_bf16 v[50:53], v[162:165], v[198:201], v[50:53]
	v_mfma_f32_16x16x32_bf16 v[46:49], v[154:157], v[214:217], v[46:49]
	v_mfma_f32_16x16x32_bf16 v[42:45], v[162:165], v[214:217], v[42:45]
	v_mfma_f32_16x16x32_bf16 v[38:41], v[154:157], v[222:225], v[38:41]
	v_mfma_f32_16x16x32_bf16 v[34:37], v[162:165], v[222:225], v[34:37]
	s_setprio 0
	s_setprio 1
	v_mfma_f32_16x16x32_bf16 v[30:33], v[166:169], v[182:185], v[30:33]
	v_mfma_f32_16x16x32_bf16 v[26:29], v[174:177], v[182:185], v[26:29]
	v_mfma_f32_16x16x32_bf16 v[22:25], v[166:169], v[190:193], v[22:25]
	v_mfma_f32_16x16x32_bf16 v[18:21], v[174:177], v[190:193], v[18:21]
	v_mfma_f32_16x16x32_bf16 v[14:17], v[166:169], v[210:213], v[14:17]
	v_mfma_f32_16x16x32_bf16 v[10:13], v[174:177], v[210:213], v[10:13]
	v_mfma_f32_16x16x32_bf16 v[6:9], v[166:169], v[218:221], v[6:9]
	v_mfma_f32_16x16x32_bf16 v[2:5], v[174:177], v[218:221], v[2:5]
	v_mfma_f32_16x16x32_bf16 v[30:33], v[170:173], v[186:189], v[30:33]
	v_mfma_f32_16x16x32_bf16 v[26:29], v[178:181], v[186:189], v[26:29]
	v_mfma_f32_16x16x32_bf16 v[22:25], v[170:173], v[198:201], v[22:25]
	v_mfma_f32_16x16x32_bf16 v[18:21], v[178:181], v[198:201], v[18:21]
	v_mfma_f32_16x16x32_bf16 v[14:17], v[170:173], v[214:217], v[14:17]
	v_mfma_f32_16x16x32_bf16 v[10:13], v[178:181], v[214:217], v[10:13]
	v_mfma_f32_16x16x32_bf16 v[6:9], v[170:173], v[222:225], v[6:9]
	v_mfma_f32_16x16x32_bf16 v[2:5], v[178:181], v[222:225], v[2:5]
	s_setprio 0
	s_barrier
	s_add_u32 s30, s30, 0x100
	s_addc_u32 s31, s31, 0
	s_add_u32 s19, s19, 0x100
	s_addc_u32 s21, s21, 0
	s_cmp_ge_i32 s29, s68
	s_mov_b32 s23, s29
	s_cbranch_scc0 .LBB0_1973
	s_branch .Lpeeldone_3
.LBB0_1973:
	ds_read_b128 v[150:153], v146
	ds_read_b128 v[154:157], v146 offset:1024
	ds_read_b128 v[158:161], v146 offset:2048
	ds_read_b128 v[162:165], v146 offset:3072
	ds_read_b128 v[166:169], v147
	ds_read_b128 v[170:173], v147 offset:1024
	ds_read_b128 v[174:177], v147 offset:2048
	ds_read_b128 v[178:181], v147 offset:3072
	s_add_i32 s29, s23, 2
	s_add_u32 s34, s30, 0xfff80080
	s_addc_u32 s35, s31, -1
	s_cmp_eq_u32 s28, s23
	s_cselect_b32 s37, s25, s35
	s_cselect_b32 s36, s24, s34
	s_cselect_b32 s35, s27, s21
	s_cselect_b32 s34, s26, s19
	v_lshl_add_u64 v[202:203], s[30:31], 0, v[140:141]
	s_add_i32 m0, s15, 0xc000
	ds_read_b128 v[182:185], v148
	ds_read_b128 v[186:189], v148 offset:1024
	ds_read_b128 v[190:193], v148 offset:2048
	ds_read_b128 v[198:201], v148 offset:3072
	ds_read_b128 v[210:213], v148 offset:4096
	ds_read_b128 v[214:217], v148 offset:5120
	ds_read_b128 v[218:221], v148 offset:6144
	ds_read_b128 v[222:225], v148 offset:7168
	global_load_lds_dwordx4 v[202:203], off
	v_lshl_add_u64 v[202:203], s[30:31], 0, v[142:143]
	s_add_i32 m0, s15, 0xe000
	s_nop 0
	global_load_lds_dwordx4 v[202:203], off
	s_waitcnt vmcnt(8)
	s_waitcnt lgkmcnt(0)
	s_barrier
	s_setprio 1
	v_mfma_f32_16x16x32_bf16 v[126:129], v[150:153], v[182:185], v[126:129]
	v_mfma_f32_16x16x32_bf16 v[122:125], v[158:161], v[182:185], v[122:125]
	v_mfma_f32_16x16x32_bf16 v[118:121], v[150:153], v[190:193], v[118:121]
	v_mfma_f32_16x16x32_bf16 v[114:117], v[158:161], v[190:193], v[114:117]
	v_mfma_f32_16x16x32_bf16 v[110:113], v[150:153], v[210:213], v[110:113]
	v_mfma_f32_16x16x32_bf16 v[106:109], v[158:161], v[210:213], v[106:109]
	v_mfma_f32_16x16x32_bf16 v[102:105], v[150:153], v[218:221], v[102:105]
	v_mfma_f32_16x16x32_bf16 v[98:101], v[158:161], v[218:221], v[98:101]
	v_mfma_f32_16x16x32_bf16 v[126:129], v[154:157], v[186:189], v[126:129]
	v_mfma_f32_16x16x32_bf16 v[122:125], v[162:165], v[186:189], v[122:125]
	v_mfma_f32_16x16x32_bf16 v[118:121], v[154:157], v[198:201], v[118:121]
	v_mfma_f32_16x16x32_bf16 v[114:117], v[162:165], v[198:201], v[114:117]
	v_mfma_f32_16x16x32_bf16 v[110:113], v[154:157], v[214:217], v[110:113]
	v_mfma_f32_16x16x32_bf16 v[106:109], v[162:165], v[214:217], v[106:109]
	v_mfma_f32_16x16x32_bf16 v[102:105], v[154:157], v[222:225], v[102:105]
	v_mfma_f32_16x16x32_bf16 v[98:101], v[162:165], v[222:225], v[98:101]
	s_setprio 0
	s_setprio 1
	v_mfma_f32_16x16x32_bf16 v[94:97], v[166:169], v[182:185], v[94:97]
	v_mfma_f32_16x16x32_bf16 v[90:93], v[174:177], v[182:185], v[90:93]
	v_mfma_f32_16x16x32_bf16 v[86:89], v[166:169], v[190:193], v[86:89]
	v_mfma_f32_16x16x32_bf16 v[82:85], v[174:177], v[190:193], v[82:85]
	v_mfma_f32_16x16x32_bf16 v[78:81], v[166:169], v[210:213], v[78:81]
	v_mfma_f32_16x16x32_bf16 v[74:77], v[174:177], v[210:213], v[74:77]
	v_mfma_f32_16x16x32_bf16 v[70:73], v[166:169], v[218:221], v[70:73]
	v_mfma_f32_16x16x32_bf16 v[66:69], v[174:177], v[218:221], v[66:69]
	v_mfma_f32_16x16x32_bf16 v[94:97], v[170:173], v[186:189], v[94:97]
	v_mfma_f32_16x16x32_bf16 v[90:93], v[178:181], v[186:189], v[90:93]
	v_mfma_f32_16x16x32_bf16 v[86:89], v[170:173], v[198:201], v[86:89]
	v_mfma_f32_16x16x32_bf16 v[82:85], v[178:181], v[198:201], v[82:85]
	v_mfma_f32_16x16x32_bf16 v[78:81], v[170:173], v[214:217], v[78:81]
	v_mfma_f32_16x16x32_bf16 v[74:77], v[178:181], v[214:217], v[74:77]
	v_mfma_f32_16x16x32_bf16 v[70:73], v[170:173], v[222:225], v[70:73]
	v_mfma_f32_16x16x32_bf16 v[66:69], v[178:181], v[222:225], v[66:69]
	s_setprio 0
	s_barrier
	s_add_i32 s23, s60, s33
	v_lshl_add_u64 v[202:203], s[34:35], 0, v[132:133]
	s_mov_b32 m0, s23
	ds_read_b128 v[182:185], v148 offset:16384
	ds_read_b128 v[186:189], v148 offset:17408
	ds_read_b128 v[190:193], v148 offset:18432
	ds_read_b128 v[198:201], v148 offset:19456
	ds_read_b128 v[210:213], v148 offset:20480
	ds_read_b128 v[214:217], v148 offset:21504
	ds_read_b128 v[218:221], v148 offset:22528
	ds_read_b128 v[222:225], v148 offset:23552
	global_load_lds_dwordx4 v[202:203], off
	s_add_i32 m0, s23, 0x2000
	s_add_u32 s38, s34, 0x80000
	v_lshl_add_u64 v[206:207], s[34:35], 0, v[136:137]
	s_addc_u32 s39, s35, 0
	s_add_i32 s23, s61, s33
	global_load_lds_dwordx4 v[206:207], off
	v_lshl_add_u64 v[226:227], s[38:39], 0, v[132:133]
	s_mov_b32 m0, s23
	v_lshl_add_u64 v[228:229], s[36:37], 0, v[134:135]
	global_load_lds_dwordx4 v[226:227], off
	v_lshl_add_u64 v[226:227], s[38:39], 0, v[136:137]
	s_add_i32 m0, s23, 0x2000
	s_nop 0
	global_load_lds_dwordx4 v[226:227], off
	v_lshl_add_u64 v[226:227], s[36:37], 0, v[130:131]
	s_mov_b32 m0, s15
	s_nop 0
	global_load_lds_dwordx4 v[226:227], off
	s_mov_b32 m0, s41
	s_nop 0
	global_load_lds_dwordx4 v[228:229], off
	s_waitcnt vmcnt(8)
	s_waitcnt lgkmcnt(0)
	s_barrier
	s_setprio 1
	v_mfma_f32_16x16x32_bf16 v[62:65], v[150:153], v[182:185], v[62:65]
	v_mfma_f32_16x16x32_bf16 v[58:61], v[158:161], v[182:185], v[58:61]
	v_mfma_f32_16x16x32_bf16 v[54:57], v[150:153], v[190:193], v[54:57]
	v_mfma_f32_16x16x32_bf16 v[50:53], v[158:161], v[190:193], v[50:53]
	v_mfma_f32_16x16x32_bf16 v[46:49], v[150:153], v[210:213], v[46:49]
	v_mfma_f32_16x16x32_bf16 v[42:45], v[158:161], v[210:213], v[42:45]
	v_mfma_f32_16x16x32_bf16 v[38:41], v[150:153], v[218:221], v[38:41]
	v_mfma_f32_16x16x32_bf16 v[34:37], v[158:161], v[218:221], v[34:37]
	v_mfma_f32_16x16x32_bf16 v[62:65], v[154:157], v[186:189], v[62:65]
	v_mfma_f32_16x16x32_bf16 v[58:61], v[162:165], v[186:189], v[58:61]
	v_mfma_f32_16x16x32_bf16 v[54:57], v[154:157], v[198:201], v[54:57]
	v_mfma_f32_16x16x32_bf16 v[50:53], v[162:165], v[198:201], v[50:53]
	v_mfma_f32_16x16x32_bf16 v[46:49], v[154:157], v[214:217], v[46:49]
	v_mfma_f32_16x16x32_bf16 v[42:45], v[162:165], v[214:217], v[42:45]
	v_mfma_f32_16x16x32_bf16 v[38:41], v[154:157], v[222:225], v[38:41]
	v_mfma_f32_16x16x32_bf16 v[34:37], v[162:165], v[222:225], v[34:37]
	s_setprio 0
	s_setprio 1
	v_mfma_f32_16x16x32_bf16 v[30:33], v[166:169], v[182:185], v[30:33]
	v_mfma_f32_16x16x32_bf16 v[26:29], v[174:177], v[182:185], v[26:29]
	v_mfma_f32_16x16x32_bf16 v[22:25], v[166:169], v[190:193], v[22:25]
	v_mfma_f32_16x16x32_bf16 v[18:21], v[174:177], v[190:193], v[18:21]
	v_mfma_f32_16x16x32_bf16 v[14:17], v[166:169], v[210:213], v[14:17]
	v_mfma_f32_16x16x32_bf16 v[10:13], v[174:177], v[210:213], v[10:13]
	v_mfma_f32_16x16x32_bf16 v[6:9], v[166:169], v[218:221], v[6:9]
	v_mfma_f32_16x16x32_bf16 v[2:5], v[174:177], v[218:221], v[2:5]
	v_mfma_f32_16x16x32_bf16 v[30:33], v[170:173], v[186:189], v[30:33]
	v_mfma_f32_16x16x32_bf16 v[26:29], v[178:181], v[186:189], v[26:29]
	v_mfma_f32_16x16x32_bf16 v[22:25], v[170:173], v[198:201], v[22:25]
	v_mfma_f32_16x16x32_bf16 v[18:21], v[178:181], v[198:201], v[18:21]
	v_mfma_f32_16x16x32_bf16 v[14:17], v[170:173], v[214:217], v[14:17]
	v_mfma_f32_16x16x32_bf16 v[10:13], v[178:181], v[214:217], v[10:13]
	v_mfma_f32_16x16x32_bf16 v[6:9], v[170:173], v[222:225], v[6:9]
	v_mfma_f32_16x16x32_bf16 v[2:5], v[178:181], v[222:225], v[2:5]
	s_setprio 0
	s_barrier
	s_add_i32 s23, 0, 0x18000
	v_add_u32_e32 v149, s23, v144
	s_add_i32 s38, 0, 0x1c000
	ds_read_b128 v[150:153], v149
	ds_read_b128 v[154:157], v149 offset:1024
	ds_read_b128 v[158:161], v149 offset:2048
	ds_read_b128 v[162:165], v149 offset:3072
	v_add_u32_e32 v149, s38, v144
	ds_read_b128 v[166:169], v149
	ds_read_b128 v[170:173], v149 offset:1024
	ds_read_b128 v[174:177], v149 offset:2048
	ds_read_b128 v[178:181], v149 offset:3072
	s_add_u32 s36, s36, 0x80000
	s_addc_u32 s37, s37, 0
	s_mov_b32 m0, s42
	v_lshl_add_u64 v[230:231], s[36:37], 0, v[130:131]
	ds_read_b128 v[182:185], v148 offset:32768
	ds_read_b128 v[186:189], v148 offset:33792
	ds_read_b128 v[190:193], v148 offset:34816
	ds_read_b128 v[198:201], v148 offset:35840
	ds_read_b128 v[210:213], v148 offset:36864
	ds_read_b128 v[214:217], v148 offset:37888
	ds_read_b128 v[218:221], v148 offset:38912
	ds_read_b128 v[222:225], v148 offset:39936
	global_load_lds_dwordx4 v[230:231], off
	v_lshl_add_u64 v[230:231], s[36:37], 0, v[134:135]
	s_mov_b32 m0, s43
	s_nop 0
	global_load_lds_dwordx4 v[230:231], off
	s_waitcnt vmcnt(8)
	s_waitcnt lgkmcnt(0)
	s_barrier
	s_setprio 1
	v_mfma_f32_16x16x32_bf16 v[126:129], v[150:153], v[182:185], v[126:129]
	v_mfma_f32_16x16x32_bf16 v[122:125], v[158:161], v[182:185], v[122:125]
	v_mfma_f32_16x16x32_bf16 v[118:121], v[150:153], v[190:193], v[118:121]
	v_mfma_f32_16x16x32_bf16 v[114:117], v[158:161], v[190:193], v[114:117]
	v_mfma_f32_16x16x32_bf16 v[110:113], v[150:153], v[210:213], v[110:113]
	v_mfma_f32_16x16x32_bf16 v[106:109], v[158:161], v[210:213], v[106:109]
	v_mfma_f32_16x16x32_bf16 v[102:105], v[150:153], v[218:221], v[102:105]
	v_mfma_f32_16x16x32_bf16 v[98:101], v[158:161], v[218:221], v[98:101]
	v_mfma_f32_16x16x32_bf16 v[126:129], v[154:157], v[186:189], v[126:129]
	v_mfma_f32_16x16x32_bf16 v[122:125], v[162:165], v[186:189], v[122:125]
	v_mfma_f32_16x16x32_bf16 v[118:121], v[154:157], v[198:201], v[118:121]
	v_mfma_f32_16x16x32_bf16 v[114:117], v[162:165], v[198:201], v[114:117]
	v_mfma_f32_16x16x32_bf16 v[110:113], v[154:157], v[214:217], v[110:113]
	v_mfma_f32_16x16x32_bf16 v[106:109], v[162:165], v[214:217], v[106:109]
	v_mfma_f32_16x16x32_bf16 v[102:105], v[154:157], v[222:225], v[102:105]
	v_mfma_f32_16x16x32_bf16 v[98:101], v[162:165], v[222:225], v[98:101]
	s_setprio 0
	s_setprio 1
	v_mfma_f32_16x16x32_bf16 v[94:97], v[166:169], v[182:185], v[94:97]
	v_mfma_f32_16x16x32_bf16 v[90:93], v[174:177], v[182:185], v[90:93]
	v_mfma_f32_16x16x32_bf16 v[86:89], v[166:169], v[190:193], v[86:89]
	v_mfma_f32_16x16x32_bf16 v[82:85], v[174:177], v[190:193], v[82:85]
	v_mfma_f32_16x16x32_bf16 v[78:81], v[166:169], v[210:213], v[78:81]
	v_mfma_f32_16x16x32_bf16 v[74:77], v[174:177], v[210:213], v[74:77]
	v_mfma_f32_16x16x32_bf16 v[70:73], v[166:169], v[218:221], v[70:73]
	v_mfma_f32_16x16x32_bf16 v[66:69], v[174:177], v[218:221], v[66:69]
	v_mfma_f32_16x16x32_bf16 v[94:97], v[170:173], v[186:189], v[94:97]
	v_mfma_f32_16x16x32_bf16 v[90:93], v[178:181], v[186:189], v[90:93]
	v_mfma_f32_16x16x32_bf16 v[86:89], v[170:173], v[198:201], v[86:89]
	v_mfma_f32_16x16x32_bf16 v[82:85], v[178:181], v[198:201], v[82:85]
	v_mfma_f32_16x16x32_bf16 v[78:81], v[170:173], v[214:217], v[78:81]
	v_mfma_f32_16x16x32_bf16 v[74:77], v[178:181], v[214:217], v[74:77]
	v_mfma_f32_16x16x32_bf16 v[70:73], v[170:173], v[222:225], v[70:73]
	v_mfma_f32_16x16x32_bf16 v[66:69], v[178:181], v[222:225], v[66:69]
	s_setprio 0
	s_barrier
	s_add_i32 s23, s23, s33
	v_lshl_add_u64 v[202:203], v[202:203], 0, s[10:11]
	s_mov_b32 m0, s23
	ds_read_b128 v[182:185], v148 offset:49152
	ds_read_b128 v[186:189], v148 offset:50176
	ds_read_b128 v[190:193], v148 offset:51200
	ds_read_b128 v[198:201], v148 offset:52224
	ds_read_b128 v[210:213], v148 offset:53248
	ds_read_b128 v[214:217], v148 offset:54272
	ds_read_b128 v[218:221], v148 offset:55296
	ds_read_b128 v[222:225], v148 offset:56320
	global_load_lds_dwordx4 v[202:203], off
	s_add_i32 m0, s23, 0x2000
	s_add_u32 s34, s34, 0x80080
	v_lshl_add_u64 v[202:203], v[206:207], 0, s[10:11]
	s_addc_u32 s35, s35, 0
	s_add_i32 s23, s38, s33
	global_load_lds_dwordx4 v[202:203], off
	v_lshl_add_u64 v[202:203], s[34:35], 0, v[132:133]
	s_mov_b32 m0, s23
	s_nop 0
	global_load_lds_dwordx4 v[202:203], off
	v_lshl_add_u64 v[202:203], s[34:35], 0, v[136:137]
	s_add_i32 m0, s23, 0x2000
	s_nop 0
	global_load_lds_dwordx4 v[202:203], off
	v_lshl_add_u64 v[202:203], v[226:227], 0, s[10:11]
	s_mov_b32 m0, s51
	s_nop 0
	global_load_lds_dwordx4 v[202:203], off
	v_lshl_add_u64 v[202:203], v[228:229], 0, s[10:11]
	s_mov_b32 m0, s52
	s_nop 0
	global_load_lds_dwordx4 v[202:203], off
	s_waitcnt vmcnt(8)
	s_waitcnt lgkmcnt(0)
	s_barrier
	s_setprio 1
	v_mfma_f32_16x16x32_bf16 v[62:65], v[150:153], v[182:185], v[62:65]
	v_mfma_f32_16x16x32_bf16 v[58:61], v[158:161], v[182:185], v[58:61]
	v_mfma_f32_16x16x32_bf16 v[54:57], v[150:153], v[190:193], v[54:57]
	v_mfma_f32_16x16x32_bf16 v[50:53], v[158:161], v[190:193], v[50:53]
	v_mfma_f32_16x16x32_bf16 v[46:49], v[150:153], v[210:213], v[46:49]
	v_mfma_f32_16x16x32_bf16 v[42:45], v[158:161], v[210:213], v[42:45]
	v_mfma_f32_16x16x32_bf16 v[38:41], v[150:153], v[218:221], v[38:41]
	v_mfma_f32_16x16x32_bf16 v[34:37], v[158:161], v[218:221], v[34:37]
	v_mfma_f32_16x16x32_bf16 v[62:65], v[154:157], v[186:189], v[62:65]
	v_mfma_f32_16x16x32_bf16 v[58:61], v[162:165], v[186:189], v[58:61]
	v_mfma_f32_16x16x32_bf16 v[54:57], v[154:157], v[198:201], v[54:57]
	v_mfma_f32_16x16x32_bf16 v[50:53], v[162:165], v[198:201], v[50:53]
	v_mfma_f32_16x16x32_bf16 v[46:49], v[154:157], v[214:217], v[46:49]
	v_mfma_f32_16x16x32_bf16 v[42:45], v[162:165], v[214:217], v[42:45]
	v_mfma_f32_16x16x32_bf16 v[38:41], v[154:157], v[222:225], v[38:41]
	v_mfma_f32_16x16x32_bf16 v[34:37], v[162:165], v[222:225], v[34:37]
	s_setprio 0
	s_setprio 1
	v_mfma_f32_16x16x32_bf16 v[30:33], v[166:169], v[182:185], v[30:33]
	v_mfma_f32_16x16x32_bf16 v[26:29], v[174:177], v[182:185], v[26:29]
	v_mfma_f32_16x16x32_bf16 v[22:25], v[166:169], v[190:193], v[22:25]
	v_mfma_f32_16x16x32_bf16 v[18:21], v[174:177], v[190:193], v[18:21]
	v_mfma_f32_16x16x32_bf16 v[14:17], v[166:169], v[210:213], v[14:17]
	v_mfma_f32_16x16x32_bf16 v[10:13], v[174:177], v[210:213], v[10:13]
	v_mfma_f32_16x16x32_bf16 v[6:9], v[166:169], v[218:221], v[6:9]
	v_mfma_f32_16x16x32_bf16 v[2:5], v[174:177], v[218:221], v[2:5]
	v_mfma_f32_16x16x32_bf16 v[30:33], v[170:173], v[186:189], v[30:33]
	v_mfma_f32_16x16x32_bf16 v[26:29], v[178:181], v[186:189], v[26:29]
	v_mfma_f32_16x16x32_bf16 v[22:25], v[170:173], v[198:201], v[22:25]
	v_mfma_f32_16x16x32_bf16 v[18:21], v[178:181], v[198:201], v[18:21]
	v_mfma_f32_16x16x32_bf16 v[14:17], v[170:173], v[214:217], v[14:17]
	v_mfma_f32_16x16x32_bf16 v[10:13], v[178:181], v[214:217], v[10:13]
	v_mfma_f32_16x16x32_bf16 v[6:9], v[170:173], v[222:225], v[6:9]
	v_mfma_f32_16x16x32_bf16 v[2:5], v[178:181], v[222:225], v[2:5]
	s_setprio 0
	s_barrier
	s_add_u32 s30, s30, 0x100
	s_addc_u32 s31, s31, 0
	s_add_u32 s19, s19, 0x100
	s_addc_u32 s21, s21, 0
	s_cmp_ge_i32 s29, s68
	s_mov_b32 s23, s29
	s_cbranch_scc0 .LBB0_1973

.Lpeel_1:
	ds_read_b128 v[152:155], v148
	ds_read_b128 v[156:159], v148 offset:1024
	s_add_i32 s29, s19, 2
	s_add_u32 s34, s30, 0xfff80080
	s_addc_u32 s35, s31, -1
	s_cmp_eq_u32 s28, s19
	s_cselect_b32 s37, s21, s35
	s_cselect_b32 s36, s20, s34
	s_cselect_b32 s35, s23, s17
	s_cselect_b32 s34, s22, s15
	v_lshl_add_u64 v[144:145], s[30:31], 0, v[140:141]
	s_add_i32 m0, s27, 0xc000
	global_load_lds_dwordx4 v[144:145], off
	v_lshl_add_u64 v[144:145], s[30:31], 0, v[142:143]
	s_add_i32 m0, s27, 0xe000
	s_nop 0
	global_load_lds_dwordx4 v[144:145], off
	s_waitcnt vmcnt(8)
	s_waitcnt lgkmcnt(0)
	s_barrier
	s_setprio 1
	v_mfma_f32_16x16x32_bf16 v[126:129], v[152:155], v[184:187], 0
	v_mfma_f32_16x16x32_bf16 v[122:125], v[160:163], v[184:187], 0
	v_mfma_f32_16x16x32_bf16 v[110:113], v[152:155], v[192:195], 0
	v_mfma_f32_16x16x32_bf16 v[106:109], v[160:163], v[192:195], 0
	v_mfma_f32_16x16x32_bf16 v[94:97], v[152:155], v[210:213], 0
	v_mfma_f32_16x16x32_bf16 v[90:93], v[160:163], v[210:213], 0
	v_mfma_f32_16x16x32_bf16 v[78:81], v[152:155], v[218:221], 0
	v_mfma_f32_16x16x32_bf16 v[74:77], v[160:163], v[218:221], 0
	v_mfma_f32_16x16x32_bf16 v[126:129], v[156:159], v[188:191], v[126:129]
	v_mfma_f32_16x16x32_bf16 v[122:125], v[164:167], v[188:191], v[122:125]
	v_mfma_f32_16x16x32_bf16 v[110:113], v[156:159], v[198:201], v[110:113]
	v_mfma_f32_16x16x32_bf16 v[106:109], v[164:167], v[198:201], v[106:109]
	v_mfma_f32_16x16x32_bf16 v[94:97], v[156:159], v[214:217], v[94:97]
	v_mfma_f32_16x16x32_bf16 v[90:93], v[164:167], v[214:217], v[90:93]
	v_mfma_f32_16x16x32_bf16 v[78:81], v[156:159], v[222:225], v[78:81]
	v_mfma_f32_16x16x32_bf16 v[74:77], v[164:167], v[222:225], v[74:77]
	s_setprio 0
	s_setprio 1
	v_mfma_f32_16x16x32_bf16 v[118:121], v[168:171], v[184:187], 0
	v_mfma_f32_16x16x32_bf16 v[114:117], v[176:179], v[184:187], 0
	v_mfma_f32_16x16x32_bf16 v[102:105], v[168:171], v[192:195], 0
	v_mfma_f32_16x16x32_bf16 v[98:101], v[176:179], v[192:195], 0
	v_mfma_f32_16x16x32_bf16 v[86:89], v[168:171], v[210:213], 0
	v_mfma_f32_16x16x32_bf16 v[82:85], v[176:179], v[210:213], 0
	v_mfma_f32_16x16x32_bf16 v[70:73], v[168:171], v[218:221], 0
	v_mfma_f32_16x16x32_bf16 v[66:69], v[176:179], v[218:221], 0
	v_mfma_f32_16x16x32_bf16 v[118:121], v[172:175], v[188:191], v[118:121]
	v_mfma_f32_16x16x32_bf16 v[114:117], v[180:183], v[188:191], v[114:117]
	v_mfma_f32_16x16x32_bf16 v[102:105], v[172:175], v[198:201], v[102:105]
	v_mfma_f32_16x16x32_bf16 v[98:101], v[180:183], v[198:201], v[98:101]
	v_mfma_f32_16x16x32_bf16 v[86:89], v[172:175], v[214:217], v[86:89]
	v_mfma_f32_16x16x32_bf16 v[82:85], v[180:183], v[214:217], v[82:85]
	v_mfma_f32_16x16x32_bf16 v[70:73], v[172:175], v[222:225], v[70:73]
	v_mfma_f32_16x16x32_bf16 v[66:69], v[180:183], v[222:225], v[66:69]
	s_setprio 0
	s_barrier
	s_add_i32 s19, s60, s33
	v_lshl_add_u64 v[144:145], s[34:35], 0, v[132:133]
	s_mov_b32 m0, s19
	ds_read_b128 v[184:187], v150 offset:16384
	ds_read_b128 v[188:191], v150 offset:17408
	ds_read_b128 v[192:195], v150 offset:18432
	ds_read_b128 v[198:201], v150 offset:19456
	ds_read_b128 v[210:213], v150 offset:20480
	ds_read_b128 v[214:217], v150 offset:21504
	ds_read_b128 v[218:221], v150 offset:22528
	ds_read_b128 v[222:225], v150 offset:23552
	global_load_lds_dwordx4 v[144:145], off
	s_add_i32 m0, s19, 0x2000
	s_add_u32 s38, s34, 0x80000
	v_lshl_add_u64 v[202:203], s[34:35], 0, v[136:137]
	s_addc_u32 s39, s35, 0
	s_add_i32 s19, s61, s33
	global_load_lds_dwordx4 v[202:203], off
	v_lshl_add_u64 v[206:207], s[38:39], 0, v[132:133]
	s_mov_b32 m0, s19
	v_lshl_add_u64 v[226:227], s[36:37], 0, v[134:135]
	global_load_lds_dwordx4 v[206:207], off
	v_lshl_add_u64 v[206:207], s[38:39], 0, v[136:137]
	s_add_i32 m0, s19, 0x2000
	s_nop 0
	global_load_lds_dwordx4 v[206:207], off
	v_lshl_add_u64 v[206:207], s[36:37], 0, v[130:131]
	s_mov_b32 m0, s27
	s_nop 0
	global_load_lds_dwordx4 v[206:207], off
	s_mov_b32 m0, s41
	s_nop 0
	global_load_lds_dwordx4 v[226:227], off
	s_waitcnt vmcnt(8)
	s_waitcnt lgkmcnt(0)
	s_barrier
	s_setprio 1
	v_mfma_f32_16x16x32_bf16 v[62:65], v[152:155], v[184:187], 0
	v_mfma_f32_16x16x32_bf16 v[58:61], v[160:163], v[184:187], 0
	v_mfma_f32_16x16x32_bf16 v[46:49], v[152:155], v[192:195], 0
	v_mfma_f32_16x16x32_bf16 v[42:45], v[160:163], v[192:195], 0
	v_mfma_f32_16x16x32_bf16 v[30:33], v[152:155], v[210:213], 0
	v_mfma_f32_16x16x32_bf16 v[26:29], v[160:163], v[210:213], 0
	v_mfma_f32_16x16x32_bf16 v[14:17], v[152:155], v[218:221], 0
	v_mfma_f32_16x16x32_bf16 v[10:13], v[160:163], v[218:221], 0
	v_mfma_f32_16x16x32_bf16 v[62:65], v[156:159], v[188:191], v[62:65]
	v_mfma_f32_16x16x32_bf16 v[58:61], v[164:167], v[188:191], v[58:61]
	v_mfma_f32_16x16x32_bf16 v[46:49], v[156:159], v[198:201], v[46:49]
	v_mfma_f32_16x16x32_bf16 v[42:45], v[164:167], v[198:201], v[42:45]
	v_mfma_f32_16x16x32_bf16 v[30:33], v[156:159], v[214:217], v[30:33]
	v_mfma_f32_16x16x32_bf16 v[26:29], v[164:167], v[214:217], v[26:29]
	v_mfma_f32_16x16x32_bf16 v[14:17], v[156:159], v[222:225], v[14:17]
	v_mfma_f32_16x16x32_bf16 v[10:13], v[164:167], v[222:225], v[10:13]
	s_setprio 0
	s_setprio 1
	v_mfma_f32_16x16x32_bf16 v[54:57], v[168:171], v[184:187], 0
	v_mfma_f32_16x16x32_bf16 v[50:53], v[176:179], v[184:187], 0
	v_mfma_f32_16x16x32_bf16 v[38:41], v[168:171], v[192:195], 0
	v_mfma_f32_16x16x32_bf16 v[34:37], v[176:179], v[192:195], 0
	v_mfma_f32_16x16x32_bf16 v[22:25], v[168:171], v[210:213], 0
	v_mfma_f32_16x16x32_bf16 v[18:21], v[176:179], v[210:213], 0
	v_mfma_f32_16x16x32_bf16 v[6:9], v[168:171], v[218:221], 0
	v_mfma_f32_16x16x32_bf16 v[2:5], v[176:179], v[218:221], 0
	v_mfma_f32_16x16x32_bf16 v[54:57], v[172:175], v[188:191], v[54:57]
	v_mfma_f32_16x16x32_bf16 v[50:53], v[180:183], v[188:191], v[50:53]
	v_mfma_f32_16x16x32_bf16 v[38:41], v[172:175], v[198:201], v[38:41]
	v_mfma_f32_16x16x32_bf16 v[34:37], v[180:183], v[198:201], v[34:37]
	v_mfma_f32_16x16x32_bf16 v[22:25], v[172:175], v[214:217], v[22:25]
	v_mfma_f32_16x16x32_bf16 v[18:21], v[180:183], v[214:217], v[18:21]
	v_mfma_f32_16x16x32_bf16 v[6:9], v[172:175], v[222:225], v[6:9]
	v_mfma_f32_16x16x32_bf16 v[2:5], v[180:183], v[222:225], v[2:5]
	s_setprio 0
	s_barrier
	s_add_i32 s19, 0, 0x18000
	v_add_u32_e32 v151, s19, v146
	s_add_i32 s38, 0, 0x1c000
	ds_read_b128 v[152:155], v151
	ds_read_b128 v[156:159], v151 offset:1024
	ds_read_b128 v[160:163], v151 offset:2048
	ds_read_b128 v[164:167], v151 offset:3072
	v_add_u32_e32 v151, s38, v146
	ds_read_b128 v[168:171], v151
	ds_read_b128 v[172:175], v151 offset:1024
	ds_read_b128 v[176:179], v151 offset:2048
	ds_read_b128 v[180:183], v151 offset:3072
	s_add_u32 s36, s36, 0x80000
	s_addc_u32 s37, s37, 0
	s_mov_b32 m0, s42
	v_lshl_add_u64 v[228:229], s[36:37], 0, v[130:131]
	ds_read_b128 v[184:187], v150 offset:32768
	ds_read_b128 v[188:191], v150 offset:33792
	ds_read_b128 v[192:195], v150 offset:34816
	ds_read_b128 v[198:201], v150 offset:35840
	ds_read_b128 v[210:213], v150 offset:36864
	ds_read_b128 v[214:217], v150 offset:37888
	ds_read_b128 v[218:221], v150 offset:38912
	ds_read_b128 v[222:225], v150 offset:39936
	global_load_lds_dwordx4 v[228:229], off
	v_lshl_add_u64 v[228:229], s[36:37], 0, v[134:135]
	s_mov_b32 m0, s43
	s_nop 0
	global_load_lds_dwordx4 v[228:229], off
	s_waitcnt vmcnt(8)
	s_waitcnt lgkmcnt(0)
	s_barrier
	s_setprio 1
	v_mfma_f32_16x16x32_bf16 v[126:129], v[152:155], v[184:187], v[126:129]
	v_mfma_f32_16x16x32_bf16 v[122:125], v[160:163], v[184:187], v[122:125]
	v_mfma_f32_16x16x32_bf16 v[110:113], v[152:155], v[192:195], v[110:113]
	v_mfma_f32_16x16x32_bf16 v[106:109], v[160:163], v[192:195], v[106:109]
	v_mfma_f32_16x16x32_bf16 v[94:97], v[152:155], v[210:213], v[94:97]
	v_mfma_f32_16x16x32_bf16 v[90:93], v[160:163], v[210:213], v[90:93]
	v_mfma_f32_16x16x32_bf16 v[78:81], v[152:155], v[218:221], v[78:81]
	v_mfma_f32_16x16x32_bf16 v[74:77], v[160:163], v[218:221], v[74:77]
	v_mfma_f32_16x16x32_bf16 v[126:129], v[156:159], v[188:191], v[126:129]
	v_mfma_f32_16x16x32_bf16 v[122:125], v[164:167], v[188:191], v[122:125]
	v_mfma_f32_16x16x32_bf16 v[110:113], v[156:159], v[198:201], v[110:113]
	v_mfma_f32_16x16x32_bf16 v[106:109], v[164:167], v[198:201], v[106:109]
	v_mfma_f32_16x16x32_bf16 v[94:97], v[156:159], v[214:217], v[94:97]
	v_mfma_f32_16x16x32_bf16 v[90:93], v[164:167], v[214:217], v[90:93]
	v_mfma_f32_16x16x32_bf16 v[78:81], v[156:159], v[222:225], v[78:81]
	v_mfma_f32_16x16x32_bf16 v[74:77], v[164:167], v[222:225], v[74:77]
	s_setprio 0
	s_setprio 1
	v_mfma_f32_16x16x32_bf16 v[118:121], v[168:171], v[184:187], v[118:121]
	v_mfma_f32_16x16x32_bf16 v[114:117], v[176:179], v[184:187], v[114:117]
	v_mfma_f32_16x16x32_bf16 v[102:105], v[168:171], v[192:195], v[102:105]
	v_mfma_f32_16x16x32_bf16 v[98:101], v[176:179], v[192:195], v[98:101]
	v_mfma_f32_16x16x32_bf16 v[86:89], v[168:171], v[210:213], v[86:89]
	v_mfma_f32_16x16x32_bf16 v[82:85], v[176:179], v[210:213], v[82:85]
	v_mfma_f32_16x16x32_bf16 v[70:73], v[168:171], v[218:221], v[70:73]
	v_mfma_f32_16x16x32_bf16 v[66:69], v[176:179], v[218:221], v[66:69]
	v_mfma_f32_16x16x32_bf16 v[118:121], v[172:175], v[188:191], v[118:121]
	v_mfma_f32_16x16x32_bf16 v[114:117], v[180:183], v[188:191], v[114:117]
	v_mfma_f32_16x16x32_bf16 v[102:105], v[172:175], v[198:201], v[102:105]
	v_mfma_f32_16x16x32_bf16 v[98:101], v[180:183], v[198:201], v[98:101]
	v_mfma_f32_16x16x32_bf16 v[86:89], v[172:175], v[214:217], v[86:89]
	v_mfma_f32_16x16x32_bf16 v[82:85], v[180:183], v[214:217], v[82:85]
	v_mfma_f32_16x16x32_bf16 v[70:73], v[172:175], v[222:225], v[70:73]
	v_mfma_f32_16x16x32_bf16 v[66:69], v[180:183], v[222:225], v[66:69]
	s_setprio 0
	s_barrier
	s_add_i32 s19, s19, s33
	v_lshl_add_u64 v[144:145], v[144:145], 0, s[10:11]
	s_mov_b32 m0, s19
	ds_read_b128 v[184:187], v150 offset:49152
	ds_read_b128 v[188:191], v150 offset:50176
	ds_read_b128 v[192:195], v150 offset:51200
	ds_read_b128 v[198:201], v150 offset:52224
	ds_read_b128 v[210:213], v150 offset:53248
	ds_read_b128 v[214:217], v150 offset:54272
	ds_read_b128 v[218:221], v150 offset:55296
	ds_read_b128 v[222:225], v150 offset:56320
	global_load_lds_dwordx4 v[144:145], off
	s_add_i32 m0, s19, 0x2000
	s_add_u32 s34, s34, 0x80080
	v_lshl_add_u64 v[144:145], v[202:203], 0, s[10:11]
	s_addc_u32 s35, s35, 0
	s_add_i32 s19, s38, s33
	global_load_lds_dwordx4 v[144:145], off
	v_lshl_add_u64 v[144:145], s[34:35], 0, v[132:133]
	s_mov_b32 m0, s19
	s_nop 0
	global_load_lds_dwordx4 v[144:145], off
	v_lshl_add_u64 v[144:145], s[34:35], 0, v[136:137]
	s_add_i32 m0, s19, 0x2000
	s_nop 0
	global_load_lds_dwordx4 v[144:145], off
	v_lshl_add_u64 v[144:145], v[206:207], 0, s[10:11]
	s_mov_b32 m0, s51
	s_nop 0
	global_load_lds_dwordx4 v[144:145], off
	v_lshl_add_u64 v[144:145], v[226:227], 0, s[10:11]
	s_mov_b32 m0, s52
	s_nop 0
	global_load_lds_dwordx4 v[144:145], off
	s_waitcnt vmcnt(8)
	s_waitcnt lgkmcnt(0)
	s_barrier
	s_setprio 1
	v_mfma_f32_16x16x32_bf16 v[62:65], v[152:155], v[184:187], v[62:65]
	v_mfma_f32_16x16x32_bf16 v[58:61], v[160:163], v[184:187], v[58:61]
	v_mfma_f32_16x16x32_bf16 v[46:49], v[152:155], v[192:195], v[46:49]
	v_mfma_f32_16x16x32_bf16 v[42:45], v[160:163], v[192:195], v[42:45]
	v_mfma_f32_16x16x32_bf16 v[30:33], v[152:155], v[210:213], v[30:33]
	v_mfma_f32_16x16x32_bf16 v[26:29], v[160:163], v[210:213], v[26:29]
	v_mfma_f32_16x16x32_bf16 v[14:17], v[152:155], v[218:221], v[14:17]
	v_mfma_f32_16x16x32_bf16 v[10:13], v[160:163], v[218:221], v[10:13]
	v_mfma_f32_16x16x32_bf16 v[62:65], v[156:159], v[188:191], v[62:65]
	v_mfma_f32_16x16x32_bf16 v[58:61], v[164:167], v[188:191], v[58:61]
	v_mfma_f32_16x16x32_bf16 v[46:49], v[156:159], v[198:201], v[46:49]
	v_mfma_f32_16x16x32_bf16 v[42:45], v[164:167], v[198:201], v[42:45]
	v_mfma_f32_16x16x32_bf16 v[30:33], v[156:159], v[214:217], v[30:33]
	v_mfma_f32_16x16x32_bf16 v[26:29], v[164:167], v[214:217], v[26:29]
	v_mfma_f32_16x16x32_bf16 v[14:17], v[156:159], v[222:225], v[14:17]
	v_mfma_f32_16x16x32_bf16 v[10:13], v[164:167], v[222:225], v[10:13]
	s_setprio 0
	s_setprio 1
	v_mfma_f32_16x16x32_bf16 v[54:57], v[168:171], v[184:187], v[54:57]
	v_mfma_f32_16x16x32_bf16 v[50:53], v[176:179], v[184:187], v[50:53]
	v_mfma_f32_16x16x32_bf16 v[38:41], v[168:171], v[192:195], v[38:41]
	v_mfma_f32_16x16x32_bf16 v[34:37], v[176:179], v[192:195], v[34:37]
	v_mfma_f32_16x16x32_bf16 v[22:25], v[168:171], v[210:213], v[22:25]
	v_mfma_f32_16x16x32_bf16 v[18:21], v[176:179], v[210:213], v[18:21]
	v_mfma_f32_16x16x32_bf16 v[6:9], v[168:171], v[218:221], v[6:9]
	v_mfma_f32_16x16x32_bf16 v[2:5], v[176:179], v[218:221], v[2:5]
	v_mfma_f32_16x16x32_bf16 v[54:57], v[172:175], v[188:191], v[54:57]
	v_mfma_f32_16x16x32_bf16 v[50:53], v[180:183], v[188:191], v[50:53]
	v_mfma_f32_16x16x32_bf16 v[38:41], v[172:175], v[198:201], v[38:41]
	v_mfma_f32_16x16x32_bf16 v[34:37], v[180:183], v[198:201], v[34:37]
	v_mfma_f32_16x16x32_bf16 v[22:25], v[172:175], v[214:217], v[22:25]
	v_mfma_f32_16x16x32_bf16 v[18:21], v[180:183], v[214:217], v[18:21]
	v_mfma_f32_16x16x32_bf16 v[6:9], v[172:175], v[222:225], v[6:9]
	v_mfma_f32_16x16x32_bf16 v[2:5], v[180:183], v[222:225], v[2:5]
	s_setprio 0
	s_barrier
	s_add_u32 s30, s30, 0x100
	s_addc_u32 s31, s31, 0
	s_add_u32 s15, s15, 0x100
	s_addc_u32 s17, s17, 0
	s_cmp_ge_i32 s29, s68
	s_mov_b32 s19, s29
	s_cbranch_scc0 .LBB0_2547
	s_branch .Lpeeldone_1
.LBB0_2547:
	ds_read_b128 v[152:155], v148
	ds_read_b128 v[156:159], v148 offset:1024
	ds_read_b128 v[160:163], v148 offset:2048
	ds_read_b128 v[164:167], v148 offset:3072
	ds_read_b128 v[168:171], v149
	ds_read_b128 v[172:175], v149 offset:1024
	ds_read_b128 v[176:179], v149 offset:2048
	ds_read_b128 v[180:183], v149 offset:3072
	s_add_i32 s29, s19, 2
	s_add_u32 s34, s30, 0xfff80080
	s_addc_u32 s35, s31, -1
	s_cmp_eq_u32 s28, s19
	s_cselect_b32 s37, s21, s35
	s_cselect_b32 s36, s20, s34
	s_cselect_b32 s35, s23, s17
	s_cselect_b32 s34, s22, s15
	v_lshl_add_u64 v[144:145], s[30:31], 0, v[140:141]
	s_add_i32 m0, s27, 0xc000
	ds_read_b128 v[184:187], v150
	ds_read_b128 v[188:191], v150 offset:1024
	ds_read_b128 v[192:195], v150 offset:2048
	ds_read_b128 v[198:201], v150 offset:3072
	ds_read_b128 v[210:213], v150 offset:4096
	ds_read_b128 v[214:217], v150 offset:5120
	ds_read_b128 v[218:221], v150 offset:6144
	ds_read_b128 v[222:225], v150 offset:7168
	global_load_lds_dwordx4 v[144:145], off
	v_lshl_add_u64 v[144:145], s[30:31], 0, v[142:143]
	s_add_i32 m0, s27, 0xe000
	s_nop 0
	global_load_lds_dwordx4 v[144:145], off
	s_waitcnt vmcnt(8)
	s_waitcnt lgkmcnt(0)
	s_barrier
	s_setprio 1
	v_mfma_f32_16x16x32_bf16 v[126:129], v[152:155], v[184:187], v[126:129]
	v_mfma_f32_16x16x32_bf16 v[122:125], v[160:163], v[184:187], v[122:125]
	v_mfma_f32_16x16x32_bf16 v[110:113], v[152:155], v[192:195], v[110:113]
	v_mfma_f32_16x16x32_bf16 v[106:109], v[160:163], v[192:195], v[106:109]
	v_mfma_f32_16x16x32_bf16 v[94:97], v[152:155], v[210:213], v[94:97]
	v_mfma_f32_16x16x32_bf16 v[90:93], v[160:163], v[210:213], v[90:93]
	v_mfma_f32_16x16x32_bf16 v[78:81], v[152:155], v[218:221], v[78:81]
	v_mfma_f32_16x16x32_bf16 v[74:77], v[160:163], v[218:221], v[74:77]
	v_mfma_f32_16x16x32_bf16 v[126:129], v[156:159], v[188:191], v[126:129]
	v_mfma_f32_16x16x32_bf16 v[122:125], v[164:167], v[188:191], v[122:125]
	v_mfma_f32_16x16x32_bf16 v[110:113], v[156:159], v[198:201], v[110:113]
	v_mfma_f32_16x16x32_bf16 v[106:109], v[164:167], v[198:201], v[106:109]
	v_mfma_f32_16x16x32_bf16 v[94:97], v[156:159], v[214:217], v[94:97]
	v_mfma_f32_16x16x32_bf16 v[90:93], v[164:167], v[214:217], v[90:93]
	v_mfma_f32_16x16x32_bf16 v[78:81], v[156:159], v[222:225], v[78:81]
	v_mfma_f32_16x16x32_bf16 v[74:77], v[164:167], v[222:225], v[74:77]
	s_setprio 0
	s_setprio 1
	v_mfma_f32_16x16x32_bf16 v[118:121], v[168:171], v[184:187], v[118:121]
	v_mfma_f32_16x16x32_bf16 v[114:117], v[176:179], v[184:187], v[114:117]
	v_mfma_f32_16x16x32_bf16 v[102:105], v[168:171], v[192:195], v[102:105]
	v_mfma_f32_16x16x32_bf16 v[98:101], v[176:179], v[192:195], v[98:101]
	v_mfma_f32_16x16x32_bf16 v[86:89], v[168:171], v[210:213], v[86:89]
	v_mfma_f32_16x16x32_bf16 v[82:85], v[176:179], v[210:213], v[82:85]
	v_mfma_f32_16x16x32_bf16 v[70:73], v[168:171], v[218:221], v[70:73]
	v_mfma_f32_16x16x32_bf16 v[66:69], v[176:179], v[218:221], v[66:69]
	v_mfma_f32_16x16x32_bf16 v[118:121], v[172:175], v[188:191], v[118:121]
	v_mfma_f32_16x16x32_bf16 v[114:117], v[180:183], v[188:191], v[114:117]
	v_mfma_f32_16x16x32_bf16 v[102:105], v[172:175], v[198:201], v[102:105]
	v_mfma_f32_16x16x32_bf16 v[98:101], v[180:183], v[198:201], v[98:101]
	v_mfma_f32_16x16x32_bf16 v[86:89], v[172:175], v[214:217], v[86:89]
	v_mfma_f32_16x16x32_bf16 v[82:85], v[180:183], v[214:217], v[82:85]
	v_mfma_f32_16x16x32_bf16 v[70:73], v[172:175], v[222:225], v[70:73]
	v_mfma_f32_16x16x32_bf16 v[66:69], v[180:183], v[222:225], v[66:69]
	s_setprio 0
	s_barrier
	s_add_i32 s19, s60, s33
	v_lshl_add_u64 v[144:145], s[34:35], 0, v[132:133]
	s_mov_b32 m0, s19
	ds_read_b128 v[184:187], v150 offset:16384
	ds_read_b128 v[188:191], v150 offset:17408
	ds_read_b128 v[192:195], v150 offset:18432
	ds_read_b128 v[198:201], v150 offset:19456
	ds_read_b128 v[210:213], v150 offset:20480
	ds_read_b128 v[214:217], v150 offset:21504
	ds_read_b128 v[218:221], v150 offset:22528
	ds_read_b128 v[222:225], v150 offset:23552
	global_load_lds_dwordx4 v[144:145], off
	s_add_i32 m0, s19, 0x2000
	s_add_u32 s38, s34, 0x80000
	v_lshl_add_u64 v[202:203], s[34:35], 0, v[136:137]
	s_addc_u32 s39, s35, 0
	s_add_i32 s19, s61, s33
	global_load_lds_dwordx4 v[202:203], off
	v_lshl_add_u64 v[206:207], s[38:39], 0, v[132:133]
	s_mov_b32 m0, s19
	v_lshl_add_u64 v[226:227], s[36:37], 0, v[134:135]
	global_load_lds_dwordx4 v[206:207], off
	v_lshl_add_u64 v[206:207], s[38:39], 0, v[136:137]
	s_add_i32 m0, s19, 0x2000
	s_nop 0
	global_load_lds_dwordx4 v[206:207], off
	v_lshl_add_u64 v[206:207], s[36:37], 0, v[130:131]
	s_mov_b32 m0, s27
	s_nop 0
	global_load_lds_dwordx4 v[206:207], off
	s_mov_b32 m0, s41
	s_nop 0
	global_load_lds_dwordx4 v[226:227], off
	s_waitcnt vmcnt(8)
	s_waitcnt lgkmcnt(0)
	s_barrier
	s_setprio 1
	v_mfma_f32_16x16x32_bf16 v[62:65], v[152:155], v[184:187], v[62:65]
	v_mfma_f32_16x16x32_bf16 v[58:61], v[160:163], v[184:187], v[58:61]
	v_mfma_f32_16x16x32_bf16 v[46:49], v[152:155], v[192:195], v[46:49]
	v_mfma_f32_16x16x32_bf16 v[42:45], v[160:163], v[192:195], v[42:45]
	v_mfma_f32_16x16x32_bf16 v[30:33], v[152:155], v[210:213], v[30:33]
	v_mfma_f32_16x16x32_bf16 v[26:29], v[160:163], v[210:213], v[26:29]
	v_mfma_f32_16x16x32_bf16 v[14:17], v[152:155], v[218:221], v[14:17]
	v_mfma_f32_16x16x32_bf16 v[10:13], v[160:163], v[218:221], v[10:13]
	v_mfma_f32_16x16x32_bf16 v[62:65], v[156:159], v[188:191], v[62:65]
	v_mfma_f32_16x16x32_bf16 v[58:61], v[164:167], v[188:191], v[58:61]
	v_mfma_f32_16x16x32_bf16 v[46:49], v[156:159], v[198:201], v[46:49]
	v_mfma_f32_16x16x32_bf16 v[42:45], v[164:167], v[198:201], v[42:45]
	v_mfma_f32_16x16x32_bf16 v[30:33], v[156:159], v[214:217], v[30:33]
	v_mfma_f32_16x16x32_bf16 v[26:29], v[164:167], v[214:217], v[26:29]
	v_mfma_f32_16x16x32_bf16 v[14:17], v[156:159], v[222:225], v[14:17]
	v_mfma_f32_16x16x32_bf16 v[10:13], v[164:167], v[222:225], v[10:13]
	s_setprio 0
	s_setprio 1
	v_mfma_f32_16x16x32_bf16 v[54:57], v[168:171], v[184:187], v[54:57]
	v_mfma_f32_16x16x32_bf16 v[50:53], v[176:179], v[184:187], v[50:53]
	v_mfma_f32_16x16x32_bf16 v[38:41], v[168:171], v[192:195], v[38:41]
	v_mfma_f32_16x16x32_bf16 v[34:37], v[176:179], v[192:195], v[34:37]
	v_mfma_f32_16x16x32_bf16 v[22:25], v[168:171], v[210:213], v[22:25]
	v_mfma_f32_16x16x32_bf16 v[18:21], v[176:179], v[210:213], v[18:21]
	v_mfma_f32_16x16x32_bf16 v[6:9], v[168:171], v[218:221], v[6:9]
	v_mfma_f32_16x16x32_bf16 v[2:5], v[176:179], v[218:221], v[2:5]
	v_mfma_f32_16x16x32_bf16 v[54:57], v[172:175], v[188:191], v[54:57]
	v_mfma_f32_16x16x32_bf16 v[50:53], v[180:183], v[188:191], v[50:53]
	v_mfma_f32_16x16x32_bf16 v[38:41], v[172:175], v[198:201], v[38:41]
	v_mfma_f32_16x16x32_bf16 v[34:37], v[180:183], v[198:201], v[34:37]
	v_mfma_f32_16x16x32_bf16 v[22:25], v[172:175], v[214:217], v[22:25]
	v_mfma_f32_16x16x32_bf16 v[18:21], v[180:183], v[214:217], v[18:21]
	v_mfma_f32_16x16x32_bf16 v[6:9], v[172:175], v[222:225], v[6:9]
	v_mfma_f32_16x16x32_bf16 v[2:5], v[180:183], v[222:225], v[2:5]
	s_setprio 0
	s_barrier
	s_add_i32 s19, 0, 0x18000
	v_add_u32_e32 v151, s19, v146
	s_add_i32 s38, 0, 0x1c000
	ds_read_b128 v[152:155], v151
	ds_read_b128 v[156:159], v151 offset:1024
	ds_read_b128 v[160:163], v151 offset:2048
	ds_read_b128 v[164:167], v151 offset:3072
	v_add_u32_e32 v151, s38, v146
	ds_read_b128 v[168:171], v151
	ds_read_b128 v[172:175], v151 offset:1024
	ds_read_b128 v[176:179], v151 offset:2048
	ds_read_b128 v[180:183], v151 offset:3072
	s_add_u32 s36, s36, 0x80000
	s_addc_u32 s37, s37, 0
	s_mov_b32 m0, s42
	v_lshl_add_u64 v[228:229], s[36:37], 0, v[130:131]
	ds_read_b128 v[184:187], v150 offset:32768
	ds_read_b128 v[188:191], v150 offset:33792
	ds_read_b128 v[192:195], v150 offset:34816
	ds_read_b128 v[198:201], v150 offset:35840
	ds_read_b128 v[210:213], v150 offset:36864
	ds_read_b128 v[214:217], v150 offset:37888
	ds_read_b128 v[218:221], v150 offset:38912
	ds_read_b128 v[222:225], v150 offset:39936
	global_load_lds_dwordx4 v[228:229], off
	v_lshl_add_u64 v[228:229], s[36:37], 0, v[134:135]
	s_mov_b32 m0, s43
	s_nop 0
	global_load_lds_dwordx4 v[228:229], off
	s_waitcnt vmcnt(8)
	s_waitcnt lgkmcnt(0)
	s_barrier
	s_setprio 1
	v_mfma_f32_16x16x32_bf16 v[126:129], v[152:155], v[184:187], v[126:129]
	v_mfma_f32_16x16x32_bf16 v[122:125], v[160:163], v[184:187], v[122:125]
	v_mfma_f32_16x16x32_bf16 v[110:113], v[152:155], v[192:195], v[110:113]
	v_mfma_f32_16x16x32_bf16 v[106:109], v[160:163], v[192:195], v[106:109]
	v_mfma_f32_16x16x32_bf16 v[94:97], v[152:155], v[210:213], v[94:97]
	v_mfma_f32_16x16x32_bf16 v[90:93], v[160:163], v[210:213], v[90:93]
	v_mfma_f32_16x16x32_bf16 v[78:81], v[152:155], v[218:221], v[78:81]
	v_mfma_f32_16x16x32_bf16 v[74:77], v[160:163], v[218:221], v[74:77]
	v_mfma_f32_16x16x32_bf16 v[126:129], v[156:159], v[188:191], v[126:129]
	v_mfma_f32_16x16x32_bf16 v[122:125], v[164:167], v[188:191], v[122:125]
	v_mfma_f32_16x16x32_bf16 v[110:113], v[156:159], v[198:201], v[110:113]
	v_mfma_f32_16x16x32_bf16 v[106:109], v[164:167], v[198:201], v[106:109]
	v_mfma_f32_16x16x32_bf16 v[94:97], v[156:159], v[214:217], v[94:97]
	v_mfma_f32_16x16x32_bf16 v[90:93], v[164:167], v[214:217], v[90:93]
	v_mfma_f32_16x16x32_bf16 v[78:81], v[156:159], v[222:225], v[78:81]
	v_mfma_f32_16x16x32_bf16 v[74:77], v[164:167], v[222:225], v[74:77]
	s_setprio 0
	s_setprio 1
	v_mfma_f32_16x16x32_bf16 v[118:121], v[168:171], v[184:187], v[118:121]
	v_mfma_f32_16x16x32_bf16 v[114:117], v[176:179], v[184:187], v[114:117]
	v_mfma_f32_16x16x32_bf16 v[102:105], v[168:171], v[192:195], v[102:105]
	v_mfma_f32_16x16x32_bf16 v[98:101], v[176:179], v[192:195], v[98:101]
	v_mfma_f32_16x16x32_bf16 v[86:89], v[168:171], v[210:213], v[86:89]
	v_mfma_f32_16x16x32_bf16 v[82:85], v[176:179], v[210:213], v[82:85]
	v_mfma_f32_16x16x32_bf16 v[70:73], v[168:171], v[218:221], v[70:73]
	v_mfma_f32_16x16x32_bf16 v[66:69], v[176:179], v[218:221], v[66:69]
	v_mfma_f32_16x16x32_bf16 v[118:121], v[172:175], v[188:191], v[118:121]
	v_mfma_f32_16x16x32_bf16 v[114:117], v[180:183], v[188:191], v[114:117]
	v_mfma_f32_16x16x32_bf16 v[102:105], v[172:175], v[198:201], v[102:105]
	v_mfma_f32_16x16x32_bf16 v[98:101], v[180:183], v[198:201], v[98:101]
	v_mfma_f32_16x16x32_bf16 v[86:89], v[172:175], v[214:217], v[86:89]
	v_mfma_f32_16x16x32_bf16 v[82:85], v[180:183], v[214:217], v[82:85]
	v_mfma_f32_16x16x32_bf16 v[70:73], v[172:175], v[222:225], v[70:73]
	v_mfma_f32_16x16x32_bf16 v[66:69], v[180:183], v[222:225], v[66:69]
	s_setprio 0
	s_barrier
	s_add_i32 s19, s19, s33
	v_lshl_add_u64 v[144:145], v[144:145], 0, s[10:11]
	s_mov_b32 m0, s19
	ds_read_b128 v[184:187], v150 offset:49152
	ds_read_b128 v[188:191], v150 offset:50176
	ds_read_b128 v[192:195], v150 offset:51200
	ds_read_b128 v[198:201], v150 offset:52224
	ds_read_b128 v[210:213], v150 offset:53248
	ds_read_b128 v[214:217], v150 offset:54272
	ds_read_b128 v[218:221], v150 offset:55296
	ds_read_b128 v[222:225], v150 offset:56320
	global_load_lds_dwordx4 v[144:145], off
	s_add_i32 m0, s19, 0x2000
	s_add_u32 s34, s34, 0x80080
	v_lshl_add_u64 v[144:145], v[202:203], 0, s[10:11]
	s_addc_u32 s35, s35, 0
	s_add_i32 s19, s38, s33
	global_load_lds_dwordx4 v[144:145], off
	v_lshl_add_u64 v[144:145], s[34:35], 0, v[132:133]
	s_mov_b32 m0, s19
	s_nop 0
	global_load_lds_dwordx4 v[144:145], off
	v_lshl_add_u64 v[144:145], s[34:35], 0, v[136:137]
	s_add_i32 m0, s19, 0x2000
	s_nop 0
	global_load_lds_dwordx4 v[144:145], off
	v_lshl_add_u64 v[144:145], v[206:207], 0, s[10:11]
	s_mov_b32 m0, s51
	s_nop 0
	global_load_lds_dwordx4 v[144:145], off
	v_lshl_add_u64 v[144:145], v[226:227], 0, s[10:11]
	s_mov_b32 m0, s52
	s_nop 0
	global_load_lds_dwordx4 v[144:145], off
	s_waitcnt vmcnt(8)
	s_waitcnt lgkmcnt(0)
	s_barrier
	s_setprio 1
	v_mfma_f32_16x16x32_bf16 v[62:65], v[152:155], v[184:187], v[62:65]
	v_mfma_f32_16x16x32_bf16 v[58:61], v[160:163], v[184:187], v[58:61]
	v_mfma_f32_16x16x32_bf16 v[46:49], v[152:155], v[192:195], v[46:49]
	v_mfma_f32_16x16x32_bf16 v[42:45], v[160:163], v[192:195], v[42:45]
	v_mfma_f32_16x16x32_bf16 v[30:33], v[152:155], v[210:213], v[30:33]
	v_mfma_f32_16x16x32_bf16 v[26:29], v[160:163], v[210:213], v[26:29]
	v_mfma_f32_16x16x32_bf16 v[14:17], v[152:155], v[218:221], v[14:17]
	v_mfma_f32_16x16x32_bf16 v[10:13], v[160:163], v[218:221], v[10:13]
	v_mfma_f32_16x16x32_bf16 v[62:65], v[156:159], v[188:191], v[62:65]
	v_mfma_f32_16x16x32_bf16 v[58:61], v[164:167], v[188:191], v[58:61]
	v_mfma_f32_16x16x32_bf16 v[46:49], v[156:159], v[198:201], v[46:49]
	v_mfma_f32_16x16x32_bf16 v[42:45], v[164:167], v[198:201], v[42:45]
	v_mfma_f32_16x16x32_bf16 v[30:33], v[156:159], v[214:217], v[30:33]
	v_mfma_f32_16x16x32_bf16 v[26:29], v[164:167], v[214:217], v[26:29]
	v_mfma_f32_16x16x32_bf16 v[14:17], v[156:159], v[222:225], v[14:17]
	v_mfma_f32_16x16x32_bf16 v[10:13], v[164:167], v[222:225], v[10:13]
	s_setprio 0
	s_setprio 1
	v_mfma_f32_16x16x32_bf16 v[54:57], v[168:171], v[184:187], v[54:57]
	v_mfma_f32_16x16x32_bf16 v[50:53], v[176:179], v[184:187], v[50:53]
	v_mfma_f32_16x16x32_bf16 v[38:41], v[168:171], v[192:195], v[38:41]
	v_mfma_f32_16x16x32_bf16 v[34:37], v[176:179], v[192:195], v[34:37]
	v_mfma_f32_16x16x32_bf16 v[22:25], v[168:171], v[210:213], v[22:25]
	v_mfma_f32_16x16x32_bf16 v[18:21], v[176:179], v[210:213], v[18:21]
	v_mfma_f32_16x16x32_bf16 v[6:9], v[168:171], v[218:221], v[6:9]
	v_mfma_f32_16x16x32_bf16 v[2:5], v[176:179], v[218:221], v[2:5]
	v_mfma_f32_16x16x32_bf16 v[54:57], v[172:175], v[188:191], v[54:57]
	v_mfma_f32_16x16x32_bf16 v[50:53], v[180:183], v[188:191], v[50:53]
	v_mfma_f32_16x16x32_bf16 v[38:41], v[172:175], v[198:201], v[38:41]
	v_mfma_f32_16x16x32_bf16 v[34:37], v[180:183], v[198:201], v[34:37]
	v_mfma_f32_16x16x32_bf16 v[22:25], v[172:175], v[214:217], v[22:25]
	v_mfma_f32_16x16x32_bf16 v[18:21], v[180:183], v[214:217], v[18:21]
	v_mfma_f32_16x16x32_bf16 v[6:9], v[172:175], v[222:225], v[6:9]
	v_mfma_f32_16x16x32_bf16 v[2:5], v[180:183], v[222:225], v[2:5]
	s_setprio 0
	s_barrier
	s_add_u32 s30, s30, 0x100
	s_addc_u32 s31, s31, 0
	s_add_u32 s15, s15, 0x100
	s_addc_u32 s17, s17, 0
	s_cmp_ge_i32 s29, s68
	s_mov_b32 s19, s29
	s_cbranch_scc0 .LBB0_2547

.Lpeel_0:
	ds_read_b128 v[144:147], v170
	ds_read_b128 v[148:151], v170 offset:1024
	ds_read_b128 v[152:155], v170 offset:2048
	ds_read_b128 v[156:159], v170 offset:3072
	ds_read_b128 v[160:163], v171
	ds_read_b128 v[164:167], v171 offset:1024
	ds_read_b128 v[174:177], v171 offset:2048
	ds_read_b128 v[178:181], v171 offset:3072
	s_add_i32 s30, s26, 2
	s_add_u32 s27, s24, 0xffea0080
	s_addc_u32 s28, s25, -1
	s_cmp_eq_u32 s22, s26
	s_cselect_b32 s26, s20, s17
	s_cselect_b32 s29, s19, s28
	s_cselect_b32 s28, s18, s27
	s_cselect_b32 s27, s21, s23
	v_lshl_add_u64 v[214:215], s[24:25], 0, v[140:141]
	s_add_i32 m0, s34, 0xc000
	ds_read_b128 v[182:185], v172
	ds_read_b128 v[186:189], v172 offset:1024
	ds_read_b128 v[190:193], v172 offset:2048
	ds_read_b128 v[194:197], v172 offset:3072
	ds_read_b128 v[198:201], v172 offset:4096
	ds_read_b128 v[202:205], v172 offset:5120
	ds_read_b128 v[206:209], v172 offset:6144
	ds_read_b128 v[210:213], v172 offset:7168
	global_load_lds_dwordx4 v[214:215], off
	v_lshl_add_u64 v[214:215], s[24:25], 0, v[142:143]
	s_add_i32 m0, s34, 0xe000
	s_nop 0
	global_load_lds_dwordx4 v[214:215], off
	s_waitcnt vmcnt(8)
	s_waitcnt lgkmcnt(0)
	s_barrier
	s_setprio 1
	v_mfma_f32_16x16x32_bf16 v[126:129], v[144:147], v[182:185], 0
	v_mfma_f32_16x16x32_bf16 v[122:125], v[152:155], v[182:185], 0
	v_mfma_f32_16x16x32_bf16 v[118:121], v[144:147], v[190:193], 0
	v_mfma_f32_16x16x32_bf16 v[110:113], v[152:155], v[190:193], 0
	v_mfma_f32_16x16x32_bf16 v[94:97], v[144:147], v[198:201], 0
	v_mfma_f32_16x16x32_bf16 v[90:93], v[152:155], v[198:201], 0
	v_mfma_f32_16x16x32_bf16 v[82:85], v[144:147], v[206:209], 0
	v_mfma_f32_16x16x32_bf16 v[74:77], v[152:155], v[206:209], 0
	v_mfma_f32_16x16x32_bf16 v[126:129], v[148:151], v[186:189], v[126:129]
	v_mfma_f32_16x16x32_bf16 v[122:125], v[156:159], v[186:189], v[122:125]
	v_mfma_f32_16x16x32_bf16 v[118:121], v[148:151], v[194:197], v[118:121]
	v_mfma_f32_16x16x32_bf16 v[110:113], v[156:159], v[194:197], v[110:113]
	v_mfma_f32_16x16x32_bf16 v[94:97], v[148:151], v[202:205], v[94:97]
	v_mfma_f32_16x16x32_bf16 v[90:93], v[156:159], v[202:205], v[90:93]
	v_mfma_f32_16x16x32_bf16 v[82:85], v[148:151], v[210:213], v[82:85]
	v_mfma_f32_16x16x32_bf16 v[74:77], v[156:159], v[210:213], v[74:77]
	s_setprio 0
	s_setprio 1
	v_mfma_f32_16x16x32_bf16 v[114:117], v[160:163], v[182:185], 0
	v_mfma_f32_16x16x32_bf16 v[106:109], v[174:177], v[182:185], 0
	v_mfma_f32_16x16x32_bf16 v[102:105], v[160:163], v[190:193], 0
	v_mfma_f32_16x16x32_bf16 v[98:101], v[174:177], v[190:193], 0
	v_mfma_f32_16x16x32_bf16 v[86:89], v[160:163], v[198:201], 0
	v_mfma_f32_16x16x32_bf16 v[78:81], v[174:177], v[198:201], 0
	v_mfma_f32_16x16x32_bf16 v[70:73], v[160:163], v[206:209], 0
	v_mfma_f32_16x16x32_bf16 v[66:69], v[174:177], v[206:209], 0
	v_mfma_f32_16x16x32_bf16 v[114:117], v[164:167], v[186:189], v[114:117]
	v_mfma_f32_16x16x32_bf16 v[106:109], v[178:181], v[186:189], v[106:109]
	v_mfma_f32_16x16x32_bf16 v[102:105], v[164:167], v[194:197], v[102:105]
	v_mfma_f32_16x16x32_bf16 v[98:101], v[178:181], v[194:197], v[98:101]
	v_mfma_f32_16x16x32_bf16 v[86:89], v[164:167], v[202:205], v[86:89]
	v_mfma_f32_16x16x32_bf16 v[78:81], v[178:181], v[202:205], v[78:81]
	v_mfma_f32_16x16x32_bf16 v[70:73], v[164:167], v[210:213], v[70:73]
	v_mfma_f32_16x16x32_bf16 v[66:69], v[178:181], v[210:213], v[66:69]
	s_setprio 0
	s_barrier
	s_add_i32 s31, s57, s33
	v_lshl_add_u64 v[214:215], s[26:27], 0, v[132:133]
	s_mov_b32 m0, s31
	ds_read_b128 v[182:185], v172 offset:16384
	ds_read_b128 v[186:189], v172 offset:17408
	ds_read_b128 v[190:193], v172 offset:18432
	ds_read_b128 v[194:197], v172 offset:19456
	ds_read_b128 v[198:201], v172 offset:20480
	ds_read_b128 v[202:205], v172 offset:21504
	ds_read_b128 v[206:209], v172 offset:22528
	ds_read_b128 v[210:213], v172 offset:23552
	global_load_lds_dwordx4 v[214:215], off
	s_add_i32 m0, s31, 0x2000
	s_add_u32 s68, s26, 0x160000
	v_lshl_add_u64 v[216:217], s[26:27], 0, v[136:137]
	s_addc_u32 s69, s27, 0
	s_add_i32 s31, s58, s33
	global_load_lds_dwordx4 v[216:217], off
	v_lshl_add_u64 v[218:219], s[68:69], 0, v[132:133]
	s_mov_b32 m0, s31
	v_lshl_add_u64 v[220:221], s[28:29], 0, v[134:135]
	global_load_lds_dwordx4 v[218:219], off
	v_lshl_add_u64 v[218:219], s[68:69], 0, v[136:137]
	s_add_i32 m0, s31, 0x2000
	s_nop 0
	global_load_lds_dwordx4 v[218:219], off
	v_lshl_add_u64 v[218:219], s[28:29], 0, v[130:131]
	s_mov_b32 m0, s34
	s_nop 0
	global_load_lds_dwordx4 v[218:219], off
	s_mov_b32 m0, s35
	s_nop 0
	global_load_lds_dwordx4 v[220:221], off
	s_waitcnt vmcnt(8)
	s_waitcnt lgkmcnt(0)
	s_barrier
	s_setprio 1
	v_mfma_f32_16x16x32_bf16 v[62:65], v[144:147], v[182:185], 0
	v_mfma_f32_16x16x32_bf16 v[58:61], v[152:155], v[182:185], 0
	v_mfma_f32_16x16x32_bf16 v[50:53], v[144:147], v[190:193], 0
	v_mfma_f32_16x16x32_bf16 v[42:45], v[152:155], v[190:193], 0
	v_mfma_f32_16x16x32_bf16 v[30:33], v[144:147], v[198:201], 0
	v_mfma_f32_16x16x32_bf16 v[26:29], v[152:155], v[198:201], 0
	v_mfma_f32_16x16x32_bf16 v[18:21], v[144:147], v[206:209], 0
	v_mfma_f32_16x16x32_bf16 v[10:13], v[152:155], v[206:209], 0
	v_mfma_f32_16x16x32_bf16 v[62:65], v[148:151], v[186:189], v[62:65]
	v_mfma_f32_16x16x32_bf16 v[58:61], v[156:159], v[186:189], v[58:61]
	v_mfma_f32_16x16x32_bf16 v[50:53], v[148:151], v[194:197], v[50:53]
	v_mfma_f32_16x16x32_bf16 v[42:45], v[156:159], v[194:197], v[42:45]
	v_mfma_f32_16x16x32_bf16 v[30:33], v[148:151], v[202:205], v[30:33]
	v_mfma_f32_16x16x32_bf16 v[26:29], v[156:159], v[202:205], v[26:29]
	v_mfma_f32_16x16x32_bf16 v[18:21], v[148:151], v[210:213], v[18:21]
	v_mfma_f32_16x16x32_bf16 v[10:13], v[156:159], v[210:213], v[10:13]
	s_setprio 0
	s_setprio 1
	v_mfma_f32_16x16x32_bf16 v[54:57], v[160:163], v[182:185], 0
	v_mfma_f32_16x16x32_bf16 v[46:49], v[174:177], v[182:185], 0
	v_mfma_f32_16x16x32_bf16 v[38:41], v[160:163], v[190:193], 0
	v_mfma_f32_16x16x32_bf16 v[34:37], v[174:177], v[190:193], 0
	v_mfma_f32_16x16x32_bf16 v[22:25], v[160:163], v[198:201], 0
	v_mfma_f32_16x16x32_bf16 v[14:17], v[174:177], v[198:201], 0
	v_mfma_f32_16x16x32_bf16 v[6:9], v[160:163], v[206:209], 0
	v_mfma_f32_16x16x32_bf16 v[2:5], v[174:177], v[206:209], 0
	v_mfma_f32_16x16x32_bf16 v[54:57], v[164:167], v[186:189], v[54:57]
	v_mfma_f32_16x16x32_bf16 v[46:49], v[178:181], v[186:189], v[46:49]
	v_mfma_f32_16x16x32_bf16 v[38:41], v[164:167], v[194:197], v[38:41]
	v_mfma_f32_16x16x32_bf16 v[34:37], v[178:181], v[194:197], v[34:37]
	v_mfma_f32_16x16x32_bf16 v[22:25], v[164:167], v[202:205], v[22:25]
	v_mfma_f32_16x16x32_bf16 v[14:17], v[178:181], v[202:205], v[14:17]
	v_mfma_f32_16x16x32_bf16 v[6:9], v[164:167], v[210:213], v[6:9]
	v_mfma_f32_16x16x32_bf16 v[2:5], v[178:181], v[210:213], v[2:5]
	s_setprio 0
	s_barrier
	s_add_i32 s31, 0, 0x18000
	s_add_i32 s68, 0, 0x1c000
	v_add_u32_e32 v156, s31, v168
	v_add_u32_e32 v173, s68, v168
	ds_read_b128 v[144:147], v156
	ds_read_b128 v[148:151], v156 offset:1024
	ds_read_b128 v[152:155], v156 offset:2048
	ds_read_b128 v[156:159], v156 offset:3072
	ds_read_b128 v[160:163], v173
	ds_read_b128 v[164:167], v173 offset:1024
	ds_read_b128 v[174:177], v173 offset:2048
	ds_read_b128 v[178:181], v173 offset:3072
	s_add_u32 s28, s28, 0x160000
	s_addc_u32 s29, s29, 0
	s_mov_b32 m0, s36
	v_lshl_add_u64 v[222:223], s[28:29], 0, v[130:131]
	ds_read_b128 v[182:185], v172 offset:32768
	ds_read_b128 v[186:189], v172 offset:33792
	ds_read_b128 v[190:193], v172 offset:34816
	ds_read_b128 v[194:197], v172 offset:35840
	ds_read_b128 v[198:201], v172 offset:36864
	ds_read_b128 v[202:205], v172 offset:37888
	ds_read_b128 v[206:209], v172 offset:38912
	ds_read_b128 v[210:213], v172 offset:39936
	global_load_lds_dwordx4 v[222:223], off
	v_lshl_add_u64 v[222:223], s[28:29], 0, v[134:135]
	s_mov_b32 m0, s37
	s_nop 0
	global_load_lds_dwordx4 v[222:223], off
	s_waitcnt vmcnt(8)
	s_waitcnt lgkmcnt(0)
	s_barrier
	s_setprio 1
	v_mfma_f32_16x16x32_bf16 v[126:129], v[144:147], v[182:185], v[126:129]
	v_mfma_f32_16x16x32_bf16 v[122:125], v[152:155], v[182:185], v[122:125]
	v_mfma_f32_16x16x32_bf16 v[118:121], v[144:147], v[190:193], v[118:121]
	v_mfma_f32_16x16x32_bf16 v[110:113], v[152:155], v[190:193], v[110:113]
	v_mfma_f32_16x16x32_bf16 v[94:97], v[144:147], v[198:201], v[94:97]
	v_mfma_f32_16x16x32_bf16 v[90:93], v[152:155], v[198:201], v[90:93]
	v_mfma_f32_16x16x32_bf16 v[82:85], v[144:147], v[206:209], v[82:85]
	v_mfma_f32_16x16x32_bf16 v[74:77], v[152:155], v[206:209], v[74:77]
	v_mfma_f32_16x16x32_bf16 v[126:129], v[148:151], v[186:189], v[126:129]
	v_mfma_f32_16x16x32_bf16 v[122:125], v[156:159], v[186:189], v[122:125]
	v_mfma_f32_16x16x32_bf16 v[118:121], v[148:151], v[194:197], v[118:121]
	v_mfma_f32_16x16x32_bf16 v[110:113], v[156:159], v[194:197], v[110:113]
	v_mfma_f32_16x16x32_bf16 v[94:97], v[148:151], v[202:205], v[94:97]
	v_mfma_f32_16x16x32_bf16 v[90:93], v[156:159], v[202:205], v[90:93]
	v_mfma_f32_16x16x32_bf16 v[82:85], v[148:151], v[210:213], v[82:85]
	v_mfma_f32_16x16x32_bf16 v[74:77], v[156:159], v[210:213], v[74:77]
	s_setprio 0
	s_setprio 1
	v_mfma_f32_16x16x32_bf16 v[114:117], v[160:163], v[182:185], v[114:117]
	v_mfma_f32_16x16x32_bf16 v[106:109], v[174:177], v[182:185], v[106:109]
	v_mfma_f32_16x16x32_bf16 v[102:105], v[160:163], v[190:193], v[102:105]
	v_mfma_f32_16x16x32_bf16 v[98:101], v[174:177], v[190:193], v[98:101]
	v_mfma_f32_16x16x32_bf16 v[86:89], v[160:163], v[198:201], v[86:89]
	v_mfma_f32_16x16x32_bf16 v[78:81], v[174:177], v[198:201], v[78:81]
	v_mfma_f32_16x16x32_bf16 v[70:73], v[160:163], v[206:209], v[70:73]
	v_mfma_f32_16x16x32_bf16 v[66:69], v[174:177], v[206:209], v[66:69]
	v_mfma_f32_16x16x32_bf16 v[114:117], v[164:167], v[186:189], v[114:117]
	v_mfma_f32_16x16x32_bf16 v[106:109], v[178:181], v[186:189], v[106:109]
	v_mfma_f32_16x16x32_bf16 v[102:105], v[164:167], v[194:197], v[102:105]
	v_mfma_f32_16x16x32_bf16 v[98:101], v[178:181], v[194:197], v[98:101]
	v_mfma_f32_16x16x32_bf16 v[86:89], v[164:167], v[202:205], v[86:89]
	v_mfma_f32_16x16x32_bf16 v[78:81], v[178:181], v[202:205], v[78:81]
	v_mfma_f32_16x16x32_bf16 v[70:73], v[164:167], v[210:213], v[70:73]
	v_mfma_f32_16x16x32_bf16 v[66:69], v[178:181], v[210:213], v[66:69]
	s_setprio 0
	s_barrier
	s_add_i32 s28, s31, s33
	v_lshl_add_u64 v[214:215], v[214:215], 0, s[12:13]
	s_mov_b32 m0, s28
	ds_read_b128 v[182:185], v172 offset:49152
	ds_read_b128 v[186:189], v172 offset:50176
	ds_read_b128 v[190:193], v172 offset:51200
	ds_read_b128 v[194:197], v172 offset:52224
	ds_read_b128 v[198:201], v172 offset:53248
	ds_read_b128 v[202:205], v172 offset:54272
	ds_read_b128 v[206:209], v172 offset:55296
	ds_read_b128 v[210:213], v172 offset:56320
	global_load_lds_dwordx4 v[214:215], off
	s_add_i32 m0, s28, 0x2000
	s_add_u32 s26, s26, 0x160080
	v_lshl_add_u64 v[214:215], v[216:217], 0, s[12:13]
	s_addc_u32 s27, s27, 0
	s_add_i32 s28, s68, s33
	global_load_lds_dwordx4 v[214:215], off
	v_lshl_add_u64 v[214:215], s[26:27], 0, v[132:133]
	s_mov_b32 m0, s28
	s_nop 0
	global_load_lds_dwordx4 v[214:215], off
	v_lshl_add_u64 v[214:215], s[26:27], 0, v[136:137]
	s_add_i32 m0, s28, 0x2000
	s_nop 0
	global_load_lds_dwordx4 v[214:215], off
	v_lshl_add_u64 v[214:215], v[218:219], 0, s[12:13]
	s_mov_b32 m0, s47
	s_nop 0
	global_load_lds_dwordx4 v[214:215], off
	v_lshl_add_u64 v[214:215], v[220:221], 0, s[12:13]
	s_mov_b32 m0, s48
	s_nop 0
	global_load_lds_dwordx4 v[214:215], off
	s_waitcnt vmcnt(8)
	s_waitcnt lgkmcnt(0)
	s_barrier
	s_setprio 1
	v_mfma_f32_16x16x32_bf16 v[62:65], v[144:147], v[182:185], v[62:65]
	v_mfma_f32_16x16x32_bf16 v[58:61], v[152:155], v[182:185], v[58:61]
	v_mfma_f32_16x16x32_bf16 v[50:53], v[144:147], v[190:193], v[50:53]
	v_mfma_f32_16x16x32_bf16 v[42:45], v[152:155], v[190:193], v[42:45]
	v_mfma_f32_16x16x32_bf16 v[30:33], v[144:147], v[198:201], v[30:33]
	v_mfma_f32_16x16x32_bf16 v[26:29], v[152:155], v[198:201], v[26:29]
	v_mfma_f32_16x16x32_bf16 v[18:21], v[144:147], v[206:209], v[18:21]
	v_mfma_f32_16x16x32_bf16 v[10:13], v[152:155], v[206:209], v[10:13]
	v_mfma_f32_16x16x32_bf16 v[62:65], v[148:151], v[186:189], v[62:65]
	v_mfma_f32_16x16x32_bf16 v[58:61], v[156:159], v[186:189], v[58:61]
	v_mfma_f32_16x16x32_bf16 v[50:53], v[148:151], v[194:197], v[50:53]
	v_mfma_f32_16x16x32_bf16 v[42:45], v[156:159], v[194:197], v[42:45]
	v_mfma_f32_16x16x32_bf16 v[30:33], v[148:151], v[202:205], v[30:33]
	v_mfma_f32_16x16x32_bf16 v[26:29], v[156:159], v[202:205], v[26:29]
	v_mfma_f32_16x16x32_bf16 v[18:21], v[148:151], v[210:213], v[18:21]
	v_mfma_f32_16x16x32_bf16 v[10:13], v[156:159], v[210:213], v[10:13]
	s_setprio 0
	s_setprio 1
	v_mfma_f32_16x16x32_bf16 v[54:57], v[160:163], v[182:185], v[54:57]
	v_mfma_f32_16x16x32_bf16 v[46:49], v[174:177], v[182:185], v[46:49]
	v_mfma_f32_16x16x32_bf16 v[38:41], v[160:163], v[190:193], v[38:41]
	v_mfma_f32_16x16x32_bf16 v[34:37], v[174:177], v[190:193], v[34:37]
	v_mfma_f32_16x16x32_bf16 v[22:25], v[160:163], v[198:201], v[22:25]
	v_mfma_f32_16x16x32_bf16 v[14:17], v[174:177], v[198:201], v[14:17]
	v_mfma_f32_16x16x32_bf16 v[6:9], v[160:163], v[206:209], v[6:9]
	v_mfma_f32_16x16x32_bf16 v[2:5], v[174:177], v[206:209], v[2:5]
	v_mfma_f32_16x16x32_bf16 v[54:57], v[164:167], v[186:189], v[54:57]
	v_mfma_f32_16x16x32_bf16 v[46:49], v[178:181], v[186:189], v[46:49]
	v_mfma_f32_16x16x32_bf16 v[38:41], v[164:167], v[194:197], v[38:41]
	v_mfma_f32_16x16x32_bf16 v[34:37], v[178:181], v[194:197], v[34:37]
	v_mfma_f32_16x16x32_bf16 v[22:25], v[164:167], v[202:205], v[22:25]
	v_mfma_f32_16x16x32_bf16 v[14:17], v[178:181], v[202:205], v[14:17]
	v_mfma_f32_16x16x32_bf16 v[6:9], v[164:167], v[210:213], v[6:9]
	v_mfma_f32_16x16x32_bf16 v[2:5], v[178:181], v[210:213], v[2:5]
	s_setprio 0
	s_barrier
	s_add_u32 s24, s24, 0x100
	s_addc_u32 s25, s25, 0
	s_add_u32 s17, s17, 0x100
	s_addc_u32 s23, s23, 0
	s_cmp_ge_i32 s30, s67
	s_mov_b32 s26, s30
	s_cbranch_scc0 .LBB0_2683
	s_branch .Lpeeldone_0
.LBB0_2683:
	ds_read_b128 v[144:147], v170
	ds_read_b128 v[148:151], v170 offset:1024
	ds_read_b128 v[152:155], v170 offset:2048
	ds_read_b128 v[156:159], v170 offset:3072
	ds_read_b128 v[160:163], v171
	ds_read_b128 v[164:167], v171 offset:1024
	ds_read_b128 v[174:177], v171 offset:2048
	ds_read_b128 v[178:181], v171 offset:3072
	s_add_i32 s30, s26, 2
	s_add_u32 s27, s24, 0xffea0080
	s_addc_u32 s28, s25, -1
	s_cmp_eq_u32 s22, s26
	s_cselect_b32 s26, s20, s17
	s_cselect_b32 s29, s19, s28
	s_cselect_b32 s28, s18, s27
	s_cselect_b32 s27, s21, s23
	v_lshl_add_u64 v[214:215], s[24:25], 0, v[140:141]
	s_add_i32 m0, s34, 0xc000
	ds_read_b128 v[182:185], v172
	ds_read_b128 v[186:189], v172 offset:1024
	ds_read_b128 v[190:193], v172 offset:2048
	ds_read_b128 v[194:197], v172 offset:3072
	ds_read_b128 v[198:201], v172 offset:4096
	ds_read_b128 v[202:205], v172 offset:5120
	ds_read_b128 v[206:209], v172 offset:6144
	ds_read_b128 v[210:213], v172 offset:7168
	global_load_lds_dwordx4 v[214:215], off
	v_lshl_add_u64 v[214:215], s[24:25], 0, v[142:143]
	s_add_i32 m0, s34, 0xe000
	s_nop 0
	global_load_lds_dwordx4 v[214:215], off
	s_waitcnt vmcnt(8)
	s_waitcnt lgkmcnt(0)
	s_barrier
	s_setprio 1
	v_mfma_f32_16x16x32_bf16 v[126:129], v[144:147], v[182:185], v[126:129]
	v_mfma_f32_16x16x32_bf16 v[122:125], v[152:155], v[182:185], v[122:125]
	v_mfma_f32_16x16x32_bf16 v[118:121], v[144:147], v[190:193], v[118:121]
	v_mfma_f32_16x16x32_bf16 v[110:113], v[152:155], v[190:193], v[110:113]
	v_mfma_f32_16x16x32_bf16 v[94:97], v[144:147], v[198:201], v[94:97]
	v_mfma_f32_16x16x32_bf16 v[90:93], v[152:155], v[198:201], v[90:93]
	v_mfma_f32_16x16x32_bf16 v[82:85], v[144:147], v[206:209], v[82:85]
	v_mfma_f32_16x16x32_bf16 v[74:77], v[152:155], v[206:209], v[74:77]
	v_mfma_f32_16x16x32_bf16 v[126:129], v[148:151], v[186:189], v[126:129]
	v_mfma_f32_16x16x32_bf16 v[122:125], v[156:159], v[186:189], v[122:125]
	v_mfma_f32_16x16x32_bf16 v[118:121], v[148:151], v[194:197], v[118:121]
	v_mfma_f32_16x16x32_bf16 v[110:113], v[156:159], v[194:197], v[110:113]
	v_mfma_f32_16x16x32_bf16 v[94:97], v[148:151], v[202:205], v[94:97]
	v_mfma_f32_16x16x32_bf16 v[90:93], v[156:159], v[202:205], v[90:93]
	v_mfma_f32_16x16x32_bf16 v[82:85], v[148:151], v[210:213], v[82:85]
	v_mfma_f32_16x16x32_bf16 v[74:77], v[156:159], v[210:213], v[74:77]
	s_setprio 0
	s_setprio 1
	v_mfma_f32_16x16x32_bf16 v[114:117], v[160:163], v[182:185], v[114:117]
	v_mfma_f32_16x16x32_bf16 v[106:109], v[174:177], v[182:185], v[106:109]
	v_mfma_f32_16x16x32_bf16 v[102:105], v[160:163], v[190:193], v[102:105]
	v_mfma_f32_16x16x32_bf16 v[98:101], v[174:177], v[190:193], v[98:101]
	v_mfma_f32_16x16x32_bf16 v[86:89], v[160:163], v[198:201], v[86:89]
	v_mfma_f32_16x16x32_bf16 v[78:81], v[174:177], v[198:201], v[78:81]
	v_mfma_f32_16x16x32_bf16 v[70:73], v[160:163], v[206:209], v[70:73]
	v_mfma_f32_16x16x32_bf16 v[66:69], v[174:177], v[206:209], v[66:69]
	v_mfma_f32_16x16x32_bf16 v[114:117], v[164:167], v[186:189], v[114:117]
	v_mfma_f32_16x16x32_bf16 v[106:109], v[178:181], v[186:189], v[106:109]
	v_mfma_f32_16x16x32_bf16 v[102:105], v[164:167], v[194:197], v[102:105]
	v_mfma_f32_16x16x32_bf16 v[98:101], v[178:181], v[194:197], v[98:101]
	v_mfma_f32_16x16x32_bf16 v[86:89], v[164:167], v[202:205], v[86:89]
	v_mfma_f32_16x16x32_bf16 v[78:81], v[178:181], v[202:205], v[78:81]
	v_mfma_f32_16x16x32_bf16 v[70:73], v[164:167], v[210:213], v[70:73]
	v_mfma_f32_16x16x32_bf16 v[66:69], v[178:181], v[210:213], v[66:69]
	s_setprio 0
	s_barrier
	s_add_i32 s31, s57, s33
	v_lshl_add_u64 v[214:215], s[26:27], 0, v[132:133]
	s_mov_b32 m0, s31
	ds_read_b128 v[182:185], v172 offset:16384
	ds_read_b128 v[186:189], v172 offset:17408
	ds_read_b128 v[190:193], v172 offset:18432
	ds_read_b128 v[194:197], v172 offset:19456
	ds_read_b128 v[198:201], v172 offset:20480
	ds_read_b128 v[202:205], v172 offset:21504
	ds_read_b128 v[206:209], v172 offset:22528
	ds_read_b128 v[210:213], v172 offset:23552
	global_load_lds_dwordx4 v[214:215], off
	s_add_i32 m0, s31, 0x2000
	s_add_u32 s68, s26, 0x160000
	v_lshl_add_u64 v[216:217], s[26:27], 0, v[136:137]
	s_addc_u32 s69, s27, 0
	s_add_i32 s31, s58, s33
	global_load_lds_dwordx4 v[216:217], off
	v_lshl_add_u64 v[218:219], s[68:69], 0, v[132:133]
	s_mov_b32 m0, s31
	v_lshl_add_u64 v[220:221], s[28:29], 0, v[134:135]
	global_load_lds_dwordx4 v[218:219], off
	v_lshl_add_u64 v[218:219], s[68:69], 0, v[136:137]
	s_add_i32 m0, s31, 0x2000
	s_nop 0
	global_load_lds_dwordx4 v[218:219], off
	v_lshl_add_u64 v[218:219], s[28:29], 0, v[130:131]
	s_mov_b32 m0, s34
	s_nop 0
	global_load_lds_dwordx4 v[218:219], off
	s_mov_b32 m0, s35
	s_nop 0
	global_load_lds_dwordx4 v[220:221], off
	s_waitcnt vmcnt(8)
	s_waitcnt lgkmcnt(0)
	s_barrier
	s_setprio 1
	v_mfma_f32_16x16x32_bf16 v[62:65], v[144:147], v[182:185], v[62:65]
	v_mfma_f32_16x16x32_bf16 v[58:61], v[152:155], v[182:185], v[58:61]
	v_mfma_f32_16x16x32_bf16 v[50:53], v[144:147], v[190:193], v[50:53]
	v_mfma_f32_16x16x32_bf16 v[42:45], v[152:155], v[190:193], v[42:45]
	v_mfma_f32_16x16x32_bf16 v[30:33], v[144:147], v[198:201], v[30:33]
	v_mfma_f32_16x16x32_bf16 v[26:29], v[152:155], v[198:201], v[26:29]
	v_mfma_f32_16x16x32_bf16 v[18:21], v[144:147], v[206:209], v[18:21]
	v_mfma_f32_16x16x32_bf16 v[10:13], v[152:155], v[206:209], v[10:13]
	v_mfma_f32_16x16x32_bf16 v[62:65], v[148:151], v[186:189], v[62:65]
	v_mfma_f32_16x16x32_bf16 v[58:61], v[156:159], v[186:189], v[58:61]
	v_mfma_f32_16x16x32_bf16 v[50:53], v[148:151], v[194:197], v[50:53]
	v_mfma_f32_16x16x32_bf16 v[42:45], v[156:159], v[194:197], v[42:45]
	v_mfma_f32_16x16x32_bf16 v[30:33], v[148:151], v[202:205], v[30:33]
	v_mfma_f32_16x16x32_bf16 v[26:29], v[156:159], v[202:205], v[26:29]
	v_mfma_f32_16x16x32_bf16 v[18:21], v[148:151], v[210:213], v[18:21]
	v_mfma_f32_16x16x32_bf16 v[10:13], v[156:159], v[210:213], v[10:13]
	s_setprio 0
	s_setprio 1
	v_mfma_f32_16x16x32_bf16 v[54:57], v[160:163], v[182:185], v[54:57]
	v_mfma_f32_16x16x32_bf16 v[46:49], v[174:177], v[182:185], v[46:49]
	v_mfma_f32_16x16x32_bf16 v[38:41], v[160:163], v[190:193], v[38:41]
	v_mfma_f32_16x16x32_bf16 v[34:37], v[174:177], v[190:193], v[34:37]
	v_mfma_f32_16x16x32_bf16 v[22:25], v[160:163], v[198:201], v[22:25]
	v_mfma_f32_16x16x32_bf16 v[14:17], v[174:177], v[198:201], v[14:17]
	v_mfma_f32_16x16x32_bf16 v[6:9], v[160:163], v[206:209], v[6:9]
	v_mfma_f32_16x16x32_bf16 v[2:5], v[174:177], v[206:209], v[2:5]
	v_mfma_f32_16x16x32_bf16 v[54:57], v[164:167], v[186:189], v[54:57]
	v_mfma_f32_16x16x32_bf16 v[46:49], v[178:181], v[186:189], v[46:49]
	v_mfma_f32_16x16x32_bf16 v[38:41], v[164:167], v[194:197], v[38:41]
	v_mfma_f32_16x16x32_bf16 v[34:37], v[178:181], v[194:197], v[34:37]
	v_mfma_f32_16x16x32_bf16 v[22:25], v[164:167], v[202:205], v[22:25]
	v_mfma_f32_16x16x32_bf16 v[14:17], v[178:181], v[202:205], v[14:17]
	v_mfma_f32_16x16x32_bf16 v[6:9], v[164:167], v[210:213], v[6:9]
	v_mfma_f32_16x16x32_bf16 v[2:5], v[178:181], v[210:213], v[2:5]
	s_setprio 0
	s_barrier
	s_add_i32 s31, 0, 0x18000
	s_add_i32 s68, 0, 0x1c000
	v_add_u32_e32 v156, s31, v168
	v_add_u32_e32 v173, s68, v168
	ds_read_b128 v[144:147], v156
	ds_read_b128 v[148:151], v156 offset:1024
	ds_read_b128 v[152:155], v156 offset:2048
	ds_read_b128 v[156:159], v156 offset:3072
	ds_read_b128 v[160:163], v173
	ds_read_b128 v[164:167], v173 offset:1024
	ds_read_b128 v[174:177], v173 offset:2048
	ds_read_b128 v[178:181], v173 offset:3072
	s_add_u32 s28, s28, 0x160000
	s_addc_u32 s29, s29, 0
	s_mov_b32 m0, s36
	v_lshl_add_u64 v[222:223], s[28:29], 0, v[130:131]
	ds_read_b128 v[182:185], v172 offset:32768
	ds_read_b128 v[186:189], v172 offset:33792
	ds_read_b128 v[190:193], v172 offset:34816
	ds_read_b128 v[194:197], v172 offset:35840
	ds_read_b128 v[198:201], v172 offset:36864
	ds_read_b128 v[202:205], v172 offset:37888
	ds_read_b128 v[206:209], v172 offset:38912
	ds_read_b128 v[210:213], v172 offset:39936
	global_load_lds_dwordx4 v[222:223], off
	v_lshl_add_u64 v[222:223], s[28:29], 0, v[134:135]
	s_mov_b32 m0, s37
	s_nop 0
	global_load_lds_dwordx4 v[222:223], off
	s_waitcnt vmcnt(8)
	s_waitcnt lgkmcnt(0)
	s_barrier
	s_setprio 1
	v_mfma_f32_16x16x32_bf16 v[126:129], v[144:147], v[182:185], v[126:129]
	v_mfma_f32_16x16x32_bf16 v[122:125], v[152:155], v[182:185], v[122:125]
	v_mfma_f32_16x16x32_bf16 v[118:121], v[144:147], v[190:193], v[118:121]
	v_mfma_f32_16x16x32_bf16 v[110:113], v[152:155], v[190:193], v[110:113]
	v_mfma_f32_16x16x32_bf16 v[94:97], v[144:147], v[198:201], v[94:97]
	v_mfma_f32_16x16x32_bf16 v[90:93], v[152:155], v[198:201], v[90:93]
	v_mfma_f32_16x16x32_bf16 v[82:85], v[144:147], v[206:209], v[82:85]
	v_mfma_f32_16x16x32_bf16 v[74:77], v[152:155], v[206:209], v[74:77]
	v_mfma_f32_16x16x32_bf16 v[126:129], v[148:151], v[186:189], v[126:129]
	v_mfma_f32_16x16x32_bf16 v[122:125], v[156:159], v[186:189], v[122:125]
	v_mfma_f32_16x16x32_bf16 v[118:121], v[148:151], v[194:197], v[118:121]
	v_mfma_f32_16x16x32_bf16 v[110:113], v[156:159], v[194:197], v[110:113]
	v_mfma_f32_16x16x32_bf16 v[94:97], v[148:151], v[202:205], v[94:97]
	v_mfma_f32_16x16x32_bf16 v[90:93], v[156:159], v[202:205], v[90:93]
	v_mfma_f32_16x16x32_bf16 v[82:85], v[148:151], v[210:213], v[82:85]
	v_mfma_f32_16x16x32_bf16 v[74:77], v[156:159], v[210:213], v[74:77]
	s_setprio 0
	s_setprio 1
	v_mfma_f32_16x16x32_bf16 v[114:117], v[160:163], v[182:185], v[114:117]
	v_mfma_f32_16x16x32_bf16 v[106:109], v[174:177], v[182:185], v[106:109]
	v_mfma_f32_16x16x32_bf16 v[102:105], v[160:163], v[190:193], v[102:105]
	v_mfma_f32_16x16x32_bf16 v[98:101], v[174:177], v[190:193], v[98:101]
	v_mfma_f32_16x16x32_bf16 v[86:89], v[160:163], v[198:201], v[86:89]
	v_mfma_f32_16x16x32_bf16 v[78:81], v[174:177], v[198:201], v[78:81]
	v_mfma_f32_16x16x32_bf16 v[70:73], v[160:163], v[206:209], v[70:73]
	v_mfma_f32_16x16x32_bf16 v[66:69], v[174:177], v[206:209], v[66:69]
	v_mfma_f32_16x16x32_bf16 v[114:117], v[164:167], v[186:189], v[114:117]
	v_mfma_f32_16x16x32_bf16 v[106:109], v[178:181], v[186:189], v[106:109]
	v_mfma_f32_16x16x32_bf16 v[102:105], v[164:167], v[194:197], v[102:105]
	v_mfma_f32_16x16x32_bf16 v[98:101], v[178:181], v[194:197], v[98:101]
	v_mfma_f32_16x16x32_bf16 v[86:89], v[164:167], v[202:205], v[86:89]
	v_mfma_f32_16x16x32_bf16 v[78:81], v[178:181], v[202:205], v[78:81]
	v_mfma_f32_16x16x32_bf16 v[70:73], v[164:167], v[210:213], v[70:73]
	v_mfma_f32_16x16x32_bf16 v[66:69], v[178:181], v[210:213], v[66:69]
	s_setprio 0
	s_barrier
	s_add_i32 s28, s31, s33
	v_lshl_add_u64 v[214:215], v[214:215], 0, s[12:13]
	s_mov_b32 m0, s28
	ds_read_b128 v[182:185], v172 offset:49152
	ds_read_b128 v[186:189], v172 offset:50176
	ds_read_b128 v[190:193], v172 offset:51200
	ds_read_b128 v[194:197], v172 offset:52224
	ds_read_b128 v[198:201], v172 offset:53248
	ds_read_b128 v[202:205], v172 offset:54272
	ds_read_b128 v[206:209], v172 offset:55296
	ds_read_b128 v[210:213], v172 offset:56320
	global_load_lds_dwordx4 v[214:215], off
	s_add_i32 m0, s28, 0x2000
	s_add_u32 s26, s26, 0x160080
	v_lshl_add_u64 v[214:215], v[216:217], 0, s[12:13]
	s_addc_u32 s27, s27, 0
	s_add_i32 s28, s68, s33
	global_load_lds_dwordx4 v[214:215], off
	v_lshl_add_u64 v[214:215], s[26:27], 0, v[132:133]
	s_mov_b32 m0, s28
	s_nop 0
	global_load_lds_dwordx4 v[214:215], off
	v_lshl_add_u64 v[214:215], s[26:27], 0, v[136:137]
	s_add_i32 m0, s28, 0x2000
	s_nop 0
	global_load_lds_dwordx4 v[214:215], off
	v_lshl_add_u64 v[214:215], v[218:219], 0, s[12:13]
	s_mov_b32 m0, s47
	s_nop 0
	global_load_lds_dwordx4 v[214:215], off
	v_lshl_add_u64 v[214:215], v[220:221], 0, s[12:13]
	s_mov_b32 m0, s48
	s_nop 0
	global_load_lds_dwordx4 v[214:215], off
	s_waitcnt vmcnt(8)
	s_waitcnt lgkmcnt(0)
	s_barrier
	s_setprio 1
	v_mfma_f32_16x16x32_bf16 v[62:65], v[144:147], v[182:185], v[62:65]
	v_mfma_f32_16x16x32_bf16 v[58:61], v[152:155], v[182:185], v[58:61]
	v_mfma_f32_16x16x32_bf16 v[50:53], v[144:147], v[190:193], v[50:53]
	v_mfma_f32_16x16x32_bf16 v[42:45], v[152:155], v[190:193], v[42:45]
	v_mfma_f32_16x16x32_bf16 v[30:33], v[144:147], v[198:201], v[30:33]
	v_mfma_f32_16x16x32_bf16 v[26:29], v[152:155], v[198:201], v[26:29]
	v_mfma_f32_16x16x32_bf16 v[18:21], v[144:147], v[206:209], v[18:21]
	v_mfma_f32_16x16x32_bf16 v[10:13], v[152:155], v[206:209], v[10:13]
	v_mfma_f32_16x16x32_bf16 v[62:65], v[148:151], v[186:189], v[62:65]
	v_mfma_f32_16x16x32_bf16 v[58:61], v[156:159], v[186:189], v[58:61]
	v_mfma_f32_16x16x32_bf16 v[50:53], v[148:151], v[194:197], v[50:53]
	v_mfma_f32_16x16x32_bf16 v[42:45], v[156:159], v[194:197], v[42:45]
	v_mfma_f32_16x16x32_bf16 v[30:33], v[148:151], v[202:205], v[30:33]
	v_mfma_f32_16x16x32_bf16 v[26:29], v[156:159], v[202:205], v[26:29]
	v_mfma_f32_16x16x32_bf16 v[18:21], v[148:151], v[210:213], v[18:21]
	v_mfma_f32_16x16x32_bf16 v[10:13], v[156:159], v[210:213], v[10:13]
	s_setprio 0
	s_setprio 1
	v_mfma_f32_16x16x32_bf16 v[54:57], v[160:163], v[182:185], v[54:57]
	v_mfma_f32_16x16x32_bf16 v[46:49], v[174:177], v[182:185], v[46:49]
	v_mfma_f32_16x16x32_bf16 v[38:41], v[160:163], v[190:193], v[38:41]
	v_mfma_f32_16x16x32_bf16 v[34:37], v[174:177], v[190:193], v[34:37]
	v_mfma_f32_16x16x32_bf16 v[22:25], v[160:163], v[198:201], v[22:25]
	v_mfma_f32_16x16x32_bf16 v[14:17], v[174:177], v[198:201], v[14:17]
	v_mfma_f32_16x16x32_bf16 v[6:9], v[160:163], v[206:209], v[6:9]
	v_mfma_f32_16x16x32_bf16 v[2:5], v[174:177], v[206:209], v[2:5]
	v_mfma_f32_16x16x32_bf16 v[54:57], v[164:167], v[186:189], v[54:57]
	v_mfma_f32_16x16x32_bf16 v[46:49], v[178:181], v[186:189], v[46:49]
	v_mfma_f32_16x16x32_bf16 v[38:41], v[164:167], v[194:197], v[38:41]
	v_mfma_f32_16x16x32_bf16 v[34:37], v[178:181], v[194:197], v[34:37]
	v_mfma_f32_16x16x32_bf16 v[22:25], v[164:167], v[202:205], v[22:25]
	v_mfma_f32_16x16x32_bf16 v[14:17], v[178:181], v[202:205], v[14:17]
	v_mfma_f32_16x16x32_bf16 v[6:9], v[164:167], v[210:213], v[6:9]
	v_mfma_f32_16x16x32_bf16 v[2:5], v[178:181], v[210:213], v[2:5]
	s_setprio 0
	s_barrier
	s_add_u32 s24, s24, 0x100
	s_addc_u32 s25, s25, 0
	s_add_u32 s17, s17, 0x100
	s_addc_u32 s23, s23, 0
	s_cmp_ge_i32 s30, s67
	s_mov_b32 s26, s30
	s_cbranch_scc0 .LBB0_2683
